# top-k stage-1 load ladder de-serialised: the one-at-a-time score loads behind vmcnt(0) get their own registers (v233+) and are issued in batches
# speedup vs baseline: 1.0172x; 1.0032x over previous
; DEV int tid_l() { int t = threadIdx.x; asm volatile("" : "+v"(t)); return t; }
; DEV void stage1(unsigned (&L)[16], const float* sp) {
;   float sv[128];
; #pragma unroll
;   for (int i = 0; i < 128; ++i) sv[i] = sp[(size_t)i * 128];
; DEV void topk_group(int hg, const float* scoresT, int* idxo, float* go) {
;   const int tid = tid_l(), token = tid & 127, hl = tid >> 7;
;   unsigned LA[16], LB[16], LC[16];
;   stage1(LA, scoresT + (size_t)(hl * 256) * 128 + token);
;   stage1(LB, scoresT + (size_t)(hl * 256 + 128) * 128 + token);
.LBB0_292:
	v_mov_b32_e32 v4, v176
	s_waitcnt vmcnt(0)
	s_waitcnt vmcnt(0) lgkmcnt(0)
	s_barrier
	v_readlane_b32 s0, v231, 21
	v_ashrrev_i32_e32 v11, 7, v4
	v_lshlrev_b32_e32 v0, 8, v11
	v_ashrrev_i32_e32 v1, 31, v0
	v_and_b32_e32 v23, 0x7f, v4
	v_lshlrev_b64 v[2:3], 9, v[0:1]
	v_readlane_b32 s1, v231, 22
	v_lshlrev_b32_e32 v120, 2, v23
	v_or_b32_e32 v0, 0x80, v0
	v_lshl_add_u64 v[2:3], s[0:1], 0, v[2:3]
	v_lshl_add_u64 v[2:3], v[2:3], 0, v[120:121]
	v_add_co_u32_e32 v6, vcc, 0x2000, v2
	s_nop 1
	v_addc_co_u32_e32 v7, vcc, 0, v3, vcc
	flat_load_dword v122, v[6:7]
	flat_load_dword v119, v[6:7] offset:512
	flat_load_dword v117, v[6:7] offset:1024
	flat_load_dword v118, v[6:7] offset:1536
	flat_load_dword v114, v[6:7] offset:2048
	flat_load_dword v113, v[6:7] offset:2560
	flat_load_dword v115, v[6:7] offset:3072
	flat_load_dword v116, v[6:7] offset:3584
	v_add_co_u32_e32 v6, vcc, 0x3000, v2
	s_nop 1
	v_addc_co_u32_e32 v7, vcc, 0, v3, vcc
	flat_load_dword v108, v[6:7]
	flat_load_dword v107, v[6:7] offset:512
	flat_load_dword v105, v[6:7] offset:1024
	flat_load_dword v106, v[6:7] offset:1536
	flat_load_dword v110, v[6:7] offset:2048
	flat_load_dword v109, v[6:7] offset:2560
	flat_load_dword v111, v[6:7] offset:3072
	flat_load_dword v112, v[6:7] offset:3584
	v_add_co_u32_e32 v6, vcc, s17, v2
	s_waitcnt vmcnt(0) lgkmcnt(0)
	v_not_b32_e32 v170, v108
	v_addc_co_u32_e32 v7, vcc, 0, v3, vcc
	flat_load_dword v104, v[6:7]
	flat_load_dword v103, v[6:7] offset:512
	flat_load_dword v101, v[6:7] offset:1024
	flat_load_dword v102, v[6:7] offset:1536
	flat_load_dword v98, v[6:7] offset:2048
	flat_load_dword v97, v[6:7] offset:2560
	flat_load_dword v99, v[6:7] offset:3072
	flat_load_dword v100, v[6:7] offset:3584
	v_add_co_u32_e32 v6, vcc, s47, v2
	v_not_b32_e32 v153, v110
	s_nop 0
	v_addc_co_u32_e32 v7, vcc, 0, v3, vcc
	flat_load_dword v92, v[6:7]
	flat_load_dword v91, v[6:7] offset:512
	flat_load_dword v89, v[6:7] offset:1024
	flat_load_dword v90, v[6:7] offset:1536
	flat_load_dword v94, v[6:7] offset:2048
	flat_load_dword v93, v[6:7] offset:2560
	flat_load_dword v95, v[6:7] offset:3072
	flat_load_dword v96, v[6:7] offset:3584
	v_add_co_u32_e32 v6, vcc, s18, v2
	v_not_b32_e32 v152, v112
	s_nop 0
	v_addc_co_u32_e32 v7, vcc, 0, v3, vcc
	flat_load_dword v88, v[6:7]
	flat_load_dword v87, v[6:7] offset:512
	flat_load_dword v85, v[6:7] offset:1024
	flat_load_dword v86, v[6:7] offset:1536
	flat_load_dword v82, v[6:7] offset:2048
	flat_load_dword v81, v[6:7] offset:2560
	flat_load_dword v83, v[6:7] offset:3072
	flat_load_dword v84, v[6:7] offset:3584
	v_add_co_u32_e32 v6, vcc, s48, v2
	v_not_b32_e32 v171, v106
	s_nop 0
	v_addc_co_u32_e32 v7, vcc, 0, v3, vcc
	flat_load_dword v75, v[6:7]
	flat_load_dword v74, v[6:7] offset:512
	flat_load_dword v72, v[6:7] offset:1024
	flat_load_dword v73, v[6:7] offset:1536
	flat_load_dword v77, v[6:7] offset:2048
	flat_load_dword v76, v[6:7] offset:2560
	flat_load_dword v79, v[6:7] offset:3072
	flat_load_dword v80, v[6:7] offset:3584
	v_add_co_u32_e32 v6, vcc, s28, v2
	s_nop 1
	v_addc_co_u32_e32 v7, vcc, 0, v3, vcc
	flat_load_dword v71, v[6:7]
	flat_load_dword v70, v[6:7] offset:512
	flat_load_dword v68, v[6:7] offset:1024
	flat_load_dword v69, v[6:7] offset:1536
	flat_load_dword v63, v[6:7] offset:2048
	flat_load_dword v62, v[6:7] offset:2560
	flat_load_dword v66, v[6:7] offset:3072
	flat_load_dword v67, v[6:7] offset:3584
	v_add_co_u32_e32 v6, vcc, s49, v2
	s_nop 1
	v_addc_co_u32_e32 v7, vcc, 0, v3, vcc
	flat_load_dword v57, v[6:7]
	flat_load_dword v56, v[6:7] offset:512
	flat_load_dword v54, v[6:7] offset:1024
	flat_load_dword v55, v[6:7] offset:1536
	flat_load_dword v59, v[6:7] offset:2048
	flat_load_dword v58, v[6:7] offset:2560
	flat_load_dword v60, v[6:7] offset:3072
	flat_load_dword v61, v[6:7] offset:3584
	v_add_co_u32_e32 v6, vcc, s19, v2
	s_nop 1
	v_addc_co_u32_e32 v7, vcc, 0, v3, vcc
	flat_load_dword v53, v[6:7]
	flat_load_dword v52, v[6:7] offset:512
	flat_load_dword v50, v[6:7] offset:1024
	flat_load_dword v51, v[6:7] offset:1536
	flat_load_dword v47, v[6:7] offset:2048
	flat_load_dword v46, v[6:7] offset:2560
	flat_load_dword v48, v[6:7] offset:3072
	flat_load_dword v49, v[6:7] offset:3584
	v_add_co_u32_e32 v6, vcc, s50, v2
	s_nop 1
	v_addc_co_u32_e32 v7, vcc, 0, v3, vcc
	flat_load_dword v41, v[6:7]
	flat_load_dword v40, v[6:7] offset:512
	flat_load_dword v38, v[6:7] offset:1024
	flat_load_dword v39, v[6:7] offset:1536
	flat_load_dword v43, v[6:7] offset:2048
	flat_load_dword v42, v[6:7] offset:2560
	flat_load_dword v44, v[6:7] offset:3072
	flat_load_dword v45, v[6:7] offset:3584
	v_add_co_u32_e32 v6, vcc, s29, v2
	s_nop 1
	v_addc_co_u32_e32 v7, vcc, 0, v3, vcc
	flat_load_dword v37, v[6:7]
	flat_load_dword v36, v[6:7] offset:512
	flat_load_dword v34, v[6:7] offset:1024
	flat_load_dword v35, v[6:7] offset:1536
	flat_load_dword v31, v[6:7] offset:2048
	flat_load_dword v30, v[6:7] offset:2560
	flat_load_dword v32, v[6:7] offset:3072
	flat_load_dword v33, v[6:7] offset:3584
	v_add_co_u32_e32 v6, vcc, s51, v2
	s_nop 1
	v_addc_co_u32_e32 v7, vcc, 0, v3, vcc
	flat_load_dword v25, v[6:7]
	flat_load_dword v24, v[6:7] offset:512
	flat_load_dword v21, v[6:7] offset:1024
	flat_load_dword v22, v[6:7] offset:1536
	flat_load_dword v27, v[6:7] offset:2048
	flat_load_dword v26, v[6:7] offset:2560
	flat_load_dword v28, v[6:7] offset:3072
	flat_load_dword v29, v[6:7] offset:3584
	v_add_co_u32_e32 v6, vcc, s30, v2
	s_nop 1
	v_addc_co_u32_e32 v7, vcc, 0, v3, vcc
	v_add_co_u32_e32 v124, vcc, s54, v2
	flat_load_dword v20, v[6:7]
	flat_load_dword v19, v[6:7] offset:512
	flat_load_dword v17, v[6:7] offset:1024
	flat_load_dword v18, v[6:7] offset:1536
	flat_load_dword v14, v[6:7] offset:2048
	flat_load_dword v13, v[6:7] offset:2560
	flat_load_dword v15, v[6:7] offset:3072
	flat_load_dword v16, v[6:7] offset:3584
	v_addc_co_u32_e32 v125, vcc, 0, v3, vcc
	flat_load_dword v7, v[124:125]
	flat_load_dword v6, v[124:125] offset:512
	flat_load_dword v1, v[124:125] offset:1024
	flat_load_dword v5, v[124:125] offset:1536
	flat_load_dword v9, v[124:125] offset:2048
	flat_load_dword v8, v[124:125] offset:2560
	flat_load_dword v10, v[124:125] offset:3072
	flat_load_dword v12, v[124:125] offset:3584
	flat_load_dword v123, v[2:3]
	flat_load_dword v126, v[2:3] offset:1536
	flat_load_dword v233, v[2:3] offset:512
	flat_load_dword v234, v[2:3] offset:1024
	flat_load_dword v235, v[2:3] offset:3584
	flat_load_dword v236, v[2:3] offset:3072
	flat_load_dword v237, v[2:3] offset:2048
	flat_load_dword v238, v[2:3] offset:2560
	s_waitcnt vmcnt(0) lgkmcnt(0)
; DEV unsigned fkey(float x) { const unsigned u = __float_as_uint(x); return (u & 0x80000000u) ? ~u : (u | 0x80000000u); }
; DEV float keyf(unsigned k) { const unsigned u = (k & 0x80000000u) ? (k & 0x7fffffffu) : ~k; return __uint_as_float(u); }
; DEV void bitonic_merge16_desc(unsigned (&v)[16]) {
; #pragma unroll
;   for (int j = 8; j >= 1; j >>= 1)
; #pragma unroll
;     for (int i = 0; i < 16; ++i) { const int l = i ^ j; if (l > i) cswap(v[i], v[l]); }
; }
; DEV void bitonic_sort16_desc(unsigned (&v)[16]) {
; #pragma unroll
;   for (int k = 2; k <= 16; k <<= 1)
; #pragma unroll
;     for (int j = k >> 1; j >= 1; j >>= 1)
; #pragma unroll
;       for (int i = 0; i < 16; ++i) { const int l = i ^ j; if (l > i) { if ((i & k) == 0) cswap(v[i], v[l]); else cswap(v[l], v[i]); } }
; }
; DEV void merge_top16(unsigned (&R)[16], const unsigned (&G)[16]) {
; #pragma unroll
;   for (int i = 0; i < 16; ++i) R[i] = max(R[i], G[15 - i]);
;   bitonic_merge16_desc(R);
; }
; DEV void stage1(unsigned (&L)[16], const float* sp) {
;   float sv[128];
; #pragma unroll
;   for (int i = 0; i < 128; ++i) sv[i] = sp[(size_t)i * 128];
; #pragma unroll
;   for (int i = 0; i < 128; i += 16) {
;     unsigned g[16];
; #pragma unroll
;     for (int e = 0; e < 16; ++e) g[e] = (fkey(sv[i + e]) & ~127u) | (unsigned)(127 - (i + e));
;     bitonic_sort16_desc(g);
;     if (i == 0) {
; #pragma unroll
;       for (int e = 0; e < 16; ++e) L[e] = g[e];
;     } else merge_top16(L, g);
;   }
; }
	v_cmp_gt_i32_e32 vcc, 0, v123
	v_not_b32_e32 v124, v123
	v_or_b32_e32 v123, 0x80000000, v123
	v_cndmask_b32_e32 v123, v123, v124, vcc
	v_not_b32_e32 v127, v126
	v_or_b32_e32 v123, 0x7f, v123
	s_waitcnt vmcnt(0) lgkmcnt(0)
	v_cmp_gt_i32_e32 vcc, 0, v233
	v_not_b32_e32 v125, v233
	v_or_b32_e32 v124, 0x80000000, v233
	v_cndmask_b32_e32 v124, v124, v125, vcc
	v_cmp_gt_i32_e32 vcc, 0, v126
	v_or_b32_e32 v126, 0x80000000, v126
	v_and_b32_e32 v124, 0xffffff80, v124
	v_cndmask_b32_e32 v126, v126, v127, vcc
	v_and_b32_e32 v126, 0xffffff80, v126
	v_or_b32_e32 v126, 0x7c, v126
	v_or_b32_e32 v124, 0x7e, v124
	v_max_u32_e32 v125, v123, v124
	v_min_u32_e32 v124, v123, v124
	s_waitcnt vmcnt(0) lgkmcnt(0)
	v_cmp_gt_i32_e32 vcc, 0, v234
	v_not_b32_e32 v128, v234
	v_or_b32_e32 v127, 0x80000000, v234
	v_cndmask_b32_e32 v127, v127, v128, vcc
	v_and_b32_e32 v127, 0xffffff80, v127
	v_or_b32_e32 v127, 0x7d, v127
	v_min_u32_e32 v128, v126, v127
	v_max_u32_e32 v126, v126, v127
	v_max_u32_e32 v130, v124, v126
	v_min_u32_e32 v124, v124, v126
	v_min_u32_e32 v139, v125, v128
	v_max_u32_e32 v129, v125, v128
	v_max_u32_e32 v123, v129, v130
	s_waitcnt vmcnt(0) lgkmcnt(0)
	v_cmp_gt_i32_e32 vcc, 0, v235
	v_not_b32_e32 v131, v235
	v_or_b32_e32 v127, 0x80000000, v235
	v_cndmask_b32_e32 v127, v127, v131, vcc
	v_and_b32_e32 v127, 0xffffff80, v127
	v_or_b32_e32 v127, 0x78, v127
	s_waitcnt vmcnt(0) lgkmcnt(0)
	v_cmp_gt_i32_e32 vcc, 0, v236
	v_not_b32_e32 v132, v236
	v_or_b32_e32 v131, 0x80000000, v236
	v_cndmask_b32_e32 v131, v131, v132, vcc
	v_and_b32_e32 v131, 0xffffff80, v131
	v_or_b32_e32 v131, 0x79, v131
	v_max_u32_e32 v133, v127, v131
	v_min_u32_e32 v137, v127, v131
	s_waitcnt vmcnt(0) lgkmcnt(0)
	v_cmp_gt_i32_e32 vcc, 0, v237
	v_not_b32_e32 v134, v237
	v_or_b32_e32 v132, 0x80000000, v237
	v_cndmask_b32_e32 v132, v132, v134, vcc
	v_and_b32_e32 v132, 0xffffff80, v132
	v_or_b32_e32 v132, 0x7b, v132
	s_waitcnt vmcnt(0) lgkmcnt(0)
	v_cmp_gt_i32_e32 vcc, 0, v238
	v_not_b32_e32 v135, v238
	v_or_b32_e32 v134, 0x80000000, v238
	v_cndmask_b32_e32 v134, v134, v135, vcc
	v_and_b32_e32 v134, 0xffffff80, v134
	v_or_b32_e32 v134, 0x7a, v134
	v_min_u32_e32 v135, v132, v134
	v_max_u32_e32 v134, v132, v134
	v_add_co_u32_e32 v2, vcc, s56, v2
	v_min_u32_e32 v136, v133, v135
	v_min_u32_e32 v138, v137, v134
	v_addc_co_u32_e32 v3, vcc, 0, v3, vcc
	flat_load_dword v239, v[2:3] offset:3584
	flat_load_dword v240, v[2:3] offset:1536
	flat_load_dword v241, v[2:3] offset:3072
	flat_load_dword v242, v[2:3] offset:2048
	flat_load_dword v243, v[2:3] offset:2560
	flat_load_dword v244, v[2:3]
	flat_load_dword v245, v[2:3] offset:512
	flat_load_dword v246, v[2:3] offset:1024
	v_min_u32_e32 v131, v136, v138
	v_max_u32_e32 v126, v133, v135
	v_max_u32_e32 v135, v136, v138
	v_max_u32_e32 v132, v139, v124
	v_min_u32_e32 v136, v139, v124
	v_max_u32_e32 v137, v137, v134
	v_min_u32_e32 v133, v126, v137
	v_min_u32_e32 v134, v129, v130
	v_max_u32_e32 v137, v126, v137
	v_max_u32_e32 v127, v123, v131
	v_max_u32_e32 v128, v132, v133
	v_max_u32_e32 v129, v134, v135
	v_max_u32_e32 v130, v136, v137
	v_min_u32_e32 v123, v123, v131
	v_min_u32_e32 v131, v132, v133
	v_min_u32_e32 v133, v134, v135
	v_min_u32_e32 v134, v136, v137
	v_max_u32_e32 v125, v127, v128
	v_max_u32_e32 v126, v129, v130
	v_max_u32_e32 v132, v123, v131
	v_max_u32_e32 v135, v133, v134
	v_min_u32_e32 v127, v127, v128
	v_min_u32_e32 v128, v129, v130
	v_min_u32_e32 v123, v123, v131
	v_min_u32_e32 v131, v133, v134
	v_max_u32_e32 v124, v125, v126
	v_max_u32_e32 v136, v132, v135
	v_max_u32_e32 v129, v127, v128
	v_max_u32_e32 v133, v123, v131
	v_min_u32_e32 v125, v125, v126
	v_min_u32_e32 v132, v132, v135
	v_min_u32_e32 v127, v127, v128
	v_min_u32_e32 v123, v123, v131
	s_waitcnt vmcnt(0) lgkmcnt(0)
	v_cmp_gt_i32_e32 vcc, 0, v239
	v_not_b32_e32 v139, v239
	v_or_b32_e32 v138, 0x80000000, v239
	v_cndmask_b32_e32 v138, v138, v139, vcc
	v_and_b32_e32 v138, 0xffffff80, v138
	v_or_b32_e32 v139, 0x70, v138
	v_not_b32_e32 v149, v240
	s_waitcnt vmcnt(0) lgkmcnt(0)
	v_cmp_gt_i32_e32 vcc, 0, v241
	v_not_b32_e32 v140, v241
	v_or_b32_e32 v138, 0x80000000, v241
	v_cndmask_b32_e32 v138, v138, v140, vcc
	v_and_b32_e32 v138, 0xffffff80, v138
	v_or_b32_e32 v141, 0x71, v138
	v_max_u32_e32 v138, v139, v141
	v_min_u32_e32 v143, v139, v141
	s_waitcnt vmcnt(0) lgkmcnt(0)
	v_cmp_gt_i32_e32 vcc, 0, v242
	v_not_b32_e32 v142, v242
	v_or_b32_e32 v140, 0x80000000, v242
	v_cndmask_b32_e32 v140, v140, v142, vcc
	v_and_b32_e32 v140, 0xffffff80, v140
	v_or_b32_e32 v144, 0x73, v140
	s_waitcnt vmcnt(0) lgkmcnt(0)
	v_cmp_gt_i32_e32 vcc, 0, v243
	v_not_b32_e32 v142, v243
	v_or_b32_e32 v140, 0x80000000, v243
	v_cndmask_b32_e32 v140, v140, v142, vcc
	v_and_b32_e32 v140, 0xffffff80, v140
	v_or_b32_e32 v145, 0x72, v140
	v_min_u32_e32 v142, v144, v145
	v_max_u32_e32 v144, v144, v145
	v_max_u32_e32 v140, v138, v142
	v_max_u32_e32 v141, v143, v144
	v_min_u32_e32 v138, v138, v142
	v_min_u32_e32 v142, v143, v144
	v_max_u32_e32 v139, v140, v141
	v_max_u32_e32 v143, v138, v142
	v_min_u32_e32 v140, v140, v141
	v_min_u32_e32 v138, v138, v142
	s_waitcnt vmcnt(0) lgkmcnt(0)
	v_cmp_gt_i32_e32 vcc, 0, v244
	v_not_b32_e32 v146, v244
	v_or_b32_e32 v145, 0x80000000, v244
	v_cndmask_b32_e32 v145, v145, v146, vcc
	v_and_b32_e32 v145, 0xffffff80, v145
	v_or_b32_e32 v145, 0x77, v145
	s_waitcnt vmcnt(0) lgkmcnt(0)
; DEV unsigned fkey(float x) { const unsigned u = __float_as_uint(x); return (u & 0x80000000u) ? ~u : (u | 0x80000000u); }
; DEV float keyf(unsigned k) { const unsigned u = (k & 0x80000000u) ? (k & 0x7fffffffu) : ~k; return __uint_as_float(u); }
; DEV void bitonic_merge16_desc(unsigned (&v)[16]) {
; #pragma unroll
;   for (int j = 8; j >= 1; j >>= 1)
; #pragma unroll
;     for (int i = 0; i < 16; ++i) { const int l = i ^ j; if (l > i) cswap(v[i], v[l]); }
; }
; DEV void bitonic_sort16_desc(unsigned (&v)[16]) {
; #pragma unroll
;   for (int k = 2; k <= 16; k <<= 1)
; #pragma unroll
;     for (int j = k >> 1; j >= 1; j >>= 1)
; #pragma unroll
;       for (int i = 0; i < 16; ++i) { const int l = i ^ j; if (l > i) { if ((i & k) == 0) cswap(v[i], v[l]); else cswap(v[l], v[i]); } }
; }
; DEV void merge_top16(unsigned (&R)[16], const unsigned (&G)[16]) {
; #pragma unroll
;   for (int i = 0; i < 16; ++i) R[i] = max(R[i], G[15 - i]);
;   bitonic_merge16_desc(R);
; }
; DEV void stage1(unsigned (&L)[16], const float* sp) {
;   float sv[128];
; #pragma unroll
;   for (int i = 0; i < 128; ++i) sv[i] = sp[(size_t)i * 128];
; #pragma unroll
;   for (int i = 0; i < 128; i += 16) {
;     unsigned g[16];
; #pragma unroll
;     for (int e = 0; e < 16; ++e) g[e] = (fkey(sv[i + e]) & ~127u) | (unsigned)(127 - (i + e));
;     bitonic_sort16_desc(g);
;     if (i == 0) {
; #pragma unroll
;       for (int e = 0; e < 16; ++e) L[e] = g[e];
;     } else merge_top16(L, g);
;   }
; }
	v_cmp_gt_i32_e32 vcc, 0, v245
	v_not_b32_e32 v147, v245
	v_or_b32_e32 v146, 0x80000000, v245
	v_cndmask_b32_e32 v146, v146, v147, vcc
	v_cmp_gt_i32_e32 vcc, 0, v240
	v_or_b32_e32 v148, 0x80000000, v240
	v_not_b32_e32 v3, v246
	v_cndmask_b32_e32 v148, v148, v149, vcc
	v_cmp_gt_i32_e32 vcc, 0, v246
	v_or_b32_e32 v2, 0x80000000, v246
	v_and_b32_e32 v146, 0xffffff80, v146
	v_cndmask_b32_e32 v2, v2, v3, vcc
	v_and_b32_e32 v148, 0xffffff80, v148
	v_and_b32_e32 v2, 0xffffff80, v2
	v_or_b32_e32 v146, 0x76, v146
	v_or_b32_e32 v148, 0x74, v148
	v_or_b32_e32 v2, 0x75, v2
	v_max_u32_e32 v147, v145, v146
	v_min_u32_e32 v3, v148, v2
	v_min_u32_e32 v145, v145, v146
	v_max_u32_e32 v2, v148, v2
	v_min_u32_e32 v149, v147, v3
	v_min_u32_e32 v146, v145, v2
	v_max_u32_e32 v3, v147, v3
	v_max_u32_e32 v2, v145, v2
	v_min_u32_e32 v148, v149, v146
	v_min_u32_e32 v144, v3, v2
	v_max_u32_e32 v141, v149, v146
	v_max_u32_e32 v2, v3, v2
	v_min_u32_e32 v150, v139, v148
	v_min_u32_e32 v145, v143, v144
	v_min_u32_e32 v146, v140, v141
	v_min_u32_e32 v3, v138, v2
	v_max_u32_e32 v137, v139, v148
	v_max_u32_e32 v139, v143, v144
	v_max_u32_e32 v140, v140, v141
	v_max_u32_e32 v2, v138, v2
	v_min_u32_e32 v147, v150, v145
	v_min_u32_e32 v142, v146, v3
	v_min_u32_e32 v143, v137, v139
	v_min_u32_e32 v138, v140, v2
	v_max_u32_e32 v130, v150, v145
	v_max_u32_e32 v3, v146, v3
	v_max_u32_e32 v134, v137, v139
	v_max_u32_e32 v2, v140, v2
	v_min_u32_e32 v149, v147, v142
	v_min_u32_e32 v141, v143, v138
	v_min_u32_e32 v145, v130, v3
	v_min_u32_e32 v137, v134, v2
	v_min_u32_e32 v151, v124, v149
	v_min_u32_e32 v144, v136, v141
	v_min_u32_e32 v146, v129, v145
	v_min_u32_e32 v139, v133, v137
	v_max_u32_e32 v124, v124, v149
	v_max_u32_e32 v136, v136, v141
	v_max_u32_e32 v129, v129, v145
	v_max_u32_e32 v133, v133, v137
	v_min_u32_e32 v141, v124, v136
	v_min_u32_e32 v137, v129, v133
	v_max_u32_e32 v124, v124, v136
	v_max_u32_e32 v129, v129, v133
	v_min_u32_e32 v133, v124, v129
	v_max_u32_e32 v124, v124, v129
	v_cmp_gt_i32_e32 vcc, 0, v122
	v_not_b32_e32 v129, v122
	v_or_b32_e32 v122, 0x80000000, v122
	v_cndmask_b32_e32 v122, v122, v129, vcc
	v_cmp_gt_i32_e32 vcc, 0, v119
	v_not_b32_e32 v129, v119
	v_or_b32_e32 v119, 0x80000000, v119
	v_cndmask_b32_e32 v119, v119, v129, vcc
	v_cmp_gt_i32_e32 vcc, 0, v118
	v_not_b32_e32 v136, v118
	v_or_b32_e32 v118, 0x80000000, v118
	v_cndmask_b32_e32 v118, v118, v136, vcc
	v_cmp_gt_i32_e32 vcc, 0, v117
	v_not_b32_e32 v136, v117
	v_or_b32_e32 v117, 0x80000000, v117
	v_cndmask_b32_e32 v117, v117, v136, vcc
	v_cmp_gt_i32_e32 vcc, 0, v116
	v_not_b32_e32 v145, v116
	v_or_b32_e32 v116, 0x80000000, v116
	v_min_u32_e32 v148, v151, v144
	v_min_u32_e32 v140, v146, v139
	v_cndmask_b32_e32 v116, v116, v145, vcc
	v_cmp_gt_i32_e32 vcc, 0, v115
	v_not_b32_e32 v145, v115
	v_or_b32_e32 v115, 0x80000000, v115
	v_min_u32_e32 v150, v148, v140
	v_max_u32_e32 v140, v148, v140
	v_cndmask_b32_e32 v115, v115, v145, vcc
	v_cmp_gt_i32_e32 vcc, 0, v114
	v_not_b32_e32 v148, v114
	v_or_b32_e32 v114, 0x80000000, v114
	v_cndmask_b32_e32 v114, v114, v148, vcc
	v_cmp_gt_i32_e32 vcc, 0, v113
	v_not_b32_e32 v148, v113
	v_or_b32_e32 v113, 0x80000000, v113
	v_cndmask_b32_e32 v113, v113, v148, vcc
	v_cmp_gt_i32_e32 vcc, 0, v112
	v_or_b32_e32 v112, 0x80000000, v112
	v_and_b32_e32 v122, 0xffffff80, v122
	v_cndmask_b32_e32 v112, v112, v152, vcc
	v_cmp_gt_i32_e32 vcc, 0, v111
	v_not_b32_e32 v152, v111
	v_or_b32_e32 v111, 0x80000000, v111
	v_cndmask_b32_e32 v111, v111, v152, vcc
	v_cmp_gt_i32_e32 vcc, 0, v110
	v_or_b32_e32 v110, 0x80000000, v110
	v_and_b32_e32 v119, 0xffffff80, v119
	v_cndmask_b32_e32 v110, v110, v153, vcc
	v_cmp_gt_i32_e32 vcc, 0, v109
	v_not_b32_e32 v153, v109
	v_or_b32_e32 v109, 0x80000000, v109
	v_cndmask_b32_e32 v109, v109, v153, vcc
	v_cmp_gt_i32_e32 vcc, 0, v108
	v_or_b32_e32 v108, 0x80000000, v108
	v_and_b32_e32 v118, 0xffffff80, v118
	v_cndmask_b32_e32 v108, v108, v170, vcc
	v_cmp_gt_i32_e32 vcc, 0, v107
	v_not_b32_e32 v170, v107
	v_or_b32_e32 v107, 0x80000000, v107
	v_cndmask_b32_e32 v107, v107, v170, vcc
	v_cmp_gt_i32_e32 vcc, 0, v106
	v_or_b32_e32 v106, 0x80000000, v106
	v_and_b32_e32 v117, 0xffffff80, v117
	v_cndmask_b32_e32 v106, v106, v171, vcc
	v_cmp_gt_i32_e32 vcc, 0, v105
	v_not_b32_e32 v171, v105
	v_or_b32_e32 v105, 0x80000000, v105
	v_cndmask_b32_e32 v105, v105, v171, vcc
	v_and_b32_e32 v116, 0xffffff80, v116
	v_and_b32_e32 v115, 0xffffff80, v115
	v_and_b32_e32 v114, 0xffffff80, v114
	v_and_b32_e32 v113, 0xffffff80, v113
	v_and_b32_e32 v112, 0xffffff80, v112
	v_and_b32_e32 v111, 0xffffff80, v111
	v_and_b32_e32 v110, 0xffffff80, v110
	v_and_b32_e32 v109, 0xffffff80, v109
	v_and_b32_e32 v108, 0xffffff80, v108
	v_and_b32_e32 v107, 0xffffff80, v107
	v_and_b32_e32 v106, 0xffffff80, v106
	v_and_b32_e32 v105, 0xffffff80, v105
	v_or_b32_e32 v122, 0x6f, v122
	v_or_b32_e32 v119, 0x6e, v119
	v_or_b32_e32 v118, 0x6c, v118
	v_or_b32_e32 v117, 0x6d, v117
	v_or_b32_e32 v116, 0x68, v116
	v_or_b32_e32 v115, 0x69, v115
	v_or_b32_e32 v114, 0x6b, v114
	v_or_b32_e32 v113, 0x6a, v113
	v_or_b32_e32 v112, 0x60, v112
	v_or_b32_e32 v111, 0x61, v111
	v_or_b32_e32 v110, 0x63, v110
	v_or_b32_e32 v109, 0x62, v109
	v_or_b32_e32 v108, 0x67, v108
	v_or_b32_e32 v107, 0x66, v107
	v_or_b32_e32 v106, 0x64, v106
	v_or_b32_e32 v105, 0x65, v105
	v_max_u32_e32 v144, v151, v144
	v_max_u32_e32 v139, v146, v139
	v_max_u32_e32 v129, v122, v119
	v_min_u32_e32 v136, v118, v117
	v_min_u32_e32 v119, v122, v119
	v_max_u32_e32 v117, v118, v117
	v_max_u32_e32 v145, v116, v115
	v_min_u32_e32 v148, v114, v113
	v_min_u32_e32 v115, v116, v115
	v_max_u32_e32 v113, v114, v113
	v_max_u32_e32 v152, v112, v111
; DEV unsigned fkey(float x) { const unsigned u = __float_as_uint(x); return (u & 0x80000000u) ? ~u : (u | 0x80000000u); }
; DEV float keyf(unsigned k) { const unsigned u = (k & 0x80000000u) ? (k & 0x7fffffffu) : ~k; return __uint_as_float(u); }
; DEV void bitonic_merge16_desc(unsigned (&v)[16]) {
; #pragma unroll
;   for (int j = 8; j >= 1; j >>= 1)
; #pragma unroll
;     for (int i = 0; i < 16; ++i) { const int l = i ^ j; if (l > i) cswap(v[i], v[l]); }
; }
; DEV void bitonic_sort16_desc(unsigned (&v)[16]) {
; #pragma unroll
;   for (int k = 2; k <= 16; k <<= 1)
; #pragma unroll
;     for (int j = k >> 1; j >= 1; j >>= 1)
; #pragma unroll
;       for (int i = 0; i < 16; ++i) { const int l = i ^ j; if (l > i) { if ((i & k) == 0) cswap(v[i], v[l]); else cswap(v[l], v[i]); } }
; }
; DEV void merge_top16(unsigned (&R)[16], const unsigned (&G)[16]) {
; #pragma unroll
;   for (int i = 0; i < 16; ++i) R[i] = max(R[i], G[15 - i]);
;   bitonic_merge16_desc(R);
; }
; DEV void stage1(unsigned (&L)[16], const float* sp) {
;   float sv[128];
; #pragma unroll
;   for (int i = 0; i < 128; ++i) sv[i] = sp[(size_t)i * 128];
; #pragma unroll
;   for (int i = 0; i < 128; i += 16) {
;     unsigned g[16];
; #pragma unroll
;     for (int e = 0; e < 16; ++e) g[e] = (fkey(sv[i + e]) & ~127u) | (unsigned)(127 - (i + e));
;     bitonic_sort16_desc(g);
;     if (i == 0) {
; #pragma unroll
;       for (int e = 0; e < 16; ++e) L[e] = g[e];
;     } else merge_top16(L, g);
;   }
; }
	v_min_u32_e32 v153, v110, v109
	v_min_u32_e32 v111, v112, v111
	v_max_u32_e32 v109, v110, v109
	v_max_u32_e32 v170, v108, v107
	v_min_u32_e32 v171, v106, v105
	v_min_u32_e32 v107, v108, v107
	v_max_u32_e32 v105, v106, v105
	v_min_u32_e32 v146, v144, v139
	v_max_u32_e32 v139, v144, v139
	v_min_u32_e32 v144, v141, v137
	v_max_u32_e32 v137, v141, v137
	v_max_u32_e32 v141, v129, v136
	v_max_u32_e32 v118, v119, v117
	v_min_u32_e32 v149, v145, v148
	v_min_u32_e32 v114, v115, v113
	v_min_u32_e32 v129, v129, v136
	v_min_u32_e32 v117, v119, v117
	v_max_u32_e32 v136, v145, v148
	v_max_u32_e32 v113, v115, v113
	v_max_u32_e32 v169, v152, v153
	v_max_u32_e32 v110, v111, v109
	v_min_u32_e32 v172, v170, v171
	v_min_u32_e32 v106, v107, v105
	v_min_u32_e32 v152, v152, v153
	v_min_u32_e32 v109, v111, v109
	v_max_u32_e32 v153, v170, v171
	v_max_u32_e32 v105, v107, v105
	v_max_u32_e32 v122, v141, v118
	v_min_u32_e32 v116, v149, v114
	v_max_u32_e32 v119, v129, v117
	v_min_u32_e32 v115, v136, v113
	v_min_u32_e32 v118, v141, v118
	v_max_u32_e32 v114, v149, v114
	v_min_u32_e32 v117, v129, v117
	v_max_u32_e32 v113, v136, v113
	v_max_u32_e32 v112, v169, v110
	v_min_u32_e32 v108, v172, v106
	v_max_u32_e32 v111, v152, v109
	v_min_u32_e32 v107, v153, v105
	v_min_u32_e32 v110, v169, v110
	v_max_u32_e32 v106, v172, v106
	v_min_u32_e32 v109, v152, v109
	v_max_u32_e32 v105, v153, v105
	v_max_u32_e32 v151, v122, v116
	v_max_u32_e32 v145, v119, v115
	v_max_u32_e32 v141, v118, v114
	v_max_u32_e32 v129, v117, v113
	v_min_u32_e32 v173, v112, v108
	v_min_u32_e32 v170, v111, v107
	v_min_u32_e32 v169, v110, v106
	v_min_u32_e32 v152, v109, v105
	v_min_u32_e32 v116, v122, v116
	v_min_u32_e32 v115, v119, v115
	v_min_u32_e32 v114, v118, v114
	v_min_u32_e32 v113, v117, v113
	v_max_u32_e32 v108, v112, v108
	v_max_u32_e32 v107, v111, v107
	v_max_u32_e32 v106, v110, v106
	v_max_u32_e32 v105, v109, v105
	v_max_u32_e32 v148, v151, v145
	v_max_u32_e32 v136, v141, v129
	v_min_u32_e32 v171, v173, v170
	v_min_u32_e32 v153, v169, v152
	v_max_u32_e32 v119, v116, v115
	v_max_u32_e32 v117, v114, v113
	v_min_u32_e32 v111, v108, v107
	v_min_u32_e32 v109, v106, v105
	v_min_u32_e32 v145, v151, v145
	v_min_u32_e32 v129, v141, v129
	v_max_u32_e32 v151, v173, v170
	v_max_u32_e32 v152, v169, v152
	v_min_u32_e32 v115, v116, v115
	v_min_u32_e32 v113, v114, v113
	v_max_u32_e32 v107, v108, v107
	v_max_u32_e32 v105, v106, v105
	v_max_u32_e32 v149, v148, v136
	v_min_u32_e32 v172, v171, v153
	v_max_u32_e32 v118, v119, v117
	v_min_u32_e32 v110, v111, v109
	v_max_u32_e32 v141, v145, v129
	v_min_u32_e32 v169, v151, v152
	v_max_u32_e32 v114, v115, v113
	v_min_u32_e32 v106, v107, v105
	v_min_u32_e32 v174, v149, v172
	v_min_u32_e32 v112, v118, v110
	v_min_u32_e32 v170, v141, v169
	v_min_u32_e32 v108, v114, v106
	v_max_u32_e32 v126, v147, v142
	v_max_u32_e32 v135, v143, v138
	v_max_u32_e32 v3, v130, v3
	v_max_u32_e32 v2, v134, v2
	v_min_u32_e32 v122, v174, v112
	v_min_u32_e32 v116, v170, v108
	v_min_u32_e32 v136, v148, v136
	v_max_u32_e32 v148, v171, v153
	v_min_u32_e32 v117, v119, v117
	v_max_u32_e32 v109, v111, v109
	v_min_u32_e32 v129, v145, v129
	v_max_u32_e32 v145, v151, v152
	v_min_u32_e32 v113, v115, v113
	v_max_u32_e32 v105, v107, v105
	v_max_u32_e32 v112, v174, v112
	v_max_u32_e32 v108, v170, v108
	v_min_u32_e32 v142, v125, v126
	v_min_u32_e32 v138, v132, v135
	v_min_u32_e32 v128, v127, v3
	v_min_u32_e32 v130, v123, v2
	v_min_u32_e32 v173, v122, v116
	v_min_u32_e32 v153, v136, v148
	v_min_u32_e32 v111, v117, v109
	v_min_u32_e32 v151, v129, v145
	v_min_u32_e32 v107, v113, v105
	v_max_u32_e32 v116, v122, v116
	v_min_u32_e32 v122, v112, v108
	v_max_u32_e32 v108, v112, v108
	v_max_u32_e32 v112, v149, v172
	v_max_u32_e32 v110, v118, v110
	v_max_u32_e32 v141, v141, v169
	v_max_u32_e32 v106, v114, v106
	v_max_u32_e32 v136, v136, v148
	v_max_u32_e32 v109, v117, v109
	v_max_u32_e32 v129, v129, v145
	v_max_u32_e32 v105, v113, v105
	v_min_u32_e32 v143, v142, v138
	v_min_u32_e32 v131, v128, v130
	v_max_u32_e32 v138, v142, v138
	v_max_u32_e32 v128, v128, v130
	v_min_u32_e32 v118, v112, v110
	v_min_u32_e32 v114, v141, v106
	v_min_u32_e32 v117, v136, v109
	v_min_u32_e32 v113, v129, v105
	v_max_u32_e32 v110, v112, v110
	v_max_u32_e32 v106, v141, v106
	v_max_u32_e32 v109, v136, v109
	v_max_u32_e32 v105, v129, v105
	v_min_u32_e32 v130, v138, v128
	v_min_u32_e32 v149, v118, v114
	v_max_u32_e32 v114, v118, v114
	v_min_u32_e32 v112, v110, v106
	v_min_u32_e32 v118, v109, v105
	v_min_u32_e32 v134, v143, v131
	v_max_u32_e32 v131, v143, v131
	v_min_u32_e32 v142, v146, v130
	v_min_u32_e32 v145, v117, v113
	v_max_u32_e32 v113, v117, v113
	v_min_u32_e32 v129, v112, v118
	v_max_u32_e32 v125, v125, v126
	v_max_u32_e32 v126, v132, v135
	v_max_u32_e32 v3, v127, v3
	v_max_u32_e32 v2, v123, v2
	v_min_u32_e32 v117, v114, v113
	v_max3_u32 v113, v142, v114, v113
	v_max3_u32 v114, v140, v131, v129
	v_cmp_gt_i32_e32 vcc, 0, v104
	v_not_b32_e32 v129, v104
	v_or_b32_e32 v104, 0x80000000, v104
	v_min_u32_e32 v132, v125, v126
	v_min_u32_e32 v123, v3, v2
	v_min_u32_e32 v119, v153, v111
	v_min_u32_e32 v115, v151, v107
	v_cndmask_b32_e32 v104, v104, v129, vcc
	v_cmp_gt_i32_e32 vcc, 0, v103
	v_not_b32_e32 v129, v103
	v_or_b32_e32 v103, 0x80000000, v103
	v_min_u32_e32 v127, v132, v123
	v_max_u32_e32 v123, v132, v123
	v_max_u32_e32 v125, v125, v126
	v_max_u32_e32 v2, v3, v2
	v_min_u32_e32 v152, v119, v115
	v_max_u32_e32 v115, v119, v115
	v_max_u32_e32 v111, v153, v111
	v_max_u32_e32 v107, v151, v107
	v_max3_u32 v117, v146, v130, v117
	v_cndmask_b32_e32 v103, v103, v129, vcc
	v_cmp_gt_i32_e32 vcc, 0, v102
	v_not_b32_e32 v130, v102
	v_or_b32_e32 v102, 0x80000000, v102
; DEV unsigned fkey(float x) { const unsigned u = __float_as_uint(x); return (u & 0x80000000u) ? ~u : (u | 0x80000000u); }
; DEV float keyf(unsigned k) { const unsigned u = (k & 0x80000000u) ? (k & 0x7fffffffu) : ~k; return __uint_as_float(u); }
; DEV void bitonic_merge16_desc(unsigned (&v)[16]) {
; #pragma unroll
;   for (int j = 8; j >= 1; j >>= 1)
; #pragma unroll
;     for (int i = 0; i < 16; ++i) { const int l = i ^ j; if (l > i) cswap(v[i], v[l]); }
; }
; DEV void bitonic_sort16_desc(unsigned (&v)[16]) {
; #pragma unroll
;   for (int k = 2; k <= 16; k <<= 1)
; #pragma unroll
;     for (int j = k >> 1; j >= 1; j >>= 1)
; #pragma unroll
;       for (int i = 0; i < 16; ++i) { const int l = i ^ j; if (l > i) { if ((i & k) == 0) cswap(v[i], v[l]); else cswap(v[l], v[i]); } }
; }
; DEV void merge_top16(unsigned (&R)[16], const unsigned (&G)[16]) {
; #pragma unroll
;   for (int i = 0; i < 16; ++i) R[i] = max(R[i], G[15 - i]);
;   bitonic_merge16_desc(R);
; }
; DEV void stage1(unsigned (&L)[16], const float* sp) {
;   float sv[128];
; #pragma unroll
;   for (int i = 0; i < 128; ++i) sv[i] = sp[(size_t)i * 128];
; #pragma unroll
;   for (int i = 0; i < 128; i += 16) {
;     unsigned g[16];
; #pragma unroll
;     for (int e = 0; e < 16; ++e) g[e] = (fkey(sv[i + e]) & ~127u) | (unsigned)(127 - (i + e));
;     bitonic_sort16_desc(g);
;     if (i == 0) {
; #pragma unroll
;       for (int e = 0; e < 16; ++e) L[e] = g[e];
;     } else merge_top16(L, g);
;   }
; }
	v_min_u32_e32 v132, v137, v123
	v_min_u32_e32 v3, v125, v2
	v_min_u32_e32 v119, v116, v115
	v_min_u32_e32 v151, v111, v107
	v_cndmask_b32_e32 v102, v102, v130, vcc
	v_cmp_gt_i32_e32 vcc, 0, v101
	v_not_b32_e32 v130, v101
	v_or_b32_e32 v101, 0x80000000, v101
	v_min_u32_e32 v126, v133, v3
	v_max3_u32 v3, v133, v3, v119
	v_max3_u32 v119, v132, v122, v151
	v_cndmask_b32_e32 v101, v101, v130, vcc
	v_cmp_gt_i32_e32 vcc, 0, v100
	v_not_b32_e32 v132, v100
	v_or_b32_e32 v100, 0x80000000, v100
	v_cndmask_b32_e32 v100, v100, v132, vcc
	v_cmp_gt_i32_e32 vcc, 0, v99
	v_not_b32_e32 v132, v99
	v_or_b32_e32 v99, 0x80000000, v99
	v_cndmask_b32_e32 v99, v99, v132, vcc
	v_cmp_gt_i32_e32 vcc, 0, v98
	v_not_b32_e32 v133, v98
	v_or_b32_e32 v98, 0x80000000, v98
	v_cndmask_b32_e32 v98, v98, v133, vcc
	v_cmp_gt_i32_e32 vcc, 0, v97
	v_not_b32_e32 v133, v97
	v_or_b32_e32 v97, 0x80000000, v97
	v_cndmask_b32_e32 v97, v97, v133, vcc
	v_cmp_gt_i32_e32 vcc, 0, v96
	v_not_b32_e32 v136, v96
	v_or_b32_e32 v96, 0x80000000, v96
	v_min_u32_e32 v153, v122, v151
	v_cndmask_b32_e32 v96, v96, v136, vcc
	v_cmp_gt_i32_e32 vcc, 0, v95
	v_not_b32_e32 v136, v95
	v_or_b32_e32 v95, 0x80000000, v95
	v_max3_u32 v115, v126, v116, v115
	v_max3_u32 v116, v137, v123, v153
	v_cndmask_b32_e32 v95, v95, v136, vcc
	v_cmp_gt_i32_e32 vcc, 0, v94
	v_not_b32_e32 v137, v94
	v_or_b32_e32 v94, 0x80000000, v94
	v_max_u32_e32 v128, v138, v128
	v_min_u32_e32 v135, v144, v127
	v_max_u32_e32 v107, v111, v107
	v_min_u32_e32 v148, v149, v145
	v_cndmask_b32_e32 v94, v94, v137, vcc
	v_cmp_gt_i32_e32 vcc, 0, v93
	v_not_b32_e32 v137, v93
	v_or_b32_e32 v93, 0x80000000, v93
	v_min_u32_e32 v138, v139, v128
	v_min_u32_e32 v111, v108, v107
	v_max3_u32 v107, v135, v108, v107
	v_max3_u32 v108, v139, v128, v148
	v_cndmask_b32_e32 v93, v93, v137, vcc
	v_cmp_gt_i32_e32 vcc, 0, v92
	v_not_b32_e32 v139, v92
	v_or_b32_e32 v92, 0x80000000, v92
	v_cndmask_b32_e32 v92, v92, v139, vcc
	v_cmp_gt_i32_e32 vcc, 0, v91
	v_not_b32_e32 v139, v91
	v_or_b32_e32 v91, 0x80000000, v91
	v_min_u32_e32 v143, v140, v131
	v_cndmask_b32_e32 v91, v91, v139, vcc
	v_cmp_gt_i32_e32 vcc, 0, v90
	v_not_b32_e32 v140, v90
	v_or_b32_e32 v90, 0x80000000, v90
	v_cndmask_b32_e32 v90, v90, v140, vcc
	v_cmp_gt_i32_e32 vcc, 0, v89
	v_not_b32_e32 v140, v89
	v_or_b32_e32 v89, 0x80000000, v89
	v_cndmask_b32_e32 v89, v89, v140, vcc
	v_and_b32_e32 v104, 0xffffff80, v104
	v_and_b32_e32 v103, 0xffffff80, v103
	v_and_b32_e32 v102, 0xffffff80, v102
	v_and_b32_e32 v101, 0xffffff80, v101
	v_and_b32_e32 v100, 0xffffff80, v100
	v_and_b32_e32 v99, 0xffffff80, v99
	v_and_b32_e32 v98, 0xffffff80, v98
	v_and_b32_e32 v97, 0xffffff80, v97
	v_and_b32_e32 v96, 0xffffff80, v96
	v_and_b32_e32 v95, 0xffffff80, v95
	v_and_b32_e32 v94, 0xffffff80, v94
	v_and_b32_e32 v93, 0xffffff80, v93
	v_and_b32_e32 v92, 0xffffff80, v92
	v_and_b32_e32 v91, 0xffffff80, v91
	v_and_b32_e32 v90, 0xffffff80, v90
	v_and_b32_e32 v89, 0xffffff80, v89
	v_max_u32_e32 v106, v110, v106
	v_max_u32_e32 v105, v109, v105
	v_or_b32_e32 v104, 0x5f, v104
	v_or_b32_e32 v103, 0x5e, v103
	v_or_b32_e32 v102, 0x5c, v102
	v_or_b32_e32 v101, 0x5d, v101
	v_or_b32_e32 v100, 0x58, v100
	v_or_b32_e32 v99, 0x59, v99
	v_or_b32_e32 v98, 0x5b, v98
	v_or_b32_e32 v97, 0x5a, v97
	v_or_b32_e32 v96, 0x50, v96
	v_or_b32_e32 v95, 0x51, v95
	v_or_b32_e32 v94, 0x53, v94
	v_or_b32_e32 v93, 0x52, v93
	v_or_b32_e32 v92, 0x57, v92
	v_or_b32_e32 v91, 0x56, v91
	v_or_b32_e32 v90, 0x54, v90
	v_or_b32_e32 v89, 0x55, v89
	v_min_u32_e32 v109, v106, v105
	v_max_u32_e32 v129, v104, v103
	v_min_u32_e32 v130, v102, v101
	v_min_u32_e32 v103, v104, v103
	v_max_u32_e32 v101, v102, v101
	v_max_u32_e32 v132, v100, v99
	v_min_u32_e32 v133, v98, v97
	v_min_u32_e32 v99, v100, v99
	v_max_u32_e32 v97, v98, v97
	v_max_u32_e32 v136, v96, v95
	v_min_u32_e32 v137, v94, v93
	v_min_u32_e32 v95, v96, v95
	v_max_u32_e32 v93, v94, v93
	v_max_u32_e32 v139, v92, v91
	v_min_u32_e32 v140, v90, v89
	v_min_u32_e32 v91, v92, v91
	v_max_u32_e32 v89, v90, v89
	v_min_u32_e32 v147, v150, v134
	v_max3_u32 v122, v138, v149, v145
	v_max3_u32 v109, v150, v134, v109
	v_max_u32_e32 v131, v129, v130
	v_max_u32_e32 v102, v103, v101
	v_min_u32_e32 v134, v132, v133
	v_min_u32_e32 v98, v99, v97
	v_min_u32_e32 v129, v129, v130
	v_min_u32_e32 v101, v103, v101
	v_max_u32_e32 v130, v132, v133
	v_max_u32_e32 v97, v99, v97
	v_max_u32_e32 v138, v136, v137
	v_max_u32_e32 v94, v95, v93
	v_min_u32_e32 v141, v139, v140
	v_min_u32_e32 v90, v91, v89
	v_min_u32_e32 v136, v136, v137
	v_min_u32_e32 v93, v95, v93
	v_max_u32_e32 v137, v139, v140
	v_max_u32_e32 v89, v91, v89
	v_max_u32_e32 v104, v131, v102
	v_min_u32_e32 v100, v134, v98
	v_max_u32_e32 v103, v129, v101
	v_min_u32_e32 v99, v130, v97
	v_min_u32_e32 v102, v131, v102
	v_max_u32_e32 v98, v134, v98
	v_min_u32_e32 v101, v129, v101
	v_max_u32_e32 v97, v130, v97
	v_max_u32_e32 v96, v138, v94
	v_min_u32_e32 v92, v141, v90
	v_max_u32_e32 v95, v136, v93
	v_min_u32_e32 v91, v137, v89
	v_min_u32_e32 v94, v138, v94
	v_max_u32_e32 v90, v141, v90
	v_min_u32_e32 v93, v136, v93
	v_max_u32_e32 v89, v137, v89
	v_max_u32_e32 v135, v104, v100
	v_max_u32_e32 v132, v103, v99
	v_max_u32_e32 v131, v102, v98
	v_max_u32_e32 v129, v101, v97
	v_min_u32_e32 v142, v96, v92
	v_min_u32_e32 v139, v95, v91
	v_min_u32_e32 v138, v94, v90
	v_min_u32_e32 v136, v93, v89
	v_min_u32_e32 v100, v104, v100
	v_min_u32_e32 v99, v103, v99
	v_min_u32_e32 v98, v102, v98
	v_min_u32_e32 v97, v101, v97
	v_max_u32_e32 v92, v96, v92
	v_max_u32_e32 v91, v95, v91
	v_max_u32_e32 v90, v94, v90
	v_max_u32_e32 v89, v93, v89
	v_max_u32_e32 v133, v135, v132
	v_max_u32_e32 v130, v131, v129
	v_min_u32_e32 v140, v142, v139
; DEV unsigned fkey(float x) { const unsigned u = __float_as_uint(x); return (u & 0x80000000u) ? ~u : (u | 0x80000000u); }
; DEV float keyf(unsigned k) { const unsigned u = (k & 0x80000000u) ? (k & 0x7fffffffu) : ~k; return __uint_as_float(u); }
; DEV void bitonic_merge16_desc(unsigned (&v)[16]) {
; #pragma unroll
;   for (int j = 8; j >= 1; j >>= 1)
; #pragma unroll
;     for (int i = 0; i < 16; ++i) { const int l = i ^ j; if (l > i) cswap(v[i], v[l]); }
; }
; DEV void bitonic_sort16_desc(unsigned (&v)[16]) {
; #pragma unroll
;   for (int k = 2; k <= 16; k <<= 1)
; #pragma unroll
;     for (int j = k >> 1; j >= 1; j >>= 1)
; #pragma unroll
;       for (int i = 0; i < 16; ++i) { const int l = i ^ j; if (l > i) { if ((i & k) == 0) cswap(v[i], v[l]); else cswap(v[l], v[i]); } }
; }
; DEV void merge_top16(unsigned (&R)[16], const unsigned (&G)[16]) {
; #pragma unroll
;   for (int i = 0; i < 16; ++i) R[i] = max(R[i], G[15 - i]);
;   bitonic_merge16_desc(R);
; }
; DEV void stage1(unsigned (&L)[16], const float* sp) {
;   float sv[128];
; #pragma unroll
;   for (int i = 0; i < 128; ++i) sv[i] = sp[(size_t)i * 128];
; #pragma unroll
;   for (int i = 0; i < 128; i += 16) {
;     unsigned g[16];
; #pragma unroll
;     for (int e = 0; e < 16; ++e) g[e] = (fkey(sv[i + e]) & ~127u) | (unsigned)(127 - (i + e));
;     bitonic_sort16_desc(g);
;     if (i == 0) {
; #pragma unroll
;       for (int e = 0; e < 16; ++e) L[e] = g[e];
;     } else merge_top16(L, g);
;   }
; }
	v_min_u32_e32 v137, v138, v136
	v_max_u32_e32 v103, v100, v99
	v_max_u32_e32 v101, v98, v97
	v_min_u32_e32 v95, v92, v91
	v_min_u32_e32 v93, v90, v89
	v_min_u32_e32 v132, v135, v132
	v_min_u32_e32 v129, v131, v129
	v_max_u32_e32 v135, v142, v139
	v_max_u32_e32 v136, v138, v136
	v_min_u32_e32 v99, v100, v99
	v_min_u32_e32 v97, v98, v97
	v_max_u32_e32 v91, v92, v91
	v_max_u32_e32 v89, v90, v89
	v_max_u32_e32 v2, v125, v2
	v_max_u32_e32 v134, v133, v130
	v_min_u32_e32 v141, v140, v137
	v_max_u32_e32 v102, v103, v101
	v_min_u32_e32 v94, v95, v93
	v_max_u32_e32 v131, v132, v129
	v_min_u32_e32 v138, v135, v136
	v_max_u32_e32 v98, v99, v97
	v_min_u32_e32 v90, v91, v89
	v_min_u32_e32 v125, v124, v2
	v_min_u32_e32 v171, v173, v152
	v_max3_u32 v112, v143, v112, v118
	v_min_u32_e32 v143, v134, v141
	v_min_u32_e32 v96, v102, v94
	v_min_u32_e32 v139, v131, v138
	v_min_u32_e32 v92, v98, v90
	v_max3_u32 v2, v124, v2, v171
	v_max3_u32 v110, v125, v173, v152
	v_max3_u32 v111, v144, v127, v111
	v_max3_u32 v105, v147, v106, v105
	v_min_u32_e32 v104, v143, v96
	v_min_u32_e32 v100, v139, v92
	v_min_u32_e32 v130, v133, v130
	v_max_u32_e32 v133, v140, v137
	v_min_u32_e32 v101, v103, v101
	v_max_u32_e32 v93, v95, v93
	v_min_u32_e32 v129, v132, v129
	v_max_u32_e32 v132, v135, v136
	v_min_u32_e32 v97, v99, v97
	v_max_u32_e32 v89, v91, v89
	v_max_u32_e32 v96, v143, v96
	v_max_u32_e32 v92, v139, v92
	v_max_u32_e32 v106, v2, v108
	v_min_u32_e32 v2, v2, v108
	v_max_u32_e32 v108, v110, v122
	v_max_u32_e32 v118, v3, v117
	v_min_u32_e32 v3, v3, v117
	v_max_u32_e32 v117, v115, v113
	v_min_u32_e32 v113, v115, v113
	v_max_u32_e32 v115, v116, v114
	v_min_u32_e32 v114, v116, v114
	v_max_u32_e32 v116, v119, v112
	v_min_u32_e32 v112, v119, v112
	v_max_u32_e32 v119, v111, v109
	v_min_u32_e32 v109, v111, v109
	v_max_u32_e32 v111, v107, v105
	v_min_u32_e32 v142, v104, v100
	v_min_u32_e32 v137, v130, v133
	v_min_u32_e32 v95, v101, v93
	v_min_u32_e32 v135, v129, v132
	v_min_u32_e32 v91, v97, v89
	v_max_u32_e32 v100, v104, v100
	v_min_u32_e32 v104, v96, v92
	v_max_u32_e32 v92, v96, v92
	v_max_u32_e32 v96, v134, v141
	v_max_u32_e32 v94, v102, v94
	v_max_u32_e32 v131, v131, v138
	v_max_u32_e32 v90, v98, v90
	v_max_u32_e32 v130, v130, v133
	v_max_u32_e32 v93, v101, v93
	v_max_u32_e32 v129, v129, v132
	v_max_u32_e32 v89, v97, v89
	v_min_u32_e32 v110, v110, v122
	v_min_u32_e32 v105, v107, v105
	v_max_u32_e32 v107, v106, v115
	v_min_u32_e32 v106, v106, v115
	v_max_u32_e32 v115, v108, v116
	v_min_u32_e32 v108, v108, v116
	v_max_u32_e32 v116, v118, v119
	v_min_u32_e32 v118, v118, v119
	v_max_u32_e32 v119, v117, v111
	v_min_u32_e32 v111, v117, v111
	v_min_u32_e32 v102, v96, v94
	v_min_u32_e32 v98, v131, v90
	v_min_u32_e32 v101, v130, v93
	v_min_u32_e32 v97, v129, v89
	v_max_u32_e32 v117, v2, v114
	v_min_u32_e32 v2, v2, v114
	v_max_u32_e32 v114, v110, v112
	v_min_u32_e32 v110, v110, v112
	v_max_u32_e32 v112, v3, v109
	v_min_u32_e32 v3, v3, v109
	v_max_u32_e32 v109, v113, v105
	v_min_u32_e32 v105, v113, v105
	v_max_u32_e32 v113, v107, v116
	v_min_u32_e32 v107, v107, v116
	v_max_u32_e32 v116, v115, v119
	v_min_u32_e32 v115, v115, v119
	v_max_u32_e32 v119, v106, v118
	v_min_u32_e32 v106, v106, v118
	v_max_u32_e32 v118, v108, v111
	v_min_u32_e32 v108, v108, v111
	v_min_u32_e32 v103, v137, v95
	v_min_u32_e32 v99, v135, v91
	v_max_u32_e32 v95, v137, v95
	v_max_u32_e32 v91, v135, v91
	v_min_u32_e32 v134, v102, v98
	v_min_u32_e32 v132, v101, v97
	v_max_u32_e32 v111, v117, v112
	v_min_u32_e32 v112, v117, v112
	v_max_u32_e32 v117, v114, v109
	v_min_u32_e32 v124, v106, v108
	v_min_u32_e32 v135, v95, v91
	v_max_u32_e32 v91, v95, v91
	v_min_u32_e32 v133, v134, v132
	v_min_u32_e32 v125, v111, v117
	v_min_u32_e32 v95, v92, v91
	v_max_u32_e32 v98, v102, v98
	v_max_u32_e32 v97, v101, v97
	v_max3_u32 v91, v124, v92, v91
	v_max3_u32 v92, v111, v117, v133
	v_cmp_gt_i32_e32 vcc, 0, v88
	v_not_b32_e32 v111, v88
	v_or_b32_e32 v88, 0x80000000, v88
	v_min_u32_e32 v109, v114, v109
	v_min_u32_e32 v101, v98, v97
	v_max_u32_e32 v94, v96, v94
	v_max_u32_e32 v90, v131, v90
	v_max_u32_e32 v93, v130, v93
	v_max_u32_e32 v89, v129, v89
	v_cndmask_b32_e32 v88, v88, v111, vcc
	v_cmp_gt_i32_e32 vcc, 0, v87
	v_not_b32_e32 v111, v87
	v_or_b32_e32 v87, 0x80000000, v87
	v_min_u32_e32 v126, v112, v109
	v_min_u32_e32 v96, v94, v90
	v_min_u32_e32 v102, v93, v89
	v_max3_u32 v101, v112, v109, v101
	v_cndmask_b32_e32 v87, v87, v111, vcc
	v_cmp_gt_i32_e32 vcc, 0, v86
	v_not_b32_e32 v112, v86
	v_or_b32_e32 v86, 0x80000000, v86
	v_max_u32_e32 v114, v2, v3
	v_min_u32_e32 v2, v2, v3
	v_max_u32_e32 v3, v110, v105
	v_min_u32_e32 v129, v96, v102
	v_cndmask_b32_e32 v86, v86, v112, vcc
	v_cmp_gt_i32_e32 vcc, 0, v85
	v_not_b32_e32 v112, v85
	v_or_b32_e32 v85, 0x80000000, v85
	v_min_u32_e32 v127, v114, v3
	v_min_u32_e32 v136, v103, v99
	v_max_u32_e32 v99, v103, v99
	v_max3_u32 v3, v114, v3, v129
	v_cndmask_b32_e32 v85, v85, v112, vcc
	v_cmp_gt_i32_e32 vcc, 0, v84
	v_not_b32_e32 v114, v84
	v_or_b32_e32 v84, 0x80000000, v84
	v_min_u32_e32 v103, v100, v99
	v_cndmask_b32_e32 v84, v84, v114, vcc
	v_cmp_gt_i32_e32 vcc, 0, v83
	v_not_b32_e32 v114, v83
	v_or_b32_e32 v83, 0x80000000, v83
	v_min_u32_e32 v122, v107, v115
	v_max3_u32 v103, v107, v115, v103
	v_cndmask_b32_e32 v83, v83, v114, vcc
	v_cmp_gt_i32_e32 vcc, 0, v82
	v_not_b32_e32 v115, v82
	v_or_b32_e32 v82, 0x80000000, v82
	v_min_u32_e32 v137, v104, v135
	v_cndmask_b32_e32 v82, v82, v115, vcc
	v_cmp_gt_i32_e32 vcc, 0, v81
	v_not_b32_e32 v115, v81
	v_or_b32_e32 v81, 0x80000000, v81
	v_min_u32_e32 v123, v119, v118
	v_max3_u32 v99, v122, v100, v99
	v_max3_u32 v100, v119, v118, v137
	v_cndmask_b32_e32 v81, v81, v115, vcc
; DEV unsigned fkey(float x) { const unsigned u = __float_as_uint(x); return (u & 0x80000000u) ? ~u : (u | 0x80000000u); }
; DEV float keyf(unsigned k) { const unsigned u = (k & 0x80000000u) ? (k & 0x7fffffffu) : ~k; return __uint_as_float(u); }
; DEV void bitonic_merge16_desc(unsigned (&v)[16]) {
; #pragma unroll
;   for (int j = 8; j >= 1; j >>= 1)
; #pragma unroll
;     for (int i = 0; i < 16; ++i) { const int l = i ^ j; if (l > i) cswap(v[i], v[l]); }
; }
; DEV void bitonic_sort16_desc(unsigned (&v)[16]) {
; #pragma unroll
;   for (int k = 2; k <= 16; k <<= 1)
; #pragma unroll
;     for (int j = k >> 1; j >= 1; j >>= 1)
; #pragma unroll
;       for (int i = 0; i < 16; ++i) { const int l = i ^ j; if (l > i) { if ((i & k) == 0) cswap(v[i], v[l]); else cswap(v[l], v[i]); } }
; }
; DEV void merge_top16(unsigned (&R)[16], const unsigned (&G)[16]) {
; #pragma unroll
;   for (int i = 0; i < 16; ++i) R[i] = max(R[i], G[15 - i]);
;   bitonic_merge16_desc(R);
; }
; DEV void stage1(unsigned (&L)[16], const float* sp) {
;   float sv[128];
; #pragma unroll
;   for (int i = 0; i < 128; ++i) sv[i] = sp[(size_t)i * 128];
; #pragma unroll
;   for (int i = 0; i < 128; i += 16) {
;     unsigned g[16];
; #pragma unroll
;     for (int e = 0; e < 16; ++e) g[e] = (fkey(sv[i + e]) & ~127u) | (unsigned)(127 - (i + e));
;     bitonic_sort16_desc(g);
;     if (i == 0) {
; #pragma unroll
;       for (int e = 0; e < 16; ++e) L[e] = g[e];
;     } else merge_top16(L, g);
;   }
; }
	v_cmp_gt_i32_e32 vcc, 0, v80
	v_not_b32_e32 v118, v80
	v_or_b32_e32 v80, 0x80000000, v80
	v_cndmask_b32_e32 v80, v80, v118, vcc
	v_cmp_gt_i32_e32 vcc, 0, v79
	v_not_b32_e32 v118, v79
	v_or_b32_e32 v79, 0x80000000, v79
	v_cndmask_b32_e32 v79, v79, v118, vcc
	v_cmp_gt_i32_e32 vcc, 0, v77
	v_not_b32_e32 v119, v77
	v_or_b32_e32 v77, 0x80000000, v77
	v_cndmask_b32_e32 v77, v77, v119, vcc
	v_cmp_gt_i32_e32 vcc, 0, v76
	v_not_b32_e32 v119, v76
	v_or_b32_e32 v76, 0x80000000, v76
	v_max3_u32 v104, v123, v104, v135
	v_cndmask_b32_e32 v76, v76, v119, vcc
	v_cmp_gt_i32_e32 vcc, 0, v75
	v_not_b32_e32 v123, v75
	v_or_b32_e32 v75, 0x80000000, v75
	v_cndmask_b32_e32 v75, v75, v123, vcc
	v_cmp_gt_i32_e32 vcc, 0, v74
	v_not_b32_e32 v123, v74
	v_or_b32_e32 v74, 0x80000000, v74
	v_cndmask_b32_e32 v74, v74, v123, vcc
	v_cmp_gt_i32_e32 vcc, 0, v73
	v_not_b32_e32 v124, v73
	v_or_b32_e32 v73, 0x80000000, v73
	v_cndmask_b32_e32 v73, v73, v124, vcc
	v_cmp_gt_i32_e32 vcc, 0, v72
	v_not_b32_e32 v124, v72
	v_or_b32_e32 v72, 0x80000000, v72
	v_cndmask_b32_e32 v72, v72, v124, vcc
	v_and_b32_e32 v88, 0xffffff80, v88
	v_and_b32_e32 v87, 0xffffff80, v87
	v_and_b32_e32 v86, 0xffffff80, v86
	v_and_b32_e32 v85, 0xffffff80, v85
	v_and_b32_e32 v84, 0xffffff80, v84
	v_and_b32_e32 v83, 0xffffff80, v83
	v_and_b32_e32 v82, 0xffffff80, v82
	v_and_b32_e32 v81, 0xffffff80, v81
	v_and_b32_e32 v79, 0xffffff80, v79
	v_and_b32_e32 v77, 0xffffff80, v77
	v_and_b32_e32 v76, 0xffffff80, v76
	v_and_b32_e32 v75, 0xffffff80, v75
	v_and_b32_e32 v74, 0xffffff80, v74
	v_and_b32_e32 v73, 0xffffff80, v73
	v_and_b32_e32 v72, 0xffffff80, v72
	v_or_b32_e32 v88, 0x4f, v88
	v_or_b32_e32 v87, 0x4e, v87
	v_or_b32_e32 v86, 0x4c, v86
	v_or_b32_e32 v85, 0x4d, v85
	v_or_b32_e32 v84, 0x48, v84
	v_or_b32_e32 v83, 0x49, v83
	v_or_b32_e32 v82, 0x4b, v82
	v_or_b32_e32 v81, 0x4a, v81
	v_and_or_b32 v80, v80, s55, 64
	v_or_b32_e32 v79, 0x41, v79
	v_or_b32_e32 v77, 0x43, v77
	v_or_b32_e32 v76, 0x42, v76
	v_or_b32_e32 v75, 0x47, v75
	v_or_b32_e32 v74, 0x46, v74
	v_or_b32_e32 v73, 0x44, v73
	v_or_b32_e32 v72, 0x45, v72
	v_min_u32_e32 v140, v142, v136
	v_max_u32_e32 v111, v88, v87
	v_min_u32_e32 v112, v86, v85
	v_min_u32_e32 v87, v88, v87
	v_max_u32_e32 v85, v86, v85
	v_max_u32_e32 v114, v84, v83
	v_min_u32_e32 v115, v82, v81
	v_min_u32_e32 v83, v84, v83
	v_max_u32_e32 v81, v82, v81
	v_max_u32_e32 v118, v80, v79
	v_min_u32_e32 v119, v77, v76
	v_min_u32_e32 v79, v80, v79
	v_max_u32_e32 v76, v77, v76
	v_max_u32_e32 v123, v75, v74
	v_min_u32_e32 v124, v73, v72
	v_min_u32_e32 v74, v75, v74
	v_max_u32_e32 v72, v73, v72
	v_min_u32_e32 v105, v110, v105
	v_min_u32_e32 v110, v113, v116
	v_max_u32_e32 v90, v94, v90
	v_max3_u32 v94, v113, v116, v140
	v_max3_u32 v95, v106, v108, v95
	v_max3_u32 v106, v125, v134, v132
	v_max_u32_e32 v113, v111, v112
	v_max_u32_e32 v86, v87, v85
	v_min_u32_e32 v116, v114, v115
	v_min_u32_e32 v82, v83, v81
	v_min_u32_e32 v111, v111, v112
	v_min_u32_e32 v85, v87, v85
	v_max_u32_e32 v112, v114, v115
	v_max_u32_e32 v81, v83, v81
	v_max_u32_e32 v122, v118, v119
	v_max_u32_e32 v77, v79, v76
	v_min_u32_e32 v125, v123, v124
	v_min_u32_e32 v73, v74, v72
	v_min_u32_e32 v118, v118, v119
	v_min_u32_e32 v76, v79, v76
	v_max_u32_e32 v119, v123, v124
	v_max_u32_e32 v72, v74, v72
	v_max_u32_e32 v88, v113, v86
	v_min_u32_e32 v84, v116, v82
	v_max_u32_e32 v87, v111, v85
	v_min_u32_e32 v83, v112, v81
	v_min_u32_e32 v86, v113, v86
	v_max_u32_e32 v82, v116, v82
	v_min_u32_e32 v85, v111, v85
	v_max_u32_e32 v81, v112, v81
	v_max_u32_e32 v80, v122, v77
	v_min_u32_e32 v75, v125, v73
	v_max_u32_e32 v79, v118, v76
	v_min_u32_e32 v74, v119, v72
	v_min_u32_e32 v77, v122, v77
	v_max_u32_e32 v73, v125, v73
	v_min_u32_e32 v76, v118, v76
	v_max_u32_e32 v72, v119, v72
	v_max3_u32 v97, v126, v98, v97
	v_max_u32_e32 v117, v88, v84
	v_max_u32_e32 v114, v87, v83
	v_max_u32_e32 v113, v86, v82
	v_max_u32_e32 v111, v85, v81
	v_min_u32_e32 v126, v80, v75
	v_min_u32_e32 v123, v79, v74
	v_min_u32_e32 v122, v77, v73
	v_min_u32_e32 v118, v76, v72
	v_min_u32_e32 v84, v88, v84
	v_min_u32_e32 v83, v87, v83
	v_min_u32_e32 v82, v86, v82
	v_min_u32_e32 v81, v85, v81
	v_max_u32_e32 v75, v80, v75
	v_max_u32_e32 v74, v79, v74
	v_max_u32_e32 v73, v77, v73
	v_max_u32_e32 v72, v76, v72
	v_max_u32_e32 v115, v117, v114
	v_max_u32_e32 v112, v113, v111
	v_min_u32_e32 v124, v126, v123
	v_min_u32_e32 v119, v122, v118
	v_max_u32_e32 v87, v84, v83
	v_max_u32_e32 v85, v82, v81
	v_min_u32_e32 v79, v75, v74
	v_min_u32_e32 v76, v73, v72
	v_min_u32_e32 v114, v117, v114
	v_min_u32_e32 v111, v113, v111
	v_max_u32_e32 v117, v126, v123
	v_max_u32_e32 v118, v122, v118
	v_min_u32_e32 v83, v84, v83
	v_min_u32_e32 v81, v82, v81
	v_max_u32_e32 v74, v75, v74
	v_max_u32_e32 v72, v73, v72
	v_max_u32_e32 v89, v93, v89
	v_max_u32_e32 v116, v115, v112
	v_min_u32_e32 v125, v124, v119
	v_max_u32_e32 v86, v87, v85
	v_min_u32_e32 v77, v79, v76
	v_max_u32_e32 v113, v114, v111
	v_min_u32_e32 v122, v117, v118
	v_max_u32_e32 v82, v83, v81
	v_min_u32_e32 v73, v74, v72
	v_min_u32_e32 v128, v2, v105
	v_min_u32_e32 v93, v90, v89
	v_max3_u32 v96, v127, v96, v102
	v_min_u32_e32 v127, v116, v125
	v_min_u32_e32 v80, v86, v77
	v_min_u32_e32 v123, v113, v122
	v_min_u32_e32 v75, v82, v73
	v_max3_u32 v110, v110, v142, v136
	v_max3_u32 v2, v2, v105, v93
	v_max3_u32 v89, v128, v90, v89
	v_min_u32_e32 v88, v127, v80
	v_min_u32_e32 v84, v123, v75
	v_min_u32_e32 v112, v115, v112
	v_max_u32_e32 v115, v124, v119
	v_min_u32_e32 v85, v87, v85
	v_max_u32_e32 v76, v79, v76
	v_min_u32_e32 v111, v114, v111
	v_max_u32_e32 v114, v117, v118
	v_min_u32_e32 v81, v83, v81
	v_max_u32_e32 v72, v74, v72
	v_max_u32_e32 v80, v127, v80
; DEV unsigned fkey(float x) { const unsigned u = __float_as_uint(x); return (u & 0x80000000u) ? ~u : (u | 0x80000000u); }
; DEV float keyf(unsigned k) { const unsigned u = (k & 0x80000000u) ? (k & 0x7fffffffu) : ~k; return __uint_as_float(u); }
; DEV void bitonic_merge16_desc(unsigned (&v)[16]) {
; #pragma unroll
;   for (int j = 8; j >= 1; j >>= 1)
; #pragma unroll
;     for (int i = 0; i < 16; ++i) { const int l = i ^ j; if (l > i) cswap(v[i], v[l]); }
; }
; DEV void bitonic_sort16_desc(unsigned (&v)[16]) {
; #pragma unroll
;   for (int k = 2; k <= 16; k <<= 1)
; #pragma unroll
;     for (int j = k >> 1; j >= 1; j >>= 1)
; #pragma unroll
;       for (int i = 0; i < 16; ++i) { const int l = i ^ j; if (l > i) { if ((i & k) == 0) cswap(v[i], v[l]); else cswap(v[l], v[i]); } }
; }
; DEV void merge_top16(unsigned (&R)[16], const unsigned (&G)[16]) {
; #pragma unroll
;   for (int i = 0; i < 16; ++i) R[i] = max(R[i], G[15 - i]);
;   bitonic_merge16_desc(R);
; }
; DEV void stage1(unsigned (&L)[16], const float* sp) {
;   float sv[128];
; #pragma unroll
;   for (int i = 0; i < 128; ++i) sv[i] = sp[(size_t)i * 128];
; #pragma unroll
;   for (int i = 0; i < 128; i += 16) {
;     unsigned g[16];
; #pragma unroll
;     for (int e = 0; e < 16; ++e) g[e] = (fkey(sv[i + e]) & ~127u) | (unsigned)(127 - (i + e));
;     bitonic_sort16_desc(g);
;     if (i == 0) {
; #pragma unroll
;       for (int e = 0; e < 16; ++e) L[e] = g[e];
;     } else merge_top16(L, g);
;   }
; }
	v_max_u32_e32 v75, v123, v75
	v_max_u32_e32 v90, v94, v92
	v_max_u32_e32 v93, v110, v106
	v_max_u32_e32 v98, v103, v101
	v_min_u32_e32 v101, v103, v101
	v_max_u32_e32 v102, v99, v97
	v_min_u32_e32 v97, v99, v97
	v_max_u32_e32 v99, v100, v3
	v_min_u32_e32 v3, v100, v3
	v_max_u32_e32 v100, v104, v96
	v_max_u32_e32 v103, v95, v2
	v_min_u32_e32 v2, v95, v2
	v_max_u32_e32 v95, v91, v89
	v_min_u32_e32 v126, v88, v84
	v_min_u32_e32 v119, v112, v115
	v_min_u32_e32 v79, v85, v76
	v_min_u32_e32 v117, v111, v114
	v_min_u32_e32 v74, v81, v72
	v_max_u32_e32 v84, v88, v84
	v_min_u32_e32 v88, v80, v75
	v_max_u32_e32 v75, v80, v75
	v_max_u32_e32 v80, v116, v125
	v_max_u32_e32 v77, v86, v77
	v_max_u32_e32 v113, v113, v122
	v_max_u32_e32 v73, v82, v73
	v_max_u32_e32 v112, v112, v115
	v_max_u32_e32 v76, v85, v76
	v_max_u32_e32 v111, v111, v114
	v_max_u32_e32 v72, v81, v72
	v_min_u32_e32 v92, v94, v92
	v_min_u32_e32 v94, v110, v106
	v_min_u32_e32 v96, v104, v96
	v_min_u32_e32 v89, v91, v89
	v_max_u32_e32 v91, v90, v99
	v_min_u32_e32 v90, v90, v99
	v_max_u32_e32 v99, v93, v100
	v_min_u32_e32 v93, v93, v100
	v_max_u32_e32 v100, v98, v103
	v_min_u32_e32 v98, v98, v103
	v_max_u32_e32 v103, v102, v95
	v_min_u32_e32 v95, v102, v95
	v_min_u32_e32 v86, v80, v77
	v_min_u32_e32 v82, v113, v73
	v_min_u32_e32 v85, v112, v76
	v_min_u32_e32 v81, v111, v72
	v_max_u32_e32 v102, v92, v3
	v_min_u32_e32 v3, v92, v3
	v_max_u32_e32 v92, v94, v96
	v_min_u32_e32 v94, v94, v96
	v_max_u32_e32 v96, v101, v2
	v_min_u32_e32 v2, v101, v2
	v_max_u32_e32 v101, v97, v89
	v_min_u32_e32 v89, v97, v89
	v_max_u32_e32 v97, v91, v100
	v_min_u32_e32 v91, v91, v100
	v_max_u32_e32 v100, v99, v103
	v_min_u32_e32 v99, v99, v103
	v_max_u32_e32 v103, v90, v98
	v_min_u32_e32 v90, v90, v98
	v_max_u32_e32 v98, v93, v95
	v_min_u32_e32 v93, v93, v95
	v_min_u32_e32 v87, v119, v79
	v_min_u32_e32 v83, v117, v74
	v_max_u32_e32 v79, v119, v79
	v_max_u32_e32 v74, v117, v74
	v_min_u32_e32 v116, v86, v82
	v_min_u32_e32 v114, v85, v81
	v_max_u32_e32 v95, v102, v96
	v_min_u32_e32 v96, v102, v96
	v_max_u32_e32 v102, v92, v101
	v_min_u32_e32 v106, v90, v93
	v_min_u32_e32 v117, v79, v74
	v_max_u32_e32 v74, v79, v74
	v_min_u32_e32 v115, v116, v114
	v_min_u32_e32 v107, v95, v102
	v_min_u32_e32 v79, v75, v74
	v_max_u32_e32 v82, v86, v82
	v_max_u32_e32 v81, v85, v81
	v_max3_u32 v74, v106, v75, v74
	v_max3_u32 v75, v95, v102, v115
	v_cmp_gt_i32_e32 vcc, 0, v71
	v_not_b32_e32 v95, v71
	v_or_b32_e32 v71, 0x80000000, v71
	v_min_u32_e32 v92, v92, v101
	v_min_u32_e32 v85, v82, v81
	v_cndmask_b32_e32 v71, v71, v95, vcc
	v_cmp_gt_i32_e32 vcc, 0, v70
	v_not_b32_e32 v95, v70
	v_or_b32_e32 v70, 0x80000000, v70
	v_min_u32_e32 v108, v96, v92
	v_max3_u32 v85, v96, v92, v85
	v_cndmask_b32_e32 v70, v70, v95, vcc
	v_cmp_gt_i32_e32 vcc, 0, v69
	v_not_b32_e32 v96, v69
	v_or_b32_e32 v69, 0x80000000, v69
	v_min_u32_e32 v104, v91, v99
	v_min_u32_e32 v118, v87, v83
	v_max_u32_e32 v83, v87, v83
	v_min_u32_e32 v119, v88, v117
	v_cndmask_b32_e32 v69, v69, v96, vcc
	v_cmp_gt_i32_e32 vcc, 0, v68
	v_not_b32_e32 v96, v68
	v_or_b32_e32 v68, 0x80000000, v68
	v_min_u32_e32 v105, v103, v98
	v_min_u32_e32 v87, v84, v83
	v_max3_u32 v83, v104, v84, v83
	v_max3_u32 v84, v103, v98, v119
	v_cndmask_b32_e32 v68, v68, v96, vcc
	v_cmp_gt_i32_e32 vcc, 0, v67
	v_not_b32_e32 v98, v67
	v_or_b32_e32 v67, 0x80000000, v67
	v_cndmask_b32_e32 v67, v67, v98, vcc
	v_cmp_gt_i32_e32 vcc, 0, v66
	v_not_b32_e32 v98, v66
	v_or_b32_e32 v66, 0x80000000, v66
	v_max3_u32 v87, v91, v99, v87
	v_cndmask_b32_e32 v66, v66, v98, vcc
	v_cmp_gt_i32_e32 vcc, 0, v63
	v_not_b32_e32 v99, v63
	v_or_b32_e32 v63, 0x80000000, v63
	v_cndmask_b32_e32 v63, v63, v99, vcc
	v_cmp_gt_i32_e32 vcc, 0, v62
	v_not_b32_e32 v99, v62
	v_or_b32_e32 v62, 0x80000000, v62
	v_cndmask_b32_e32 v62, v62, v99, vcc
	v_cmp_gt_i32_e32 vcc, 0, v61
	v_not_b32_e32 v102, v61
	v_or_b32_e32 v61, 0x80000000, v61
	v_cndmask_b32_e32 v61, v61, v102, vcc
	v_cmp_gt_i32_e32 vcc, 0, v60
	v_not_b32_e32 v102, v60
	v_or_b32_e32 v60, 0x80000000, v60
	v_cndmask_b32_e32 v60, v60, v102, vcc
	v_cmp_gt_i32_e32 vcc, 0, v59
	v_not_b32_e32 v103, v59
	v_or_b32_e32 v59, 0x80000000, v59
	v_cndmask_b32_e32 v59, v59, v103, vcc
	v_cmp_gt_i32_e32 vcc, 0, v58
	v_not_b32_e32 v103, v58
	v_or_b32_e32 v58, 0x80000000, v58
	v_max3_u32 v88, v105, v88, v117
	v_cndmask_b32_e32 v58, v58, v103, vcc
	v_cmp_gt_i32_e32 vcc, 0, v57
	v_not_b32_e32 v105, v57
	v_or_b32_e32 v57, 0x80000000, v57
	v_cndmask_b32_e32 v57, v57, v105, vcc
	v_cmp_gt_i32_e32 vcc, 0, v56
	v_not_b32_e32 v105, v56
	v_or_b32_e32 v56, 0x80000000, v56
	v_cndmask_b32_e32 v56, v56, v105, vcc
	v_cmp_gt_i32_e32 vcc, 0, v55
	v_not_b32_e32 v106, v55
	v_or_b32_e32 v55, 0x80000000, v55
	v_cndmask_b32_e32 v55, v55, v106, vcc
	v_cmp_gt_i32_e32 vcc, 0, v54
	v_not_b32_e32 v106, v54
	v_or_b32_e32 v54, 0x80000000, v54
	v_cndmask_b32_e32 v54, v54, v106, vcc
	v_and_or_b32 v71, v71, s55, 63
	v_and_or_b32 v70, v70, s55, 62
	v_and_or_b32 v69, v69, s55, 60
	v_and_or_b32 v68, v68, s55, 61
	v_and_or_b32 v67, v67, s55, 56
	v_and_or_b32 v66, v66, s55, 57
	v_and_or_b32 v63, v63, s55, 59
	v_and_or_b32 v62, v62, s55, 58
	v_and_or_b32 v61, v61, s55, 48
	v_and_or_b32 v60, v60, s55, 49
	v_and_or_b32 v59, v59, s55, 51
	v_and_or_b32 v58, v58, s55, 50
	v_and_or_b32 v57, v57, s55, 55
	v_and_or_b32 v56, v56, s55, 54
	v_and_or_b32 v55, v55, s55, 52
	v_and_or_b32 v54, v54, s55, 53
	v_min_u32_e32 v124, v126, v118
	v_max_u32_e32 v77, v80, v77
	v_max_u32_e32 v73, v113, v73
	v_max_u32_e32 v76, v112, v76
	v_max_u32_e32 v72, v111, v72
	v_max_u32_e32 v95, v71, v70
	v_min_u32_e32 v96, v69, v68
	v_min_u32_e32 v70, v71, v70
	v_max_u32_e32 v68, v69, v68
; DEV unsigned fkey(float x) { const unsigned u = __float_as_uint(x); return (u & 0x80000000u) ? ~u : (u | 0x80000000u); }
; DEV float keyf(unsigned k) { const unsigned u = (k & 0x80000000u) ? (k & 0x7fffffffu) : ~k; return __uint_as_float(u); }
; DEV void bitonic_merge16_desc(unsigned (&v)[16]) {
; #pragma unroll
;   for (int j = 8; j >= 1; j >>= 1)
; #pragma unroll
;     for (int i = 0; i < 16; ++i) { const int l = i ^ j; if (l > i) cswap(v[i], v[l]); }
; }
; DEV void bitonic_sort16_desc(unsigned (&v)[16]) {
; #pragma unroll
;   for (int k = 2; k <= 16; k <<= 1)
; #pragma unroll
;     for (int j = k >> 1; j >= 1; j >>= 1)
; #pragma unroll
;       for (int i = 0; i < 16; ++i) { const int l = i ^ j; if (l > i) { if ((i & k) == 0) cswap(v[i], v[l]); else cswap(v[l], v[i]); } }
; }
; DEV void merge_top16(unsigned (&R)[16], const unsigned (&G)[16]) {
; #pragma unroll
;   for (int i = 0; i < 16; ++i) R[i] = max(R[i], G[15 - i]);
;   bitonic_merge16_desc(R);
; }
; DEV void stage1(unsigned (&L)[16], const float* sp) {
;   float sv[128];
; #pragma unroll
;   for (int i = 0; i < 128; ++i) sv[i] = sp[(size_t)i * 128];
; #pragma unroll
;   for (int i = 0; i < 128; i += 16) {
;     unsigned g[16];
; #pragma unroll
;     for (int e = 0; e < 16; ++e) g[e] = (fkey(sv[i + e]) & ~127u) | (unsigned)(127 - (i + e));
;     bitonic_sort16_desc(g);
;     if (i == 0) {
; #pragma unroll
;       for (int e = 0; e < 16; ++e) L[e] = g[e];
;     } else merge_top16(L, g);
;   }
; }
	v_max_u32_e32 v98, v67, v66
	v_min_u32_e32 v99, v63, v62
	v_min_u32_e32 v66, v67, v66
	v_max_u32_e32 v62, v63, v62
	v_max_u32_e32 v102, v61, v60
	v_min_u32_e32 v103, v59, v58
	v_min_u32_e32 v60, v61, v60
	v_max_u32_e32 v58, v59, v58
	v_max_u32_e32 v105, v57, v56
	v_min_u32_e32 v106, v55, v54
	v_min_u32_e32 v56, v57, v56
	v_max_u32_e32 v54, v55, v54
	v_max_u32_e32 v101, v3, v2
	v_min_u32_e32 v2, v3, v2
	v_max_u32_e32 v3, v94, v89
	v_min_u32_e32 v89, v94, v89
	v_min_u32_e32 v94, v97, v100
	v_min_u32_e32 v80, v77, v73
	v_min_u32_e32 v86, v76, v72
	v_max_u32_e32 v73, v77, v73
	v_max3_u32 v77, v97, v100, v124
	v_max3_u32 v79, v90, v93, v79
	v_max3_u32 v90, v107, v116, v114
	v_max_u32_e32 v97, v95, v96
	v_max_u32_e32 v69, v70, v68
	v_min_u32_e32 v100, v98, v99
	v_min_u32_e32 v63, v66, v62
	v_min_u32_e32 v95, v95, v96
	v_min_u32_e32 v68, v70, v68
	v_max_u32_e32 v96, v98, v99
	v_max_u32_e32 v62, v66, v62
	v_max_u32_e32 v104, v102, v103
	v_max_u32_e32 v59, v60, v58
	v_min_u32_e32 v107, v105, v106
	v_min_u32_e32 v55, v56, v54
	v_min_u32_e32 v102, v102, v103
	v_min_u32_e32 v58, v60, v58
	v_max_u32_e32 v103, v105, v106
	v_max_u32_e32 v54, v56, v54
	v_min_u32_e32 v111, v80, v86
	v_max_u32_e32 v71, v97, v69
	v_min_u32_e32 v67, v100, v63
	v_max_u32_e32 v70, v95, v68
	v_min_u32_e32 v66, v96, v62
	v_min_u32_e32 v69, v97, v69
	v_max_u32_e32 v63, v100, v63
	v_min_u32_e32 v68, v95, v68
	v_max_u32_e32 v62, v96, v62
	v_max_u32_e32 v61, v104, v59
	v_min_u32_e32 v57, v107, v55
	v_max_u32_e32 v60, v102, v58
	v_min_u32_e32 v56, v103, v54
	v_min_u32_e32 v59, v104, v59
	v_max_u32_e32 v55, v107, v55
	v_min_u32_e32 v58, v102, v58
	v_max_u32_e32 v54, v103, v54
	v_min_u32_e32 v109, v101, v3
	v_max3_u32 v81, v108, v82, v81
	v_max3_u32 v3, v101, v3, v111
	v_max_u32_e32 v101, v71, v67
	v_max_u32_e32 v98, v70, v66
	v_max_u32_e32 v97, v69, v63
	v_max_u32_e32 v95, v68, v62
	v_min_u32_e32 v108, v61, v57
	v_min_u32_e32 v105, v60, v56
	v_min_u32_e32 v104, v59, v55
	v_min_u32_e32 v102, v58, v54
	v_min_u32_e32 v67, v71, v67
	v_min_u32_e32 v66, v70, v66
	v_min_u32_e32 v63, v69, v63
	v_min_u32_e32 v62, v68, v62
	v_max_u32_e32 v57, v61, v57
	v_max_u32_e32 v56, v60, v56
	v_max_u32_e32 v55, v59, v55
	v_max_u32_e32 v54, v58, v54
	v_max_u32_e32 v99, v101, v98
	v_max_u32_e32 v96, v97, v95
	v_min_u32_e32 v106, v108, v105
	v_min_u32_e32 v103, v104, v102
	v_max_u32_e32 v70, v67, v66
	v_max_u32_e32 v68, v63, v62
	v_min_u32_e32 v60, v57, v56
	v_min_u32_e32 v58, v55, v54
	v_min_u32_e32 v98, v101, v98
	v_min_u32_e32 v95, v97, v95
	v_max_u32_e32 v101, v108, v105
	v_max_u32_e32 v102, v104, v102
	v_min_u32_e32 v66, v67, v66
	v_min_u32_e32 v62, v63, v62
	v_max_u32_e32 v56, v57, v56
	v_max_u32_e32 v54, v55, v54
	v_max_u32_e32 v72, v76, v72
	v_max_u32_e32 v100, v99, v96
	v_min_u32_e32 v107, v106, v103
	v_max_u32_e32 v69, v70, v68
	v_min_u32_e32 v59, v60, v58
	v_max_u32_e32 v97, v98, v95
	v_min_u32_e32 v104, v101, v102
	v_max_u32_e32 v63, v66, v62
	v_min_u32_e32 v55, v56, v54
	v_min_u32_e32 v110, v2, v89
	v_min_u32_e32 v76, v73, v72
	v_max3_u32 v80, v109, v80, v86
	v_min_u32_e32 v109, v100, v107
	v_min_u32_e32 v61, v69, v59
	v_min_u32_e32 v105, v97, v104
	v_min_u32_e32 v57, v63, v55
	v_max3_u32 v94, v94, v126, v118
	v_max3_u32 v2, v2, v89, v76
	v_max3_u32 v72, v110, v73, v72
	v_min_u32_e32 v71, v109, v61
	v_min_u32_e32 v67, v105, v57
	v_min_u32_e32 v96, v99, v96
	v_max_u32_e32 v99, v106, v103
	v_min_u32_e32 v68, v70, v68
	v_max_u32_e32 v58, v60, v58
	v_min_u32_e32 v95, v98, v95
	v_max_u32_e32 v98, v101, v102
	v_min_u32_e32 v62, v66, v62
	v_max_u32_e32 v54, v56, v54
	v_max_u32_e32 v61, v109, v61
	v_max_u32_e32 v57, v105, v57
	v_max_u32_e32 v73, v77, v75
	v_max_u32_e32 v76, v94, v90
	v_max_u32_e32 v82, v87, v85
	v_min_u32_e32 v85, v87, v85
	v_max_u32_e32 v86, v83, v81
	v_min_u32_e32 v81, v83, v81
	v_max_u32_e32 v83, v84, v3
	v_min_u32_e32 v3, v84, v3
	v_max_u32_e32 v84, v88, v80
	v_max_u32_e32 v87, v79, v2
	v_min_u32_e32 v2, v79, v2
	v_max_u32_e32 v79, v74, v72
	v_min_u32_e32 v108, v71, v67
	v_min_u32_e32 v103, v96, v99
	v_min_u32_e32 v60, v68, v58
	v_min_u32_e32 v101, v95, v98
	v_min_u32_e32 v56, v62, v54
	v_max_u32_e32 v67, v71, v67
	v_min_u32_e32 v71, v61, v57
	v_max_u32_e32 v57, v61, v57
	v_max_u32_e32 v61, v100, v107
	v_max_u32_e32 v59, v69, v59
	v_max_u32_e32 v97, v97, v104
	v_max_u32_e32 v55, v63, v55
	v_max_u32_e32 v96, v96, v99
	v_max_u32_e32 v58, v68, v58
	v_max_u32_e32 v95, v95, v98
	v_max_u32_e32 v54, v62, v54
	v_min_u32_e32 v75, v77, v75
	v_min_u32_e32 v77, v94, v90
	v_min_u32_e32 v80, v88, v80
	v_min_u32_e32 v72, v74, v72
	v_max_u32_e32 v74, v73, v83
	v_min_u32_e32 v73, v73, v83
	v_max_u32_e32 v83, v76, v84
	v_min_u32_e32 v76, v76, v84
	v_max_u32_e32 v84, v82, v87
	v_min_u32_e32 v82, v82, v87
	v_max_u32_e32 v87, v86, v79
	v_min_u32_e32 v79, v86, v79
	v_min_u32_e32 v69, v61, v59
	v_min_u32_e32 v63, v97, v55
	v_min_u32_e32 v68, v96, v58
	v_min_u32_e32 v62, v95, v54
	v_max_u32_e32 v86, v75, v3
	v_min_u32_e32 v3, v75, v3
	v_max_u32_e32 v75, v77, v80
	v_min_u32_e32 v77, v77, v80
	v_max_u32_e32 v80, v85, v2
	v_min_u32_e32 v2, v85, v2
	v_max_u32_e32 v85, v81, v72
	v_min_u32_e32 v72, v81, v72
	v_max_u32_e32 v81, v74, v84
	v_min_u32_e32 v74, v74, v84
	v_max_u32_e32 v84, v83, v87
	v_min_u32_e32 v83, v83, v87
	v_max_u32_e32 v87, v73, v82
	v_min_u32_e32 v73, v73, v82
	v_max_u32_e32 v82, v76, v79
	v_min_u32_e32 v76, v76, v79
	v_min_u32_e32 v70, v103, v60
	v_min_u32_e32 v66, v101, v56
	v_max_u32_e32 v60, v103, v60
	v_max_u32_e32 v56, v101, v56
	v_min_u32_e32 v100, v69, v63
	v_min_u32_e32 v98, v68, v62
	v_max_u32_e32 v79, v86, v80
	v_min_u32_e32 v80, v86, v80
	v_max_u32_e32 v86, v75, v85
; DEV unsigned fkey(float x) { const unsigned u = __float_as_uint(x); return (u & 0x80000000u) ? ~u : (u | 0x80000000u); }
; DEV float keyf(unsigned k) { const unsigned u = (k & 0x80000000u) ? (k & 0x7fffffffu) : ~k; return __uint_as_float(u); }
; DEV void bitonic_merge16_desc(unsigned (&v)[16]) {
; #pragma unroll
;   for (int j = 8; j >= 1; j >>= 1)
; #pragma unroll
;     for (int i = 0; i < 16; ++i) { const int l = i ^ j; if (l > i) cswap(v[i], v[l]); }
; }
; DEV void bitonic_sort16_desc(unsigned (&v)[16]) {
; #pragma unroll
;   for (int k = 2; k <= 16; k <<= 1)
; #pragma unroll
;     for (int j = k >> 1; j >= 1; j >>= 1)
; #pragma unroll
;       for (int i = 0; i < 16; ++i) { const int l = i ^ j; if (l > i) { if ((i & k) == 0) cswap(v[i], v[l]); else cswap(v[l], v[i]); } }
; }
; DEV void merge_top16(unsigned (&R)[16], const unsigned (&G)[16]) {
; #pragma unroll
;   for (int i = 0; i < 16; ++i) R[i] = max(R[i], G[15 - i]);
;   bitonic_merge16_desc(R);
; }
; DEV void stage1(unsigned (&L)[16], const float* sp) {
;   float sv[128];
; #pragma unroll
;   for (int i = 0; i < 128; ++i) sv[i] = sp[(size_t)i * 128];
; #pragma unroll
;   for (int i = 0; i < 128; i += 16) {
;     unsigned g[16];
; #pragma unroll
;     for (int e = 0; e < 16; ++e) g[e] = (fkey(sv[i + e]) & ~127u) | (unsigned)(127 - (i + e));
;     bitonic_sort16_desc(g);
;     if (i == 0) {
; #pragma unroll
;       for (int e = 0; e < 16; ++e) L[e] = g[e];
;     } else merge_top16(L, g);
;   }
; }
	v_min_u32_e32 v90, v73, v76
	v_min_u32_e32 v101, v60, v56
	v_max_u32_e32 v56, v60, v56
	v_min_u32_e32 v99, v100, v98
	v_min_u32_e32 v91, v79, v86
	v_min_u32_e32 v60, v57, v56
	v_max_u32_e32 v63, v69, v63
	v_max_u32_e32 v62, v68, v62
	v_max3_u32 v56, v90, v57, v56
	v_max3_u32 v57, v79, v86, v99
	v_cmp_gt_i32_e32 vcc, 0, v53
	v_not_b32_e32 v79, v53
	v_or_b32_e32 v53, 0x80000000, v53
	v_min_u32_e32 v75, v75, v85
	v_min_u32_e32 v68, v63, v62
	v_cndmask_b32_e32 v53, v53, v79, vcc
	v_cmp_gt_i32_e32 vcc, 0, v52
	v_not_b32_e32 v79, v52
	v_or_b32_e32 v52, 0x80000000, v52
	v_min_u32_e32 v92, v80, v75
	v_max3_u32 v68, v80, v75, v68
	v_cndmask_b32_e32 v52, v52, v79, vcc
	v_cmp_gt_i32_e32 vcc, 0, v51
	v_not_b32_e32 v80, v51
	v_or_b32_e32 v51, 0x80000000, v51
	v_min_u32_e32 v88, v74, v83
	v_min_u32_e32 v102, v70, v66
	v_max_u32_e32 v66, v70, v66
	v_min_u32_e32 v103, v71, v101
	v_cndmask_b32_e32 v51, v51, v80, vcc
	v_cmp_gt_i32_e32 vcc, 0, v50
	v_not_b32_e32 v80, v50
	v_or_b32_e32 v50, 0x80000000, v50
	v_min_u32_e32 v89, v87, v82
	v_min_u32_e32 v70, v67, v66
	v_max3_u32 v66, v88, v67, v66
	v_max3_u32 v67, v87, v82, v103
	v_cndmask_b32_e32 v50, v50, v80, vcc
	v_cmp_gt_i32_e32 vcc, 0, v49
	v_not_b32_e32 v82, v49
	v_or_b32_e32 v49, 0x80000000, v49
	v_cndmask_b32_e32 v49, v49, v82, vcc
	v_cmp_gt_i32_e32 vcc, 0, v48
	v_not_b32_e32 v82, v48
	v_or_b32_e32 v48, 0x80000000, v48
	v_max3_u32 v70, v74, v83, v70
	v_cndmask_b32_e32 v48, v48, v82, vcc
	v_cmp_gt_i32_e32 vcc, 0, v47
	v_not_b32_e32 v83, v47
	v_or_b32_e32 v47, 0x80000000, v47
	v_cndmask_b32_e32 v47, v47, v83, vcc
	v_cmp_gt_i32_e32 vcc, 0, v46
	v_not_b32_e32 v83, v46
	v_or_b32_e32 v46, 0x80000000, v46
	v_cndmask_b32_e32 v46, v46, v83, vcc
	v_cmp_gt_i32_e32 vcc, 0, v45
	v_not_b32_e32 v86, v45
	v_or_b32_e32 v45, 0x80000000, v45
	v_cndmask_b32_e32 v45, v45, v86, vcc
	v_cmp_gt_i32_e32 vcc, 0, v44
	v_not_b32_e32 v86, v44
	v_or_b32_e32 v44, 0x80000000, v44
	v_cndmask_b32_e32 v44, v44, v86, vcc
	v_cmp_gt_i32_e32 vcc, 0, v43
	v_not_b32_e32 v87, v43
	v_or_b32_e32 v43, 0x80000000, v43
	v_cndmask_b32_e32 v43, v43, v87, vcc
	v_cmp_gt_i32_e32 vcc, 0, v42
	v_not_b32_e32 v87, v42
	v_or_b32_e32 v42, 0x80000000, v42
	v_max3_u32 v71, v89, v71, v101
	v_cndmask_b32_e32 v42, v42, v87, vcc
	v_cmp_gt_i32_e32 vcc, 0, v41
	v_not_b32_e32 v89, v41
	v_or_b32_e32 v41, 0x80000000, v41
	v_cndmask_b32_e32 v41, v41, v89, vcc
	v_cmp_gt_i32_e32 vcc, 0, v40
	v_not_b32_e32 v89, v40
	v_or_b32_e32 v40, 0x80000000, v40
	v_cndmask_b32_e32 v40, v40, v89, vcc
	v_cmp_gt_i32_e32 vcc, 0, v39
	v_not_b32_e32 v90, v39
	v_or_b32_e32 v39, 0x80000000, v39
	v_cndmask_b32_e32 v39, v39, v90, vcc
	v_cmp_gt_i32_e32 vcc, 0, v38
	v_not_b32_e32 v90, v38
	v_or_b32_e32 v38, 0x80000000, v38
	v_cndmask_b32_e32 v38, v38, v90, vcc
	v_and_or_b32 v53, v53, s55, 47
	v_and_or_b32 v52, v52, s55, 46
	v_and_or_b32 v51, v51, s55, 44
	v_and_or_b32 v50, v50, s55, 45
	v_and_or_b32 v49, v49, s55, 40
	v_and_or_b32 v48, v48, s55, 41
	v_and_or_b32 v47, v47, s55, 43
	v_and_or_b32 v46, v46, s55, 42
	v_and_or_b32 v45, v45, s55, 32
	v_and_or_b32 v44, v44, s55, 33
	v_and_or_b32 v43, v43, s55, 35
	v_and_or_b32 v42, v42, s55, 34
	v_and_or_b32 v41, v41, s55, 39
	v_and_or_b32 v40, v40, s55, 38
	v_and_or_b32 v39, v39, s55, 36
	v_and_or_b32 v38, v38, s55, 37
	v_min_u32_e32 v106, v108, v102
	v_max_u32_e32 v59, v61, v59
	v_max_u32_e32 v55, v97, v55
	v_max_u32_e32 v58, v96, v58
	v_max_u32_e32 v54, v95, v54
	v_max_u32_e32 v79, v53, v52
	v_min_u32_e32 v80, v51, v50
	v_min_u32_e32 v52, v53, v52
	v_max_u32_e32 v50, v51, v50
	v_max_u32_e32 v82, v49, v48
	v_min_u32_e32 v83, v47, v46
	v_min_u32_e32 v48, v49, v48
	v_max_u32_e32 v46, v47, v46
	v_max_u32_e32 v86, v45, v44
	v_min_u32_e32 v87, v43, v42
	v_min_u32_e32 v44, v45, v44
	v_max_u32_e32 v42, v43, v42
	v_max_u32_e32 v89, v41, v40
	v_min_u32_e32 v90, v39, v38
	v_min_u32_e32 v40, v41, v40
	v_max_u32_e32 v38, v39, v38
	v_max_u32_e32 v85, v3, v2
	v_min_u32_e32 v2, v3, v2
	v_max_u32_e32 v3, v77, v72
	v_min_u32_e32 v72, v77, v72
	v_min_u32_e32 v77, v81, v84
	v_min_u32_e32 v61, v59, v55
	v_min_u32_e32 v69, v58, v54
	v_max_u32_e32 v55, v59, v55
	v_max3_u32 v59, v81, v84, v106
	v_max3_u32 v60, v73, v76, v60
	v_max3_u32 v73, v91, v100, v98
	v_max_u32_e32 v81, v79, v80
	v_max_u32_e32 v51, v52, v50
	v_min_u32_e32 v84, v82, v83
	v_min_u32_e32 v47, v48, v46
	v_min_u32_e32 v79, v79, v80
	v_min_u32_e32 v50, v52, v50
	v_max_u32_e32 v80, v82, v83
	v_max_u32_e32 v46, v48, v46
	v_max_u32_e32 v88, v86, v87
	v_max_u32_e32 v43, v44, v42
	v_min_u32_e32 v91, v89, v90
	v_min_u32_e32 v39, v40, v38
	v_min_u32_e32 v86, v86, v87
	v_min_u32_e32 v42, v44, v42
	v_max_u32_e32 v87, v89, v90
	v_max_u32_e32 v38, v40, v38
	v_min_u32_e32 v95, v61, v69
	v_max_u32_e32 v53, v81, v51
	v_min_u32_e32 v49, v84, v47
	v_max_u32_e32 v52, v79, v50
	v_min_u32_e32 v48, v80, v46
	v_min_u32_e32 v51, v81, v51
	v_max_u32_e32 v47, v84, v47
	v_min_u32_e32 v50, v79, v50
	v_max_u32_e32 v46, v80, v46
	v_max_u32_e32 v45, v88, v43
	v_min_u32_e32 v41, v91, v39
	v_max_u32_e32 v44, v86, v42
	v_min_u32_e32 v40, v87, v38
	v_min_u32_e32 v43, v88, v43
	v_max_u32_e32 v39, v91, v39
	v_min_u32_e32 v42, v86, v42
	v_max_u32_e32 v38, v87, v38
	v_min_u32_e32 v93, v85, v3
	v_max3_u32 v62, v92, v63, v62
	v_max3_u32 v3, v85, v3, v95
	v_max_u32_e32 v85, v53, v49
	v_max_u32_e32 v82, v52, v48
	v_max_u32_e32 v81, v51, v47
	v_max_u32_e32 v79, v50, v46
	v_min_u32_e32 v92, v45, v41
	v_min_u32_e32 v89, v44, v40
	v_min_u32_e32 v88, v43, v39
	v_min_u32_e32 v86, v42, v38
	v_min_u32_e32 v49, v53, v49
	v_min_u32_e32 v48, v52, v48
	v_min_u32_e32 v47, v51, v47
	v_min_u32_e32 v46, v50, v46
	v_max_u32_e32 v41, v45, v41
	v_max_u32_e32 v40, v44, v40
; DEV unsigned fkey(float x) { const unsigned u = __float_as_uint(x); return (u & 0x80000000u) ? ~u : (u | 0x80000000u); }
; DEV float keyf(unsigned k) { const unsigned u = (k & 0x80000000u) ? (k & 0x7fffffffu) : ~k; return __uint_as_float(u); }
; DEV void bitonic_merge16_desc(unsigned (&v)[16]) {
; #pragma unroll
;   for (int j = 8; j >= 1; j >>= 1)
; #pragma unroll
;     for (int i = 0; i < 16; ++i) { const int l = i ^ j; if (l > i) cswap(v[i], v[l]); }
; }
; DEV void bitonic_sort16_desc(unsigned (&v)[16]) {
; #pragma unroll
;   for (int k = 2; k <= 16; k <<= 1)
; #pragma unroll
;     for (int j = k >> 1; j >= 1; j >>= 1)
; #pragma unroll
;       for (int i = 0; i < 16; ++i) { const int l = i ^ j; if (l > i) { if ((i & k) == 0) cswap(v[i], v[l]); else cswap(v[l], v[i]); } }
; }
; DEV void merge_top16(unsigned (&R)[16], const unsigned (&G)[16]) {
; #pragma unroll
;   for (int i = 0; i < 16; ++i) R[i] = max(R[i], G[15 - i]);
;   bitonic_merge16_desc(R);
; }
; DEV void stage1(unsigned (&L)[16], const float* sp) {
;   float sv[128];
; #pragma unroll
;   for (int i = 0; i < 128; ++i) sv[i] = sp[(size_t)i * 128];
; #pragma unroll
;   for (int i = 0; i < 128; i += 16) {
;     unsigned g[16];
; #pragma unroll
;     for (int e = 0; e < 16; ++e) g[e] = (fkey(sv[i + e]) & ~127u) | (unsigned)(127 - (i + e));
;     bitonic_sort16_desc(g);
;     if (i == 0) {
; #pragma unroll
;       for (int e = 0; e < 16; ++e) L[e] = g[e];
;     } else merge_top16(L, g);
;   }
; }
	v_max_u32_e32 v39, v43, v39
	v_max_u32_e32 v38, v42, v38
	v_max_u32_e32 v83, v85, v82
	v_max_u32_e32 v80, v81, v79
	v_min_u32_e32 v90, v92, v89
	v_min_u32_e32 v87, v88, v86
	v_max_u32_e32 v52, v49, v48
	v_max_u32_e32 v50, v47, v46
	v_min_u32_e32 v44, v41, v40
	v_min_u32_e32 v42, v39, v38
	v_min_u32_e32 v82, v85, v82
	v_min_u32_e32 v79, v81, v79
	v_max_u32_e32 v85, v92, v89
	v_max_u32_e32 v86, v88, v86
	v_min_u32_e32 v48, v49, v48
	v_min_u32_e32 v46, v47, v46
	v_max_u32_e32 v40, v41, v40
	v_max_u32_e32 v38, v39, v38
	v_max_u32_e32 v54, v58, v54
	v_max_u32_e32 v84, v83, v80
	v_min_u32_e32 v91, v90, v87
	v_max_u32_e32 v51, v52, v50
	v_min_u32_e32 v43, v44, v42
	v_max_u32_e32 v81, v82, v79
	v_min_u32_e32 v88, v85, v86
	v_max_u32_e32 v47, v48, v46
	v_min_u32_e32 v39, v40, v38
	v_min_u32_e32 v94, v2, v72
	v_min_u32_e32 v58, v55, v54
	v_max3_u32 v61, v93, v61, v69
	v_min_u32_e32 v93, v84, v91
	v_min_u32_e32 v45, v51, v43
	v_min_u32_e32 v89, v81, v88
	v_min_u32_e32 v41, v47, v39
	v_max3_u32 v77, v77, v108, v102
	v_max3_u32 v2, v2, v72, v58
	v_max3_u32 v54, v94, v55, v54
	v_min_u32_e32 v53, v93, v45
	v_min_u32_e32 v49, v89, v41
	v_min_u32_e32 v80, v83, v80
	v_max_u32_e32 v83, v90, v87
	v_min_u32_e32 v50, v52, v50
	v_max_u32_e32 v42, v44, v42
	v_min_u32_e32 v79, v82, v79
	v_max_u32_e32 v82, v85, v86
	v_min_u32_e32 v46, v48, v46
	v_max_u32_e32 v38, v40, v38
	v_max_u32_e32 v45, v93, v45
	v_max_u32_e32 v41, v89, v41
	v_max_u32_e32 v55, v59, v57
	v_max_u32_e32 v58, v77, v73
	v_max_u32_e32 v63, v70, v68
	v_min_u32_e32 v68, v70, v68
	v_max_u32_e32 v69, v66, v62
	v_min_u32_e32 v62, v66, v62
	v_max_u32_e32 v66, v67, v3
	v_min_u32_e32 v3, v67, v3
	v_max_u32_e32 v67, v71, v61
	v_max_u32_e32 v70, v60, v2
	v_min_u32_e32 v2, v60, v2
	v_max_u32_e32 v60, v56, v54
	v_min_u32_e32 v92, v53, v49
	v_min_u32_e32 v87, v80, v83
	v_min_u32_e32 v44, v50, v42
	v_min_u32_e32 v85, v79, v82
	v_min_u32_e32 v40, v46, v38
	v_max_u32_e32 v49, v53, v49
	v_min_u32_e32 v53, v45, v41
	v_max_u32_e32 v41, v45, v41
	v_max_u32_e32 v45, v84, v91
	v_max_u32_e32 v43, v51, v43
	v_max_u32_e32 v81, v81, v88
	v_max_u32_e32 v39, v47, v39
	v_max_u32_e32 v80, v80, v83
	v_max_u32_e32 v42, v50, v42
	v_max_u32_e32 v79, v79, v82
	v_max_u32_e32 v38, v46, v38
	v_min_u32_e32 v57, v59, v57
	v_min_u32_e32 v59, v77, v73
	v_min_u32_e32 v61, v71, v61
	v_min_u32_e32 v54, v56, v54
	v_max_u32_e32 v56, v55, v66
	v_min_u32_e32 v55, v55, v66
	v_max_u32_e32 v66, v58, v67
	v_min_u32_e32 v58, v58, v67
	v_max_u32_e32 v67, v63, v70
	v_min_u32_e32 v63, v63, v70
	v_max_u32_e32 v70, v69, v60
	v_min_u32_e32 v60, v69, v60
	v_min_u32_e32 v51, v45, v43
	v_min_u32_e32 v47, v81, v39
	v_min_u32_e32 v50, v80, v42
	v_min_u32_e32 v46, v79, v38
	v_max_u32_e32 v69, v57, v3
	v_min_u32_e32 v3, v57, v3
	v_max_u32_e32 v57, v59, v61
	v_min_u32_e32 v59, v59, v61
	v_max_u32_e32 v61, v68, v2
	v_min_u32_e32 v2, v68, v2
	v_max_u32_e32 v68, v62, v54
	v_min_u32_e32 v54, v62, v54
	v_max_u32_e32 v62, v56, v67
	v_min_u32_e32 v56, v56, v67
	v_max_u32_e32 v67, v66, v70
	v_min_u32_e32 v66, v66, v70
	v_max_u32_e32 v70, v55, v63
	v_min_u32_e32 v55, v55, v63
	v_max_u32_e32 v63, v58, v60
	v_min_u32_e32 v58, v58, v60
	v_min_u32_e32 v52, v87, v44
	v_min_u32_e32 v48, v85, v40
	v_max_u32_e32 v44, v87, v44
	v_max_u32_e32 v40, v85, v40
	v_min_u32_e32 v84, v51, v47
	v_min_u32_e32 v82, v50, v46
	v_max_u32_e32 v60, v69, v61
	v_min_u32_e32 v61, v69, v61
	v_max_u32_e32 v69, v57, v68
	v_min_u32_e32 v73, v55, v58
	v_min_u32_e32 v85, v44, v40
	v_max_u32_e32 v40, v44, v40
	v_min_u32_e32 v83, v84, v82
	v_min_u32_e32 v74, v60, v69
	v_min_u32_e32 v44, v41, v40
	v_max_u32_e32 v47, v51, v47
	v_max_u32_e32 v46, v50, v46
	v_max3_u32 v40, v73, v41, v40
	v_max3_u32 v41, v60, v69, v83
	v_cmp_gt_i32_e32 vcc, 0, v37
	v_not_b32_e32 v60, v37
	v_or_b32_e32 v37, 0x80000000, v37
	v_min_u32_e32 v57, v57, v68
	v_min_u32_e32 v50, v47, v46
	v_cndmask_b32_e32 v37, v37, v60, vcc
	v_cmp_gt_i32_e32 vcc, 0, v36
	v_not_b32_e32 v60, v36
	v_or_b32_e32 v36, 0x80000000, v36
	v_min_u32_e32 v75, v61, v57
	v_max3_u32 v50, v61, v57, v50
	v_cndmask_b32_e32 v36, v36, v60, vcc
	v_cmp_gt_i32_e32 vcc, 0, v35
	v_not_b32_e32 v61, v35
	v_or_b32_e32 v35, 0x80000000, v35
	v_min_u32_e32 v71, v56, v66
	v_min_u32_e32 v86, v52, v48
	v_max_u32_e32 v48, v52, v48
	v_min_u32_e32 v87, v53, v85
	v_cndmask_b32_e32 v35, v35, v61, vcc
	v_cmp_gt_i32_e32 vcc, 0, v34
	v_not_b32_e32 v61, v34
	v_or_b32_e32 v34, 0x80000000, v34
	v_min_u32_e32 v72, v70, v63
	v_min_u32_e32 v52, v49, v48
	v_max3_u32 v48, v71, v49, v48
	v_max3_u32 v49, v70, v63, v87
	v_cndmask_b32_e32 v34, v34, v61, vcc
	v_cmp_gt_i32_e32 vcc, 0, v33
	v_not_b32_e32 v63, v33
	v_or_b32_e32 v33, 0x80000000, v33
	v_cndmask_b32_e32 v33, v33, v63, vcc
	v_cmp_gt_i32_e32 vcc, 0, v32
	v_not_b32_e32 v63, v32
	v_or_b32_e32 v32, 0x80000000, v32
	v_max3_u32 v52, v56, v66, v52
	v_cndmask_b32_e32 v32, v32, v63, vcc
	v_cmp_gt_i32_e32 vcc, 0, v31
	v_not_b32_e32 v66, v31
	v_or_b32_e32 v31, 0x80000000, v31
	v_cndmask_b32_e32 v31, v31, v66, vcc
	v_cmp_gt_i32_e32 vcc, 0, v30
	v_not_b32_e32 v66, v30
	v_or_b32_e32 v30, 0x80000000, v30
	v_cndmask_b32_e32 v30, v30, v66, vcc
	v_cmp_gt_i32_e32 vcc, 0, v29
	v_not_b32_e32 v69, v29
	v_or_b32_e32 v29, 0x80000000, v29
	v_cndmask_b32_e32 v29, v29, v69, vcc
	v_cmp_gt_i32_e32 vcc, 0, v28
	v_not_b32_e32 v69, v28
	v_or_b32_e32 v28, 0x80000000, v28
	v_cndmask_b32_e32 v28, v28, v69, vcc
	v_cmp_gt_i32_e32 vcc, 0, v27
	v_not_b32_e32 v70, v27
	v_or_b32_e32 v27, 0x80000000, v27
	v_cndmask_b32_e32 v27, v27, v70, vcc
	v_cmp_gt_i32_e32 vcc, 0, v26
	v_not_b32_e32 v70, v26
	v_or_b32_e32 v26, 0x80000000, v26
	v_max3_u32 v53, v72, v53, v85
	v_cndmask_b32_e32 v26, v26, v70, vcc
; DEV unsigned fkey(float x) { const unsigned u = __float_as_uint(x); return (u & 0x80000000u) ? ~u : (u | 0x80000000u); }
; DEV float keyf(unsigned k) { const unsigned u = (k & 0x80000000u) ? (k & 0x7fffffffu) : ~k; return __uint_as_float(u); }
; DEV void bitonic_merge16_desc(unsigned (&v)[16]) {
; #pragma unroll
;   for (int j = 8; j >= 1; j >>= 1)
; #pragma unroll
;     for (int i = 0; i < 16; ++i) { const int l = i ^ j; if (l > i) cswap(v[i], v[l]); }
; }
; DEV void bitonic_sort16_desc(unsigned (&v)[16]) {
; #pragma unroll
;   for (int k = 2; k <= 16; k <<= 1)
; #pragma unroll
;     for (int j = k >> 1; j >= 1; j >>= 1)
; #pragma unroll
;       for (int i = 0; i < 16; ++i) { const int l = i ^ j; if (l > i) { if ((i & k) == 0) cswap(v[i], v[l]); else cswap(v[l], v[i]); } }
; }
; DEV void merge_top16(unsigned (&R)[16], const unsigned (&G)[16]) {
; #pragma unroll
;   for (int i = 0; i < 16; ++i) R[i] = max(R[i], G[15 - i]);
;   bitonic_merge16_desc(R);
; }
; DEV void stage1(unsigned (&L)[16], const float* sp) {
;   float sv[128];
; #pragma unroll
;   for (int i = 0; i < 128; ++i) sv[i] = sp[(size_t)i * 128];
; #pragma unroll
;   for (int i = 0; i < 128; i += 16) {
;     unsigned g[16];
; #pragma unroll
;     for (int e = 0; e < 16; ++e) g[e] = (fkey(sv[i + e]) & ~127u) | (unsigned)(127 - (i + e));
;     bitonic_sort16_desc(g);
;     if (i == 0) {
; #pragma unroll
;       for (int e = 0; e < 16; ++e) L[e] = g[e];
;     } else merge_top16(L, g);
;   }
; }
	v_cmp_gt_i32_e32 vcc, 0, v25
	v_not_b32_e32 v72, v25
	v_or_b32_e32 v25, 0x80000000, v25
	v_cndmask_b32_e32 v25, v25, v72, vcc
	v_cmp_gt_i32_e32 vcc, 0, v24
	v_not_b32_e32 v72, v24
	v_or_b32_e32 v24, 0x80000000, v24
	v_cndmask_b32_e32 v24, v24, v72, vcc
	v_cmp_gt_i32_e32 vcc, 0, v22
	v_not_b32_e32 v73, v22
	v_or_b32_e32 v22, 0x80000000, v22
	v_cndmask_b32_e32 v22, v22, v73, vcc
	v_cmp_gt_i32_e32 vcc, 0, v21
	v_not_b32_e32 v73, v21
	v_or_b32_e32 v21, 0x80000000, v21
	v_cndmask_b32_e32 v21, v21, v73, vcc
	v_and_or_b32 v37, v37, s55, 31
	v_and_or_b32 v36, v36, s55, 30
	v_and_or_b32 v35, v35, s55, 28
	v_and_or_b32 v34, v34, s55, 29
	v_and_or_b32 v33, v33, s55, 24
	v_and_or_b32 v32, v32, s55, 25
	v_and_or_b32 v31, v31, s55, 27
	v_and_or_b32 v30, v30, s55, 26
	v_and_or_b32 v29, v29, s55, 16
	v_and_or_b32 v28, v28, s55, 17
	v_and_or_b32 v27, v27, s55, 19
	v_and_or_b32 v26, v26, s55, 18
	v_and_or_b32 v25, v25, s55, 23
	v_and_or_b32 v24, v24, s55, 22
	v_and_or_b32 v22, v22, s55, 20
	v_and_or_b32 v21, v21, s55, 21
	v_min_u32_e32 v90, v92, v86
	v_max_u32_e32 v43, v45, v43
	v_max_u32_e32 v39, v81, v39
	v_max_u32_e32 v42, v80, v42
	v_max_u32_e32 v38, v79, v38
	v_max_u32_e32 v60, v37, v36
	v_min_u32_e32 v61, v35, v34
	v_min_u32_e32 v36, v37, v36
	v_max_u32_e32 v34, v35, v34
	v_max_u32_e32 v63, v33, v32
	v_min_u32_e32 v66, v31, v30
	v_min_u32_e32 v32, v33, v32
	v_max_u32_e32 v30, v31, v30
	v_max_u32_e32 v69, v29, v28
	v_min_u32_e32 v70, v27, v26
	v_min_u32_e32 v28, v29, v28
	v_max_u32_e32 v26, v27, v26
	v_max_u32_e32 v72, v25, v24
	v_min_u32_e32 v73, v22, v21
	v_min_u32_e32 v24, v25, v24
	v_max_u32_e32 v21, v22, v21
	v_max_u32_e32 v68, v3, v2
	v_min_u32_e32 v2, v3, v2
	v_max_u32_e32 v3, v59, v54
	v_min_u32_e32 v54, v59, v54
	v_min_u32_e32 v59, v62, v67
	v_min_u32_e32 v45, v43, v39
	v_min_u32_e32 v51, v42, v38
	v_max_u32_e32 v39, v43, v39
	v_max3_u32 v43, v62, v67, v90
	v_max3_u32 v44, v55, v58, v44
	v_max3_u32 v55, v74, v84, v82
	v_max_u32_e32 v62, v60, v61
	v_max_u32_e32 v35, v36, v34
	v_min_u32_e32 v67, v63, v66
	v_min_u32_e32 v31, v32, v30
	v_min_u32_e32 v60, v60, v61
	v_min_u32_e32 v34, v36, v34
	v_max_u32_e32 v61, v63, v66
	v_max_u32_e32 v30, v32, v30
	v_max_u32_e32 v71, v69, v70
	v_max_u32_e32 v27, v28, v26
	v_min_u32_e32 v74, v72, v73
	v_min_u32_e32 v22, v24, v21
	v_min_u32_e32 v69, v69, v70
	v_min_u32_e32 v26, v28, v26
	v_max_u32_e32 v70, v72, v73
	v_max_u32_e32 v21, v24, v21
	v_min_u32_e32 v79, v45, v51
	v_max_u32_e32 v37, v62, v35
	v_min_u32_e32 v33, v67, v31
	v_max_u32_e32 v36, v60, v34
	v_min_u32_e32 v32, v61, v30
	v_min_u32_e32 v35, v62, v35
	v_max_u32_e32 v31, v67, v31
	v_min_u32_e32 v34, v60, v34
	v_max_u32_e32 v30, v61, v30
	v_max_u32_e32 v29, v71, v27
	v_min_u32_e32 v25, v74, v22
	v_max_u32_e32 v28, v69, v26
	v_min_u32_e32 v24, v70, v21
	v_min_u32_e32 v27, v71, v27
	v_max_u32_e32 v22, v74, v22
	v_min_u32_e32 v26, v69, v26
	v_max_u32_e32 v21, v70, v21
	v_min_u32_e32 v76, v68, v3
	v_max3_u32 v46, v75, v47, v46
	v_max3_u32 v3, v68, v3, v79
	v_max_u32_e32 v68, v37, v33
	v_max_u32_e32 v63, v36, v32
	v_max_u32_e32 v62, v35, v31
	v_max_u32_e32 v60, v34, v30
	v_min_u32_e32 v75, v29, v25
	v_min_u32_e32 v72, v28, v24
	v_min_u32_e32 v71, v27, v22
	v_min_u32_e32 v69, v26, v21
	v_min_u32_e32 v33, v37, v33
	v_min_u32_e32 v32, v36, v32
	v_min_u32_e32 v31, v35, v31
	v_min_u32_e32 v30, v34, v30
	v_max_u32_e32 v25, v29, v25
	v_max_u32_e32 v24, v28, v24
	v_max_u32_e32 v22, v27, v22
	v_max_u32_e32 v21, v26, v21
	v_max_u32_e32 v66, v68, v63
	v_max_u32_e32 v61, v62, v60
	v_min_u32_e32 v73, v75, v72
	v_min_u32_e32 v70, v71, v69
	v_max_u32_e32 v36, v33, v32
	v_max_u32_e32 v34, v31, v30
	v_min_u32_e32 v28, v25, v24
	v_min_u32_e32 v26, v22, v21
	v_min_u32_e32 v63, v68, v63
	v_min_u32_e32 v60, v62, v60
	v_max_u32_e32 v68, v75, v72
	v_max_u32_e32 v69, v71, v69
	v_min_u32_e32 v32, v33, v32
	v_min_u32_e32 v30, v31, v30
	v_max_u32_e32 v24, v25, v24
	v_max_u32_e32 v21, v22, v21
	v_max_u32_e32 v38, v42, v38
	v_max_u32_e32 v67, v66, v61
	v_min_u32_e32 v74, v73, v70
	v_max_u32_e32 v35, v36, v34
	v_min_u32_e32 v27, v28, v26
	v_max_u32_e32 v62, v63, v60
	v_min_u32_e32 v71, v68, v69
	v_max_u32_e32 v31, v32, v30
	v_min_u32_e32 v22, v24, v21
	v_min_u32_e32 v77, v2, v54
	v_min_u32_e32 v42, v39, v38
	v_max3_u32 v45, v76, v45, v51
	v_min_u32_e32 v76, v67, v74
	v_min_u32_e32 v29, v35, v27
	v_min_u32_e32 v72, v62, v71
	v_min_u32_e32 v25, v31, v22
	v_max3_u32 v59, v59, v92, v86
	v_max3_u32 v2, v2, v54, v42
	v_max3_u32 v38, v77, v39, v38
	v_min_u32_e32 v37, v76, v29
	v_min_u32_e32 v33, v72, v25
	v_min_u32_e32 v61, v66, v61
	v_max_u32_e32 v66, v73, v70
	v_min_u32_e32 v34, v36, v34
	v_max_u32_e32 v26, v28, v26
	v_min_u32_e32 v60, v63, v60
	v_max_u32_e32 v63, v68, v69
	v_min_u32_e32 v30, v32, v30
	v_max_u32_e32 v21, v24, v21
	v_max_u32_e32 v29, v76, v29
	v_max_u32_e32 v25, v72, v25
	v_max_u32_e32 v39, v43, v41
	v_max_u32_e32 v42, v59, v55
	v_max_u32_e32 v47, v52, v50
	v_min_u32_e32 v50, v52, v50
	v_max_u32_e32 v51, v48, v46
	v_min_u32_e32 v46, v48, v46
	v_max_u32_e32 v48, v49, v3
	v_min_u32_e32 v3, v49, v3
	v_max_u32_e32 v49, v53, v45
	v_max_u32_e32 v52, v44, v2
	v_min_u32_e32 v2, v44, v2
	v_max_u32_e32 v44, v40, v38
	v_min_u32_e32 v75, v37, v33
	v_min_u32_e32 v70, v61, v66
	v_min_u32_e32 v28, v34, v26
	v_min_u32_e32 v68, v60, v63
	v_min_u32_e32 v24, v30, v21
	v_max_u32_e32 v33, v37, v33
	v_min_u32_e32 v37, v29, v25
	v_max_u32_e32 v25, v29, v25
	v_max_u32_e32 v29, v67, v74
	v_max_u32_e32 v27, v35, v27
	v_max_u32_e32 v62, v62, v71
	v_max_u32_e32 v22, v31, v22
	v_max_u32_e32 v61, v61, v66
	v_max_u32_e32 v26, v34, v26
	v_max_u32_e32 v60, v60, v63
	v_max_u32_e32 v21, v30, v21
; DEV unsigned fkey(float x) { const unsigned u = __float_as_uint(x); return (u & 0x80000000u) ? ~u : (u | 0x80000000u); }
; DEV float keyf(unsigned k) { const unsigned u = (k & 0x80000000u) ? (k & 0x7fffffffu) : ~k; return __uint_as_float(u); }
; DEV void bitonic_merge16_desc(unsigned (&v)[16]) {
; #pragma unroll
;   for (int j = 8; j >= 1; j >>= 1)
; #pragma unroll
;     for (int i = 0; i < 16; ++i) { const int l = i ^ j; if (l > i) cswap(v[i], v[l]); }
; }
; DEV void bitonic_sort16_desc(unsigned (&v)[16]) {
; #pragma unroll
;   for (int k = 2; k <= 16; k <<= 1)
; #pragma unroll
;     for (int j = k >> 1; j >= 1; j >>= 1)
; #pragma unroll
;       for (int i = 0; i < 16; ++i) { const int l = i ^ j; if (l > i) { if ((i & k) == 0) cswap(v[i], v[l]); else cswap(v[l], v[i]); } }
; }
; DEV void merge_top16(unsigned (&R)[16], const unsigned (&G)[16]) {
; #pragma unroll
;   for (int i = 0; i < 16; ++i) R[i] = max(R[i], G[15 - i]);
;   bitonic_merge16_desc(R);
; }
; DEV void stage1(unsigned (&L)[16], const float* sp) {
;   float sv[128];
; #pragma unroll
;   for (int i = 0; i < 128; ++i) sv[i] = sp[(size_t)i * 128];
; #pragma unroll
;   for (int i = 0; i < 128; i += 16) {
;     unsigned g[16];
; #pragma unroll
;     for (int e = 0; e < 16; ++e) g[e] = (fkey(sv[i + e]) & ~127u) | (unsigned)(127 - (i + e));
;     bitonic_sort16_desc(g);
;     if (i == 0) {
; #pragma unroll
;       for (int e = 0; e < 16; ++e) L[e] = g[e];
;     } else merge_top16(L, g);
;   }
; }
	v_min_u32_e32 v41, v43, v41
	v_min_u32_e32 v43, v59, v55
	v_min_u32_e32 v45, v53, v45
	v_min_u32_e32 v38, v40, v38
	v_max_u32_e32 v40, v39, v48
	v_min_u32_e32 v39, v39, v48
	v_max_u32_e32 v48, v42, v49
	v_min_u32_e32 v42, v42, v49
	v_max_u32_e32 v49, v47, v52
	v_min_u32_e32 v47, v47, v52
	v_max_u32_e32 v52, v51, v44
	v_min_u32_e32 v44, v51, v44
	v_min_u32_e32 v35, v29, v27
	v_min_u32_e32 v31, v62, v22
	v_min_u32_e32 v34, v61, v26
	v_min_u32_e32 v30, v60, v21
	v_max_u32_e32 v51, v41, v3
	v_min_u32_e32 v3, v41, v3
	v_max_u32_e32 v41, v43, v45
	v_min_u32_e32 v43, v43, v45
	v_max_u32_e32 v45, v50, v2
	v_min_u32_e32 v2, v50, v2
	v_max_u32_e32 v50, v46, v38
	v_min_u32_e32 v38, v46, v38
	v_max_u32_e32 v46, v40, v49
	v_min_u32_e32 v40, v40, v49
	v_max_u32_e32 v49, v48, v52
	v_min_u32_e32 v48, v48, v52
	v_max_u32_e32 v52, v39, v47
	v_min_u32_e32 v39, v39, v47
	v_max_u32_e32 v47, v42, v44
	v_min_u32_e32 v42, v42, v44
	v_min_u32_e32 v36, v70, v28
	v_min_u32_e32 v32, v68, v24
	v_max_u32_e32 v28, v70, v28
	v_max_u32_e32 v24, v68, v24
	v_min_u32_e32 v67, v35, v31
	v_min_u32_e32 v63, v34, v30
	v_max_u32_e32 v44, v51, v45
	v_min_u32_e32 v45, v51, v45
	v_max_u32_e32 v51, v41, v50
	v_min_u32_e32 v55, v39, v42
	v_min_u32_e32 v68, v28, v24
	v_max_u32_e32 v24, v28, v24
	v_min_u32_e32 v66, v67, v63
	v_min_u32_e32 v56, v44, v51
	v_min_u32_e32 v28, v25, v24
	v_max_u32_e32 v31, v35, v31
	v_max_u32_e32 v30, v34, v30
	v_max3_u32 v24, v55, v25, v24
	v_max3_u32 v25, v44, v51, v66
	v_cmp_gt_i32_e32 vcc, 0, v20
	v_not_b32_e32 v44, v20
	v_or_b32_e32 v20, 0x80000000, v20
	v_min_u32_e32 v41, v41, v50
	v_min_u32_e32 v34, v31, v30
	v_cndmask_b32_e32 v20, v20, v44, vcc
	v_cmp_gt_i32_e32 vcc, 0, v19
	v_not_b32_e32 v44, v19
	v_or_b32_e32 v19, 0x80000000, v19
	v_min_u32_e32 v57, v45, v41
	v_max3_u32 v34, v45, v41, v34
	v_cndmask_b32_e32 v19, v19, v44, vcc
	v_cmp_gt_i32_e32 vcc, 0, v18
	v_not_b32_e32 v45, v18
	v_or_b32_e32 v18, 0x80000000, v18
	v_min_u32_e32 v53, v40, v48
	v_min_u32_e32 v69, v36, v32
	v_max_u32_e32 v32, v36, v32
	v_min_u32_e32 v70, v37, v68
	v_cndmask_b32_e32 v18, v18, v45, vcc
	v_cmp_gt_i32_e32 vcc, 0, v17
	v_not_b32_e32 v45, v17
	v_or_b32_e32 v17, 0x80000000, v17
	v_min_u32_e32 v54, v52, v47
	v_min_u32_e32 v36, v33, v32
	v_max3_u32 v32, v53, v33, v32
	v_max3_u32 v33, v52, v47, v70
	v_cndmask_b32_e32 v17, v17, v45, vcc
	v_cmp_gt_i32_e32 vcc, 0, v16
	v_not_b32_e32 v47, v16
	v_or_b32_e32 v16, 0x80000000, v16
	v_cndmask_b32_e32 v16, v16, v47, vcc
	v_cmp_gt_i32_e32 vcc, 0, v15
	v_not_b32_e32 v47, v15
	v_or_b32_e32 v15, 0x80000000, v15
	v_max3_u32 v36, v40, v48, v36
	v_cndmask_b32_e32 v15, v15, v47, vcc
	v_cmp_gt_i32_e32 vcc, 0, v14
	v_not_b32_e32 v48, v14
	v_or_b32_e32 v14, 0x80000000, v14
	v_cndmask_b32_e32 v14, v14, v48, vcc
	v_cmp_gt_i32_e32 vcc, 0, v13
	v_not_b32_e32 v48, v13
	v_or_b32_e32 v13, 0x80000000, v13
	v_cndmask_b32_e32 v13, v13, v48, vcc
	v_cmp_gt_i32_e32 vcc, 0, v12
	v_not_b32_e32 v51, v12
	v_or_b32_e32 v12, 0x80000000, v12
	v_cndmask_b32_e32 v12, v12, v51, vcc
	v_cmp_gt_i32_e32 vcc, 0, v10
	v_not_b32_e32 v51, v10
	v_or_b32_e32 v10, 0x80000000, v10
	v_cndmask_b32_e32 v10, v10, v51, vcc
	v_cmp_gt_i32_e32 vcc, 0, v9
	v_not_b32_e32 v52, v9
	v_or_b32_e32 v9, 0x80000000, v9
	v_cndmask_b32_e32 v9, v9, v52, vcc
	v_cmp_gt_i32_e32 vcc, 0, v8
	v_not_b32_e32 v52, v8
	v_or_b32_e32 v8, 0x80000000, v8
	v_max3_u32 v37, v54, v37, v68
	v_cndmask_b32_e32 v8, v8, v52, vcc
	v_cmp_gt_i32_e32 vcc, 0, v7
	v_not_b32_e32 v54, v7
	v_or_b32_e32 v7, 0x80000000, v7
	v_cndmask_b32_e32 v7, v7, v54, vcc
	v_cmp_gt_i32_e32 vcc, 0, v6
	v_not_b32_e32 v54, v6
	v_or_b32_e32 v6, 0x80000000, v6
	v_cndmask_b32_e32 v6, v6, v54, vcc
	v_cmp_gt_i32_e32 vcc, 0, v5
	v_not_b32_e32 v55, v5
	v_or_b32_e32 v5, 0x80000000, v5
	v_cndmask_b32_e32 v5, v5, v55, vcc
	v_cmp_gt_i32_e32 vcc, 0, v1
	v_not_b32_e32 v55, v1
	v_or_b32_e32 v1, 0x80000000, v1
	v_cndmask_b32_e32 v1, v1, v55, vcc
	v_and_or_b32 v20, v20, s55, 15
	v_and_or_b32 v19, v19, s55, 14
	v_and_or_b32 v18, v18, s55, 12
	v_and_or_b32 v17, v17, s55, 13
	v_and_or_b32 v16, v16, s55, 8
	v_and_or_b32 v15, v15, s55, 9
	v_and_or_b32 v14, v14, s55, 11
	v_and_or_b32 v13, v13, s55, 10
	v_and_b32_e32 v12, 0xffffff80, v12
	v_and_or_b32 v10, v10, s55, 1
	v_and_or_b32 v9, v9, s55, 3
	v_and_or_b32 v8, v8, s55, 2
	v_and_or_b32 v7, v7, s55, 7
	v_and_or_b32 v6, v6, s55, 6
	v_and_or_b32 v5, v5, s55, 4
	v_and_or_b32 v1, v1, s55, 5
	v_min_u32_e32 v73, v75, v69
	v_max_u32_e32 v27, v29, v27
	v_max_u32_e32 v22, v62, v22
	v_max_u32_e32 v26, v61, v26
	v_max_u32_e32 v21, v60, v21
	v_max_u32_e32 v44, v20, v19
	v_min_u32_e32 v45, v18, v17
	v_min_u32_e32 v19, v20, v19
	v_max_u32_e32 v17, v18, v17
	v_max_u32_e32 v47, v16, v15
	v_min_u32_e32 v48, v14, v13
	v_min_u32_e32 v15, v16, v15
	v_max_u32_e32 v13, v14, v13
	v_max_u32_e32 v51, v12, v10
	v_min_u32_e32 v52, v9, v8
	v_min_u32_e32 v10, v12, v10
	v_max_u32_e32 v8, v9, v8
	v_max_u32_e32 v54, v7, v6
	v_min_u32_e32 v55, v5, v1
	v_min_u32_e32 v6, v7, v6
	v_max_u32_e32 v1, v5, v1
	v_max_u32_e32 v50, v3, v2
	v_min_u32_e32 v2, v3, v2
	v_max_u32_e32 v3, v43, v38
	v_min_u32_e32 v38, v43, v38
	v_min_u32_e32 v43, v46, v49
	v_min_u32_e32 v29, v27, v22
	v_min_u32_e32 v35, v26, v21
	v_max_u32_e32 v22, v27, v22
	v_max3_u32 v27, v46, v49, v73
	v_max3_u32 v28, v39, v42, v28
	v_max3_u32 v39, v56, v67, v63
	v_max_u32_e32 v46, v44, v45
	v_max_u32_e32 v18, v19, v17
	v_min_u32_e32 v49, v47, v48
	v_min_u32_e32 v14, v15, v13
	v_min_u32_e32 v44, v44, v45
	v_min_u32_e32 v17, v19, v17
	v_max_u32_e32 v45, v47, v48
	v_max_u32_e32 v13, v15, v13
	v_max_u32_e32 v53, v51, v52
	v_max_u32_e32 v9, v10, v8
	v_min_u32_e32 v56, v54, v55
	v_min_u32_e32 v5, v6, v1
; DEV unsigned fkey(float x) { const unsigned u = __float_as_uint(x); return (u & 0x80000000u) ? ~u : (u | 0x80000000u); }
; DEV float keyf(unsigned k) { const unsigned u = (k & 0x80000000u) ? (k & 0x7fffffffu) : ~k; return __uint_as_float(u); }
; DEV void bitonic_merge16_desc(unsigned (&v)[16]) {
; #pragma unroll
;   for (int j = 8; j >= 1; j >>= 1)
; #pragma unroll
;     for (int i = 0; i < 16; ++i) { const int l = i ^ j; if (l > i) cswap(v[i], v[l]); }
; }
; DEV void bitonic_sort16_desc(unsigned (&v)[16]) {
; #pragma unroll
;   for (int k = 2; k <= 16; k <<= 1)
; #pragma unroll
;     for (int j = k >> 1; j >= 1; j >>= 1)
; #pragma unroll
;       for (int i = 0; i < 16; ++i) { const int l = i ^ j; if (l > i) { if ((i & k) == 0) cswap(v[i], v[l]); else cswap(v[l], v[i]); } }
; }
; DEV void merge_top16(unsigned (&R)[16], const unsigned (&G)[16]) {
; #pragma unroll
;   for (int i = 0; i < 16; ++i) R[i] = max(R[i], G[15 - i]);
;   bitonic_merge16_desc(R);
; }
; DEV void stage1(unsigned (&L)[16], const float* sp) {
;   float sv[128];
; #pragma unroll
;   for (int i = 0; i < 128; ++i) sv[i] = sp[(size_t)i * 128];
; #pragma unroll
;   for (int i = 0; i < 128; i += 16) {
;     unsigned g[16];
; #pragma unroll
;     for (int e = 0; e < 16; ++e) g[e] = (fkey(sv[i + e]) & ~127u) | (unsigned)(127 - (i + e));
;     bitonic_sort16_desc(g);
;     if (i == 0) {
; #pragma unroll
;       for (int e = 0; e < 16; ++e) L[e] = g[e];
;     } else merge_top16(L, g);
;   }
; }
	v_min_u32_e32 v51, v51, v52
	v_min_u32_e32 v8, v10, v8
	v_max_u32_e32 v52, v54, v55
	v_max_u32_e32 v1, v6, v1
	v_min_u32_e32 v60, v29, v35
	v_max_u32_e32 v20, v46, v18
	v_min_u32_e32 v16, v49, v14
	v_max_u32_e32 v19, v44, v17
	v_min_u32_e32 v15, v45, v13
	v_min_u32_e32 v18, v46, v18
	v_max_u32_e32 v14, v49, v14
	v_min_u32_e32 v17, v44, v17
	v_max_u32_e32 v13, v45, v13
	v_max_u32_e32 v12, v53, v9
	v_min_u32_e32 v7, v56, v5
	v_max_u32_e32 v10, v51, v8
	v_min_u32_e32 v6, v52, v1
	v_min_u32_e32 v9, v53, v9
	v_max_u32_e32 v5, v56, v5
	v_min_u32_e32 v8, v51, v8
	v_max_u32_e32 v1, v52, v1
	v_min_u32_e32 v58, v50, v3
	v_max3_u32 v30, v57, v31, v30
	v_max3_u32 v3, v50, v3, v60
	v_max_u32_e32 v50, v20, v16
	v_max_u32_e32 v47, v19, v15
	v_max_u32_e32 v46, v18, v14
	v_max_u32_e32 v44, v17, v13
	v_min_u32_e32 v57, v12, v7
	v_min_u32_e32 v54, v10, v6
	v_min_u32_e32 v53, v9, v5
	v_min_u32_e32 v51, v8, v1
	v_min_u32_e32 v16, v20, v16
	v_min_u32_e32 v15, v19, v15
	v_min_u32_e32 v14, v18, v14
	v_min_u32_e32 v13, v17, v13
	v_max_u32_e32 v7, v12, v7
	v_max_u32_e32 v6, v10, v6
	v_max_u32_e32 v5, v9, v5
	v_max_u32_e32 v1, v8, v1
	v_max_u32_e32 v48, v50, v47
	v_max_u32_e32 v45, v46, v44
	v_min_u32_e32 v55, v57, v54
	v_min_u32_e32 v52, v53, v51
	v_max_u32_e32 v19, v16, v15
	v_max_u32_e32 v17, v14, v13
	v_min_u32_e32 v10, v7, v6
	v_min_u32_e32 v8, v5, v1
	v_min_u32_e32 v47, v50, v47
	v_min_u32_e32 v44, v46, v44
	v_max_u32_e32 v50, v57, v54
	v_max_u32_e32 v51, v53, v51
	v_min_u32_e32 v15, v16, v15
	v_min_u32_e32 v13, v14, v13
	v_max_u32_e32 v6, v7, v6
	v_max_u32_e32 v1, v5, v1
	v_max_u32_e32 v21, v26, v21
	v_max_u32_e32 v49, v48, v45
	v_min_u32_e32 v56, v55, v52
	v_max_u32_e32 v18, v19, v17
	v_min_u32_e32 v9, v10, v8
	v_max_u32_e32 v46, v47, v44
	v_min_u32_e32 v53, v50, v51
	v_max_u32_e32 v14, v15, v13
	v_min_u32_e32 v5, v6, v1
	v_min_u32_e32 v59, v2, v38
	v_min_u32_e32 v26, v22, v21
	v_max3_u32 v29, v58, v29, v35
	v_min_u32_e32 v58, v49, v56
	v_min_u32_e32 v12, v18, v9
	v_min_u32_e32 v54, v46, v53
	v_min_u32_e32 v7, v14, v5
	v_max3_u32 v43, v43, v75, v69
	v_max3_u32 v2, v2, v38, v26
	v_max3_u32 v21, v59, v22, v21
	v_min_u32_e32 v20, v58, v12
	v_min_u32_e32 v16, v54, v7
	v_min_u32_e32 v45, v48, v45
	v_max_u32_e32 v48, v55, v52
	v_min_u32_e32 v17, v19, v17
	v_max_u32_e32 v8, v10, v8
	v_min_u32_e32 v44, v47, v44
	v_max_u32_e32 v47, v50, v51
	v_min_u32_e32 v13, v15, v13
	v_max_u32_e32 v1, v6, v1
	v_max_u32_e32 v12, v58, v12
	v_max_u32_e32 v7, v54, v7
	v_max_u32_e32 v22, v27, v25
	v_min_u32_e32 v25, v27, v25
	v_max_u32_e32 v26, v43, v39
	v_min_u32_e32 v27, v43, v39
	v_max_u32_e32 v31, v36, v34
	v_min_u32_e32 v34, v36, v34
	v_max_u32_e32 v35, v32, v30
	v_min_u32_e32 v30, v32, v30
	v_max_u32_e32 v32, v33, v3
	v_min_u32_e32 v3, v33, v3
	v_max_u32_e32 v33, v37, v29
	v_min_u32_e32 v29, v37, v29
	v_max_u32_e32 v36, v28, v2
	v_min_u32_e32 v2, v28, v2
	v_max_u32_e32 v28, v24, v21
	v_min_u32_e32 v21, v24, v21
	v_min_u32_e32 v57, v20, v16
	v_min_u32_e32 v52, v45, v48
	v_min_u32_e32 v10, v17, v8
	v_min_u32_e32 v50, v44, v47
	v_min_u32_e32 v6, v13, v1
	v_max_u32_e32 v16, v20, v16
	v_min_u32_e32 v20, v12, v7
	v_max_u32_e32 v7, v12, v7
	v_max_u32_e32 v12, v49, v56
	v_max_u32_e32 v9, v18, v9
	v_max_u32_e32 v46, v46, v53
	v_max_u32_e32 v5, v14, v5
	v_max_u32_e32 v45, v45, v48
	v_max_u32_e32 v8, v17, v8
	v_max_u32_e32 v44, v44, v47
	v_max_u32_e32 v1, v13, v1
	v_max_u32_e32 v24, v22, v32
	v_min_u32_e32 v22, v22, v32
	v_max_u32_e32 v32, v26, v33
	v_min_u32_e32 v26, v26, v33
	v_max_u32_e32 v33, v31, v36
	v_min_u32_e32 v31, v31, v36
	v_max_u32_e32 v36, v35, v28
	v_min_u32_e32 v28, v35, v28
	v_max_u32_e32 v35, v25, v3
	v_min_u32_e32 v3, v25, v3
	v_max_u32_e32 v25, v27, v29
	v_min_u32_e32 v27, v27, v29
	v_max_u32_e32 v29, v34, v2
	v_min_u32_e32 v2, v34, v2
	v_max_u32_e32 v34, v30, v21
	v_min_u32_e32 v21, v30, v21
	v_min_u32_e32 v19, v52, v10
	v_min_u32_e32 v15, v50, v6
	v_max_u32_e32 v10, v52, v10
	v_max_u32_e32 v6, v50, v6
	v_min_u32_e32 v18, v12, v9
	v_min_u32_e32 v14, v46, v5
	v_min_u32_e32 v17, v45, v8
	v_min_u32_e32 v13, v44, v1
	v_max_u32_e32 v9, v12, v9
	v_max_u32_e32 v5, v46, v5
	v_max_u32_e32 v8, v45, v8
	v_max_u32_e32 v1, v44, v1
	v_max_u32_e32 v30, v24, v33
	v_min_u32_e32 v24, v24, v33
	v_max_u32_e32 v33, v32, v36
	v_min_u32_e32 v32, v32, v36
	v_max_u32_e32 v36, v22, v31
	v_min_u32_e32 v22, v22, v31
	v_max_u32_e32 v31, v26, v28
	v_min_u32_e32 v26, v26, v28
	v_max_u32_e32 v28, v35, v29
	v_min_u32_e32 v29, v35, v29
	v_max_u32_e32 v35, v25, v34
	v_min_u32_e32 v25, v25, v34
	v_max_u32_e32 v34, v3, v2
	v_min_u32_e32 v2, v3, v2
	v_max_u32_e32 v3, v27, v21
	v_min_u32_e32 v21, v27, v21
	v_min_u32_e32 v51, v19, v15
	v_max_u32_e32 v15, v19, v15
	v_min_u32_e32 v50, v10, v6
	v_max_u32_e32 v6, v10, v6
	v_min_u32_e32 v49, v18, v14
	v_min_u32_e32 v47, v17, v13
	v_max_u32_e32 v14, v18, v14
	v_max_u32_e32 v13, v17, v13
	v_min_u32_e32 v12, v9, v5
	v_min_u32_e32 v18, v8, v1
	v_max_u32_e32 v5, v9, v5
	v_max_u32_e32 v1, v8, v1
	v_min_u32_e32 v27, v30, v33
	v_min_u32_e32 v37, v24, v32
	v_min_u32_e32 v38, v36, v31
	v_min_u32_e32 v39, v22, v26
	v_min_u32_e32 v40, v28, v35
	v_min_u32_e32 v41, v29, v25
	v_min_u32_e32 v42, v34, v3
	v_min_u32_e32 v43, v2, v21
	v_min_u32_e32 v55, v57, v51
	v_min_u32_e32 v19, v16, v15
	v_min_u32_e32 v52, v20, v50
	v_min_u32_e32 v10, v7, v6
	v_min_u32_e32 v48, v49, v47
	v_min_u32_e32 v17, v14, v13
	v_min_u32_e32 v44, v12, v18
	v_min_u32_e32 v8, v5, v1
	v_max3_u32 v9, v30, v33, v55
	v_max3_u32 v27, v27, v57, v51
	v_max3_u32 v19, v24, v32, v19
	v_max3_u32 v15, v37, v16, v15
	v_max3_u32 v16, v36, v31, v52
	v_max3_u32 v20, v38, v20, v50
	v_max3_u32 v10, v22, v26, v10
; DEV int tid_l() { int t = threadIdx.x; asm volatile("" : "+v"(t)); return t; }
; DEV unsigned fkey(float x) { const unsigned u = __float_as_uint(x); return (u & 0x80000000u) ? ~u : (u | 0x80000000u); }
; DEV float keyf(unsigned k) { const unsigned u = (k & 0x80000000u) ? (k & 0x7fffffffu) : ~k; return __uint_as_float(u); }
; DEV void bitonic_merge16_desc(unsigned (&v)[16]) {
; #pragma unroll
;   for (int j = 8; j >= 1; j >>= 1)
; #pragma unroll
;     for (int i = 0; i < 16; ++i) { const int l = i ^ j; if (l > i) cswap(v[i], v[l]); }
; }
; DEV void bitonic_sort16_desc(unsigned (&v)[16]) {
; #pragma unroll
;   for (int k = 2; k <= 16; k <<= 1)
; #pragma unroll
;     for (int j = k >> 1; j >= 1; j >>= 1)
; #pragma unroll
;       for (int i = 0; i < 16; ++i) { const int l = i ^ j; if (l > i) { if ((i & k) == 0) cswap(v[i], v[l]); else cswap(v[l], v[i]); } }
; }
; DEV void merge_top16(unsigned (&R)[16], const unsigned (&G)[16]) {
; #pragma unroll
;   for (int i = 0; i < 16; ++i) R[i] = max(R[i], G[15 - i]);
;   bitonic_merge16_desc(R);
; }
; DEV void stage1(unsigned (&L)[16], const float* sp) {
;   float sv[128];
; #pragma unroll
;   for (int i = 0; i < 128; ++i) sv[i] = sp[(size_t)i * 128];
; #pragma unroll
;   for (int i = 0; i < 128; i += 16) {
;     unsigned g[16];
; #pragma unroll
;     for (int e = 0; e < 16; ++e) g[e] = (fkey(sv[i + e]) & ~127u) | (unsigned)(127 - (i + e));
;     bitonic_sort16_desc(g);
;     if (i == 0) {
; #pragma unroll
;       for (int e = 0; e < 16; ++e) L[e] = g[e];
;     } else merge_top16(L, g);
;   }
; }
; DEV void topk_group(int hg, const float* scoresT, int* idxo, float* go) {
;   const int tid = tid_l(), token = tid & 127, hl = tid >> 7;
;   unsigned LA[16], LB[16], LC[16];
;   stage1(LA, scoresT + (size_t)(hl * 256) * 128 + token);
;   stage1(LB, scoresT + (size_t)(hl * 256 + 128) * 128 + token);
	v_max3_u32 v6, v39, v7, v6
	v_max3_u32 v7, v28, v35, v48
	v_max3_u32 v22, v40, v49, v47
	v_max3_u32 v17, v29, v25, v17
	v_max3_u32 v13, v41, v14, v13
	v_max3_u32 v3, v34, v3, v44
	v_max3_u32 v12, v42, v12, v18
	v_max3_u32 v2, v2, v21, v8
	v_max3_u32 v1, v43, v5, v1
	v_max_u32_e32 v5, v9, v7
	v_min_u32_e32 v7, v9, v7
	v_max_u32_e32 v8, v27, v22
	v_min_u32_e32 v9, v27, v22
	v_max_u32_e32 v14, v19, v17
	v_min_u32_e32 v17, v19, v17
	v_max_u32_e32 v18, v15, v13
	v_min_u32_e32 v13, v15, v13
	v_max_u32_e32 v15, v16, v3
	v_min_u32_e32 v3, v16, v3
	v_max_u32_e32 v16, v20, v12
	v_min_u32_e32 v12, v20, v12
	v_max_u32_e32 v19, v10, v2
	v_min_u32_e32 v2, v10, v2
	v_max_u32_e32 v10, v6, v1
	v_min_u32_e32 v1, v6, v1
	v_max_u32_e32 v6, v5, v15
	v_min_u32_e32 v5, v5, v15
	v_max_u32_e32 v15, v8, v16
	v_min_u32_e32 v8, v8, v16
	v_max_u32_e32 v16, v14, v19
	v_min_u32_e32 v14, v14, v19
	v_max_u32_e32 v19, v18, v10
	v_min_u32_e32 v10, v18, v10
	v_max_u32_e32 v18, v7, v3
	v_min_u32_e32 v3, v7, v3
	v_max_u32_e32 v7, v9, v12
	v_min_u32_e32 v9, v9, v12
	v_max_u32_e32 v12, v17, v2
	v_min_u32_e32 v2, v17, v2
	v_max_u32_e32 v17, v13, v1
	v_min_u32_e32 v1, v13, v1
	v_max_u32_e32 v13, v6, v16
	v_max_u32_e32 v20, v15, v19
	v_min_u32_e32 v15, v15, v19
	v_max_u32_e32 v19, v5, v14
	v_min_u32_e32 v21, v5, v14
	v_max_u32_e32 v5, v8, v10
	v_min_u32_e32 v10, v8, v10
	v_max_u32_e32 v22, v18, v12
	v_min_u32_e32 v12, v18, v12
	v_max_u32_e32 v18, v7, v17
	v_min_u32_e32 v17, v7, v17
	v_max_u32_e32 v25, v3, v2
	v_min_u32_e32 v2, v3, v2
	v_max_u32_e32 v26, v9, v1
	v_min_u32_e32 v1, v9, v1
	v_min_u32_e32 v16, v6, v16
	v_max_u32_e32 v6, v13, v20
	v_min_u32_e32 v3, v13, v20
	v_max_u32_e32 v14, v19, v5
	v_min_u32_e32 v20, v19, v5
	v_max_u32_e32 v5, v21, v10
	v_min_u32_e32 v10, v21, v10
	v_max_u32_e32 v19, v12, v17
	v_min_u32_e32 v21, v12, v17
	v_max_u32_e32 v17, v2, v1
	v_min_u32_e32 v13, v2, v1
	v_ashrrev_i32_e32 v1, 31, v0
	v_lshlrev_b64 v[0:1], 9, v[0:1]
	v_lshl_add_u64 v[0:1], s[0:1], 0, v[0:1]
	v_lshl_add_u64 v[0:1], v[0:1], 0, v[120:121]
	s_movk_i32 s0, 0x2000
	v_max_u32_e32 v24, v25, v26
	v_min_u32_e32 v25, v25, v26
	v_add_co_u32_e32 v26, vcc, s0, v0
	s_movk_i32 s0, 0x3000
	s_nop 0
	v_addc_co_u32_e32 v27, vcc, 0, v1, vcc
	flat_load_dword v136, v[26:27]
	flat_load_dword v135, v[26:27] offset:512
	flat_load_dword v133, v[26:27] offset:1024
	flat_load_dword v134, v[26:27] offset:1536
	flat_load_dword v130, v[26:27] offset:2048
	flat_load_dword v129, v[26:27] offset:2560
	flat_load_dword v131, v[26:27] offset:3072
	flat_load_dword v132, v[26:27] offset:3584
	v_add_co_u32_e32 v26, vcc, s0, v0
	v_max_u32_e32 v9, v16, v15
	s_nop 0
	v_addc_co_u32_e32 v27, vcc, 0, v1, vcc
	flat_load_dword v124, v[26:27]
	flat_load_dword v123, v[26:27] offset:512
	flat_load_dword v120, v[26:27] offset:1024
	flat_load_dword v122, v[26:27] offset:1536
	flat_load_dword v126, v[26:27] offset:2048
	flat_load_dword v125, v[26:27] offset:2560
	flat_load_dword v127, v[26:27] offset:3072
	flat_load_dword v128, v[26:27] offset:3584
	v_add_co_u32_e32 v26, vcc, s17, v0
	v_min_u32_e32 v8, v16, v15
	s_nop 0
	v_addc_co_u32_e32 v27, vcc, 0, v1, vcc
	flat_load_dword v119, v[26:27]
	flat_load_dword v118, v[26:27] offset:512
	flat_load_dword v116, v[26:27] offset:1024
	flat_load_dword v117, v[26:27] offset:1536
	flat_load_dword v113, v[26:27] offset:2048
	flat_load_dword v112, v[26:27] offset:2560
	flat_load_dword v114, v[26:27] offset:3072
	flat_load_dword v115, v[26:27] offset:3584
	v_add_co_u32_e32 v26, vcc, s47, v0
	v_max_u32_e32 v7, v22, v18
	s_nop 0
	v_addc_co_u32_e32 v27, vcc, 0, v1, vcc
	flat_load_dword v107, v[26:27]
	flat_load_dword v106, v[26:27] offset:512
	flat_load_dword v104, v[26:27] offset:1024
	flat_load_dword v105, v[26:27] offset:1536
	flat_load_dword v109, v[26:27] offset:2048
	flat_load_dword v108, v[26:27] offset:2560
	flat_load_dword v110, v[26:27] offset:3072
	flat_load_dword v111, v[26:27] offset:3584
	v_add_co_u32_e32 v26, vcc, s18, v0
	v_min_u32_e32 v15, v22, v18
	s_nop 0
	v_addc_co_u32_e32 v27, vcc, 0, v1, vcc
	flat_load_dword v103, v[26:27]
	flat_load_dword v102, v[26:27] offset:512
	flat_load_dword v100, v[26:27] offset:1024
	flat_load_dword v101, v[26:27] offset:1536
	flat_load_dword v97, v[26:27] offset:2048
	flat_load_dword v96, v[26:27] offset:2560
	flat_load_dword v98, v[26:27] offset:3072
	flat_load_dword v99, v[26:27] offset:3584
	v_add_co_u32_e32 v26, vcc, s48, v0
	s_waitcnt vmcnt(0) lgkmcnt(0)
; DEV unsigned fkey(float x) { const unsigned u = __float_as_uint(x); return (u & 0x80000000u) ? ~u : (u | 0x80000000u); }
; DEV void stage1(unsigned (&L)[16], const float* sp) {
;   float sv[128];
; #pragma unroll
;   for (int i = 0; i < 128; ++i) sv[i] = sp[(size_t)i * 128];
; #pragma unroll
;   for (int i = 0; i < 128; i += 16) {
;     unsigned g[16];
; #pragma unroll
;     for (int e = 0; e < 16; ++e) g[e] = (fkey(sv[i + e]) & ~127u) | (unsigned)(127 - (i + e));
;     bitonic_sort16_desc(g);
; DEV void topk_group(int hg, const float* scoresT, int* idxo, float* go) {
;     ...
;   stage1(LA, scoresT + (size_t)(hl * 256) * 128 + token);
;   stage1(LB, scoresT + (size_t)(hl * 256 + 128) * 128 + token);
	v_not_b32_e32 v185, v124
	v_addc_co_u32_e32 v27, vcc, 0, v1, vcc
	flat_load_dword v91, v[26:27]
	flat_load_dword v90, v[26:27] offset:512
	flat_load_dword v88, v[26:27] offset:1024
	flat_load_dword v89, v[26:27] offset:1536
	flat_load_dword v93, v[26:27] offset:2048
	flat_load_dword v92, v[26:27] offset:2560
	flat_load_dword v94, v[26:27] offset:3072
	flat_load_dword v95, v[26:27] offset:3584
	v_add_co_u32_e32 v26, vcc, s28, v0
	v_not_b32_e32 v183, v126
	s_nop 0
	v_addc_co_u32_e32 v27, vcc, 0, v1, vcc
	flat_load_dword v87, v[26:27]
	flat_load_dword v86, v[26:27] offset:512
	flat_load_dword v84, v[26:27] offset:1024
	flat_load_dword v85, v[26:27] offset:1536
	flat_load_dword v81, v[26:27] offset:2048
	flat_load_dword v80, v[26:27] offset:2560
	flat_load_dword v82, v[26:27] offset:3072
	flat_load_dword v83, v[26:27] offset:3584
	v_add_co_u32_e32 v26, vcc, s49, v0
	v_not_b32_e32 v182, v128
	s_nop 0
	v_addc_co_u32_e32 v27, vcc, 0, v1, vcc
	flat_load_dword v74, v[26:27]
	flat_load_dword v73, v[26:27] offset:512
	flat_load_dword v71, v[26:27] offset:1024
	flat_load_dword v72, v[26:27] offset:1536
	flat_load_dword v76, v[26:27] offset:2048
	flat_load_dword v75, v[26:27] offset:2560
	flat_load_dword v77, v[26:27] offset:3072
	flat_load_dword v79, v[26:27] offset:3584
	v_add_co_u32_e32 v26, vcc, s19, v0
	v_not_b32_e32 v186, v122
	s_nop 0
	v_addc_co_u32_e32 v27, vcc, 0, v1, vcc
	flat_load_dword v70, v[26:27]
	flat_load_dword v69, v[26:27] offset:512
	flat_load_dword v67, v[26:27] offset:1024
	flat_load_dword v68, v[26:27] offset:1536
	flat_load_dword v62, v[26:27] offset:2048
	flat_load_dword v61, v[26:27] offset:2560
	flat_load_dword v63, v[26:27] offset:3072
	flat_load_dword v66, v[26:27] offset:3584
	v_add_co_u32_e32 v26, vcc, s50, v0
	s_nop 1
	v_addc_co_u32_e32 v27, vcc, 0, v1, vcc
	flat_load_dword v56, v[26:27]
	flat_load_dword v55, v[26:27] offset:512
	flat_load_dword v53, v[26:27] offset:1024
	flat_load_dword v54, v[26:27] offset:1536
	flat_load_dword v58, v[26:27] offset:2048
	flat_load_dword v57, v[26:27] offset:2560
	flat_load_dword v59, v[26:27] offset:3072
	flat_load_dword v60, v[26:27] offset:3584
	v_add_co_u32_e32 v26, vcc, s29, v0
	s_nop 1
	v_addc_co_u32_e32 v27, vcc, 0, v1, vcc
	flat_load_dword v52, v[26:27]
	flat_load_dword v51, v[26:27] offset:512
	flat_load_dword v49, v[26:27] offset:1024
	flat_load_dword v50, v[26:27] offset:1536
	flat_load_dword v46, v[26:27] offset:2048
	flat_load_dword v45, v[26:27] offset:2560
	flat_load_dword v47, v[26:27] offset:3072
	flat_load_dword v48, v[26:27] offset:3584
	v_add_co_u32_e32 v26, vcc, s51, v0
	s_nop 1
	v_addc_co_u32_e32 v27, vcc, 0, v1, vcc
	flat_load_dword v40, v[26:27]
	flat_load_dword v39, v[26:27] offset:512
	flat_load_dword v37, v[26:27] offset:1024
	flat_load_dword v38, v[26:27] offset:1536
	flat_load_dword v42, v[26:27] offset:2048
	flat_load_dword v41, v[26:27] offset:2560
	flat_load_dword v43, v[26:27] offset:3072
	flat_load_dword v44, v[26:27] offset:3584
	v_add_co_u32_e32 v26, vcc, s30, v0
	s_nop 1
	v_addc_co_u32_e32 v27, vcc, 0, v1, vcc
	v_add_co_u32_e32 v138, vcc, s54, v0
	flat_load_dword v36, v[26:27]
	flat_load_dword v35, v[26:27] offset:512
	flat_load_dword v33, v[26:27] offset:1024
	flat_load_dword v34, v[26:27] offset:1536
	flat_load_dword v30, v[26:27] offset:2048
	flat_load_dword v29, v[26:27] offset:2560
	flat_load_dword v31, v[26:27] offset:3072
	flat_load_dword v32, v[26:27] offset:3584
	v_addc_co_u32_e32 v139, vcc, 0, v1, vcc
	flat_load_dword v18, v[138:139]
	flat_load_dword v16, v[138:139] offset:512
	flat_load_dword v2, v[138:139] offset:1024
	flat_load_dword v12, v[138:139] offset:1536
	flat_load_dword v26, v[138:139] offset:2048
	flat_load_dword v22, v[138:139] offset:2560
	flat_load_dword v27, v[138:139] offset:3072
	flat_load_dword v28, v[138:139] offset:3584
	flat_load_dword v137, v[0:1]
	flat_load_dword v140, v[0:1] offset:1536
	flat_load_dword v233, v[0:1] offset:512
	flat_load_dword v234, v[0:1] offset:1024
	flat_load_dword v235, v[0:1] offset:3584
	flat_load_dword v236, v[0:1] offset:3072
	flat_load_dword v237, v[0:1] offset:2048
	flat_load_dword v238, v[0:1] offset:2560
	s_waitcnt vmcnt(0) lgkmcnt(0)
	v_cmp_gt_i32_e32 vcc, 0, v137
	v_not_b32_e32 v138, v137
	v_or_b32_e32 v137, 0x80000000, v137
	v_cndmask_b32_e32 v137, v137, v138, vcc
	v_not_b32_e32 v141, v140
	v_or_b32_e32 v137, 0x7f, v137
	s_waitcnt vmcnt(0) lgkmcnt(0)
	v_cmp_gt_i32_e32 vcc, 0, v233
	v_not_b32_e32 v139, v233
	v_or_b32_e32 v138, 0x80000000, v233
	v_cndmask_b32_e32 v138, v138, v139, vcc
	v_cmp_gt_i32_e32 vcc, 0, v140
	v_or_b32_e32 v140, 0x80000000, v140
	v_and_b32_e32 v138, 0xffffff80, v138
	v_cndmask_b32_e32 v140, v140, v141, vcc
	v_and_b32_e32 v140, 0xffffff80, v140
	v_or_b32_e32 v140, 0x7c, v140
	v_or_b32_e32 v138, 0x7e, v138
	v_max_u32_e32 v139, v137, v138
	v_min_u32_e32 v138, v137, v138
	s_waitcnt vmcnt(0) lgkmcnt(0)
	v_cmp_gt_i32_e32 vcc, 0, v234
	v_not_b32_e32 v142, v234
	v_or_b32_e32 v141, 0x80000000, v234
	v_cndmask_b32_e32 v141, v141, v142, vcc
	v_and_b32_e32 v141, 0xffffff80, v141
	v_or_b32_e32 v141, 0x7d, v141
	v_min_u32_e32 v142, v140, v141
	v_max_u32_e32 v140, v140, v141
	v_max_u32_e32 v144, v138, v140
	v_min_u32_e32 v138, v138, v140
	v_min_u32_e32 v153, v139, v142
	v_max_u32_e32 v143, v139, v142
	v_max_u32_e32 v137, v143, v144
	s_waitcnt vmcnt(0) lgkmcnt(0)
	v_cmp_gt_i32_e32 vcc, 0, v235
	v_not_b32_e32 v145, v235
	v_or_b32_e32 v141, 0x80000000, v235
	v_cndmask_b32_e32 v141, v141, v145, vcc
	v_and_b32_e32 v141, 0xffffff80, v141
	v_or_b32_e32 v141, 0x78, v141
	s_waitcnt vmcnt(0) lgkmcnt(0)
; DEV unsigned fkey(float x) { const unsigned u = __float_as_uint(x); return (u & 0x80000000u) ? ~u : (u | 0x80000000u); }
; DEV float keyf(unsigned k) { const unsigned u = (k & 0x80000000u) ? (k & 0x7fffffffu) : ~k; return __uint_as_float(u); }
; DEV void bitonic_merge16_desc(unsigned (&v)[16]) {
; #pragma unroll
;   for (int j = 8; j >= 1; j >>= 1)
; #pragma unroll
;     for (int i = 0; i < 16; ++i) { const int l = i ^ j; if (l > i) cswap(v[i], v[l]); }
; }
; DEV void bitonic_sort16_desc(unsigned (&v)[16]) {
; #pragma unroll
;   for (int k = 2; k <= 16; k <<= 1)
; #pragma unroll
;     for (int j = k >> 1; j >= 1; j >>= 1)
; #pragma unroll
;       for (int i = 0; i < 16; ++i) { const int l = i ^ j; if (l > i) { if ((i & k) == 0) cswap(v[i], v[l]); else cswap(v[l], v[i]); } }
; }
; DEV void merge_top16(unsigned (&R)[16], const unsigned (&G)[16]) {
; #pragma unroll
;   for (int i = 0; i < 16; ++i) R[i] = max(R[i], G[15 - i]);
;   bitonic_merge16_desc(R);
; }
; DEV void stage1(unsigned (&L)[16], const float* sp) {
;   float sv[128];
; #pragma unroll
;   for (int i = 0; i < 128; ++i) sv[i] = sp[(size_t)i * 128];
; #pragma unroll
;   for (int i = 0; i < 128; i += 16) {
;     unsigned g[16];
; #pragma unroll
;     for (int e = 0; e < 16; ++e) g[e] = (fkey(sv[i + e]) & ~127u) | (unsigned)(127 - (i + e));
;     bitonic_sort16_desc(g);
;     if (i == 0) {
; #pragma unroll
;       for (int e = 0; e < 16; ++e) L[e] = g[e];
;     } else merge_top16(L, g);
;   }
; }
	v_cmp_gt_i32_e32 vcc, 0, v236
	v_not_b32_e32 v146, v236
	v_or_b32_e32 v145, 0x80000000, v236
	v_cndmask_b32_e32 v145, v145, v146, vcc
	v_and_b32_e32 v145, 0xffffff80, v145
	v_or_b32_e32 v145, 0x79, v145
	v_max_u32_e32 v147, v141, v145
	v_min_u32_e32 v151, v141, v145
	s_waitcnt vmcnt(0) lgkmcnt(0)
	v_cmp_gt_i32_e32 vcc, 0, v237
	v_not_b32_e32 v148, v237
	v_or_b32_e32 v146, 0x80000000, v237
	v_cndmask_b32_e32 v146, v146, v148, vcc
	v_and_b32_e32 v146, 0xffffff80, v146
	v_or_b32_e32 v146, 0x7b, v146
	s_waitcnt vmcnt(0) lgkmcnt(0)
	v_cmp_gt_i32_e32 vcc, 0, v238
	v_not_b32_e32 v149, v238
	v_or_b32_e32 v148, 0x80000000, v238
	v_cndmask_b32_e32 v148, v148, v149, vcc
	v_and_b32_e32 v148, 0xffffff80, v148
	v_or_b32_e32 v148, 0x7a, v148
	v_min_u32_e32 v149, v146, v148
	v_max_u32_e32 v148, v146, v148
	v_add_co_u32_e32 v0, vcc, s56, v0
	v_min_u32_e32 v150, v147, v149
	v_min_u32_e32 v152, v151, v148
	v_addc_co_u32_e32 v1, vcc, 0, v1, vcc
	flat_load_dword v239, v[0:1] offset:3584
	flat_load_dword v240, v[0:1] offset:1536
	flat_load_dword v241, v[0:1] offset:3072
	flat_load_dword v242, v[0:1] offset:2048
	flat_load_dword v243, v[0:1] offset:2560
	flat_load_dword v244, v[0:1]
	flat_load_dword v245, v[0:1] offset:512
	flat_load_dword v246, v[0:1] offset:1024
	v_min_u32_e32 v145, v150, v152
	v_max_u32_e32 v140, v147, v149
	v_max_u32_e32 v149, v150, v152
	v_max_u32_e32 v146, v153, v138
	v_min_u32_e32 v150, v153, v138
	v_max_u32_e32 v151, v151, v148
	v_min_u32_e32 v147, v140, v151
	v_min_u32_e32 v148, v143, v144
	v_max_u32_e32 v151, v140, v151
	v_max_u32_e32 v141, v137, v145
	v_max_u32_e32 v142, v146, v147
	v_max_u32_e32 v143, v148, v149
	v_max_u32_e32 v144, v150, v151
	v_min_u32_e32 v137, v137, v145
	v_min_u32_e32 v145, v146, v147
	v_min_u32_e32 v147, v148, v149
	v_min_u32_e32 v148, v150, v151
	v_max_u32_e32 v139, v141, v142
	v_max_u32_e32 v140, v143, v144
	v_max_u32_e32 v146, v137, v145
	v_max_u32_e32 v149, v147, v148
	v_min_u32_e32 v141, v141, v142
	v_min_u32_e32 v142, v143, v144
	v_min_u32_e32 v137, v137, v145
	v_min_u32_e32 v145, v147, v148
	v_max_u32_e32 v138, v139, v140
	v_max_u32_e32 v150, v146, v149
	v_max_u32_e32 v143, v141, v142
	v_max_u32_e32 v147, v137, v145
	v_min_u32_e32 v139, v139, v140
	v_min_u32_e32 v146, v146, v149
	v_min_u32_e32 v141, v141, v142
	v_min_u32_e32 v137, v137, v145
	s_waitcnt vmcnt(0) lgkmcnt(0)
	v_cmp_gt_i32_e32 vcc, 0, v239
	v_not_b32_e32 v153, v239
	v_or_b32_e32 v152, 0x80000000, v239
	v_cndmask_b32_e32 v152, v152, v153, vcc
	v_and_b32_e32 v152, 0xffffff80, v152
	v_or_b32_e32 v153, 0x70, v152
	v_not_b32_e32 v179, v240
	s_waitcnt vmcnt(0) lgkmcnt(0)
	v_cmp_gt_i32_e32 vcc, 0, v241
	v_not_b32_e32 v169, v241
	v_or_b32_e32 v152, 0x80000000, v241
	v_cndmask_b32_e32 v152, v152, v169, vcc
	v_and_b32_e32 v152, 0xffffff80, v152
	v_or_b32_e32 v170, 0x71, v152
	v_max_u32_e32 v152, v153, v170
	v_min_u32_e32 v172, v153, v170
	s_waitcnt vmcnt(0) lgkmcnt(0)
	v_cmp_gt_i32_e32 vcc, 0, v242
	v_not_b32_e32 v171, v242
	v_or_b32_e32 v169, 0x80000000, v242
	v_cndmask_b32_e32 v169, v169, v171, vcc
	v_and_b32_e32 v169, 0xffffff80, v169
	v_or_b32_e32 v173, 0x73, v169
	s_waitcnt vmcnt(0) lgkmcnt(0)
	v_cmp_gt_i32_e32 vcc, 0, v243
	v_not_b32_e32 v171, v243
	v_or_b32_e32 v169, 0x80000000, v243
	v_cndmask_b32_e32 v169, v169, v171, vcc
	v_and_b32_e32 v169, 0xffffff80, v169
	v_or_b32_e32 v174, 0x72, v169
	v_min_u32_e32 v171, v173, v174
	v_max_u32_e32 v173, v173, v174
	v_max_u32_e32 v169, v152, v171
	v_max_u32_e32 v170, v172, v173
	v_min_u32_e32 v152, v152, v171
	v_min_u32_e32 v171, v172, v173
	v_max_u32_e32 v153, v169, v170
	v_max_u32_e32 v172, v152, v171
	v_min_u32_e32 v169, v169, v170
	v_min_u32_e32 v152, v152, v171
	s_waitcnt vmcnt(0) lgkmcnt(0)
	v_cmp_gt_i32_e32 vcc, 0, v244
	v_not_b32_e32 v175, v244
	v_or_b32_e32 v174, 0x80000000, v244
	v_cndmask_b32_e32 v174, v174, v175, vcc
	v_and_b32_e32 v174, 0xffffff80, v174
	v_or_b32_e32 v174, 0x77, v174
	s_waitcnt vmcnt(0) lgkmcnt(0)
	v_cmp_gt_i32_e32 vcc, 0, v245
	v_not_b32_e32 v177, v245
	v_or_b32_e32 v175, 0x80000000, v245
	v_cndmask_b32_e32 v175, v175, v177, vcc
	v_cmp_gt_i32_e32 vcc, 0, v240
	v_or_b32_e32 v178, 0x80000000, v240
	v_not_b32_e32 v1, v246
	v_cndmask_b32_e32 v178, v178, v179, vcc
	v_cmp_gt_i32_e32 vcc, 0, v246
	v_or_b32_e32 v0, 0x80000000, v246
	v_and_b32_e32 v175, 0xffffff80, v175
	v_cndmask_b32_e32 v0, v0, v1, vcc
	v_and_b32_e32 v178, 0xffffff80, v178
	v_and_b32_e32 v0, 0xffffff80, v0
	v_or_b32_e32 v175, 0x76, v175
	v_or_b32_e32 v178, 0x74, v178
	v_or_b32_e32 v0, 0x75, v0
	v_max_u32_e32 v177, v174, v175
	v_min_u32_e32 v1, v178, v0
	v_min_u32_e32 v174, v174, v175
	v_max_u32_e32 v0, v178, v0
	v_min_u32_e32 v179, v177, v1
	v_min_u32_e32 v175, v174, v0
	v_max_u32_e32 v1, v177, v1
	v_max_u32_e32 v0, v174, v0
	v_min_u32_e32 v178, v179, v175
	v_min_u32_e32 v173, v1, v0
	v_max_u32_e32 v170, v179, v175
	v_max_u32_e32 v0, v1, v0
	v_min_u32_e32 v180, v153, v178
	v_min_u32_e32 v174, v172, v173
	v_min_u32_e32 v175, v169, v170
	v_min_u32_e32 v1, v152, v0
	v_max_u32_e32 v151, v153, v178
	v_max_u32_e32 v153, v172, v173
	v_max_u32_e32 v169, v169, v170
	v_max_u32_e32 v0, v152, v0
	v_min_u32_e32 v177, v180, v174
	v_min_u32_e32 v171, v175, v1
	v_min_u32_e32 v172, v151, v153
	v_min_u32_e32 v152, v169, v0
	v_max_u32_e32 v144, v180, v174
	v_max_u32_e32 v1, v175, v1
	v_max_u32_e32 v148, v151, v153
	v_max_u32_e32 v0, v169, v0
	v_min_u32_e32 v179, v177, v171
	v_min_u32_e32 v170, v172, v152
	v_min_u32_e32 v174, v144, v1
	v_min_u32_e32 v151, v148, v0
	v_min_u32_e32 v181, v138, v179
	v_min_u32_e32 v173, v150, v170
	v_min_u32_e32 v175, v143, v174
	v_min_u32_e32 v153, v147, v151
	v_max_u32_e32 v138, v138, v179
; DEV unsigned fkey(float x) { const unsigned u = __float_as_uint(x); return (u & 0x80000000u) ? ~u : (u | 0x80000000u); }
; DEV float keyf(unsigned k) { const unsigned u = (k & 0x80000000u) ? (k & 0x7fffffffu) : ~k; return __uint_as_float(u); }
; DEV void bitonic_merge16_desc(unsigned (&v)[16]) {
; #pragma unroll
;   for (int j = 8; j >= 1; j >>= 1)
; #pragma unroll
;     for (int i = 0; i < 16; ++i) { const int l = i ^ j; if (l > i) cswap(v[i], v[l]); }
; }
; DEV void bitonic_sort16_desc(unsigned (&v)[16]) {
; #pragma unroll
;   for (int k = 2; k <= 16; k <<= 1)
; #pragma unroll
;     for (int j = k >> 1; j >= 1; j >>= 1)
; #pragma unroll
;       for (int i = 0; i < 16; ++i) { const int l = i ^ j; if (l > i) { if ((i & k) == 0) cswap(v[i], v[l]); else cswap(v[l], v[i]); } }
; }
; DEV void merge_top16(unsigned (&R)[16], const unsigned (&G)[16]) {
; #pragma unroll
;   for (int i = 0; i < 16; ++i) R[i] = max(R[i], G[15 - i]);
;   bitonic_merge16_desc(R);
; }
; DEV void stage1(unsigned (&L)[16], const float* sp) {
;   float sv[128];
; #pragma unroll
;   for (int i = 0; i < 128; ++i) sv[i] = sp[(size_t)i * 128];
; #pragma unroll
;   for (int i = 0; i < 128; i += 16) {
;     unsigned g[16];
; #pragma unroll
;     for (int e = 0; e < 16; ++e) g[e] = (fkey(sv[i + e]) & ~127u) | (unsigned)(127 - (i + e));
;     bitonic_sort16_desc(g);
;     if (i == 0) {
; #pragma unroll
;       for (int e = 0; e < 16; ++e) L[e] = g[e];
;     } else merge_top16(L, g);
;   }
; }
	v_max_u32_e32 v150, v150, v170
	v_max_u32_e32 v143, v143, v174
	v_max_u32_e32 v147, v147, v151
	v_min_u32_e32 v170, v138, v150
	v_min_u32_e32 v151, v143, v147
	v_max_u32_e32 v138, v138, v150
	v_max_u32_e32 v143, v143, v147
	v_min_u32_e32 v147, v138, v143
	v_max_u32_e32 v138, v138, v143
	v_cmp_gt_i32_e32 vcc, 0, v136
	v_not_b32_e32 v143, v136
	v_or_b32_e32 v136, 0x80000000, v136
	v_cndmask_b32_e32 v136, v136, v143, vcc
	v_cmp_gt_i32_e32 vcc, 0, v135
	v_not_b32_e32 v143, v135
	v_or_b32_e32 v135, 0x80000000, v135
	v_cndmask_b32_e32 v135, v135, v143, vcc
	v_cmp_gt_i32_e32 vcc, 0, v134
	v_not_b32_e32 v150, v134
	v_or_b32_e32 v134, 0x80000000, v134
	v_cndmask_b32_e32 v134, v134, v150, vcc
	v_cmp_gt_i32_e32 vcc, 0, v133
	v_not_b32_e32 v150, v133
	v_or_b32_e32 v133, 0x80000000, v133
	v_cndmask_b32_e32 v133, v133, v150, vcc
	v_cmp_gt_i32_e32 vcc, 0, v132
	v_not_b32_e32 v174, v132
	v_or_b32_e32 v132, 0x80000000, v132
	v_min_u32_e32 v178, v181, v173
	v_min_u32_e32 v169, v175, v153
	v_cndmask_b32_e32 v132, v132, v174, vcc
	v_cmp_gt_i32_e32 vcc, 0, v131
	v_not_b32_e32 v174, v131
	v_or_b32_e32 v131, 0x80000000, v131
	v_min_u32_e32 v180, v178, v169
	v_max_u32_e32 v169, v178, v169
	v_cndmask_b32_e32 v131, v131, v174, vcc
	v_cmp_gt_i32_e32 vcc, 0, v130
	v_not_b32_e32 v178, v130
	v_or_b32_e32 v130, 0x80000000, v130
	v_cndmask_b32_e32 v130, v130, v178, vcc
	v_cmp_gt_i32_e32 vcc, 0, v129
	v_not_b32_e32 v178, v129
	v_or_b32_e32 v129, 0x80000000, v129
	v_cndmask_b32_e32 v129, v129, v178, vcc
	v_cmp_gt_i32_e32 vcc, 0, v128
	v_or_b32_e32 v128, 0x80000000, v128
	v_and_b32_e32 v136, 0xffffff80, v136
	v_cndmask_b32_e32 v128, v128, v182, vcc
	v_cmp_gt_i32_e32 vcc, 0, v127
	v_not_b32_e32 v182, v127
	v_or_b32_e32 v127, 0x80000000, v127
	v_cndmask_b32_e32 v127, v127, v182, vcc
	v_cmp_gt_i32_e32 vcc, 0, v126
	v_or_b32_e32 v126, 0x80000000, v126
	v_and_b32_e32 v135, 0xffffff80, v135
	v_cndmask_b32_e32 v126, v126, v183, vcc
	v_cmp_gt_i32_e32 vcc, 0, v125
	v_not_b32_e32 v183, v125
	v_or_b32_e32 v125, 0x80000000, v125
	v_cndmask_b32_e32 v125, v125, v183, vcc
	v_cmp_gt_i32_e32 vcc, 0, v124
	v_or_b32_e32 v124, 0x80000000, v124
	v_and_b32_e32 v134, 0xffffff80, v134
	v_cndmask_b32_e32 v124, v124, v185, vcc
	v_cmp_gt_i32_e32 vcc, 0, v123
	v_not_b32_e32 v185, v123
	v_or_b32_e32 v123, 0x80000000, v123
	v_cndmask_b32_e32 v123, v123, v185, vcc
	v_cmp_gt_i32_e32 vcc, 0, v122
	v_or_b32_e32 v122, 0x80000000, v122
	v_and_b32_e32 v133, 0xffffff80, v133
	v_cndmask_b32_e32 v122, v122, v186, vcc
	v_cmp_gt_i32_e32 vcc, 0, v120
	v_not_b32_e32 v186, v120
	v_or_b32_e32 v120, 0x80000000, v120
	v_cndmask_b32_e32 v120, v120, v186, vcc
	v_and_b32_e32 v132, 0xffffff80, v132
	v_and_b32_e32 v131, 0xffffff80, v131
	v_and_b32_e32 v130, 0xffffff80, v130
	v_and_b32_e32 v129, 0xffffff80, v129
	v_and_b32_e32 v128, 0xffffff80, v128
	v_and_b32_e32 v127, 0xffffff80, v127
	v_and_b32_e32 v126, 0xffffff80, v126
	v_and_b32_e32 v125, 0xffffff80, v125
	v_and_b32_e32 v124, 0xffffff80, v124
	v_and_b32_e32 v123, 0xffffff80, v123
	v_and_b32_e32 v122, 0xffffff80, v122
	v_and_b32_e32 v120, 0xffffff80, v120
	v_or_b32_e32 v136, 0x6f, v136
	v_or_b32_e32 v135, 0x6e, v135
	v_or_b32_e32 v134, 0x6c, v134
	v_or_b32_e32 v133, 0x6d, v133
	v_or_b32_e32 v132, 0x68, v132
	v_or_b32_e32 v131, 0x69, v131
	v_or_b32_e32 v130, 0x6b, v130
	v_or_b32_e32 v129, 0x6a, v129
	v_or_b32_e32 v128, 0x60, v128
	v_or_b32_e32 v127, 0x61, v127
	v_or_b32_e32 v126, 0x63, v126
	v_or_b32_e32 v125, 0x62, v125
	v_or_b32_e32 v124, 0x67, v124
	v_or_b32_e32 v123, 0x66, v123
	v_or_b32_e32 v122, 0x64, v122
	v_or_b32_e32 v120, 0x65, v120
	v_max_u32_e32 v173, v181, v173
	v_max_u32_e32 v153, v175, v153
	v_max_u32_e32 v143, v136, v135
	v_min_u32_e32 v150, v134, v133
	v_min_u32_e32 v135, v136, v135
	v_max_u32_e32 v133, v134, v133
	v_max_u32_e32 v174, v132, v131
	v_min_u32_e32 v178, v130, v129
	v_min_u32_e32 v131, v132, v131
	v_max_u32_e32 v129, v130, v129
	v_max_u32_e32 v182, v128, v127
	v_min_u32_e32 v183, v126, v125
	v_min_u32_e32 v127, v128, v127
	v_max_u32_e32 v125, v126, v125
	v_max_u32_e32 v185, v124, v123
	v_min_u32_e32 v186, v122, v120
	v_min_u32_e32 v123, v124, v123
	v_max_u32_e32 v120, v122, v120
	v_min_u32_e32 v175, v173, v153
	v_max_u32_e32 v153, v173, v153
	v_min_u32_e32 v173, v170, v151
	v_max_u32_e32 v151, v170, v151
	v_max_u32_e32 v170, v143, v150
	v_max_u32_e32 v134, v135, v133
	v_min_u32_e32 v179, v174, v178
	v_min_u32_e32 v130, v131, v129
	v_min_u32_e32 v143, v143, v150
	v_min_u32_e32 v133, v135, v133
	v_max_u32_e32 v150, v174, v178
	v_max_u32_e32 v129, v131, v129
	v_max_u32_e32 v184, v182, v183
	v_max_u32_e32 v126, v127, v125
	v_min_u32_e32 v187, v185, v186
	v_min_u32_e32 v122, v123, v120
	v_min_u32_e32 v182, v182, v183
	v_min_u32_e32 v125, v127, v125
	v_max_u32_e32 v183, v185, v186
	v_max_u32_e32 v120, v123, v120
	v_max_u32_e32 v136, v170, v134
	v_min_u32_e32 v132, v179, v130
	v_max_u32_e32 v135, v143, v133
	v_min_u32_e32 v131, v150, v129
	v_min_u32_e32 v134, v170, v134
	v_max_u32_e32 v130, v179, v130
	v_min_u32_e32 v133, v143, v133
	v_max_u32_e32 v129, v150, v129
	v_max_u32_e32 v128, v184, v126
	v_min_u32_e32 v124, v187, v122
	v_max_u32_e32 v127, v182, v125
	v_min_u32_e32 v123, v183, v120
	v_min_u32_e32 v126, v184, v126
	v_max_u32_e32 v122, v187, v122
	v_min_u32_e32 v125, v182, v125
	v_max_u32_e32 v120, v183, v120
	v_max_u32_e32 v181, v136, v132
	v_max_u32_e32 v174, v135, v131
	v_max_u32_e32 v170, v134, v130
	v_max_u32_e32 v143, v133, v129
	v_min_u32_e32 v188, v128, v124
	v_min_u32_e32 v185, v127, v123
	v_min_u32_e32 v184, v126, v122
	v_min_u32_e32 v182, v125, v120
	v_min_u32_e32 v132, v136, v132
	v_min_u32_e32 v131, v135, v131
; DEV unsigned fkey(float x) { const unsigned u = __float_as_uint(x); return (u & 0x80000000u) ? ~u : (u | 0x80000000u); }
; DEV float keyf(unsigned k) { const unsigned u = (k & 0x80000000u) ? (k & 0x7fffffffu) : ~k; return __uint_as_float(u); }
; DEV void bitonic_merge16_desc(unsigned (&v)[16]) {
; #pragma unroll
;   for (int j = 8; j >= 1; j >>= 1)
; #pragma unroll
;     for (int i = 0; i < 16; ++i) { const int l = i ^ j; if (l > i) cswap(v[i], v[l]); }
; }
; DEV void bitonic_sort16_desc(unsigned (&v)[16]) {
; #pragma unroll
;   for (int k = 2; k <= 16; k <<= 1)
; #pragma unroll
;     for (int j = k >> 1; j >= 1; j >>= 1)
; #pragma unroll
;       for (int i = 0; i < 16; ++i) { const int l = i ^ j; if (l > i) { if ((i & k) == 0) cswap(v[i], v[l]); else cswap(v[l], v[i]); } }
; }
; DEV void merge_top16(unsigned (&R)[16], const unsigned (&G)[16]) {
; #pragma unroll
;   for (int i = 0; i < 16; ++i) R[i] = max(R[i], G[15 - i]);
;   bitonic_merge16_desc(R);
; }
; DEV void stage1(unsigned (&L)[16], const float* sp) {
;   float sv[128];
; #pragma unroll
;   for (int i = 0; i < 128; ++i) sv[i] = sp[(size_t)i * 128];
; #pragma unroll
;   for (int i = 0; i < 128; i += 16) {
;     unsigned g[16];
; #pragma unroll
;     for (int e = 0; e < 16; ++e) g[e] = (fkey(sv[i + e]) & ~127u) | (unsigned)(127 - (i + e));
;     bitonic_sort16_desc(g);
;     if (i == 0) {
; #pragma unroll
;       for (int e = 0; e < 16; ++e) L[e] = g[e];
;     } else merge_top16(L, g);
;   }
; }
	v_min_u32_e32 v130, v134, v130
	v_min_u32_e32 v129, v133, v129
	v_max_u32_e32 v124, v128, v124
	v_max_u32_e32 v123, v127, v123
	v_max_u32_e32 v122, v126, v122
	v_max_u32_e32 v120, v125, v120
	v_max_u32_e32 v178, v181, v174
	v_max_u32_e32 v150, v170, v143
	v_min_u32_e32 v186, v188, v185
	v_min_u32_e32 v183, v184, v182
	v_max_u32_e32 v135, v132, v131
	v_max_u32_e32 v133, v130, v129
	v_min_u32_e32 v127, v124, v123
	v_min_u32_e32 v125, v122, v120
	v_min_u32_e32 v174, v181, v174
	v_min_u32_e32 v143, v170, v143
	v_max_u32_e32 v181, v188, v185
	v_max_u32_e32 v182, v184, v182
	v_min_u32_e32 v131, v132, v131
	v_min_u32_e32 v129, v130, v129
	v_max_u32_e32 v123, v124, v123
	v_max_u32_e32 v120, v122, v120
	v_max_u32_e32 v179, v178, v150
	v_min_u32_e32 v187, v186, v183
	v_max_u32_e32 v134, v135, v133
	v_min_u32_e32 v126, v127, v125
	v_max_u32_e32 v170, v174, v143
	v_min_u32_e32 v184, v181, v182
	v_max_u32_e32 v130, v131, v129
	v_min_u32_e32 v122, v123, v120
	v_min_u32_e32 v189, v179, v187
	v_min_u32_e32 v128, v134, v126
	v_min_u32_e32 v185, v170, v184
	v_min_u32_e32 v124, v130, v122
	v_max_u32_e32 v140, v177, v171
	v_max_u32_e32 v149, v172, v152
	v_max_u32_e32 v1, v144, v1
	v_max_u32_e32 v0, v148, v0
	v_min_u32_e32 v136, v189, v128
	v_min_u32_e32 v132, v185, v124
	v_min_u32_e32 v150, v178, v150
	v_max_u32_e32 v178, v186, v183
	v_min_u32_e32 v133, v135, v133
	v_max_u32_e32 v125, v127, v125
	v_min_u32_e32 v143, v174, v143
	v_max_u32_e32 v174, v181, v182
	v_min_u32_e32 v129, v131, v129
	v_max_u32_e32 v120, v123, v120
	v_max_u32_e32 v128, v189, v128
	v_max_u32_e32 v124, v185, v124
	v_min_u32_e32 v171, v139, v140
	v_min_u32_e32 v152, v146, v149
	v_min_u32_e32 v142, v141, v1
	v_min_u32_e32 v144, v137, v0
	v_min_u32_e32 v188, v136, v132
	v_min_u32_e32 v183, v150, v178
	v_min_u32_e32 v127, v133, v125
	v_min_u32_e32 v181, v143, v174
	v_min_u32_e32 v123, v129, v120
	v_max_u32_e32 v132, v136, v132
	v_min_u32_e32 v136, v128, v124
	v_max_u32_e32 v124, v128, v124
	v_max_u32_e32 v128, v179, v187
	v_max_u32_e32 v126, v134, v126
	v_max_u32_e32 v170, v170, v184
	v_max_u32_e32 v122, v130, v122
	v_max_u32_e32 v150, v150, v178
	v_max_u32_e32 v125, v133, v125
	v_max_u32_e32 v143, v143, v174
	v_max_u32_e32 v120, v129, v120
	v_min_u32_e32 v172, v171, v152
	v_min_u32_e32 v145, v142, v144
	v_max_u32_e32 v152, v171, v152
	v_max_u32_e32 v142, v142, v144
	v_min_u32_e32 v134, v128, v126
	v_min_u32_e32 v130, v170, v122
	v_min_u32_e32 v133, v150, v125
	v_min_u32_e32 v129, v143, v120
	v_max_u32_e32 v126, v128, v126
	v_max_u32_e32 v122, v170, v122
	v_max_u32_e32 v125, v150, v125
	v_max_u32_e32 v120, v143, v120
	v_min_u32_e32 v144, v152, v142
	v_min_u32_e32 v179, v134, v130
	v_max_u32_e32 v130, v134, v130
	v_min_u32_e32 v128, v126, v122
	v_min_u32_e32 v134, v125, v120
	v_min_u32_e32 v148, v172, v145
	v_max_u32_e32 v145, v172, v145
	v_min_u32_e32 v171, v175, v144
	v_min_u32_e32 v174, v133, v129
	v_max_u32_e32 v129, v133, v129
	v_min_u32_e32 v143, v128, v134
	v_max_u32_e32 v139, v139, v140
	v_max_u32_e32 v140, v146, v149
	v_max_u32_e32 v1, v141, v1
	v_max_u32_e32 v0, v137, v0
	v_min_u32_e32 v133, v130, v129
	v_max3_u32 v129, v171, v130, v129
	v_max3_u32 v130, v169, v145, v143
	v_cmp_gt_i32_e32 vcc, 0, v119
	v_not_b32_e32 v143, v119
	v_or_b32_e32 v119, 0x80000000, v119
	v_min_u32_e32 v146, v139, v140
	v_min_u32_e32 v137, v1, v0
	v_min_u32_e32 v135, v183, v127
	v_min_u32_e32 v131, v181, v123
	v_cndmask_b32_e32 v119, v119, v143, vcc
	v_cmp_gt_i32_e32 vcc, 0, v118
	v_not_b32_e32 v143, v118
	v_or_b32_e32 v118, 0x80000000, v118
	v_min_u32_e32 v141, v146, v137
	v_max_u32_e32 v137, v146, v137
	v_max_u32_e32 v139, v139, v140
	v_max_u32_e32 v0, v1, v0
	v_min_u32_e32 v182, v135, v131
	v_max_u32_e32 v131, v135, v131
	v_max_u32_e32 v127, v183, v127
	v_max_u32_e32 v123, v181, v123
	v_max3_u32 v133, v175, v144, v133
	v_cndmask_b32_e32 v118, v118, v143, vcc
	v_cmp_gt_i32_e32 vcc, 0, v117
	v_not_b32_e32 v144, v117
	v_or_b32_e32 v117, 0x80000000, v117
	v_min_u32_e32 v146, v151, v137
	v_min_u32_e32 v1, v139, v0
	v_min_u32_e32 v135, v132, v131
	v_min_u32_e32 v181, v127, v123
	v_cndmask_b32_e32 v117, v117, v144, vcc
	v_cmp_gt_i32_e32 vcc, 0, v116
	v_not_b32_e32 v144, v116
	v_or_b32_e32 v116, 0x80000000, v116
	v_min_u32_e32 v140, v147, v1
	v_max3_u32 v1, v147, v1, v135
	v_max3_u32 v135, v146, v136, v181
	v_cndmask_b32_e32 v116, v116, v144, vcc
	v_cmp_gt_i32_e32 vcc, 0, v115
	v_not_b32_e32 v146, v115
	v_or_b32_e32 v115, 0x80000000, v115
	v_cndmask_b32_e32 v115, v115, v146, vcc
	v_cmp_gt_i32_e32 vcc, 0, v114
	v_not_b32_e32 v146, v114
	v_or_b32_e32 v114, 0x80000000, v114
	v_cndmask_b32_e32 v114, v114, v146, vcc
	v_cmp_gt_i32_e32 vcc, 0, v113
	v_not_b32_e32 v147, v113
	v_or_b32_e32 v113, 0x80000000, v113
	v_cndmask_b32_e32 v113, v113, v147, vcc
	v_cmp_gt_i32_e32 vcc, 0, v112
	v_not_b32_e32 v147, v112
	v_or_b32_e32 v112, 0x80000000, v112
	v_cndmask_b32_e32 v112, v112, v147, vcc
	v_cmp_gt_i32_e32 vcc, 0, v111
	v_not_b32_e32 v150, v111
	v_or_b32_e32 v111, 0x80000000, v111
	v_min_u32_e32 v183, v136, v181
	v_cndmask_b32_e32 v111, v111, v150, vcc
	v_cmp_gt_i32_e32 vcc, 0, v110
	v_not_b32_e32 v150, v110
	v_or_b32_e32 v110, 0x80000000, v110
	v_max3_u32 v131, v140, v132, v131
	v_max3_u32 v132, v151, v137, v183
	v_cndmask_b32_e32 v110, v110, v150, vcc
	v_cmp_gt_i32_e32 vcc, 0, v109
	v_not_b32_e32 v151, v109
	v_or_b32_e32 v109, 0x80000000, v109
	v_max_u32_e32 v142, v152, v142
	v_min_u32_e32 v149, v173, v141
	v_max_u32_e32 v123, v127, v123
	v_min_u32_e32 v178, v179, v174
	v_cndmask_b32_e32 v109, v109, v151, vcc
	v_cmp_gt_i32_e32 vcc, 0, v108
	v_not_b32_e32 v151, v108
	v_or_b32_e32 v108, 0x80000000, v108
; DEV unsigned fkey(float x) { const unsigned u = __float_as_uint(x); return (u & 0x80000000u) ? ~u : (u | 0x80000000u); }
; DEV float keyf(unsigned k) { const unsigned u = (k & 0x80000000u) ? (k & 0x7fffffffu) : ~k; return __uint_as_float(u); }
; DEV void bitonic_merge16_desc(unsigned (&v)[16]) {
; #pragma unroll
;   for (int j = 8; j >= 1; j >>= 1)
; #pragma unroll
;     for (int i = 0; i < 16; ++i) { const int l = i ^ j; if (l > i) cswap(v[i], v[l]); }
; }
; DEV void bitonic_sort16_desc(unsigned (&v)[16]) {
; #pragma unroll
;   for (int k = 2; k <= 16; k <<= 1)
; #pragma unroll
;     for (int j = k >> 1; j >= 1; j >>= 1)
; #pragma unroll
;       for (int i = 0; i < 16; ++i) { const int l = i ^ j; if (l > i) { if ((i & k) == 0) cswap(v[i], v[l]); else cswap(v[l], v[i]); } }
; }
; DEV void merge_top16(unsigned (&R)[16], const unsigned (&G)[16]) {
; #pragma unroll
;   for (int i = 0; i < 16; ++i) R[i] = max(R[i], G[15 - i]);
;   bitonic_merge16_desc(R);
; }
; DEV void stage1(unsigned (&L)[16], const float* sp) {
;   float sv[128];
; #pragma unroll
;   for (int i = 0; i < 128; ++i) sv[i] = sp[(size_t)i * 128];
; #pragma unroll
;   for (int i = 0; i < 128; i += 16) {
;     unsigned g[16];
; #pragma unroll
;     for (int e = 0; e < 16; ++e) g[e] = (fkey(sv[i + e]) & ~127u) | (unsigned)(127 - (i + e));
;     bitonic_sort16_desc(g);
;     if (i == 0) {
; #pragma unroll
;       for (int e = 0; e < 16; ++e) L[e] = g[e];
;     } else merge_top16(L, g);
;   }
; }
	v_min_u32_e32 v152, v153, v142
	v_min_u32_e32 v127, v124, v123
	v_max3_u32 v123, v149, v124, v123
	v_max3_u32 v124, v153, v142, v178
	v_cndmask_b32_e32 v108, v108, v151, vcc
	v_cmp_gt_i32_e32 vcc, 0, v107
	v_not_b32_e32 v153, v107
	v_or_b32_e32 v107, 0x80000000, v107
	v_cndmask_b32_e32 v107, v107, v153, vcc
	v_cmp_gt_i32_e32 vcc, 0, v106
	v_not_b32_e32 v153, v106
	v_or_b32_e32 v106, 0x80000000, v106
	v_min_u32_e32 v172, v169, v145
	v_cndmask_b32_e32 v106, v106, v153, vcc
	v_cmp_gt_i32_e32 vcc, 0, v105
	v_not_b32_e32 v169, v105
	v_or_b32_e32 v105, 0x80000000, v105
	v_cndmask_b32_e32 v105, v105, v169, vcc
	v_cmp_gt_i32_e32 vcc, 0, v104
	v_not_b32_e32 v169, v104
	v_or_b32_e32 v104, 0x80000000, v104
	v_cndmask_b32_e32 v104, v104, v169, vcc
	v_and_b32_e32 v119, 0xffffff80, v119
	v_and_b32_e32 v118, 0xffffff80, v118
	v_and_b32_e32 v117, 0xffffff80, v117
	v_and_b32_e32 v116, 0xffffff80, v116
	v_and_b32_e32 v115, 0xffffff80, v115
	v_and_b32_e32 v114, 0xffffff80, v114
	v_and_b32_e32 v113, 0xffffff80, v113
	v_and_b32_e32 v112, 0xffffff80, v112
	v_and_b32_e32 v111, 0xffffff80, v111
	v_and_b32_e32 v110, 0xffffff80, v110
	v_and_b32_e32 v109, 0xffffff80, v109
	v_and_b32_e32 v108, 0xffffff80, v108
	v_and_b32_e32 v107, 0xffffff80, v107
	v_and_b32_e32 v106, 0xffffff80, v106
	v_and_b32_e32 v105, 0xffffff80, v105
	v_and_b32_e32 v104, 0xffffff80, v104
	v_max_u32_e32 v122, v126, v122
	v_max_u32_e32 v120, v125, v120
	v_or_b32_e32 v119, 0x5f, v119
	v_or_b32_e32 v118, 0x5e, v118
	v_or_b32_e32 v117, 0x5c, v117
	v_or_b32_e32 v116, 0x5d, v116
	v_or_b32_e32 v115, 0x58, v115
	v_or_b32_e32 v114, 0x59, v114
	v_or_b32_e32 v113, 0x5b, v113
	v_or_b32_e32 v112, 0x5a, v112
	v_or_b32_e32 v111, 0x50, v111
	v_or_b32_e32 v110, 0x51, v110
	v_or_b32_e32 v109, 0x53, v109
	v_or_b32_e32 v108, 0x52, v108
	v_or_b32_e32 v107, 0x57, v107
	v_or_b32_e32 v106, 0x56, v106
	v_or_b32_e32 v105, 0x54, v105
	v_or_b32_e32 v104, 0x55, v104
	v_min_u32_e32 v125, v122, v120
	v_max_u32_e32 v143, v119, v118
	v_min_u32_e32 v144, v117, v116
	v_min_u32_e32 v118, v119, v118
	v_max_u32_e32 v116, v117, v116
	v_max_u32_e32 v146, v115, v114
	v_min_u32_e32 v147, v113, v112
	v_min_u32_e32 v114, v115, v114
	v_max_u32_e32 v112, v113, v112
	v_max_u32_e32 v150, v111, v110
	v_min_u32_e32 v151, v109, v108
	v_min_u32_e32 v110, v111, v110
	v_max_u32_e32 v108, v109, v108
	v_max_u32_e32 v153, v107, v106
	v_min_u32_e32 v169, v105, v104
	v_min_u32_e32 v106, v107, v106
	v_max_u32_e32 v104, v105, v104
	v_min_u32_e32 v177, v180, v148
	v_max3_u32 v136, v152, v179, v174
	v_max3_u32 v125, v180, v148, v125
	v_max_u32_e32 v145, v143, v144
	v_max_u32_e32 v117, v118, v116
	v_min_u32_e32 v148, v146, v147
	v_min_u32_e32 v113, v114, v112
	v_min_u32_e32 v143, v143, v144
	v_min_u32_e32 v116, v118, v116
	v_max_u32_e32 v144, v146, v147
	v_max_u32_e32 v112, v114, v112
	v_max_u32_e32 v152, v150, v151
	v_max_u32_e32 v109, v110, v108
	v_min_u32_e32 v170, v153, v169
	v_min_u32_e32 v105, v106, v104
	v_min_u32_e32 v150, v150, v151
	v_min_u32_e32 v108, v110, v108
	v_max_u32_e32 v151, v153, v169
	v_max_u32_e32 v104, v106, v104
	v_max_u32_e32 v119, v145, v117
	v_min_u32_e32 v115, v148, v113
	v_max_u32_e32 v118, v143, v116
	v_min_u32_e32 v114, v144, v112
	v_min_u32_e32 v117, v145, v117
	v_max_u32_e32 v113, v148, v113
	v_min_u32_e32 v116, v143, v116
	v_max_u32_e32 v112, v144, v112
	v_max_u32_e32 v111, v152, v109
	v_min_u32_e32 v107, v170, v105
	v_max_u32_e32 v110, v150, v108
	v_min_u32_e32 v106, v151, v104
	v_min_u32_e32 v109, v152, v109
	v_max_u32_e32 v105, v170, v105
	v_min_u32_e32 v108, v150, v108
	v_max_u32_e32 v104, v151, v104
	v_max_u32_e32 v149, v119, v115
	v_max_u32_e32 v146, v118, v114
	v_max_u32_e32 v145, v117, v113
	v_max_u32_e32 v143, v116, v112
	v_min_u32_e32 v171, v111, v107
	v_min_u32_e32 v153, v110, v106
	v_min_u32_e32 v152, v109, v105
	v_min_u32_e32 v150, v108, v104
	v_min_u32_e32 v115, v119, v115
	v_min_u32_e32 v114, v118, v114
	v_min_u32_e32 v113, v117, v113
	v_min_u32_e32 v112, v116, v112
	v_max_u32_e32 v107, v111, v107
	v_max_u32_e32 v106, v110, v106
	v_max_u32_e32 v105, v109, v105
	v_max_u32_e32 v104, v108, v104
	v_max_u32_e32 v147, v149, v146
	v_max_u32_e32 v144, v145, v143
	v_min_u32_e32 v169, v171, v153
	v_min_u32_e32 v151, v152, v150
	v_max_u32_e32 v118, v115, v114
	v_max_u32_e32 v116, v113, v112
	v_min_u32_e32 v110, v107, v106
	v_min_u32_e32 v108, v105, v104
	v_min_u32_e32 v146, v149, v146
	v_min_u32_e32 v143, v145, v143
	v_max_u32_e32 v149, v171, v153
	v_max_u32_e32 v150, v152, v150
	v_min_u32_e32 v114, v115, v114
	v_min_u32_e32 v112, v113, v112
	v_max_u32_e32 v106, v107, v106
	v_max_u32_e32 v104, v105, v104
	v_max_u32_e32 v0, v139, v0
	v_max_u32_e32 v148, v147, v144
	v_min_u32_e32 v170, v169, v151
	v_max_u32_e32 v117, v118, v116
	v_min_u32_e32 v109, v110, v108
	v_max_u32_e32 v145, v146, v143
	v_min_u32_e32 v152, v149, v150
	v_max_u32_e32 v113, v114, v112
	v_min_u32_e32 v105, v106, v104
	v_min_u32_e32 v139, v138, v0
	v_min_u32_e32 v186, v188, v182
	v_max3_u32 v128, v172, v128, v134
	v_min_u32_e32 v172, v148, v170
	v_min_u32_e32 v111, v117, v109
	v_min_u32_e32 v153, v145, v152
	v_min_u32_e32 v107, v113, v105
	v_max3_u32 v0, v138, v0, v186
	v_max3_u32 v126, v139, v188, v182
	v_max3_u32 v127, v173, v141, v127
	v_max3_u32 v120, v177, v122, v120
	v_min_u32_e32 v119, v172, v111
	v_min_u32_e32 v115, v153, v107
	v_min_u32_e32 v144, v147, v144
	v_max_u32_e32 v147, v169, v151
	v_min_u32_e32 v116, v118, v116
	v_max_u32_e32 v108, v110, v108
	v_min_u32_e32 v143, v146, v143
	v_max_u32_e32 v146, v149, v150
	v_min_u32_e32 v112, v114, v112
	v_max_u32_e32 v104, v106, v104
	v_max_u32_e32 v111, v172, v111
	v_max_u32_e32 v107, v153, v107
; DEV unsigned fkey(float x) { const unsigned u = __float_as_uint(x); return (u & 0x80000000u) ? ~u : (u | 0x80000000u); }
; DEV float keyf(unsigned k) { const unsigned u = (k & 0x80000000u) ? (k & 0x7fffffffu) : ~k; return __uint_as_float(u); }
; DEV void bitonic_merge16_desc(unsigned (&v)[16]) {
; #pragma unroll
;   for (int j = 8; j >= 1; j >>= 1)
; #pragma unroll
;     for (int i = 0; i < 16; ++i) { const int l = i ^ j; if (l > i) cswap(v[i], v[l]); }
; }
; DEV void bitonic_sort16_desc(unsigned (&v)[16]) {
; #pragma unroll
;   for (int k = 2; k <= 16; k <<= 1)
; #pragma unroll
;     for (int j = k >> 1; j >= 1; j >>= 1)
; #pragma unroll
;       for (int i = 0; i < 16; ++i) { const int l = i ^ j; if (l > i) { if ((i & k) == 0) cswap(v[i], v[l]); else cswap(v[l], v[i]); } }
; }
; DEV void merge_top16(unsigned (&R)[16], const unsigned (&G)[16]) {
; #pragma unroll
;   for (int i = 0; i < 16; ++i) R[i] = max(R[i], G[15 - i]);
;   bitonic_merge16_desc(R);
; }
; DEV void stage1(unsigned (&L)[16], const float* sp) {
;   float sv[128];
; #pragma unroll
;   for (int i = 0; i < 128; ++i) sv[i] = sp[(size_t)i * 128];
; #pragma unroll
;   for (int i = 0; i < 128; i += 16) {
;     unsigned g[16];
; #pragma unroll
;     for (int e = 0; e < 16; ++e) g[e] = (fkey(sv[i + e]) & ~127u) | (unsigned)(127 - (i + e));
;     bitonic_sort16_desc(g);
;     if (i == 0) {
; #pragma unroll
;       for (int e = 0; e < 16; ++e) L[e] = g[e];
;     } else merge_top16(L, g);
;   }
; }
	v_max_u32_e32 v122, v0, v124
	v_min_u32_e32 v0, v0, v124
	v_max_u32_e32 v124, v126, v136
	v_max_u32_e32 v134, v1, v133
	v_min_u32_e32 v1, v1, v133
	v_max_u32_e32 v133, v131, v129
	v_min_u32_e32 v129, v131, v129
	v_max_u32_e32 v131, v132, v130
	v_min_u32_e32 v130, v132, v130
	v_max_u32_e32 v132, v135, v128
	v_min_u32_e32 v128, v135, v128
	v_max_u32_e32 v135, v127, v125
	v_min_u32_e32 v125, v127, v125
	v_max_u32_e32 v127, v123, v120
	v_min_u32_e32 v171, v119, v115
	v_min_u32_e32 v151, v144, v147
	v_min_u32_e32 v110, v116, v108
	v_min_u32_e32 v149, v143, v146
	v_min_u32_e32 v106, v112, v104
	v_max_u32_e32 v115, v119, v115
	v_min_u32_e32 v119, v111, v107
	v_max_u32_e32 v107, v111, v107
	v_max_u32_e32 v111, v148, v170
	v_max_u32_e32 v109, v117, v109
	v_max_u32_e32 v145, v145, v152
	v_max_u32_e32 v105, v113, v105
	v_max_u32_e32 v144, v144, v147
	v_max_u32_e32 v108, v116, v108
	v_max_u32_e32 v143, v143, v146
	v_max_u32_e32 v104, v112, v104
	v_min_u32_e32 v126, v126, v136
	v_min_u32_e32 v120, v123, v120
	v_max_u32_e32 v123, v122, v131
	v_min_u32_e32 v122, v122, v131
	v_max_u32_e32 v131, v124, v132
	v_min_u32_e32 v124, v124, v132
	v_max_u32_e32 v132, v134, v135
	v_min_u32_e32 v134, v134, v135
	v_max_u32_e32 v135, v133, v127
	v_min_u32_e32 v127, v133, v127
	v_min_u32_e32 v117, v111, v109
	v_min_u32_e32 v113, v145, v105
	v_min_u32_e32 v116, v144, v108
	v_min_u32_e32 v112, v143, v104
	v_max_u32_e32 v133, v0, v130
	v_min_u32_e32 v0, v0, v130
	v_max_u32_e32 v130, v126, v128
	v_min_u32_e32 v126, v126, v128
	v_max_u32_e32 v128, v1, v125
	v_min_u32_e32 v1, v1, v125
	v_max_u32_e32 v125, v129, v120
	v_min_u32_e32 v120, v129, v120
	v_max_u32_e32 v129, v123, v132
	v_min_u32_e32 v123, v123, v132
	v_max_u32_e32 v132, v131, v135
	v_min_u32_e32 v131, v131, v135
	v_max_u32_e32 v135, v122, v134
	v_min_u32_e32 v122, v122, v134
	v_max_u32_e32 v134, v124, v127
	v_min_u32_e32 v124, v124, v127
	v_min_u32_e32 v118, v151, v110
	v_min_u32_e32 v114, v149, v106
	v_max_u32_e32 v110, v151, v110
	v_max_u32_e32 v106, v149, v106
	v_min_u32_e32 v148, v117, v113
	v_min_u32_e32 v146, v116, v112
	v_max_u32_e32 v127, v133, v128
	v_min_u32_e32 v128, v133, v128
	v_max_u32_e32 v133, v130, v125
	v_min_u32_e32 v138, v122, v124
	v_min_u32_e32 v149, v110, v106
	v_max_u32_e32 v106, v110, v106
	v_min_u32_e32 v147, v148, v146
	v_min_u32_e32 v139, v127, v133
	v_min_u32_e32 v110, v107, v106
	v_max_u32_e32 v113, v117, v113
	v_max_u32_e32 v112, v116, v112
	v_max3_u32 v106, v138, v107, v106
	v_max3_u32 v107, v127, v133, v147
	v_cmp_gt_i32_e32 vcc, 0, v103
	v_not_b32_e32 v127, v103
	v_or_b32_e32 v103, 0x80000000, v103
	v_min_u32_e32 v125, v130, v125
	v_min_u32_e32 v116, v113, v112
	v_max_u32_e32 v109, v111, v109
	v_max_u32_e32 v105, v145, v105
	v_max_u32_e32 v108, v144, v108
	v_max_u32_e32 v104, v143, v104
	v_cndmask_b32_e32 v103, v103, v127, vcc
	v_cmp_gt_i32_e32 vcc, 0, v102
	v_not_b32_e32 v127, v102
	v_or_b32_e32 v102, 0x80000000, v102
	v_min_u32_e32 v140, v128, v125
	v_min_u32_e32 v111, v109, v105
	v_min_u32_e32 v117, v108, v104
	v_max3_u32 v116, v128, v125, v116
	v_cndmask_b32_e32 v102, v102, v127, vcc
	v_cmp_gt_i32_e32 vcc, 0, v101
	v_not_b32_e32 v128, v101
	v_or_b32_e32 v101, 0x80000000, v101
	v_max_u32_e32 v130, v0, v1
	v_min_u32_e32 v0, v0, v1
	v_max_u32_e32 v1, v126, v120
	v_min_u32_e32 v143, v111, v117
	v_cndmask_b32_e32 v101, v101, v128, vcc
	v_cmp_gt_i32_e32 vcc, 0, v100
	v_not_b32_e32 v128, v100
	v_or_b32_e32 v100, 0x80000000, v100
	v_min_u32_e32 v141, v130, v1
	v_min_u32_e32 v150, v118, v114
	v_max_u32_e32 v114, v118, v114
	v_max3_u32 v1, v130, v1, v143
	v_cndmask_b32_e32 v100, v100, v128, vcc
	v_cmp_gt_i32_e32 vcc, 0, v99
	v_not_b32_e32 v130, v99
	v_or_b32_e32 v99, 0x80000000, v99
	v_min_u32_e32 v118, v115, v114
	v_cndmask_b32_e32 v99, v99, v130, vcc
	v_cmp_gt_i32_e32 vcc, 0, v98
	v_not_b32_e32 v130, v98
	v_or_b32_e32 v98, 0x80000000, v98
	v_min_u32_e32 v136, v123, v131
	v_max3_u32 v118, v123, v131, v118
	v_cndmask_b32_e32 v98, v98, v130, vcc
	v_cmp_gt_i32_e32 vcc, 0, v97
	v_not_b32_e32 v131, v97
	v_or_b32_e32 v97, 0x80000000, v97
	v_min_u32_e32 v151, v119, v149
	v_cndmask_b32_e32 v97, v97, v131, vcc
	v_cmp_gt_i32_e32 vcc, 0, v96
	v_not_b32_e32 v131, v96
	v_or_b32_e32 v96, 0x80000000, v96
	v_min_u32_e32 v137, v135, v134
	v_max3_u32 v114, v136, v115, v114
	v_max3_u32 v115, v135, v134, v151
	v_cndmask_b32_e32 v96, v96, v131, vcc
	v_cmp_gt_i32_e32 vcc, 0, v95
	v_not_b32_e32 v134, v95
	v_or_b32_e32 v95, 0x80000000, v95
	v_cndmask_b32_e32 v95, v95, v134, vcc
	v_cmp_gt_i32_e32 vcc, 0, v94
	v_not_b32_e32 v134, v94
	v_or_b32_e32 v94, 0x80000000, v94
	v_cndmask_b32_e32 v94, v94, v134, vcc
	v_cmp_gt_i32_e32 vcc, 0, v93
	v_not_b32_e32 v135, v93
	v_or_b32_e32 v93, 0x80000000, v93
	v_cndmask_b32_e32 v93, v93, v135, vcc
	v_cmp_gt_i32_e32 vcc, 0, v92
	v_not_b32_e32 v135, v92
	v_or_b32_e32 v92, 0x80000000, v92
	v_max3_u32 v119, v137, v119, v149
	v_cndmask_b32_e32 v92, v92, v135, vcc
	v_cmp_gt_i32_e32 vcc, 0, v91
	v_not_b32_e32 v137, v91
	v_or_b32_e32 v91, 0x80000000, v91
	v_cndmask_b32_e32 v91, v91, v137, vcc
	v_cmp_gt_i32_e32 vcc, 0, v90
	v_not_b32_e32 v137, v90
	v_or_b32_e32 v90, 0x80000000, v90
	v_cndmask_b32_e32 v90, v90, v137, vcc
	v_cmp_gt_i32_e32 vcc, 0, v89
	v_not_b32_e32 v138, v89
	v_or_b32_e32 v89, 0x80000000, v89
	v_cndmask_b32_e32 v89, v89, v138, vcc
	v_cmp_gt_i32_e32 vcc, 0, v88
	v_not_b32_e32 v138, v88
	v_or_b32_e32 v88, 0x80000000, v88
	v_cndmask_b32_e32 v88, v88, v138, vcc
	v_and_b32_e32 v103, 0xffffff80, v103
	v_and_b32_e32 v102, 0xffffff80, v102
	v_and_b32_e32 v101, 0xffffff80, v101
	v_and_b32_e32 v100, 0xffffff80, v100
	v_and_b32_e32 v99, 0xffffff80, v99
	v_and_b32_e32 v98, 0xffffff80, v98
; DEV unsigned fkey(float x) { const unsigned u = __float_as_uint(x); return (u & 0x80000000u) ? ~u : (u | 0x80000000u); }
; DEV float keyf(unsigned k) { const unsigned u = (k & 0x80000000u) ? (k & 0x7fffffffu) : ~k; return __uint_as_float(u); }
; DEV void bitonic_merge16_desc(unsigned (&v)[16]) {
; #pragma unroll
;   for (int j = 8; j >= 1; j >>= 1)
; #pragma unroll
;     for (int i = 0; i < 16; ++i) { const int l = i ^ j; if (l > i) cswap(v[i], v[l]); }
; }
; DEV void bitonic_sort16_desc(unsigned (&v)[16]) {
; #pragma unroll
;   for (int k = 2; k <= 16; k <<= 1)
; #pragma unroll
;     for (int j = k >> 1; j >= 1; j >>= 1)
; #pragma unroll
;       for (int i = 0; i < 16; ++i) { const int l = i ^ j; if (l > i) { if ((i & k) == 0) cswap(v[i], v[l]); else cswap(v[l], v[i]); } }
; }
; DEV void merge_top16(unsigned (&R)[16], const unsigned (&G)[16]) {
; #pragma unroll
;   for (int i = 0; i < 16; ++i) R[i] = max(R[i], G[15 - i]);
;   bitonic_merge16_desc(R);
; }
; DEV void stage1(unsigned (&L)[16], const float* sp) {
;   float sv[128];
; #pragma unroll
;   for (int i = 0; i < 128; ++i) sv[i] = sp[(size_t)i * 128];
; #pragma unroll
;   for (int i = 0; i < 128; i += 16) {
;     unsigned g[16];
; #pragma unroll
;     for (int e = 0; e < 16; ++e) g[e] = (fkey(sv[i + e]) & ~127u) | (unsigned)(127 - (i + e));
;     bitonic_sort16_desc(g);
;     if (i == 0) {
; #pragma unroll
;       for (int e = 0; e < 16; ++e) L[e] = g[e];
;     } else merge_top16(L, g);
;   }
; }
	v_and_b32_e32 v97, 0xffffff80, v97
	v_and_b32_e32 v96, 0xffffff80, v96
	v_and_b32_e32 v94, 0xffffff80, v94
	v_and_b32_e32 v93, 0xffffff80, v93
	v_and_b32_e32 v92, 0xffffff80, v92
	v_and_b32_e32 v91, 0xffffff80, v91
	v_and_b32_e32 v90, 0xffffff80, v90
	v_and_b32_e32 v89, 0xffffff80, v89
	v_and_b32_e32 v88, 0xffffff80, v88
	v_or_b32_e32 v103, 0x4f, v103
	v_or_b32_e32 v102, 0x4e, v102
	v_or_b32_e32 v101, 0x4c, v101
	v_or_b32_e32 v100, 0x4d, v100
	v_or_b32_e32 v99, 0x48, v99
	v_or_b32_e32 v98, 0x49, v98
	v_or_b32_e32 v97, 0x4b, v97
	v_or_b32_e32 v96, 0x4a, v96
	v_and_or_b32 v95, v95, s55, 64
	v_or_b32_e32 v94, 0x41, v94
	v_or_b32_e32 v93, 0x43, v93
	v_or_b32_e32 v92, 0x42, v92
	v_or_b32_e32 v91, 0x47, v91
	v_or_b32_e32 v90, 0x46, v90
	v_or_b32_e32 v89, 0x44, v89
	v_or_b32_e32 v88, 0x45, v88
	v_min_u32_e32 v169, v171, v150
	v_max_u32_e32 v127, v103, v102
	v_min_u32_e32 v128, v101, v100
	v_min_u32_e32 v102, v103, v102
	v_max_u32_e32 v100, v101, v100
	v_max_u32_e32 v130, v99, v98
	v_min_u32_e32 v131, v97, v96
	v_min_u32_e32 v98, v99, v98
	v_max_u32_e32 v96, v97, v96
	v_max_u32_e32 v134, v95, v94
	v_min_u32_e32 v135, v93, v92
	v_min_u32_e32 v94, v95, v94
	v_max_u32_e32 v92, v93, v92
	v_max_u32_e32 v137, v91, v90
	v_min_u32_e32 v138, v89, v88
	v_min_u32_e32 v90, v91, v90
	v_max_u32_e32 v88, v89, v88
	v_min_u32_e32 v120, v126, v120
	v_min_u32_e32 v126, v129, v132
	v_max_u32_e32 v105, v109, v105
	v_max3_u32 v109, v129, v132, v169
	v_max3_u32 v110, v122, v124, v110
	v_max3_u32 v122, v139, v148, v146
	v_max_u32_e32 v129, v127, v128
	v_max_u32_e32 v101, v102, v100
	v_min_u32_e32 v132, v130, v131
	v_min_u32_e32 v97, v98, v96
	v_min_u32_e32 v127, v127, v128
	v_min_u32_e32 v100, v102, v100
	v_max_u32_e32 v128, v130, v131
	v_max_u32_e32 v96, v98, v96
	v_max_u32_e32 v136, v134, v135
	v_max_u32_e32 v93, v94, v92
	v_min_u32_e32 v139, v137, v138
	v_min_u32_e32 v89, v90, v88
	v_min_u32_e32 v134, v134, v135
	v_min_u32_e32 v92, v94, v92
	v_max_u32_e32 v135, v137, v138
	v_max_u32_e32 v88, v90, v88
	v_max_u32_e32 v103, v129, v101
	v_min_u32_e32 v99, v132, v97
	v_max_u32_e32 v102, v127, v100
	v_min_u32_e32 v98, v128, v96
	v_min_u32_e32 v101, v129, v101
	v_max_u32_e32 v97, v132, v97
	v_min_u32_e32 v100, v127, v100
	v_max_u32_e32 v96, v128, v96
	v_max_u32_e32 v95, v136, v93
	v_min_u32_e32 v91, v139, v89
	v_max_u32_e32 v94, v134, v92
	v_min_u32_e32 v90, v135, v88
	v_min_u32_e32 v93, v136, v93
	v_max_u32_e32 v89, v139, v89
	v_min_u32_e32 v92, v134, v92
	v_max_u32_e32 v88, v135, v88
	v_max3_u32 v112, v140, v113, v112
	v_max_u32_e32 v133, v103, v99
	v_max_u32_e32 v130, v102, v98
	v_max_u32_e32 v129, v101, v97
	v_max_u32_e32 v127, v100, v96
	v_min_u32_e32 v140, v95, v91
	v_min_u32_e32 v137, v94, v90
	v_min_u32_e32 v136, v93, v89
	v_min_u32_e32 v134, v92, v88
	v_min_u32_e32 v99, v103, v99
	v_min_u32_e32 v98, v102, v98
	v_min_u32_e32 v97, v101, v97
	v_min_u32_e32 v96, v100, v96
	v_max_u32_e32 v91, v95, v91
	v_max_u32_e32 v90, v94, v90
	v_max_u32_e32 v89, v93, v89
	v_max_u32_e32 v88, v92, v88
	v_max_u32_e32 v131, v133, v130
	v_max_u32_e32 v128, v129, v127
	v_min_u32_e32 v138, v140, v137
	v_min_u32_e32 v135, v136, v134
	v_max_u32_e32 v102, v99, v98
	v_max_u32_e32 v100, v97, v96
	v_min_u32_e32 v94, v91, v90
	v_min_u32_e32 v92, v89, v88
	v_min_u32_e32 v130, v133, v130
	v_min_u32_e32 v127, v129, v127
	v_max_u32_e32 v133, v140, v137
	v_max_u32_e32 v134, v136, v134
	v_min_u32_e32 v98, v99, v98
	v_min_u32_e32 v96, v97, v96
	v_max_u32_e32 v90, v91, v90
	v_max_u32_e32 v88, v89, v88
	v_max_u32_e32 v104, v108, v104
	v_max_u32_e32 v132, v131, v128
	v_min_u32_e32 v139, v138, v135
	v_max_u32_e32 v101, v102, v100
	v_min_u32_e32 v93, v94, v92
	v_max_u32_e32 v129, v130, v127
	v_min_u32_e32 v136, v133, v134
	v_max_u32_e32 v97, v98, v96
	v_min_u32_e32 v89, v90, v88
	v_min_u32_e32 v142, v0, v120
	v_min_u32_e32 v108, v105, v104
	v_max3_u32 v111, v141, v111, v117
	v_min_u32_e32 v141, v132, v139
	v_min_u32_e32 v95, v101, v93
	v_min_u32_e32 v137, v129, v136
	v_min_u32_e32 v91, v97, v89
	v_max3_u32 v126, v126, v171, v150
	v_max3_u32 v0, v0, v120, v108
	v_max3_u32 v104, v142, v105, v104
	v_min_u32_e32 v103, v141, v95
	v_min_u32_e32 v99, v137, v91
	v_min_u32_e32 v128, v131, v128
	v_max_u32_e32 v131, v138, v135
	v_min_u32_e32 v100, v102, v100
	v_max_u32_e32 v92, v94, v92
	v_min_u32_e32 v127, v130, v127
	v_max_u32_e32 v130, v133, v134
	v_min_u32_e32 v96, v98, v96
	v_max_u32_e32 v88, v90, v88
	v_max_u32_e32 v95, v141, v95
	v_max_u32_e32 v91, v137, v91
	v_max_u32_e32 v105, v109, v107
	v_max_u32_e32 v108, v126, v122
	v_max_u32_e32 v113, v118, v116
	v_min_u32_e32 v116, v118, v116
	v_max_u32_e32 v117, v114, v112
	v_min_u32_e32 v112, v114, v112
	v_max_u32_e32 v114, v115, v1
	v_min_u32_e32 v1, v115, v1
	v_max_u32_e32 v115, v119, v111
	v_max_u32_e32 v118, v110, v0
	v_min_u32_e32 v0, v110, v0
	v_max_u32_e32 v110, v106, v104
	v_min_u32_e32 v140, v103, v99
	v_min_u32_e32 v135, v128, v131
	v_min_u32_e32 v94, v100, v92
	v_min_u32_e32 v133, v127, v130
	v_min_u32_e32 v90, v96, v88
	v_max_u32_e32 v99, v103, v99
	v_min_u32_e32 v103, v95, v91
	v_max_u32_e32 v91, v95, v91
	v_max_u32_e32 v95, v132, v139
	v_max_u32_e32 v93, v101, v93
	v_max_u32_e32 v129, v129, v136
	v_max_u32_e32 v89, v97, v89
	v_max_u32_e32 v128, v128, v131
	v_max_u32_e32 v92, v100, v92
	v_max_u32_e32 v127, v127, v130
	v_max_u32_e32 v88, v96, v88
	v_min_u32_e32 v107, v109, v107
	v_min_u32_e32 v109, v126, v122
	v_min_u32_e32 v111, v119, v111
	v_min_u32_e32 v104, v106, v104
	v_max_u32_e32 v106, v105, v114
	v_min_u32_e32 v105, v105, v114
	v_max_u32_e32 v114, v108, v115
	v_min_u32_e32 v108, v108, v115
	v_max_u32_e32 v115, v113, v118
	v_min_u32_e32 v113, v113, v118
; DEV unsigned fkey(float x) { const unsigned u = __float_as_uint(x); return (u & 0x80000000u) ? ~u : (u | 0x80000000u); }
; DEV float keyf(unsigned k) { const unsigned u = (k & 0x80000000u) ? (k & 0x7fffffffu) : ~k; return __uint_as_float(u); }
; DEV void bitonic_merge16_desc(unsigned (&v)[16]) {
; #pragma unroll
;   for (int j = 8; j >= 1; j >>= 1)
; #pragma unroll
;     for (int i = 0; i < 16; ++i) { const int l = i ^ j; if (l > i) cswap(v[i], v[l]); }
; }
; DEV void bitonic_sort16_desc(unsigned (&v)[16]) {
; #pragma unroll
;   for (int k = 2; k <= 16; k <<= 1)
; #pragma unroll
;     for (int j = k >> 1; j >= 1; j >>= 1)
; #pragma unroll
;       for (int i = 0; i < 16; ++i) { const int l = i ^ j; if (l > i) { if ((i & k) == 0) cswap(v[i], v[l]); else cswap(v[l], v[i]); } }
; DEV void stage1(unsigned (&L)[16], const float* sp) {
;   float sv[128];
; #pragma unroll
;   for (int i = 0; i < 128; ++i) sv[i] = sp[(size_t)i * 128];
; #pragma unroll
;   for (int i = 0; i < 128; i += 16) {
;     unsigned g[16];
; #pragma unroll
;     for (int e = 0; e < 16; ++e) g[e] = (fkey(sv[i + e]) & ~127u) | (unsigned)(127 - (i + e));
;     bitonic_sort16_desc(g);
;     if (i == 0) {
; #pragma unroll
;       for (int e = 0; e < 16; ++e) L[e] = g[e];
;     } else merge_top16(L, g);
;   }
; }
	v_max_u32_e32 v118, v117, v110
	v_min_u32_e32 v110, v117, v110
	v_min_u32_e32 v101, v95, v93
	v_min_u32_e32 v97, v129, v89
	v_min_u32_e32 v100, v128, v92
	v_min_u32_e32 v96, v127, v88
	v_max_u32_e32 v117, v107, v1
	v_min_u32_e32 v1, v107, v1
	v_max_u32_e32 v107, v109, v111
	v_min_u32_e32 v109, v109, v111
	v_max_u32_e32 v111, v116, v0
	v_min_u32_e32 v0, v116, v0
	v_max_u32_e32 v116, v112, v104
	v_min_u32_e32 v104, v112, v104
	v_max_u32_e32 v112, v106, v115
	v_min_u32_e32 v106, v106, v115
	v_max_u32_e32 v115, v114, v118
	v_min_u32_e32 v114, v114, v118
	v_max_u32_e32 v118, v105, v113
	v_min_u32_e32 v105, v105, v113
	v_max_u32_e32 v113, v108, v110
	v_min_u32_e32 v108, v108, v110
	v_min_u32_e32 v102, v135, v94
	v_min_u32_e32 v98, v133, v90
	v_max_u32_e32 v94, v135, v94
	v_max_u32_e32 v90, v133, v90
	v_min_u32_e32 v132, v101, v97
	v_min_u32_e32 v130, v100, v96
	v_max_u32_e32 v110, v117, v111
	v_min_u32_e32 v111, v117, v111
	v_max_u32_e32 v117, v107, v116
	v_min_u32_e32 v122, v105, v108
	v_min_u32_e32 v133, v94, v90
	v_max_u32_e32 v90, v94, v90
	v_min_u32_e32 v131, v132, v130
	v_min_u32_e32 v123, v110, v117
	v_min_u32_e32 v94, v91, v90
	v_max_u32_e32 v97, v101, v97
	v_max_u32_e32 v96, v100, v96
	v_max3_u32 v90, v122, v91, v90
	v_max3_u32 v91, v110, v117, v131
	v_cmp_gt_i32_e32 vcc, 0, v87
	v_not_b32_e32 v110, v87
	v_or_b32_e32 v87, 0x80000000, v87
	v_min_u32_e32 v107, v107, v116
	v_min_u32_e32 v100, v97, v96
	v_cndmask_b32_e32 v87, v87, v110, vcc
	v_cmp_gt_i32_e32 vcc, 0, v86
	v_not_b32_e32 v110, v86
	v_or_b32_e32 v86, 0x80000000, v86
	v_min_u32_e32 v124, v111, v107
	v_max3_u32 v100, v111, v107, v100
	v_cndmask_b32_e32 v86, v86, v110, vcc
	v_cmp_gt_i32_e32 vcc, 0, v85
	v_not_b32_e32 v111, v85
	v_or_b32_e32 v85, 0x80000000, v85
	v_min_u32_e32 v119, v106, v114
	v_min_u32_e32 v134, v102, v98
	v_max_u32_e32 v98, v102, v98
	v_min_u32_e32 v135, v103, v133
	v_cndmask_b32_e32 v85, v85, v111, vcc
	v_cmp_gt_i32_e32 vcc, 0, v84
	v_not_b32_e32 v111, v84
	v_or_b32_e32 v84, 0x80000000, v84
	v_min_u32_e32 v120, v118, v113
	v_min_u32_e32 v102, v99, v98
	v_max3_u32 v98, v119, v99, v98
	v_max3_u32 v99, v118, v113, v135
	v_cndmask_b32_e32 v84, v84, v111, vcc
	v_cmp_gt_i32_e32 vcc, 0, v83
	v_not_b32_e32 v113, v83
	v_or_b32_e32 v83, 0x80000000, v83
	v_cndmask_b32_e32 v83, v83, v113, vcc
	v_cmp_gt_i32_e32 vcc, 0, v82
	v_not_b32_e32 v113, v82
	v_or_b32_e32 v82, 0x80000000, v82
	v_max3_u32 v102, v106, v114, v102
	v_cndmask_b32_e32 v82, v82, v113, vcc
	v_cmp_gt_i32_e32 vcc, 0, v81
	v_not_b32_e32 v114, v81
	v_or_b32_e32 v81, 0x80000000, v81
	v_cndmask_b32_e32 v81, v81, v114, vcc
	v_cmp_gt_i32_e32 vcc, 0, v80
	v_not_b32_e32 v114, v80
	v_or_b32_e32 v80, 0x80000000, v80
	v_cndmask_b32_e32 v80, v80, v114, vcc
	v_cmp_gt_i32_e32 vcc, 0, v79
	v_not_b32_e32 v117, v79
	v_or_b32_e32 v79, 0x80000000, v79
	v_cndmask_b32_e32 v79, v79, v117, vcc
	v_cmp_gt_i32_e32 vcc, 0, v77
	v_not_b32_e32 v117, v77
	v_or_b32_e32 v77, 0x80000000, v77
	v_cndmask_b32_e32 v77, v77, v117, vcc
	v_cmp_gt_i32_e32 vcc, 0, v76
	v_not_b32_e32 v118, v76
	v_or_b32_e32 v76, 0x80000000, v76
	v_cndmask_b32_e32 v76, v76, v118, vcc
	v_cmp_gt_i32_e32 vcc, 0, v75
	v_not_b32_e32 v118, v75
	v_or_b32_e32 v75, 0x80000000, v75
	v_max3_u32 v103, v120, v103, v133
	v_cndmask_b32_e32 v75, v75, v118, vcc
	v_cmp_gt_i32_e32 vcc, 0, v74
	v_not_b32_e32 v120, v74
	v_or_b32_e32 v74, 0x80000000, v74
	v_cndmask_b32_e32 v74, v74, v120, vcc
	v_cmp_gt_i32_e32 vcc, 0, v73
	v_not_b32_e32 v120, v73
	v_or_b32_e32 v73, 0x80000000, v73
	v_cndmask_b32_e32 v73, v73, v120, vcc
	v_cmp_gt_i32_e32 vcc, 0, v72
	v_not_b32_e32 v122, v72
	v_or_b32_e32 v72, 0x80000000, v72
	v_cndmask_b32_e32 v72, v72, v122, vcc
	v_cmp_gt_i32_e32 vcc, 0, v71
	v_not_b32_e32 v122, v71
	v_or_b32_e32 v71, 0x80000000, v71
	v_cndmask_b32_e32 v71, v71, v122, vcc
	v_and_or_b32 v87, v87, s55, 63
	v_and_or_b32 v86, v86, s55, 62
	v_and_or_b32 v85, v85, s55, 60
	v_and_or_b32 v84, v84, s55, 61
	v_and_or_b32 v83, v83, s55, 56
	v_and_or_b32 v82, v82, s55, 57
	v_and_or_b32 v81, v81, s55, 59
	v_and_or_b32 v80, v80, s55, 58
	v_and_or_b32 v79, v79, s55, 48
	v_and_or_b32 v77, v77, s55, 49
	v_and_or_b32 v76, v76, s55, 51
	v_and_or_b32 v75, v75, s55, 50
	v_and_or_b32 v74, v74, s55, 55
	v_and_or_b32 v73, v73, s55, 54
	v_and_or_b32 v72, v72, s55, 52
	v_and_or_b32 v71, v71, s55, 53
	v_min_u32_e32 v138, v140, v134
	v_max_u32_e32 v93, v95, v93
	v_max_u32_e32 v89, v129, v89
	v_max_u32_e32 v92, v128, v92
	v_max_u32_e32 v88, v127, v88
	v_max_u32_e32 v110, v87, v86
	v_min_u32_e32 v111, v85, v84
	v_min_u32_e32 v86, v87, v86
	v_max_u32_e32 v84, v85, v84
	v_max_u32_e32 v113, v83, v82
	v_min_u32_e32 v114, v81, v80
	v_min_u32_e32 v82, v83, v82
	v_max_u32_e32 v80, v81, v80
	v_max_u32_e32 v117, v79, v77
	v_min_u32_e32 v118, v76, v75
	v_min_u32_e32 v77, v79, v77
	v_max_u32_e32 v75, v76, v75
	v_max_u32_e32 v120, v74, v73
	v_min_u32_e32 v122, v72, v71
	v_min_u32_e32 v73, v74, v73
	v_max_u32_e32 v71, v72, v71
	v_max_u32_e32 v116, v1, v0
	v_min_u32_e32 v0, v1, v0
	v_max_u32_e32 v1, v109, v104
	v_min_u32_e32 v104, v109, v104
	v_min_u32_e32 v109, v112, v115
	v_min_u32_e32 v95, v93, v89
	v_min_u32_e32 v101, v92, v88
	v_max_u32_e32 v89, v93, v89
	v_max3_u32 v93, v112, v115, v138
	v_max3_u32 v94, v105, v108, v94
	v_max3_u32 v105, v123, v132, v130
	v_max_u32_e32 v112, v110, v111
	v_max_u32_e32 v85, v86, v84
	v_min_u32_e32 v115, v113, v114
	v_min_u32_e32 v81, v82, v80
	v_min_u32_e32 v110, v110, v111
	v_min_u32_e32 v84, v86, v84
	v_max_u32_e32 v111, v113, v114
	v_max_u32_e32 v80, v82, v80
	v_max_u32_e32 v119, v117, v118
	v_max_u32_e32 v76, v77, v75
	v_min_u32_e32 v123, v120, v122
	v_min_u32_e32 v72, v73, v71
; DEV unsigned fkey(float x) { const unsigned u = __float_as_uint(x); return (u & 0x80000000u) ? ~u : (u | 0x80000000u); }
; DEV void bitonic_merge16_desc(unsigned (&v)[16]) {
; #pragma unroll
;   for (int j = 8; j >= 1; j >>= 1)
; #pragma unroll
;     for (int i = 0; i < 16; ++i) { const int l = i ^ j; if (l > i) cswap(v[i], v[l]); }
; }
; DEV void bitonic_sort16_desc(unsigned (&v)[16]) {
; #pragma unroll
;   for (int k = 2; k <= 16; k <<= 1)
; #pragma unroll
;     for (int j = k >> 1; j >= 1; j >>= 1)
; #pragma unroll
;       for (int i = 0; i < 16; ++i) { const int l = i ^ j; if (l > i) { if ((i & k) == 0) cswap(v[i], v[l]); else cswap(v[l], v[i]); } }
; }
; DEV void merge_top16(unsigned (&R)[16], const unsigned (&G)[16]) {
; #pragma unroll
;   for (int i = 0; i < 16; ++i) R[i] = max(R[i], G[15 - i]);
;   bitonic_merge16_desc(R);
; }
; DEV void stage1(unsigned (&L)[16], const float* sp) {
;     ...
;     for (int e = 0; e < 16; ++e) g[e] = (fkey(sv[i + e]) & ~127u) | (unsigned)(127 - (i + e));
	v_min_u32_e32 v117, v117, v118
	v_min_u32_e32 v75, v77, v75
	v_max_u32_e32 v118, v120, v122
	v_max_u32_e32 v71, v73, v71
	v_min_u32_e32 v127, v95, v101
	v_max_u32_e32 v87, v112, v85
	v_min_u32_e32 v83, v115, v81
	v_max_u32_e32 v86, v110, v84
	v_min_u32_e32 v82, v111, v80
	v_min_u32_e32 v85, v112, v85
	v_max_u32_e32 v81, v115, v81
	v_min_u32_e32 v84, v110, v84
	v_max_u32_e32 v80, v111, v80
	v_max_u32_e32 v79, v119, v76
	v_min_u32_e32 v74, v123, v72
	v_max_u32_e32 v77, v117, v75
	v_min_u32_e32 v73, v118, v71
	v_min_u32_e32 v76, v119, v76
	v_max_u32_e32 v72, v123, v72
	v_min_u32_e32 v75, v117, v75
	v_max_u32_e32 v71, v118, v71
	v_min_u32_e32 v125, v116, v1
	v_max3_u32 v96, v124, v97, v96
	v_max3_u32 v1, v116, v1, v127
	v_max_u32_e32 v116, v87, v83
	v_max_u32_e32 v113, v86, v82
	v_max_u32_e32 v112, v85, v81
	v_max_u32_e32 v110, v84, v80
	v_min_u32_e32 v124, v79, v74
	v_min_u32_e32 v120, v77, v73
	v_min_u32_e32 v119, v76, v72
	v_min_u32_e32 v117, v75, v71
	v_min_u32_e32 v83, v87, v83
	v_min_u32_e32 v82, v86, v82
	v_min_u32_e32 v81, v85, v81
	v_min_u32_e32 v80, v84, v80
	v_max_u32_e32 v74, v79, v74
	v_max_u32_e32 v73, v77, v73
	v_max_u32_e32 v72, v76, v72
	v_max_u32_e32 v71, v75, v71
	v_max_u32_e32 v114, v116, v113
	v_max_u32_e32 v111, v112, v110
	v_min_u32_e32 v122, v124, v120
	v_min_u32_e32 v118, v119, v117
	v_max_u32_e32 v86, v83, v82
	v_max_u32_e32 v84, v81, v80
	v_min_u32_e32 v77, v74, v73
	v_min_u32_e32 v75, v72, v71
	v_min_u32_e32 v113, v116, v113
	v_min_u32_e32 v110, v112, v110
	v_max_u32_e32 v116, v124, v120
	v_max_u32_e32 v117, v119, v117
	v_min_u32_e32 v82, v83, v82
	v_min_u32_e32 v80, v81, v80
	v_max_u32_e32 v73, v74, v73
	v_max_u32_e32 v71, v72, v71
	v_max_u32_e32 v88, v92, v88
	v_max_u32_e32 v115, v114, v111
	v_min_u32_e32 v123, v122, v118
	v_max_u32_e32 v85, v86, v84
	v_min_u32_e32 v76, v77, v75
	v_max_u32_e32 v112, v113, v110
	v_min_u32_e32 v119, v116, v117
	v_max_u32_e32 v81, v82, v80
	v_min_u32_e32 v72, v73, v71
	v_min_u32_e32 v126, v0, v104
	v_min_u32_e32 v92, v89, v88
	v_max3_u32 v95, v125, v95, v101
	v_min_u32_e32 v125, v115, v123
	v_min_u32_e32 v79, v85, v76
	v_min_u32_e32 v120, v112, v119
	v_min_u32_e32 v74, v81, v72
	v_max3_u32 v109, v109, v140, v134
	v_max3_u32 v0, v0, v104, v92
	v_max3_u32 v88, v126, v89, v88
	v_min_u32_e32 v87, v125, v79
	v_min_u32_e32 v83, v120, v74
	v_min_u32_e32 v111, v114, v111
	v_max_u32_e32 v114, v122, v118
	v_min_u32_e32 v84, v86, v84
	v_max_u32_e32 v75, v77, v75
	v_min_u32_e32 v110, v113, v110
	v_max_u32_e32 v113, v116, v117
	v_min_u32_e32 v80, v82, v80
	v_max_u32_e32 v71, v73, v71
	v_max_u32_e32 v79, v125, v79
	v_max_u32_e32 v74, v120, v74
	v_max_u32_e32 v89, v93, v91
	v_max_u32_e32 v92, v109, v105
	v_max_u32_e32 v97, v102, v100
	v_min_u32_e32 v100, v102, v100
	v_max_u32_e32 v101, v98, v96
	v_min_u32_e32 v96, v98, v96
	v_max_u32_e32 v98, v99, v1
	v_min_u32_e32 v1, v99, v1
	v_max_u32_e32 v99, v103, v95
	v_max_u32_e32 v102, v94, v0
	v_min_u32_e32 v0, v94, v0
	v_max_u32_e32 v94, v90, v88
	v_min_u32_e32 v124, v87, v83
	v_min_u32_e32 v118, v111, v114
	v_min_u32_e32 v77, v84, v75
	v_min_u32_e32 v116, v110, v113
	v_min_u32_e32 v73, v80, v71
	v_max_u32_e32 v83, v87, v83
	v_min_u32_e32 v87, v79, v74
	v_max_u32_e32 v74, v79, v74
	v_max_u32_e32 v79, v115, v123
	v_max_u32_e32 v76, v85, v76
	v_max_u32_e32 v112, v112, v119
	v_max_u32_e32 v72, v81, v72
	v_max_u32_e32 v111, v111, v114
	v_max_u32_e32 v75, v84, v75
	v_max_u32_e32 v110, v110, v113
	v_max_u32_e32 v71, v80, v71
	v_min_u32_e32 v91, v93, v91
	v_min_u32_e32 v93, v109, v105
	v_min_u32_e32 v95, v103, v95
	v_min_u32_e32 v88, v90, v88
	v_max_u32_e32 v90, v89, v98
	v_min_u32_e32 v89, v89, v98
	v_max_u32_e32 v98, v92, v99
	v_min_u32_e32 v92, v92, v99
	v_max_u32_e32 v99, v97, v102
	v_min_u32_e32 v97, v97, v102
	v_max_u32_e32 v102, v101, v94
	v_min_u32_e32 v94, v101, v94
	v_min_u32_e32 v85, v79, v76
	v_min_u32_e32 v81, v112, v72
	v_min_u32_e32 v84, v111, v75
	v_min_u32_e32 v80, v110, v71
	v_max_u32_e32 v101, v91, v1
	v_min_u32_e32 v1, v91, v1
	v_max_u32_e32 v91, v93, v95
	v_min_u32_e32 v93, v93, v95
	v_max_u32_e32 v95, v100, v0
	v_min_u32_e32 v0, v100, v0
	v_max_u32_e32 v100, v96, v88
	v_min_u32_e32 v88, v96, v88
	v_max_u32_e32 v96, v90, v99
	v_min_u32_e32 v90, v90, v99
	v_max_u32_e32 v99, v98, v102
	v_min_u32_e32 v98, v98, v102
	v_max_u32_e32 v102, v89, v97
	v_min_u32_e32 v89, v89, v97
	v_max_u32_e32 v97, v92, v94
	v_min_u32_e32 v92, v92, v94
	v_min_u32_e32 v86, v118, v77
	v_min_u32_e32 v82, v116, v73
	v_max_u32_e32 v77, v118, v77
	v_max_u32_e32 v73, v116, v73
	v_min_u32_e32 v115, v85, v81
	v_min_u32_e32 v113, v84, v80
	v_max_u32_e32 v94, v101, v95
	v_min_u32_e32 v95, v101, v95
	v_max_u32_e32 v101, v91, v100
	v_min_u32_e32 v105, v89, v92
	v_min_u32_e32 v116, v77, v73
	v_max_u32_e32 v73, v77, v73
	v_min_u32_e32 v114, v115, v113
	v_min_u32_e32 v106, v94, v101
	v_min_u32_e32 v77, v74, v73
	v_max_u32_e32 v81, v85, v81
	v_max_u32_e32 v80, v84, v80
	v_max3_u32 v73, v105, v74, v73
	v_max3_u32 v74, v94, v101, v114
	v_cmp_gt_i32_e32 vcc, 0, v70
	v_not_b32_e32 v94, v70
	v_or_b32_e32 v70, 0x80000000, v70
	v_min_u32_e32 v91, v91, v100
	v_min_u32_e32 v84, v81, v80
	v_cndmask_b32_e32 v70, v70, v94, vcc
	v_cmp_gt_i32_e32 vcc, 0, v69
	v_not_b32_e32 v94, v69
	v_or_b32_e32 v69, 0x80000000, v69
	v_min_u32_e32 v107, v95, v91
	v_max3_u32 v84, v95, v91, v84
	v_cndmask_b32_e32 v69, v69, v94, vcc
	v_cmp_gt_i32_e32 vcc, 0, v68
	v_not_b32_e32 v95, v68
	v_or_b32_e32 v68, 0x80000000, v68
	v_min_u32_e32 v103, v90, v98
	v_min_u32_e32 v117, v86, v82
	v_max_u32_e32 v82, v86, v82
	v_min_u32_e32 v118, v87, v116
	v_cndmask_b32_e32 v68, v68, v95, vcc
	v_cmp_gt_i32_e32 vcc, 0, v67
; DEV unsigned fkey(float x) { const unsigned u = __float_as_uint(x); return (u & 0x80000000u) ? ~u : (u | 0x80000000u); }
; DEV void bitonic_merge16_desc(unsigned (&v)[16]) {
; #pragma unroll
;   for (int j = 8; j >= 1; j >>= 1)
; #pragma unroll
;     for (int i = 0; i < 16; ++i) { const int l = i ^ j; if (l > i) cswap(v[i], v[l]); }
; }
; DEV void bitonic_sort16_desc(unsigned (&v)[16]) {
; #pragma unroll
;   for (int k = 2; k <= 16; k <<= 1)
; #pragma unroll
;     for (int j = k >> 1; j >= 1; j >>= 1)
; #pragma unroll
;       for (int i = 0; i < 16; ++i) { const int l = i ^ j; if (l > i) { if ((i & k) == 0) cswap(v[i], v[l]); else cswap(v[l], v[i]); } }
; }
; DEV void merge_top16(unsigned (&R)[16], const unsigned (&G)[16]) {
; #pragma unroll
;   for (int i = 0; i < 16; ++i) R[i] = max(R[i], G[15 - i]);
;   bitonic_merge16_desc(R);
; }
; DEV void stage1(unsigned (&L)[16], const float* sp) {
;     ...
;     for (int e = 0; e < 16; ++e) g[e] = (fkey(sv[i + e]) & ~127u) | (unsigned)(127 - (i + e));
	v_not_b32_e32 v95, v67
	v_or_b32_e32 v67, 0x80000000, v67
	v_min_u32_e32 v104, v102, v97
	v_min_u32_e32 v86, v83, v82
	v_max3_u32 v82, v103, v83, v82
	v_max3_u32 v83, v102, v97, v118
	v_cndmask_b32_e32 v67, v67, v95, vcc
	v_cmp_gt_i32_e32 vcc, 0, v66
	v_not_b32_e32 v97, v66
	v_or_b32_e32 v66, 0x80000000, v66
	v_cndmask_b32_e32 v66, v66, v97, vcc
	v_cmp_gt_i32_e32 vcc, 0, v63
	v_not_b32_e32 v97, v63
	v_or_b32_e32 v63, 0x80000000, v63
	v_max3_u32 v86, v90, v98, v86
	v_cndmask_b32_e32 v63, v63, v97, vcc
	v_cmp_gt_i32_e32 vcc, 0, v62
	v_not_b32_e32 v98, v62
	v_or_b32_e32 v62, 0x80000000, v62
	v_cndmask_b32_e32 v62, v62, v98, vcc
	v_cmp_gt_i32_e32 vcc, 0, v61
	v_not_b32_e32 v98, v61
	v_or_b32_e32 v61, 0x80000000, v61
	v_cndmask_b32_e32 v61, v61, v98, vcc
	v_cmp_gt_i32_e32 vcc, 0, v60
	v_not_b32_e32 v101, v60
	v_or_b32_e32 v60, 0x80000000, v60
	v_cndmask_b32_e32 v60, v60, v101, vcc
	v_cmp_gt_i32_e32 vcc, 0, v59
	v_not_b32_e32 v101, v59
	v_or_b32_e32 v59, 0x80000000, v59
	v_cndmask_b32_e32 v59, v59, v101, vcc
	v_cmp_gt_i32_e32 vcc, 0, v58
	v_not_b32_e32 v102, v58
	v_or_b32_e32 v58, 0x80000000, v58
	v_cndmask_b32_e32 v58, v58, v102, vcc
	v_cmp_gt_i32_e32 vcc, 0, v57
	v_not_b32_e32 v102, v57
	v_or_b32_e32 v57, 0x80000000, v57
	v_max3_u32 v87, v104, v87, v116
	v_cndmask_b32_e32 v57, v57, v102, vcc
	v_cmp_gt_i32_e32 vcc, 0, v56
	v_not_b32_e32 v104, v56
	v_or_b32_e32 v56, 0x80000000, v56
	v_cndmask_b32_e32 v56, v56, v104, vcc
	v_cmp_gt_i32_e32 vcc, 0, v55
	v_not_b32_e32 v104, v55
	v_or_b32_e32 v55, 0x80000000, v55
	v_cndmask_b32_e32 v55, v55, v104, vcc
	v_cmp_gt_i32_e32 vcc, 0, v54
	v_not_b32_e32 v105, v54
	v_or_b32_e32 v54, 0x80000000, v54
	v_cndmask_b32_e32 v54, v54, v105, vcc
	v_cmp_gt_i32_e32 vcc, 0, v53
	v_not_b32_e32 v105, v53
	v_or_b32_e32 v53, 0x80000000, v53
	v_cndmask_b32_e32 v53, v53, v105, vcc
	v_and_or_b32 v70, v70, s55, 47
	v_and_or_b32 v69, v69, s55, 46
	v_and_or_b32 v68, v68, s55, 44
	v_and_or_b32 v67, v67, s55, 45
	v_and_or_b32 v66, v66, s55, 40
	v_and_or_b32 v63, v63, s55, 41
	v_and_or_b32 v62, v62, s55, 43
	v_and_or_b32 v61, v61, s55, 42
	v_and_or_b32 v60, v60, s55, 32
	v_and_or_b32 v59, v59, s55, 33
	v_and_or_b32 v58, v58, s55, 35
	v_and_or_b32 v57, v57, s55, 34
	v_and_or_b32 v56, v56, s55, 39
	v_and_or_b32 v55, v55, s55, 38
	v_and_or_b32 v54, v54, s55, 36
	v_and_or_b32 v53, v53, s55, 37
	v_min_u32_e32 v122, v124, v117
	v_max_u32_e32 v76, v79, v76
	v_max_u32_e32 v72, v112, v72
	v_max_u32_e32 v75, v111, v75
	v_max_u32_e32 v71, v110, v71
	v_max_u32_e32 v94, v70, v69
	v_min_u32_e32 v95, v68, v67
	v_min_u32_e32 v69, v70, v69
	v_max_u32_e32 v67, v68, v67
	v_max_u32_e32 v97, v66, v63
	v_min_u32_e32 v98, v62, v61
	v_min_u32_e32 v63, v66, v63
	v_max_u32_e32 v61, v62, v61
	v_max_u32_e32 v101, v60, v59
	v_min_u32_e32 v102, v58, v57
	v_min_u32_e32 v59, v60, v59
	v_max_u32_e32 v57, v58, v57
	v_max_u32_e32 v104, v56, v55
	v_min_u32_e32 v105, v54, v53
	v_min_u32_e32 v55, v56, v55
	v_max_u32_e32 v53, v54, v53
	v_max_u32_e32 v100, v1, v0
	v_min_u32_e32 v0, v1, v0
	v_max_u32_e32 v1, v93, v88
	v_min_u32_e32 v88, v93, v88
	v_min_u32_e32 v93, v96, v99
	v_min_u32_e32 v79, v76, v72
	v_min_u32_e32 v85, v75, v71
	v_max_u32_e32 v72, v76, v72
	v_max3_u32 v76, v96, v99, v122
	v_max3_u32 v77, v89, v92, v77
	v_max3_u32 v89, v106, v115, v113
	v_max_u32_e32 v96, v94, v95
	v_max_u32_e32 v68, v69, v67
	v_min_u32_e32 v99, v97, v98
	v_min_u32_e32 v62, v63, v61
	v_min_u32_e32 v94, v94, v95
	v_min_u32_e32 v67, v69, v67
	v_max_u32_e32 v95, v97, v98
	v_max_u32_e32 v61, v63, v61
	v_max_u32_e32 v103, v101, v102
	v_max_u32_e32 v58, v59, v57
	v_min_u32_e32 v106, v104, v105
	v_min_u32_e32 v54, v55, v53
	v_min_u32_e32 v101, v101, v102
	v_min_u32_e32 v57, v59, v57
	v_max_u32_e32 v102, v104, v105
	v_max_u32_e32 v53, v55, v53
	v_min_u32_e32 v110, v79, v85
	v_max_u32_e32 v70, v96, v68
	v_min_u32_e32 v66, v99, v62
	v_max_u32_e32 v69, v94, v67
	v_min_u32_e32 v63, v95, v61
	v_min_u32_e32 v68, v96, v68
	v_max_u32_e32 v62, v99, v62
	v_min_u32_e32 v67, v94, v67
	v_max_u32_e32 v61, v95, v61
	v_max_u32_e32 v60, v103, v58
	v_min_u32_e32 v56, v106, v54
	v_max_u32_e32 v59, v101, v57
	v_min_u32_e32 v55, v102, v53
	v_min_u32_e32 v58, v103, v58
	v_max_u32_e32 v54, v106, v54
	v_min_u32_e32 v57, v101, v57
	v_max_u32_e32 v53, v102, v53
	v_min_u32_e32 v108, v100, v1
	v_max3_u32 v80, v107, v81, v80
	v_max3_u32 v1, v100, v1, v110
	v_max_u32_e32 v100, v70, v66
	v_max_u32_e32 v97, v69, v63
	v_max_u32_e32 v96, v68, v62
	v_max_u32_e32 v94, v67, v61
	v_min_u32_e32 v107, v60, v56
	v_min_u32_e32 v104, v59, v55
	v_min_u32_e32 v103, v58, v54
	v_min_u32_e32 v101, v57, v53
	v_min_u32_e32 v66, v70, v66
	v_min_u32_e32 v63, v69, v63
	v_min_u32_e32 v62, v68, v62
	v_min_u32_e32 v61, v67, v61
	v_max_u32_e32 v56, v60, v56
	v_max_u32_e32 v55, v59, v55
	v_max_u32_e32 v54, v58, v54
	v_max_u32_e32 v53, v57, v53
	v_max_u32_e32 v98, v100, v97
	v_max_u32_e32 v95, v96, v94
	v_min_u32_e32 v105, v107, v104
	v_min_u32_e32 v102, v103, v101
	v_max_u32_e32 v69, v66, v63
	v_max_u32_e32 v67, v62, v61
	v_min_u32_e32 v59, v56, v55
	v_min_u32_e32 v57, v54, v53
	v_min_u32_e32 v97, v100, v97
	v_min_u32_e32 v94, v96, v94
	v_max_u32_e32 v100, v107, v104
	v_max_u32_e32 v101, v103, v101
	v_min_u32_e32 v63, v66, v63
	v_min_u32_e32 v61, v62, v61
	v_max_u32_e32 v55, v56, v55
	v_max_u32_e32 v53, v54, v53
	v_max_u32_e32 v71, v75, v71
	v_max_u32_e32 v99, v98, v95
	v_min_u32_e32 v106, v105, v102
	v_max_u32_e32 v68, v69, v67
	v_min_u32_e32 v58, v59, v57
	v_max_u32_e32 v96, v97, v94
	v_min_u32_e32 v103, v100, v101
	v_max_u32_e32 v62, v63, v61
	v_min_u32_e32 v54, v55, v53
	v_min_u32_e32 v109, v0, v88
	v_min_u32_e32 v75, v72, v71
; DEV unsigned fkey(float x) { const unsigned u = __float_as_uint(x); return (u & 0x80000000u) ? ~u : (u | 0x80000000u); }
; DEV void merge_top16(unsigned (&R)[16], const unsigned (&G)[16]) {
; #pragma unroll
;   for (int i = 0; i < 16; ++i) R[i] = max(R[i], G[15 - i]);
;   bitonic_merge16_desc(R);
; }
; DEV void stage1(unsigned (&L)[16], const float* sp) {
;     ...
;     for (int e = 0; e < 16; ++e) g[e] = (fkey(sv[i + e]) & ~127u) | (unsigned)(127 - (i + e));
	v_max3_u32 v79, v108, v79, v85
	v_min_u32_e32 v108, v99, v106
	v_min_u32_e32 v60, v68, v58
	v_min_u32_e32 v104, v96, v103
	v_min_u32_e32 v56, v62, v54
	v_max3_u32 v93, v93, v124, v117
	v_max3_u32 v0, v0, v88, v75
	v_max3_u32 v71, v109, v72, v71
	v_min_u32_e32 v70, v108, v60
	v_min_u32_e32 v66, v104, v56
	v_min_u32_e32 v95, v98, v95
	v_max_u32_e32 v98, v105, v102
	v_min_u32_e32 v67, v69, v67
	v_max_u32_e32 v57, v59, v57
	v_min_u32_e32 v94, v97, v94
	v_max_u32_e32 v97, v100, v101
	v_min_u32_e32 v61, v63, v61
	v_max_u32_e32 v53, v55, v53
	v_max_u32_e32 v60, v108, v60
	v_max_u32_e32 v56, v104, v56
	v_max_u32_e32 v72, v76, v74
	v_max_u32_e32 v75, v93, v89
	v_max_u32_e32 v81, v86, v84
	v_min_u32_e32 v84, v86, v84
	v_max_u32_e32 v85, v82, v80
	v_min_u32_e32 v80, v82, v80
	v_max_u32_e32 v82, v83, v1
	v_min_u32_e32 v1, v83, v1
	v_max_u32_e32 v83, v87, v79
	v_max_u32_e32 v86, v77, v0
	v_min_u32_e32 v0, v77, v0
	v_max_u32_e32 v77, v73, v71
	v_min_u32_e32 v107, v70, v66
	v_min_u32_e32 v102, v95, v98
	v_min_u32_e32 v59, v67, v57
	v_min_u32_e32 v100, v94, v97
	v_min_u32_e32 v55, v61, v53
	v_max_u32_e32 v66, v70, v66
	v_min_u32_e32 v70, v60, v56
	v_max_u32_e32 v56, v60, v56
	v_max_u32_e32 v60, v99, v106
	v_max_u32_e32 v58, v68, v58
	v_max_u32_e32 v96, v96, v103
	v_max_u32_e32 v54, v62, v54
	v_max_u32_e32 v95, v95, v98
	v_max_u32_e32 v57, v67, v57
	v_max_u32_e32 v94, v94, v97
	v_max_u32_e32 v53, v61, v53
	v_min_u32_e32 v74, v76, v74
	v_min_u32_e32 v76, v93, v89
	v_min_u32_e32 v79, v87, v79
	v_min_u32_e32 v71, v73, v71
	v_max_u32_e32 v73, v72, v82
	v_min_u32_e32 v72, v72, v82
	v_max_u32_e32 v82, v75, v83
	v_min_u32_e32 v75, v75, v83
	v_max_u32_e32 v83, v81, v86
	v_min_u32_e32 v81, v81, v86
	v_max_u32_e32 v86, v85, v77
	v_min_u32_e32 v77, v85, v77
	v_min_u32_e32 v68, v60, v58
	v_min_u32_e32 v62, v96, v54
	v_min_u32_e32 v67, v95, v57
	v_min_u32_e32 v61, v94, v53
	v_max_u32_e32 v85, v74, v1
	v_min_u32_e32 v1, v74, v1
	v_max_u32_e32 v74, v76, v79
	v_min_u32_e32 v76, v76, v79
	v_max_u32_e32 v79, v84, v0
	v_min_u32_e32 v0, v84, v0
	v_max_u32_e32 v84, v80, v71
	v_min_u32_e32 v71, v80, v71
	v_max_u32_e32 v80, v73, v83
	v_min_u32_e32 v73, v73, v83
	v_max_u32_e32 v83, v82, v86
	v_min_u32_e32 v82, v82, v86
	v_max_u32_e32 v86, v72, v81
	v_min_u32_e32 v72, v72, v81
	v_max_u32_e32 v81, v75, v77
	v_min_u32_e32 v75, v75, v77
	v_min_u32_e32 v69, v102, v59
	v_min_u32_e32 v63, v100, v55
	v_max_u32_e32 v59, v102, v59
	v_max_u32_e32 v55, v100, v55
	v_min_u32_e32 v99, v68, v62
	v_min_u32_e32 v97, v67, v61
	v_max_u32_e32 v77, v85, v79
	v_min_u32_e32 v79, v85, v79
	v_max_u32_e32 v85, v74, v84
	v_min_u32_e32 v89, v72, v75
	v_min_u32_e32 v100, v59, v55
	v_max_u32_e32 v55, v59, v55
	v_min_u32_e32 v98, v99, v97
	v_min_u32_e32 v90, v77, v85
	v_min_u32_e32 v59, v56, v55
	v_max_u32_e32 v62, v68, v62
	v_max_u32_e32 v61, v67, v61
	v_max3_u32 v55, v89, v56, v55
	v_max3_u32 v56, v77, v85, v98
	v_cmp_gt_i32_e32 vcc, 0, v52
	v_not_b32_e32 v77, v52
	v_or_b32_e32 v52, 0x80000000, v52
	v_min_u32_e32 v74, v74, v84
	v_min_u32_e32 v67, v62, v61
	v_cndmask_b32_e32 v52, v52, v77, vcc
	v_cmp_gt_i32_e32 vcc, 0, v51
	v_not_b32_e32 v77, v51
	v_or_b32_e32 v51, 0x80000000, v51
	v_min_u32_e32 v91, v79, v74
	v_max3_u32 v67, v79, v74, v67
	v_cndmask_b32_e32 v51, v51, v77, vcc
	v_cmp_gt_i32_e32 vcc, 0, v50
	v_not_b32_e32 v79, v50
	v_or_b32_e32 v50, 0x80000000, v50
	v_min_u32_e32 v87, v73, v82
	v_min_u32_e32 v101, v69, v63
	v_max_u32_e32 v63, v69, v63
	v_min_u32_e32 v102, v70, v100
	v_cndmask_b32_e32 v50, v50, v79, vcc
	v_cmp_gt_i32_e32 vcc, 0, v49
	v_not_b32_e32 v79, v49
	v_or_b32_e32 v49, 0x80000000, v49
	v_min_u32_e32 v88, v86, v81
	v_min_u32_e32 v69, v66, v63
	v_max3_u32 v63, v87, v66, v63
	v_max3_u32 v66, v86, v81, v102
	v_cndmask_b32_e32 v49, v49, v79, vcc
	v_cmp_gt_i32_e32 vcc, 0, v48
	v_not_b32_e32 v81, v48
	v_or_b32_e32 v48, 0x80000000, v48
	v_cndmask_b32_e32 v48, v48, v81, vcc
	v_cmp_gt_i32_e32 vcc, 0, v47
	v_not_b32_e32 v81, v47
	v_or_b32_e32 v47, 0x80000000, v47
	v_max3_u32 v69, v73, v82, v69
	v_cndmask_b32_e32 v47, v47, v81, vcc
	v_cmp_gt_i32_e32 vcc, 0, v46
	v_not_b32_e32 v82, v46
	v_or_b32_e32 v46, 0x80000000, v46
	v_cndmask_b32_e32 v46, v46, v82, vcc
	v_cmp_gt_i32_e32 vcc, 0, v45
	v_not_b32_e32 v82, v45
	v_or_b32_e32 v45, 0x80000000, v45
	v_cndmask_b32_e32 v45, v45, v82, vcc
	v_cmp_gt_i32_e32 vcc, 0, v44
	v_not_b32_e32 v85, v44
	v_or_b32_e32 v44, 0x80000000, v44
	v_cndmask_b32_e32 v44, v44, v85, vcc
	v_cmp_gt_i32_e32 vcc, 0, v43
	v_not_b32_e32 v85, v43
	v_or_b32_e32 v43, 0x80000000, v43
	v_cndmask_b32_e32 v43, v43, v85, vcc
	v_cmp_gt_i32_e32 vcc, 0, v42
	v_not_b32_e32 v86, v42
	v_or_b32_e32 v42, 0x80000000, v42
	v_cndmask_b32_e32 v42, v42, v86, vcc
	v_cmp_gt_i32_e32 vcc, 0, v41
	v_not_b32_e32 v86, v41
	v_or_b32_e32 v41, 0x80000000, v41
	v_max3_u32 v70, v88, v70, v100
	v_cndmask_b32_e32 v41, v41, v86, vcc
	v_cmp_gt_i32_e32 vcc, 0, v40
	v_not_b32_e32 v88, v40
	v_or_b32_e32 v40, 0x80000000, v40
	v_cndmask_b32_e32 v40, v40, v88, vcc
	v_cmp_gt_i32_e32 vcc, 0, v39
	v_not_b32_e32 v88, v39
	v_or_b32_e32 v39, 0x80000000, v39
	v_cndmask_b32_e32 v39, v39, v88, vcc
	v_cmp_gt_i32_e32 vcc, 0, v38
	v_not_b32_e32 v89, v38
	v_or_b32_e32 v38, 0x80000000, v38
	v_cndmask_b32_e32 v38, v38, v89, vcc
	v_cmp_gt_i32_e32 vcc, 0, v37
	v_not_b32_e32 v89, v37
	v_or_b32_e32 v37, 0x80000000, v37
	v_cndmask_b32_e32 v37, v37, v89, vcc
	v_and_or_b32 v52, v52, s55, 31
	v_and_or_b32 v51, v51, s55, 30
	v_and_or_b32 v50, v50, s55, 28
	v_and_or_b32 v49, v49, s55, 29
	v_and_or_b32 v48, v48, s55, 24
	v_and_or_b32 v47, v47, s55, 25
	v_and_or_b32 v46, v46, s55, 27
	v_and_or_b32 v45, v45, s55, 26
	v_and_or_b32 v44, v44, s55, 16
; DEV unsigned fkey(float x) { const unsigned u = __float_as_uint(x); return (u & 0x80000000u) ? ~u : (u | 0x80000000u); }
; DEV void bitonic_sort16_desc(unsigned (&v)[16]) {
; #pragma unroll
;   for (int k = 2; k <= 16; k <<= 1)
; #pragma unroll
;     for (int j = k >> 1; j >= 1; j >>= 1)
; #pragma unroll
;       for (int i = 0; i < 16; ++i) { const int l = i ^ j; if (l > i) { if ((i & k) == 0) cswap(v[i], v[l]); else cswap(v[l], v[i]); } }
; }
; DEV void merge_top16(unsigned (&R)[16], const unsigned (&G)[16]) {
; #pragma unroll
;   for (int i = 0; i < 16; ++i) R[i] = max(R[i], G[15 - i]);
;   bitonic_merge16_desc(R);
; }
; DEV void stage1(unsigned (&L)[16], const float* sp) {
;     ...
;     for (int e = 0; e < 16; ++e) g[e] = (fkey(sv[i + e]) & ~127u) | (unsigned)(127 - (i + e));
	v_and_or_b32 v43, v43, s55, 17
	v_and_or_b32 v42, v42, s55, 19
	v_and_or_b32 v41, v41, s55, 18
	v_and_or_b32 v40, v40, s55, 23
	v_and_or_b32 v39, v39, s55, 22
	v_and_or_b32 v38, v38, s55, 20
	v_and_or_b32 v37, v37, s55, 21
	v_min_u32_e32 v105, v107, v101
	v_max_u32_e32 v58, v60, v58
	v_max_u32_e32 v54, v96, v54
	v_max_u32_e32 v57, v95, v57
	v_max_u32_e32 v53, v94, v53
	v_max_u32_e32 v77, v52, v51
	v_min_u32_e32 v79, v50, v49
	v_min_u32_e32 v51, v52, v51
	v_max_u32_e32 v49, v50, v49
	v_max_u32_e32 v81, v48, v47
	v_min_u32_e32 v82, v46, v45
	v_min_u32_e32 v47, v48, v47
	v_max_u32_e32 v45, v46, v45
	v_max_u32_e32 v85, v44, v43
	v_min_u32_e32 v86, v42, v41
	v_min_u32_e32 v43, v44, v43
	v_max_u32_e32 v41, v42, v41
	v_max_u32_e32 v88, v40, v39
	v_min_u32_e32 v89, v38, v37
	v_min_u32_e32 v39, v40, v39
	v_max_u32_e32 v37, v38, v37
	v_max_u32_e32 v84, v1, v0
	v_min_u32_e32 v0, v1, v0
	v_max_u32_e32 v1, v76, v71
	v_min_u32_e32 v71, v76, v71
	v_min_u32_e32 v76, v80, v83
	v_min_u32_e32 v60, v58, v54
	v_min_u32_e32 v68, v57, v53
	v_max_u32_e32 v54, v58, v54
	v_max3_u32 v58, v80, v83, v105
	v_max3_u32 v59, v72, v75, v59
	v_max3_u32 v72, v90, v99, v97
	v_max_u32_e32 v80, v77, v79
	v_max_u32_e32 v50, v51, v49
	v_min_u32_e32 v83, v81, v82
	v_min_u32_e32 v46, v47, v45
	v_min_u32_e32 v77, v77, v79
	v_min_u32_e32 v49, v51, v49
	v_max_u32_e32 v79, v81, v82
	v_max_u32_e32 v45, v47, v45
	v_max_u32_e32 v87, v85, v86
	v_max_u32_e32 v42, v43, v41
	v_min_u32_e32 v90, v88, v89
	v_min_u32_e32 v38, v39, v37
	v_min_u32_e32 v85, v85, v86
	v_min_u32_e32 v41, v43, v41
	v_max_u32_e32 v86, v88, v89
	v_max_u32_e32 v37, v39, v37
	v_min_u32_e32 v94, v60, v68
	v_max_u32_e32 v52, v80, v50
	v_min_u32_e32 v48, v83, v46
	v_max_u32_e32 v51, v77, v49
	v_min_u32_e32 v47, v79, v45
	v_min_u32_e32 v50, v80, v50
	v_max_u32_e32 v46, v83, v46
	v_min_u32_e32 v49, v77, v49
	v_max_u32_e32 v45, v79, v45
	v_max_u32_e32 v44, v87, v42
	v_min_u32_e32 v40, v90, v38
	v_max_u32_e32 v43, v85, v41
	v_min_u32_e32 v39, v86, v37
	v_min_u32_e32 v42, v87, v42
	v_max_u32_e32 v38, v90, v38
	v_min_u32_e32 v41, v85, v41
	v_max_u32_e32 v37, v86, v37
	v_min_u32_e32 v92, v84, v1
	v_max3_u32 v61, v91, v62, v61
	v_max3_u32 v1, v84, v1, v94
	v_max_u32_e32 v84, v52, v48
	v_max_u32_e32 v81, v51, v47
	v_max_u32_e32 v80, v50, v46
	v_max_u32_e32 v77, v49, v45
	v_min_u32_e32 v91, v44, v40
	v_min_u32_e32 v88, v43, v39
	v_min_u32_e32 v87, v42, v38
	v_min_u32_e32 v85, v41, v37
	v_min_u32_e32 v48, v52, v48
	v_min_u32_e32 v47, v51, v47
	v_min_u32_e32 v46, v50, v46
	v_min_u32_e32 v45, v49, v45
	v_max_u32_e32 v40, v44, v40
	v_max_u32_e32 v39, v43, v39
	v_max_u32_e32 v38, v42, v38
	v_max_u32_e32 v37, v41, v37
	v_max_u32_e32 v82, v84, v81
	v_max_u32_e32 v79, v80, v77
	v_min_u32_e32 v89, v91, v88
	v_min_u32_e32 v86, v87, v85
	v_max_u32_e32 v51, v48, v47
	v_max_u32_e32 v49, v46, v45
	v_min_u32_e32 v43, v40, v39
	v_min_u32_e32 v41, v38, v37
	v_min_u32_e32 v81, v84, v81
	v_min_u32_e32 v77, v80, v77
	v_max_u32_e32 v84, v91, v88
	v_max_u32_e32 v85, v87, v85
	v_min_u32_e32 v47, v48, v47
	v_min_u32_e32 v45, v46, v45
	v_max_u32_e32 v39, v40, v39
	v_max_u32_e32 v37, v38, v37
	v_max_u32_e32 v53, v57, v53
	v_max_u32_e32 v83, v82, v79
	v_min_u32_e32 v90, v89, v86
	v_max_u32_e32 v50, v51, v49
	v_min_u32_e32 v42, v43, v41
	v_max_u32_e32 v80, v81, v77
	v_min_u32_e32 v87, v84, v85
	v_max_u32_e32 v46, v47, v45
	v_min_u32_e32 v38, v39, v37
	v_min_u32_e32 v93, v0, v71
	v_min_u32_e32 v57, v54, v53
	v_max3_u32 v60, v92, v60, v68
	v_min_u32_e32 v92, v83, v90
	v_min_u32_e32 v44, v50, v42
	v_min_u32_e32 v88, v80, v87
	v_min_u32_e32 v40, v46, v38
	v_max3_u32 v76, v76, v107, v101
	v_max3_u32 v0, v0, v71, v57
	v_max3_u32 v53, v93, v54, v53
	v_min_u32_e32 v52, v92, v44
	v_min_u32_e32 v48, v88, v40
	v_min_u32_e32 v79, v82, v79
	v_max_u32_e32 v82, v89, v86
	v_min_u32_e32 v49, v51, v49
	v_max_u32_e32 v41, v43, v41
	v_min_u32_e32 v77, v81, v77
	v_max_u32_e32 v81, v84, v85
	v_min_u32_e32 v45, v47, v45
	v_max_u32_e32 v37, v39, v37
	v_max_u32_e32 v44, v92, v44
	v_max_u32_e32 v40, v88, v40
	v_max_u32_e32 v54, v58, v56
	v_max_u32_e32 v57, v76, v72
	v_max_u32_e32 v62, v69, v67
	v_min_u32_e32 v67, v69, v67
	v_max_u32_e32 v68, v63, v61
	v_min_u32_e32 v61, v63, v61
	v_max_u32_e32 v63, v66, v1
	v_min_u32_e32 v1, v66, v1
	v_max_u32_e32 v66, v70, v60
	v_max_u32_e32 v69, v59, v0
	v_min_u32_e32 v0, v59, v0
	v_max_u32_e32 v59, v55, v53
	v_min_u32_e32 v91, v52, v48
	v_min_u32_e32 v86, v79, v82
	v_min_u32_e32 v43, v49, v41
	v_min_u32_e32 v84, v77, v81
	v_min_u32_e32 v39, v45, v37
	v_max_u32_e32 v48, v52, v48
	v_min_u32_e32 v52, v44, v40
	v_max_u32_e32 v40, v44, v40
	v_max_u32_e32 v44, v83, v90
	v_max_u32_e32 v42, v50, v42
	v_max_u32_e32 v80, v80, v87
	v_max_u32_e32 v38, v46, v38
	v_max_u32_e32 v79, v79, v82
	v_max_u32_e32 v41, v49, v41
	v_max_u32_e32 v77, v77, v81
	v_max_u32_e32 v37, v45, v37
	v_min_u32_e32 v56, v58, v56
	v_min_u32_e32 v58, v76, v72
	v_min_u32_e32 v60, v70, v60
	v_min_u32_e32 v53, v55, v53
	v_max_u32_e32 v55, v54, v63
	v_min_u32_e32 v54, v54, v63
	v_max_u32_e32 v63, v57, v66
	v_min_u32_e32 v57, v57, v66
	v_max_u32_e32 v66, v62, v69
	v_min_u32_e32 v62, v62, v69
	v_max_u32_e32 v69, v68, v59
	v_min_u32_e32 v59, v68, v59
	v_min_u32_e32 v50, v44, v42
	v_min_u32_e32 v46, v80, v38
	v_min_u32_e32 v49, v79, v41
	v_min_u32_e32 v45, v77, v37
	v_max_u32_e32 v68, v56, v1
	v_min_u32_e32 v1, v56, v1
	v_max_u32_e32 v56, v58, v60
	v_min_u32_e32 v58, v58, v60
	v_max_u32_e32 v60, v67, v0
	v_min_u32_e32 v0, v67, v0
	v_max_u32_e32 v67, v61, v53
	v_min_u32_e32 v53, v61, v53
	v_max_u32_e32 v61, v55, v66
	v_min_u32_e32 v55, v55, v66
	v_max_u32_e32 v66, v63, v69
	v_min_u32_e32 v63, v63, v69
; DEV unsigned fkey(float x) { const unsigned u = __float_as_uint(x); return (u & 0x80000000u) ? ~u : (u | 0x80000000u); }
; DEV void bitonic_merge16_desc(unsigned (&v)[16]) {
; #pragma unroll
;   for (int j = 8; j >= 1; j >>= 1)
; #pragma unroll
;     for (int i = 0; i < 16; ++i) { const int l = i ^ j; if (l > i) cswap(v[i], v[l]); }
; }
; DEV void bitonic_sort16_desc(unsigned (&v)[16]) {
; #pragma unroll
;   for (int k = 2; k <= 16; k <<= 1)
; #pragma unroll
;     for (int j = k >> 1; j >= 1; j >>= 1)
; #pragma unroll
;       for (int i = 0; i < 16; ++i) { const int l = i ^ j; if (l > i) { if ((i & k) == 0) cswap(v[i], v[l]); else cswap(v[l], v[i]); } }
; }
; DEV void merge_top16(unsigned (&R)[16], const unsigned (&G)[16]) {
; #pragma unroll
;   for (int i = 0; i < 16; ++i) R[i] = max(R[i], G[15 - i]);
;   bitonic_merge16_desc(R);
; }
; DEV void stage1(unsigned (&L)[16], const float* sp) {
;     ...
;     for (int e = 0; e < 16; ++e) g[e] = (fkey(sv[i + e]) & ~127u) | (unsigned)(127 - (i + e));
	v_max_u32_e32 v69, v54, v62
	v_min_u32_e32 v54, v54, v62
	v_max_u32_e32 v62, v57, v59
	v_min_u32_e32 v57, v57, v59
	v_min_u32_e32 v51, v86, v43
	v_min_u32_e32 v47, v84, v39
	v_max_u32_e32 v43, v86, v43
	v_max_u32_e32 v39, v84, v39
	v_min_u32_e32 v83, v50, v46
	v_min_u32_e32 v81, v49, v45
	v_max_u32_e32 v59, v68, v60
	v_min_u32_e32 v60, v68, v60
	v_max_u32_e32 v68, v56, v67
	v_min_u32_e32 v72, v54, v57
	v_min_u32_e32 v84, v43, v39
	v_max_u32_e32 v39, v43, v39
	v_min_u32_e32 v82, v83, v81
	v_min_u32_e32 v73, v59, v68
	v_min_u32_e32 v43, v40, v39
	v_max_u32_e32 v46, v50, v46
	v_max_u32_e32 v45, v49, v45
	v_max3_u32 v39, v72, v40, v39
	v_max3_u32 v40, v59, v68, v82
	v_cmp_gt_i32_e32 vcc, 0, v36
	v_not_b32_e32 v59, v36
	v_or_b32_e32 v36, 0x80000000, v36
	v_min_u32_e32 v56, v56, v67
	v_min_u32_e32 v49, v46, v45
	v_cndmask_b32_e32 v36, v36, v59, vcc
	v_cmp_gt_i32_e32 vcc, 0, v35
	v_not_b32_e32 v59, v35
	v_or_b32_e32 v35, 0x80000000, v35
	v_min_u32_e32 v74, v60, v56
	v_max3_u32 v49, v60, v56, v49
	v_cndmask_b32_e32 v35, v35, v59, vcc
	v_cmp_gt_i32_e32 vcc, 0, v34
	v_not_b32_e32 v60, v34
	v_or_b32_e32 v34, 0x80000000, v34
	v_min_u32_e32 v70, v55, v63
	v_min_u32_e32 v85, v51, v47
	v_max_u32_e32 v47, v51, v47
	v_min_u32_e32 v86, v52, v84
	v_cndmask_b32_e32 v34, v34, v60, vcc
	v_cmp_gt_i32_e32 vcc, 0, v33
	v_not_b32_e32 v60, v33
	v_or_b32_e32 v33, 0x80000000, v33
	v_min_u32_e32 v71, v69, v62
	v_min_u32_e32 v51, v48, v47
	v_max3_u32 v47, v70, v48, v47
	v_max3_u32 v48, v69, v62, v86
	v_cndmask_b32_e32 v33, v33, v60, vcc
	v_cmp_gt_i32_e32 vcc, 0, v32
	v_not_b32_e32 v62, v32
	v_or_b32_e32 v32, 0x80000000, v32
	v_cndmask_b32_e32 v32, v32, v62, vcc
	v_cmp_gt_i32_e32 vcc, 0, v31
	v_not_b32_e32 v62, v31
	v_or_b32_e32 v31, 0x80000000, v31
	v_max3_u32 v51, v55, v63, v51
	v_cndmask_b32_e32 v31, v31, v62, vcc
	v_cmp_gt_i32_e32 vcc, 0, v30
	v_not_b32_e32 v63, v30
	v_or_b32_e32 v30, 0x80000000, v30
	v_cndmask_b32_e32 v30, v30, v63, vcc
	v_cmp_gt_i32_e32 vcc, 0, v29
	v_not_b32_e32 v63, v29
	v_or_b32_e32 v29, 0x80000000, v29
	v_cndmask_b32_e32 v29, v29, v63, vcc
	v_cmp_gt_i32_e32 vcc, 0, v28
	v_not_b32_e32 v68, v28
	v_or_b32_e32 v28, 0x80000000, v28
	v_cndmask_b32_e32 v28, v28, v68, vcc
	v_cmp_gt_i32_e32 vcc, 0, v27
	v_not_b32_e32 v68, v27
	v_or_b32_e32 v27, 0x80000000, v27
	v_cndmask_b32_e32 v27, v27, v68, vcc
	v_cmp_gt_i32_e32 vcc, 0, v26
	v_not_b32_e32 v69, v26
	v_or_b32_e32 v26, 0x80000000, v26
	v_cndmask_b32_e32 v26, v26, v69, vcc
	v_cmp_gt_i32_e32 vcc, 0, v22
	v_not_b32_e32 v69, v22
	v_or_b32_e32 v22, 0x80000000, v22
	v_max3_u32 v52, v71, v52, v84
	v_cndmask_b32_e32 v22, v22, v69, vcc
	v_cmp_gt_i32_e32 vcc, 0, v18
	v_not_b32_e32 v71, v18
	v_or_b32_e32 v18, 0x80000000, v18
	v_cndmask_b32_e32 v18, v18, v71, vcc
	v_cmp_gt_i32_e32 vcc, 0, v16
	v_not_b32_e32 v71, v16
	v_or_b32_e32 v16, 0x80000000, v16
	v_cndmask_b32_e32 v16, v16, v71, vcc
	v_cmp_gt_i32_e32 vcc, 0, v12
	v_not_b32_e32 v72, v12
	v_or_b32_e32 v12, 0x80000000, v12
	v_cndmask_b32_e32 v12, v12, v72, vcc
	v_cmp_gt_i32_e32 vcc, 0, v2
	v_not_b32_e32 v72, v2
	v_or_b32_e32 v2, 0x80000000, v2
	v_cndmask_b32_e32 v2, v2, v72, vcc
	v_and_or_b32 v36, v36, s55, 15
	v_and_or_b32 v35, v35, s55, 14
	v_and_or_b32 v34, v34, s55, 12
	v_and_or_b32 v33, v33, s55, 13
	v_and_or_b32 v32, v32, s55, 8
	v_and_or_b32 v31, v31, s55, 9
	v_and_or_b32 v30, v30, s55, 11
	v_and_or_b32 v29, v29, s55, 10
	v_and_b32_e32 v28, 0xffffff80, v28
	v_and_or_b32 v27, v27, s55, 1
	v_and_or_b32 v26, v26, s55, 3
	v_and_or_b32 v22, v22, s55, 2
	v_and_or_b32 v18, v18, s55, 7
	v_and_or_b32 v16, v16, s55, 6
	v_and_or_b32 v12, v12, s55, 4
	v_and_or_b32 v2, v2, s55, 5
	v_min_u32_e32 v89, v91, v85
	v_max_u32_e32 v42, v44, v42
	v_max_u32_e32 v38, v80, v38
	v_max_u32_e32 v41, v79, v41
	v_max_u32_e32 v37, v77, v37
	v_max_u32_e32 v59, v36, v35
	v_min_u32_e32 v60, v34, v33
	v_min_u32_e32 v35, v36, v35
	v_max_u32_e32 v33, v34, v33
	v_max_u32_e32 v62, v32, v31
	v_min_u32_e32 v63, v30, v29
	v_min_u32_e32 v31, v32, v31
	v_max_u32_e32 v29, v30, v29
	v_max_u32_e32 v68, v28, v27
	v_min_u32_e32 v69, v26, v22
	v_min_u32_e32 v27, v28, v27
	v_max_u32_e32 v22, v26, v22
	v_max_u32_e32 v71, v18, v16
	v_min_u32_e32 v72, v12, v2
	v_min_u32_e32 v16, v18, v16
	v_max_u32_e32 v2, v12, v2
	v_max_u32_e32 v67, v1, v0
	v_min_u32_e32 v0, v1, v0
	v_max_u32_e32 v1, v58, v53
	v_min_u32_e32 v53, v58, v53
	v_min_u32_e32 v58, v61, v66
	v_min_u32_e32 v44, v42, v38
	v_min_u32_e32 v50, v41, v37
	v_max_u32_e32 v38, v42, v38
	v_max3_u32 v42, v61, v66, v89
	v_max3_u32 v43, v54, v57, v43
	v_max3_u32 v54, v73, v83, v81
	v_max_u32_e32 v61, v59, v60
	v_max_u32_e32 v34, v35, v33
	v_min_u32_e32 v66, v62, v63
	v_min_u32_e32 v30, v31, v29
	v_min_u32_e32 v59, v59, v60
	v_min_u32_e32 v33, v35, v33
	v_max_u32_e32 v60, v62, v63
	v_max_u32_e32 v29, v31, v29
	v_max_u32_e32 v70, v68, v69
	v_max_u32_e32 v26, v27, v22
	v_min_u32_e32 v73, v71, v72
	v_min_u32_e32 v12, v16, v2
	v_min_u32_e32 v68, v68, v69
	v_min_u32_e32 v22, v27, v22
	v_max_u32_e32 v69, v71, v72
	v_max_u32_e32 v2, v16, v2
	v_min_u32_e32 v77, v44, v50
	v_max_u32_e32 v36, v61, v34
	v_min_u32_e32 v32, v66, v30
	v_max_u32_e32 v35, v59, v33
	v_min_u32_e32 v31, v60, v29
	v_min_u32_e32 v34, v61, v34
	v_max_u32_e32 v30, v66, v30
	v_min_u32_e32 v33, v59, v33
	v_max_u32_e32 v29, v60, v29
	v_max_u32_e32 v28, v70, v26
	v_min_u32_e32 v18, v73, v12
	v_max_u32_e32 v27, v68, v22
	v_min_u32_e32 v16, v69, v2
	v_min_u32_e32 v26, v70, v26
	v_max_u32_e32 v12, v73, v12
	v_min_u32_e32 v22, v68, v22
	v_max_u32_e32 v2, v69, v2
	v_min_u32_e32 v75, v67, v1
	v_max3_u32 v45, v74, v46, v45
	v_max3_u32 v1, v67, v1, v77
	v_max_u32_e32 v67, v36, v32
	v_max_u32_e32 v62, v35, v31
; DEV void merge_top16(unsigned (&R)[16], const unsigned (&G)[16]) {
; #pragma unroll
;   for (int i = 0; i < 16; ++i) R[i] = max(R[i], G[15 - i]);
;   bitonic_merge16_desc(R);
; }
	v_max_u32_e32 v61, v34, v30
	v_max_u32_e32 v59, v33, v29
	v_min_u32_e32 v74, v28, v18
	v_min_u32_e32 v71, v27, v16
	v_min_u32_e32 v70, v26, v12
	v_min_u32_e32 v68, v22, v2
	v_min_u32_e32 v32, v36, v32
	v_min_u32_e32 v31, v35, v31
	v_min_u32_e32 v30, v34, v30
	v_min_u32_e32 v29, v33, v29
	v_max_u32_e32 v18, v28, v18
	v_max_u32_e32 v16, v27, v16
	v_max_u32_e32 v12, v26, v12
	v_max_u32_e32 v2, v22, v2
	v_max_u32_e32 v63, v67, v62
	v_max_u32_e32 v60, v61, v59
	v_min_u32_e32 v72, v74, v71
	v_min_u32_e32 v69, v70, v68
	v_max_u32_e32 v35, v32, v31
	v_max_u32_e32 v33, v30, v29
	v_min_u32_e32 v27, v18, v16
	v_min_u32_e32 v22, v12, v2
	v_min_u32_e32 v62, v67, v62
	v_min_u32_e32 v59, v61, v59
	v_max_u32_e32 v67, v74, v71
	v_max_u32_e32 v68, v70, v68
	v_min_u32_e32 v31, v32, v31
	v_min_u32_e32 v29, v30, v29
	v_max_u32_e32 v16, v18, v16
	v_max_u32_e32 v2, v12, v2
	v_max_u32_e32 v37, v41, v37
	v_max_u32_e32 v66, v63, v60
	v_min_u32_e32 v73, v72, v69
	v_max_u32_e32 v34, v35, v33
	v_min_u32_e32 v26, v27, v22
	v_max_u32_e32 v61, v62, v59
	v_min_u32_e32 v70, v67, v68
	v_max_u32_e32 v30, v31, v29
	v_min_u32_e32 v12, v16, v2
	v_min_u32_e32 v76, v0, v53
	v_min_u32_e32 v41, v38, v37
	v_max3_u32 v44, v75, v44, v50
	v_min_u32_e32 v75, v66, v73
	v_min_u32_e32 v28, v34, v26
	v_min_u32_e32 v71, v61, v70
	v_min_u32_e32 v18, v30, v12
	v_max3_u32 v58, v58, v91, v85
	v_max3_u32 v0, v0, v53, v41
	v_max3_u32 v37, v76, v38, v37
	v_min_u32_e32 v36, v75, v28
	v_min_u32_e32 v32, v71, v18
	v_min_u32_e32 v60, v63, v60
	v_max_u32_e32 v63, v72, v69
	v_min_u32_e32 v33, v35, v33
	v_max_u32_e32 v22, v27, v22
	v_min_u32_e32 v59, v62, v59
	v_max_u32_e32 v62, v67, v68
	v_min_u32_e32 v29, v31, v29
	v_max_u32_e32 v2, v16, v2
	v_max_u32_e32 v28, v75, v28
	v_max_u32_e32 v18, v71, v18
	v_max_u32_e32 v38, v42, v40
	v_min_u32_e32 v40, v42, v40
	v_max_u32_e32 v41, v58, v54
	v_min_u32_e32 v42, v58, v54
	v_max_u32_e32 v46, v51, v49
	v_min_u32_e32 v49, v51, v49
	v_max_u32_e32 v50, v47, v45
	v_min_u32_e32 v45, v47, v45
	v_max_u32_e32 v47, v48, v1
	v_min_u32_e32 v1, v48, v1
	v_max_u32_e32 v48, v52, v44
	v_min_u32_e32 v44, v52, v44
	v_max_u32_e32 v51, v43, v0
	v_min_u32_e32 v0, v43, v0
	v_max_u32_e32 v43, v39, v37
	v_min_u32_e32 v37, v39, v37
	v_min_u32_e32 v74, v36, v32
	v_min_u32_e32 v69, v60, v63
	v_min_u32_e32 v27, v33, v22
	v_min_u32_e32 v67, v59, v62
	v_min_u32_e32 v16, v29, v2
	v_max_u32_e32 v32, v36, v32
	v_min_u32_e32 v36, v28, v18
	v_max_u32_e32 v18, v28, v18
	v_max_u32_e32 v28, v66, v73
	v_max_u32_e32 v26, v34, v26
	v_max_u32_e32 v61, v61, v70
	v_max_u32_e32 v12, v30, v12
	v_max_u32_e32 v60, v60, v63
	v_max_u32_e32 v22, v33, v22
	v_max_u32_e32 v59, v59, v62
	v_max_u32_e32 v2, v29, v2
	v_max_u32_e32 v39, v38, v47
	v_min_u32_e32 v38, v38, v47
	v_max_u32_e32 v47, v41, v48
	v_min_u32_e32 v41, v41, v48
	v_max_u32_e32 v48, v46, v51
	v_min_u32_e32 v46, v46, v51
	v_max_u32_e32 v51, v50, v43
	v_min_u32_e32 v43, v50, v43
	v_max_u32_e32 v50, v40, v1
	v_min_u32_e32 v1, v40, v1
	v_max_u32_e32 v40, v42, v44
	v_min_u32_e32 v42, v42, v44
	v_max_u32_e32 v44, v49, v0
	v_min_u32_e32 v0, v49, v0
	v_max_u32_e32 v49, v45, v37
	v_min_u32_e32 v37, v45, v37
	v_min_u32_e32 v35, v69, v27
	v_min_u32_e32 v31, v67, v16
	v_max_u32_e32 v27, v69, v27
	v_max_u32_e32 v16, v67, v16
	v_min_u32_e32 v34, v28, v26
	v_min_u32_e32 v30, v61, v12
	v_min_u32_e32 v33, v60, v22
	v_min_u32_e32 v29, v59, v2
	v_max_u32_e32 v26, v28, v26
	v_max_u32_e32 v12, v61, v12
	v_max_u32_e32 v22, v60, v22
	v_max_u32_e32 v2, v59, v2
	v_max_u32_e32 v45, v39, v48
	v_min_u32_e32 v39, v39, v48
	v_max_u32_e32 v48, v47, v51
	v_min_u32_e32 v47, v47, v51
	v_max_u32_e32 v51, v38, v46
	v_min_u32_e32 v38, v38, v46
	v_max_u32_e32 v46, v41, v43
	v_min_u32_e32 v41, v41, v43
	v_max_u32_e32 v43, v50, v44
	v_min_u32_e32 v44, v50, v44
	v_max_u32_e32 v50, v40, v49
	v_min_u32_e32 v40, v40, v49
	v_max_u32_e32 v49, v1, v0
	v_min_u32_e32 v0, v1, v0
	v_max_u32_e32 v1, v42, v37
	v_min_u32_e32 v37, v42, v37
	v_min_u32_e32 v68, v35, v31
	v_max_u32_e32 v31, v35, v31
	v_min_u32_e32 v67, v27, v16
	v_max_u32_e32 v16, v27, v16
	v_min_u32_e32 v66, v34, v30
	v_min_u32_e32 v62, v33, v29
	v_max_u32_e32 v30, v34, v30
	v_max_u32_e32 v29, v33, v29
	v_min_u32_e32 v28, v26, v12
	v_min_u32_e32 v34, v22, v2
	v_max_u32_e32 v12, v26, v12
	v_max_u32_e32 v2, v22, v2
	v_min_u32_e32 v42, v45, v48
	v_min_u32_e32 v52, v39, v47
	v_min_u32_e32 v53, v51, v46
	v_min_u32_e32 v54, v38, v41
	v_min_u32_e32 v55, v43, v50
	v_min_u32_e32 v56, v44, v40
	v_min_u32_e32 v57, v49, v1
	v_min_u32_e32 v58, v0, v37
	v_min_u32_e32 v72, v74, v68
	v_min_u32_e32 v35, v32, v31
	v_min_u32_e32 v69, v36, v67
	v_min_u32_e32 v27, v18, v16
	v_min_u32_e32 v63, v66, v62
	v_min_u32_e32 v33, v30, v29
	v_min_u32_e32 v59, v28, v34
	v_min_u32_e32 v22, v12, v2
	v_max3_u32 v26, v45, v48, v72
	v_max3_u32 v42, v42, v74, v68
	v_max3_u32 v35, v39, v47, v35
	v_max3_u32 v31, v52, v32, v31
	v_max3_u32 v32, v51, v46, v69
	v_max3_u32 v36, v53, v36, v67
	v_max3_u32 v27, v38, v41, v27
	v_max3_u32 v16, v54, v18, v16
	v_max3_u32 v18, v43, v50, v63
	v_max3_u32 v38, v55, v66, v62
	v_max3_u32 v33, v44, v40, v33
	v_max3_u32 v29, v56, v30, v29
	v_max3_u32 v1, v49, v1, v59
	v_max3_u32 v28, v57, v28, v34
	v_max3_u32 v0, v0, v37, v22
	v_max3_u32 v2, v58, v12, v2
	v_max_u32_e32 v12, v26, v18
	v_max_u32_e32 v22, v42, v38
	v_max_u32_e32 v30, v35, v33
	v_min_u32_e32 v33, v35, v33
	v_max_u32_e32 v34, v31, v29
	v_min_u32_e32 v29, v31, v29
	v_max_u32_e32 v31, v32, v1
	v_min_u32_e32 v1, v32, v1
	v_max_u32_e32 v32, v36, v28
	v_max_u32_e32 v35, v27, v0
	v_min_u32_e32 v0, v27, v0
	v_max_u32_e32 v27, v16, v2
	v_min_u32_e32 v18, v26, v18
	v_min_u32_e32 v26, v42, v38
; DEV unsigned fkey(float x) { const unsigned u = __float_as_uint(x); return (u & 0x80000000u) ? ~u : (u | 0x80000000u); }
; DEV float keyf(unsigned k) { const unsigned u = (k & 0x80000000u) ? (k & 0x7fffffffu) : ~k; return __uint_as_float(u); }
; DEV void topk_group(int hg, const float* scoresT, int* idxo, float* go) {
;     ...
;   unsigned* la = (unsigned*)smem; unsigned* lb = la + 16 * 512;
;   float bv[16];
; #pragma unroll
;   for (int j = 0; j < 16; ++j) { bv[j] = keyf(LB[j] & ~127u); la[j * 512 + tid] = LA[j]; lb[j * 512 + tid] = LB[j]; }
;   {
;     constexpr int CI[64] = {0,0,0,0,0,0,0,0,0,0,0,0,0,0,0,0, 1,1,1,1,1,1,1,1, 2,2,2,2,2, 3,3,3,3, 4,4,4, 5,5, 6,6, 7,7, 8,9,10,11,12,13,14,15, 0,0,0,0,0,0,0,0,0,0,0,0,0,0};
;     constexpr int CJ[64] = {0,1,2,3,4,5,6,7,8,9,10,11,12,13,14,15, 0,1,2,3,4,5,6,7, 0,1,2,3,4, 0,1,2,3, 0,1,2, 0,1, 0,1, 0,1, 0,0,0,0,0,0,0,0, 0,0,0,0,0,0,0,0,0,0,0,0,0,0};
;     float av[16];
; #pragma unroll
;     for (int i = 0; i < 16; ++i) av[i] = keyf(LA[i] & ~127u);
; #pragma unroll
;     for (int gq = 0; gq < 4; ++gq) {
;       unsigned g[16];
; #pragma unroll
;       for (int e = 0; e < 16; ++e) {
;         const int ci = CI[gq * 16 + e], cj = CJ[gq * 16 + e];
;         g[e] = (gq * 16 + e < 50) ? ((fkey(av[ci] + bv[cj]) & ~255u) | (unsigned)(255 - (ci * 16 + cj))) : 0u;
;       }
;       bitonic_sort16_desc(g);
;       if (gq == 0) {
; #pragma unroll
;         for (int e = 0; e < 16; ++e) LC[e] = g[e];
;       } else merge_top16(LC, g);
;     }
	v_min_u32_e32 v28, v36, v28
	v_min_u32_e32 v2, v16, v2
	v_max_u32_e32 v16, v12, v31
	v_min_u32_e32 v12, v12, v31
	v_max_u32_e32 v31, v22, v32
	v_min_u32_e32 v22, v22, v32
	v_max_u32_e32 v32, v30, v35
	v_min_u32_e32 v30, v30, v35
	v_max_u32_e32 v35, v34, v27
	v_min_u32_e32 v27, v34, v27
	v_max_u32_e32 v34, v18, v1
	v_min_u32_e32 v1, v18, v1
	v_max_u32_e32 v18, v26, v28
	v_min_u32_e32 v26, v26, v28
	v_max_u32_e32 v28, v33, v0
	v_min_u32_e32 v0, v33, v0
	v_max_u32_e32 v33, v29, v2
	v_min_u32_e32 v2, v29, v2
	v_max_u32_e32 v29, v16, v32
	v_min_u32_e32 v16, v16, v32
	v_max_u32_e32 v32, v31, v35
	v_min_u32_e32 v31, v31, v35
	v_max_u32_e32 v35, v12, v30
	v_min_u32_e32 v12, v12, v30
	v_max_u32_e32 v30, v22, v27
	v_min_u32_e32 v22, v22, v27
	v_max_u32_e32 v27, v34, v28
	v_min_u32_e32 v28, v34, v28
	v_max_u32_e32 v34, v18, v33
	v_min_u32_e32 v18, v18, v33
	v_max_u32_e32 v33, v1, v0
	v_min_u32_e32 v36, v1, v0
	v_max_u32_e32 v37, v26, v2
	v_min_u32_e32 v2, v26, v2
	v_max_u32_e32 v0, v29, v32
	v_min_u32_e32 v1, v29, v32
	v_min_u32_e32 v29, v35, v30
	v_max_u32_e32 v40, v16, v31
	v_min_u32_e32 v16, v16, v31
	v_max_u32_e32 v38, v35, v30
	v_max_u32_e32 v32, v28, v18
	v_min_u32_e32 v18, v28, v18
	v_max_u32_e32 v30, v36, v2
	v_min_u32_e32 v31, v36, v2
	v_lshl_add_u32 v26, v4, 2, 0
	v_cmp_gt_i32_e32 vcc, 0, v29
	v_and_b32_e32 v2, 0x7fffff80, v29
	v_bitop3_b32 v4, v29, s45, v29 bitop3:0xcf
	v_max_u32_e32 v35, v12, v22
	v_min_u32_e32 v12, v12, v22
	v_max_u32_e32 v22, v27, v34
	v_min_u32_e32 v27, v27, v34
	v_max_u32_e32 v28, v33, v37
	v_min_u32_e32 v33, v33, v37
	ds_write2st64_b32 v26, v6, v3 offset1:8
	ds_write2st64_b32 v26, v0, v1 offset0:128 offset1:136
	ds_write2st64_b32 v26, v9, v8 offset0:16 offset1:24
	ds_write2st64_b32 v26, v40, v16 offset0:144 offset1:152
	ds_write2st64_b32 v26, v14, v20 offset0:32 offset1:40
	ds_write2st64_b32 v26, v38, v29 offset0:160 offset1:168
	ds_write2st64_b32 v26, v5, v10 offset0:48 offset1:56
	ds_write2st64_b32 v26, v35, v12 offset0:176 offset1:184
	ds_write2st64_b32 v26, v7, v15 offset0:64 offset1:72
	ds_write2st64_b32 v26, v22, v27 offset0:192 offset1:200
	ds_write2st64_b32 v26, v19, v21 offset0:80 offset1:88
	ds_write2st64_b32 v26, v32, v18 offset0:208 offset1:216
	ds_write2st64_b32 v26, v24, v25 offset0:96 offset1:104
	ds_write2st64_b32 v26, v28, v33 offset0:224 offset1:232
	ds_write2st64_b32 v26, v17, v13 offset0:112 offset1:120
	ds_write2st64_b32 v26, v30, v31 offset0:240 offset1:248
	v_cndmask_b32_e32 v2, v4, v2, vcc
	v_cmp_gt_i32_e32 vcc, 0, v6
	v_cmp_gt_i32_e64 s[6:7], 0, v18
	v_and_b32_e32 v4, 0x7fffff80, v18
	v_and_b32_e32 v34, 0x7fffff80, v6
	v_and_b32_e32 v18, 0xffffff80, v18
	v_and_b32_e32 v6, 0xffffff80, v6
	v_xor_b32_e32 v18, -1, v18
	v_xor_b32_e32 v6, -1, v6
	v_cndmask_b32_e64 v29, v18, v4, s[6:7]
	v_cndmask_b32_e32 v6, v6, v34, vcc
	v_cmp_gt_i32_e32 vcc, 0, v30
	v_cmp_gt_i32_e64 s[6:7], 0, v31
	v_and_b32_e32 v4, 0x7fffff80, v31
	v_and_b32_e32 v18, 0x7fffff80, v30
	v_and_b32_e32 v31, 0xffffff80, v31
	v_and_b32_e32 v30, 0xffffff80, v30
	v_xor_b32_e32 v31, -1, v31
	v_xor_b32_e32 v30, -1, v30
	v_cndmask_b32_e64 v31, v31, v4, s[6:7]
	v_cndmask_b32_e32 v30, v30, v18, vcc
	v_pk_add_f32 v[30:31], v[6:7], v[30:31] op_sel_hi:[0,1]
	v_not_b32_e32 v4, v31
	v_or_b32_e32 v18, 0x80000000, v31
	v_cmp_gt_i32_e64 s[6:7], 0, v31
	v_cmp_gt_i32_e32 vcc, 0, v30
	v_and_b32_e32 v31, 0xffffff80, v33
	v_cndmask_b32_e64 v4, v18, v4, s[6:7]
	v_not_b32_e32 v18, v30
	v_or_b32_e32 v30, 0x80000000, v30
	v_cndmask_b32_e32 v18, v30, v18, vcc
	v_cmp_gt_i32_e64 s[6:7], 0, v28
	v_and_b32_e32 v30, 0x7fffff80, v28
	v_and_b32_e32 v28, 0xffffff80, v28
	v_cmp_gt_i32_e32 vcc, 0, v33
	v_and_b32_e32 v36, 0x7fffff80, v33
	v_xor_b32_e32 v28, -1, v28
	v_xor_b32_e32 v33, -1, v31
	v_cndmask_b32_e64 v31, v28, v30, s[6:7]
	v_cndmask_b32_e32 v30, v33, v36, vcc
	v_pk_add_f32 v[30:31], v[6:7], v[30:31] op_sel_hi:[0,1]
	v_not_b32_e32 v28, v31
	v_or_b32_e32 v33, 0x80000000, v31
	v_cmp_gt_i32_e32 vcc, 0, v30
	v_cmp_gt_i32_e64 s[6:7], 0, v31
	v_not_b32_e32 v31, v30
	v_or_b32_e32 v30, 0x80000000, v30
	v_cndmask_b32_e64 v28, v33, v28, s[6:7]
	v_cndmask_b32_e32 v30, v30, v31, vcc
	v_and_b32_e32 v4, 0xffffff00, v4
	v_and_b32_e32 v18, 0xffffff00, v18
	v_and_b32_e32 v28, 0xffffff00, v28
	v_and_b32_e32 v30, 0xffffff00, v30
	v_or_b32_e32 v4, 0xf0, v4
	v_or_b32_e32 v18, 0xf1, v18
	v_or_b32_e32 v28, 0xf3, v28
	v_or_b32_e32 v30, 0xf2, v30
	v_max_u32_e32 v34, v4, v18
	v_min_u32_e32 v33, v28, v30
	v_min_u32_e32 v4, v4, v18
	v_max_u32_e32 v18, v28, v30
	v_cmp_gt_i32_e32 vcc, 0, v27
	v_cmp_gt_i32_e64 s[6:7], 0, v22
	v_and_b32_e32 v28, 0x7fffff80, v22
	v_and_b32_e32 v30, 0x7fffff80, v27
	v_and_b32_e32 v22, 0xffffff80, v22
	v_and_b32_e32 v27, 0xffffff80, v27
	v_xor_b32_e32 v22, -1, v22
	v_xor_b32_e32 v27, -1, v27
	v_cndmask_b32_e64 v31, v22, v28, s[6:7]
	v_cndmask_b32_e32 v30, v27, v30, vcc
	v_pk_add_f32 v[30:31], v[6:7], v[30:31] op_sel_hi:[0,1]
	v_not_b32_e32 v22, v31
	v_or_b32_e32 v27, 0x80000000, v31
	v_cmp_gt_i32_e64 s[6:7], 0, v31
	v_cmp_gt_i32_e32 vcc, 0, v30
	v_or_b32_e32 v28, 0x80000000, v30
	v_cndmask_b32_e64 v22, v27, v22, s[6:7]
	v_not_b32_e32 v27, v30
	v_cndmask_b32_e32 v27, v28, v27, vcc
	v_cmp_gt_i32_e32 vcc, 0, v32
	v_and_b32_e32 v28, 0x7fffff80, v32
	v_bitop3_b32 v31, v32, s45, v32 bitop3:0xcf
	v_cndmask_b32_e32 v28, v31, v28, vcc
	v_pk_add_f32 v[28:29], v[6:7], v[28:29] op_sel_hi:[0,1]
	v_not_b32_e32 v31, v29
	v_or_b32_e32 v32, 0x80000000, v29
	v_cmp_gt_i32_e64 s[6:7], 0, v29
	v_cmp_gt_i32_e32 vcc, 0, v28
	v_and_b32_e32 v22, 0xffffff00, v22
	v_cndmask_b32_e64 v29, v32, v31, s[6:7]
	v_not_b32_e32 v31, v28
	v_or_b32_e32 v28, 0x80000000, v28
	v_cndmask_b32_e32 v28, v28, v31, vcc
; DEV unsigned fkey(float x) { const unsigned u = __float_as_uint(x); return (u & 0x80000000u) ? ~u : (u | 0x80000000u); }
; DEV void topk_group(int hg, const float* scoresT, int* idxo, float* go) {
;     ...
;     for (int gq = 0; gq < 4; ++gq) {
;       unsigned g[16];
; #pragma unroll
;       for (int e = 0; e < 16; ++e) {
;         const int ci = CI[gq * 16 + e], cj = CJ[gq * 16 + e];
;         g[e] = (gq * 16 + e < 50) ? ((fkey(av[ci] + bv[cj]) & ~255u) | (unsigned)(255 - (ci * 16 + cj))) : 0u;
;       }
;       bitonic_sort16_desc(g);
;       if (gq == 0) {
; #pragma unroll
;         for (int e = 0; e < 16; ++e) LC[e] = g[e];
;       } else merge_top16(LC, g);
;     }
	v_and_b32_e32 v27, 0xffffff00, v27
	v_and_b32_e32 v29, 0xffffff00, v29
	v_and_b32_e32 v28, 0xffffff00, v28
	v_or_b32_e32 v22, 0xf7, v22
	v_or_b32_e32 v27, 0xf6, v27
	v_or_b32_e32 v29, 0xf4, v29
	v_or_b32_e32 v28, 0xf5, v28
	v_max_u32_e32 v30, v22, v27
	v_min_u32_e32 v31, v29, v28
	v_min_u32_e32 v22, v22, v27
	v_max_u32_e32 v27, v29, v28
	v_max_u32_e32 v36, v34, v33
	v_max_u32_e32 v37, v4, v18
	v_min_u32_e32 v32, v30, v31
	v_min_u32_e32 v28, v22, v27
	v_min_u32_e32 v33, v34, v33
	v_min_u32_e32 v4, v4, v18
	v_max_u32_e32 v30, v30, v31
	v_max_u32_e32 v22, v22, v27
	v_max_u32_e32 v39, v36, v37
	v_min_u32_e32 v29, v32, v28
	v_max_u32_e32 v18, v33, v4
	v_min_u32_e32 v31, v30, v22
	v_min_u32_e32 v36, v36, v37
	v_max_u32_e32 v28, v32, v28
	v_min_u32_e32 v4, v33, v4
	v_max_u32_e32 v22, v30, v22
	v_min_u32_e32 v41, v39, v29
	v_min_u32_e32 v34, v18, v31
	v_min_u32_e32 v32, v36, v28
	v_min_u32_e32 v30, v4, v22
	v_max_u32_e32 v29, v39, v29
	v_max_u32_e32 v18, v18, v31
	v_max_u32_e32 v36, v36, v28
	v_max_u32_e32 v4, v4, v22
	v_min_u32_e32 v42, v41, v34
	v_min_u32_e32 v33, v32, v30
	v_min_u32_e32 v37, v29, v18
	v_min_u32_e32 v22, v36, v4
	v_min_u32_e32 v27, v42, v33
	v_min_u32_e32 v28, v37, v22
	v_max_u32_e32 v39, v41, v34
	v_max_u32_e32 v30, v32, v30
	v_max_u32_e32 v18, v29, v18
	v_max_u32_e32 v4, v36, v4
	v_max_u32_e32 v32, v42, v33
	v_max_u32_e32 v33, v37, v22
	v_and_b32_e32 v22, 0xffffff80, v38
	v_min_u32_e32 v31, v39, v30
	v_min_u32_e32 v34, v18, v4
	v_max_u32_e32 v29, v39, v30
	v_max_u32_e32 v30, v18, v4
	v_cmp_gt_i32_e32 vcc, 0, v3
	v_cmp_gt_i32_e64 s[6:7], 0, v38
	v_and_b32_e32 v4, 0x7fffff80, v38
	v_and_b32_e32 v18, 0x7fffff80, v3
	v_and_b32_e32 v3, 0xffffff80, v3
	v_xor_b32_e32 v22, -1, v22
	v_xor_b32_e32 v36, -1, v3
	v_cndmask_b32_e64 v3, v22, v4, s[6:7]
	v_cndmask_b32_e32 v18, v36, v18, vcc
	v_pk_add_f32 v[36:37], v[6:7], v[2:3] op_sel_hi:[0,1]
	v_not_b32_e32 v4, v36
	v_or_b32_e32 v22, 0x80000000, v36
	v_cmp_gt_i32_e64 s[6:7], 0, v36
	v_cmp_gt_i32_e32 vcc, 0, v37
	v_or_b32_e32 v36, 0x80000000, v37
	v_cndmask_b32_e64 v4, v22, v4, s[6:7]
	v_not_b32_e32 v22, v37
	v_cndmask_b32_e32 v22, v36, v22, vcc
	v_and_b32_e32 v4, 0xffffff00, v4
	v_and_b32_e32 v22, 0xffffff00, v22
	v_or_b32_e32 v4, 0xfa, v4
	v_or_b32_e32 v22, 0xfb, v22
	v_min_u32_e32 v41, v22, v4
	v_max_u32_e32 v4, v22, v4
	v_cmp_gt_i32_e32 vcc, 0, v35
	v_cmp_gt_i32_e64 s[6:7], 0, v12
	v_and_b32_e32 v22, 0x7fffff80, v12
	v_and_b32_e32 v36, 0x7fffff80, v35
	v_and_b32_e32 v12, 0xffffff80, v12
	v_and_b32_e32 v35, 0xffffff80, v35
	v_xor_b32_e32 v12, -1, v12
	v_xor_b32_e32 v35, -1, v35
	v_cndmask_b32_e64 v37, v12, v22, s[6:7]
	v_cndmask_b32_e32 v36, v35, v36, vcc
	v_pk_add_f32 v[38:39], v[6:7], v[36:37] op_sel_hi:[0,1]
	v_not_b32_e32 v12, v39
	v_or_b32_e32 v22, 0x80000000, v39
	v_cmp_gt_i32_e64 s[6:7], 0, v39
	v_cmp_gt_i32_e32 vcc, 0, v38
	v_or_b32_e32 v35, 0x80000000, v38
	v_cndmask_b32_e64 v12, v22, v12, s[6:7]
	v_not_b32_e32 v22, v38
	v_cndmask_b32_e32 v22, v35, v22, vcc
	v_and_b32_e32 v12, 0xffffff00, v12
	v_and_b32_e32 v22, 0xffffff00, v22
	v_or_b32_e32 v12, 0xf8, v12
	v_or_b32_e32 v22, 0xf9, v22
	v_max_u32_e32 v35, v12, v22
	v_min_u32_e32 v12, v12, v22
	v_min_u32_e32 v22, v35, v41
	v_min_u32_e32 v38, v12, v4
	v_max_u32_e32 v35, v35, v41
	v_max_u32_e32 v4, v12, v4
	v_pk_add_f32 v[36:37], v[18:19], v[36:37] op_sel_hi:[0,1]
	v_min_u32_e32 v41, v35, v4
	v_max_u32_e32 v35, v35, v4
	v_not_b32_e32 v4, v37
	v_or_b32_e32 v12, 0x80000000, v37
	v_cmp_gt_i32_e64 s[6:7], 0, v37
	v_min_u32_e32 v39, v22, v38
	v_max_u32_e32 v38, v22, v38
	v_cmp_gt_i32_e32 vcc, 0, v36
	v_cndmask_b32_e64 v4, v12, v4, s[6:7]
	v_not_b32_e32 v12, v36
	v_or_b32_e32 v22, 0x80000000, v36
	v_pk_add_f32 v[36:37], v[18:19], v[2:3] op_sel_hi:[0,1]
	v_cndmask_b32_e32 v12, v22, v12, vcc
	v_not_b32_e32 v2, v37
	v_or_b32_e32 v42, 0x80000000, v37
	v_cmp_gt_i32_e32 vcc, 0, v36
	v_cmp_gt_i32_e64 s[6:7], 0, v37
	v_not_b32_e32 v37, v36
	v_or_b32_e32 v36, 0x80000000, v36
	v_cndmask_b32_e64 v2, v42, v2, s[6:7]
	v_cndmask_b32_e32 v36, v36, v37, vcc
	v_and_b32_e32 v4, 0xffffff00, v4
	v_and_b32_e32 v12, 0xffffff00, v12
	v_and_b32_e32 v2, 0xffffff00, v2
	v_and_b32_e32 v36, 0xffffff00, v36
	v_or_b32_e32 v4, 0xe8, v4
	v_or_b32_e32 v12, 0xe9, v12
	v_or_b32_e32 v2, 0xeb, v2
	v_or_b32_e32 v36, 0xea, v36
	v_max_u32_e32 v22, v4, v12
	v_min_u32_e32 v37, v2, v36
	v_min_u32_e32 v4, v4, v12
	v_max_u32_e32 v2, v2, v36
	v_min_u32_e32 v42, v22, v37
	v_min_u32_e32 v12, v4, v2
	v_min_u32_e32 v43, v42, v12
	v_max_u32_e32 v22, v22, v37
	v_max_u32_e32 v2, v4, v2
	v_max_u32_e32 v42, v42, v12
	v_and_b32_e32 v12, 0xffffff80, v40
	v_min_u32_e32 v44, v22, v2
	v_max_u32_e32 v45, v22, v2
	v_cmp_gt_i32_e32 vcc, 0, v8
	v_cmp_gt_i32_e64 s[6:7], 0, v40
	v_and_b32_e32 v2, 0x7fffff80, v40
	v_and_b32_e32 v4, 0x7fffff80, v8
	v_and_b32_e32 v8, 0xffffff80, v8
	v_xor_b32_e32 v12, -1, v12
	v_xor_b32_e32 v22, -1, v8
	v_cndmask_b32_e64 v8, v12, v2, s[6:7]
	v_cmp_gt_i32_e64 s[6:7], 0, v16
	v_and_b32_e32 v2, 0x7fffff80, v16
	v_and_b32_e32 v16, 0xffffff80, v16
	v_cndmask_b32_e32 v12, v22, v4, vcc
	v_cmp_gt_i32_e32 vcc, 0, v9
	v_and_b32_e32 v4, 0x7fffff80, v9
	v_and_b32_e32 v9, 0xffffff80, v9
	v_xor_b32_e32 v16, -1, v16
	v_xor_b32_e32 v22, -1, v9
	v_cndmask_b32_e64 v9, v16, v2, s[6:7]
	v_pk_add_f32 v[36:37], v[6:7], v[8:9] op_sel_hi:[0,1]
	v_cndmask_b32_e32 v22, v22, v4, vcc
	v_not_b32_e32 v2, v36
	v_or_b32_e32 v4, 0x80000000, v36
	v_cmp_gt_i32_e64 s[6:7], 0, v36
	v_cmp_gt_i32_e32 vcc, 0, v37
	v_or_b32_e32 v16, 0x80000000, v37
	v_cndmask_b32_e64 v2, v4, v2, s[6:7]
	v_not_b32_e32 v4, v37
	v_cndmask_b32_e32 v4, v16, v4, vcc
	v_and_b32_e32 v2, 0xffffff00, v2
	v_and_b32_e32 v4, 0xffffff00, v4
; DEV unsigned fkey(float x) { const unsigned u = __float_as_uint(x); return (u & 0x80000000u) ? ~u : (u | 0x80000000u); }
; DEV void topk_group(int hg, const float* scoresT, int* idxo, float* go) {
;     ...
;     for (int gq = 0; gq < 4; ++gq) {
;       unsigned g[16];
; #pragma unroll
;       for (int e = 0; e < 16; ++e) {
;         const int ci = CI[gq * 16 + e], cj = CJ[gq * 16 + e];
;         g[e] = (gq * 16 + e < 50) ? ((fkey(av[ci] + bv[cj]) & ~255u) | (unsigned)(255 - (ci * 16 + cj))) : 0u;
;       }
;       bitonic_sort16_desc(g);
;       if (gq == 0) {
; #pragma unroll
;         for (int e = 0; e < 16; ++e) LC[e] = g[e];
;       } else merge_top16(LC, g);
;     }
	v_or_b32_e32 v2, 0xfd, v2
	v_or_b32_e32 v4, 0xfc, v4
	v_pk_add_f32 v[36:37], v[18:19], v[8:9] op_sel_hi:[0,1]
	v_min_u32_e32 v40, v4, v2
	v_max_u32_e32 v2, v4, v2
	v_not_b32_e32 v4, v36
	v_or_b32_e32 v16, 0x80000000, v36
	v_cmp_gt_i32_e64 s[6:7], 0, v36
	v_cmp_gt_i32_e32 vcc, 0, v37
	v_or_b32_e32 v36, 0x80000000, v37
	v_cndmask_b32_e64 v4, v16, v4, s[6:7]
	v_not_b32_e32 v16, v37
	v_cndmask_b32_e32 v16, v36, v16, vcc
	v_and_b32_e32 v4, 0xffffff00, v4
	v_and_b32_e32 v16, 0xffffff00, v16
	v_or_b32_e32 v4, 0xed, v4
	v_or_b32_e32 v16, 0xec, v16
	v_pk_add_f32 v[36:37], v[22:23], v[8:9] op_sel_hi:[0,1]
	v_min_u32_e32 v46, v16, v4
	v_max_u32_e32 v47, v16, v4
	v_not_b32_e32 v4, v37
	v_or_b32_e32 v16, 0x80000000, v37
	v_cmp_gt_i32_e64 s[6:7], 0, v37
	v_cmp_gt_i32_e32 vcc, 0, v36
	s_nop 0
	v_cndmask_b32_e64 v4, v16, v4, s[6:7]
	v_not_b32_e32 v16, v36
	v_or_b32_e32 v36, 0x80000000, v36
	v_cndmask_b32_e32 v16, v36, v16, vcc
	v_and_b32_e32 v4, 0xffffff00, v4
	v_and_b32_e32 v16, 0xffffff00, v16
	v_or_b32_e32 v4, 0xdc, v4
	v_or_b32_e32 v16, 0xdd, v16
	v_min_u32_e32 v48, v4, v16
	v_max_u32_e32 v49, v4, v16
	v_cmp_gt_i32_e32 vcc, 0, v14
	v_and_b32_e32 v4, 0x7fffff80, v14
	v_bitop3_b32 v14, v14, s45, v14 bitop3:0xcf
	v_cndmask_b32_e32 v16, v14, v4, vcc
	v_cmp_gt_i32_e32 vcc, 0, v5
	v_cmp_gt_i32_e64 s[6:7], 0, v1
	v_and_b32_e32 v4, 0x7fffff80, v1
	v_and_b32_e32 v14, 0x7fffff80, v5
	v_and_b32_e32 v1, 0xffffff80, v1
	v_and_b32_e32 v5, 0xffffff80, v5
	v_xor_b32_e32 v1, -1, v1
	v_xor_b32_e32 v5, -1, v5
	v_cndmask_b32_e64 v4, v1, v4, s[6:7]
	v_cndmask_b32_e32 v14, v5, v14, vcc
	v_mov_b32_e32 v5, v8
	v_pk_add_f32 v[36:37], v[12:13], v[4:5] op_sel_hi:[0,1]
	v_not_b32_e32 v1, v37
	v_or_b32_e32 v8, 0x80000000, v37
	v_cmp_gt_i32_e64 s[6:7], 0, v37
	v_cmp_gt_i32_e32 vcc, 0, v36
	s_nop 0
	v_cndmask_b32_e64 v1, v8, v1, s[6:7]
	v_not_b32_e32 v8, v36
	v_or_b32_e32 v36, 0x80000000, v36
	v_cndmask_b32_e32 v8, v36, v8, vcc
	v_and_b32_e32 v1, 0xffffff00, v1
	v_and_b32_e32 v8, 0xffffff00, v8
	v_or_b32_e32 v1, 0xcd, v1
	v_or_b32_e32 v8, 0xce, v8
	v_pk_add_f32 v[36:37], v[16:17], v[4:5] op_sel_hi:[0,1]
	v_max_u32_e32 v50, v1, v8
	v_min_u32_e32 v8, v1, v8
	v_not_b32_e32 v1, v37
	v_or_b32_e32 v5, 0x80000000, v37
	v_cmp_gt_i32_e64 s[6:7], 0, v37
	v_cmp_gt_i32_e32 vcc, 0, v36
	s_nop 0
	v_cndmask_b32_e64 v1, v5, v1, s[6:7]
	v_not_b32_e32 v5, v36
	v_or_b32_e32 v36, 0x80000000, v36
	v_cndmask_b32_e32 v5, v36, v5, vcc
	v_and_b32_e32 v1, 0xffffff00, v1
	v_and_b32_e32 v5, 0xffffff00, v5
	v_or_b32_e32 v1, 0xbd, v1
	v_or_b32_e32 v5, 0xbe, v5
	v_min_u32_e32 v51, v1, v5
	v_max_u32_e32 v52, v1, v5
	v_cmp_gt_i32_e32 vcc, 0, v20
	v_and_b32_e32 v1, 0x7fffff80, v20
	v_bitop3_b32 v5, v20, s45, v20 bitop3:0xcf
	v_cndmask_b32_e32 v20, v5, v1, vcc
	v_cmp_gt_i32_e32 vcc, 0, v10
	v_and_b32_e32 v1, 0x7fffff80, v10
	v_bitop3_b32 v5, v10, s45, v10 bitop3:0xcf
	v_cndmask_b32_e32 v10, v5, v1, vcc
	v_cmp_gt_i32_e32 vcc, 0, v17
	v_and_b32_e32 v1, 0x7fffff80, v17
	v_bitop3_b32 v5, v17, s45, v17 bitop3:0xcf
	v_cndmask_b32_e32 v1, v5, v1, vcc
	v_cmp_gt_i32_e64 s[6:7], 0, v0
	v_and_b32_e32 v5, 0x7fffff80, v0
	v_and_b32_e32 v0, 0xffffff80, v0
	v_xor_b32_e32 v0, -1, v0
	v_cmp_gt_i32_e32 vcc, 0, v13
	v_and_b32_e32 v17, 0x7fffff80, v13
	v_and_b32_e32 v13, 0xffffff80, v13
	v_cndmask_b32_e64 v5, v0, v5, s[6:7]
	v_xor_b32_e32 v13, -1, v13
	v_pk_add_f32 v[36:37], v[6:7], v[4:5] op_sel_hi:[0,1]
	v_cndmask_b32_e32 v0, v13, v17, vcc
	v_not_b32_e32 v6, v36
	v_or_b32_e32 v13, 0x80000000, v36
	v_cmp_gt_i32_e64 s[6:7], 0, v36
	v_cmp_gt_i32_e32 vcc, 0, v37
	v_or_b32_e32 v17, 0x80000000, v37
	v_cndmask_b32_e64 v6, v13, v6, s[6:7]
	v_not_b32_e32 v13, v37
	v_and_b32_e32 v6, 0xffffff00, v6
	v_cndmask_b32_e32 v13, v17, v13, vcc
	v_or_b32_e32 v6, 0xfe, v6
	v_or_b32_e32 v13, 0xff, v13
	v_max_u32_e32 v17, v13, v6
	v_min_u32_e32 v6, v13, v6
	v_max_u32_e32 v36, v17, v40
	v_max_u32_e32 v13, v6, v2
	v_min_u32_e32 v17, v17, v40
	v_min_u32_e32 v2, v6, v2
	v_max_u32_e32 v37, v36, v13
	v_max_u32_e32 v6, v17, v2
	v_min_u32_e32 v13, v36, v13
	v_min_u32_e32 v2, v17, v2
	v_max_u32_e32 v53, v37, v39
	v_max_u32_e32 v40, v6, v41
	v_max_u32_e32 v36, v13, v38
	v_max_u32_e32 v17, v2, v35
	v_min_u32_e32 v37, v37, v39
	v_min_u32_e32 v6, v6, v41
	v_min_u32_e32 v13, v13, v38
	v_min_u32_e32 v2, v2, v35
	v_max_u32_e32 v55, v36, v17
	v_max_u32_e32 v39, v37, v6
	v_max_u32_e32 v35, v13, v2
	v_min_u32_e32 v17, v36, v17
	v_min_u32_e32 v6, v37, v6
	v_min_u32_e32 v2, v13, v2
	v_pk_add_f32 v[36:37], v[18:19], v[4:5] op_sel_hi:[0,1]
	v_max_u32_e32 v60, v6, v2
	v_min_u32_e32 v6, v6, v2
	v_not_b32_e32 v2, v36
	v_or_b32_e32 v13, 0x80000000, v36
	v_cmp_gt_i32_e64 s[6:7], 0, v36
	v_cmp_gt_i32_e32 vcc, 0, v37
	v_or_b32_e32 v18, 0x80000000, v37
	v_cndmask_b32_e64 v2, v13, v2, s[6:7]
	v_not_b32_e32 v13, v37
	v_cndmask_b32_e32 v13, v18, v13, vcc
	v_and_b32_e32 v2, 0xffffff00, v2
	v_and_b32_e32 v13, 0xffffff00, v13
	v_or_b32_e32 v2, 0xee, v2
	v_or_b32_e32 v13, 0xef, v13
	v_max_u32_e32 v18, v13, v2
	v_min_u32_e32 v2, v13, v2
	v_max_u32_e32 v36, v18, v46
	v_max_u32_e32 v13, v2, v47
	v_min_u32_e32 v18, v18, v46
	v_min_u32_e32 v2, v2, v47
	v_max_u32_e32 v37, v36, v13
	v_max_u32_e32 v46, v18, v2
	v_min_u32_e32 v36, v36, v13
	v_min_u32_e32 v18, v18, v2
	v_mov_b32_e32 v13, v22
	v_mov_b32_e32 v2, v5
	v_pk_add_f32 v[2:3], v[12:13], v[2:3]
	v_max_u32_e32 v70, v37, v43
	v_not_b32_e32 v13, v3
	v_or_b32_e32 v76, 0x80000000, v3
	v_cmp_gt_i32_e64 s[6:7], 0, v3
	v_cmp_gt_i32_e32 vcc, 0, v2
	v_max_u32_e32 v47, v46, v44
	v_cndmask_b32_e64 v3, v76, v13, s[6:7]
	v_not_b32_e32 v13, v2
	v_or_b32_e32 v2, 0x80000000, v2
	v_cndmask_b32_e32 v2, v2, v13, vcc
	v_and_b32_e32 v3, 0xffffff00, v3
; DEV unsigned fkey(float x) { const unsigned u = __float_as_uint(x); return (u & 0x80000000u) ? ~u : (u | 0x80000000u); }
; DEV void merge_top16(unsigned (&R)[16], const unsigned (&G)[16]) {
; #pragma unroll
;   for (int i = 0; i < 16; ++i) R[i] = max(R[i], G[15 - i]);
;   bitonic_merge16_desc(R);
; }
; DEV void topk_group(int hg, const float* scoresT, int* idxo, float* go) {
;     ...
;     for (int gq = 0; gq < 4; ++gq) {
;       unsigned g[16];
; #pragma unroll
;       for (int e = 0; e < 16; ++e) {
;         const int ci = CI[gq * 16 + e], cj = CJ[gq * 16 + e];
;         g[e] = (gq * 16 + e < 50) ? ((fkey(av[ci] + bv[cj]) & ~255u) | (unsigned)(255 - (ci * 16 + cj))) : 0u;
;       }
;       bitonic_sort16_desc(g);
;       if (gq == 0) {
; #pragma unroll
;         for (int e = 0; e < 16; ++e) LC[e] = g[e];
;       } else merge_top16(LC, g);
;     }
	v_and_b32_e32 v2, 0xffffff00, v2
	v_or_b32_e32 v3, 0xdb, v3
	v_or_b32_e32 v2, 0xcf, v2
	v_min_u32_e32 v13, v3, v2
	v_max_u32_e32 v77, v3, v2
	v_pk_add_f32 v[2:3], v[22:23], v[4:5] op_sel_hi:[0,1]
	v_not_b32_e32 v22, v2
	v_or_b32_e32 v81, 0x80000000, v2
	v_cmp_gt_i32_e64 s[6:7], 0, v2
	v_cmp_gt_i32_e32 vcc, 0, v3
	v_max_u32_e32 v76, v50, v13
	v_cndmask_b32_e64 v2, v81, v22, s[6:7]
	v_not_b32_e32 v22, v3
	v_or_b32_e32 v3, 0x80000000, v3
	v_cndmask_b32_e32 v3, v3, v22, vcc
	v_and_b32_e32 v2, 0xffffff00, v2
	v_and_b32_e32 v3, 0xffffff00, v3
	v_or_b32_e32 v2, 0xde, v2
	v_or_b32_e32 v3, 0xdf, v3
	v_max_u32_e32 v22, v3, v2
	v_min_u32_e32 v2, v3, v2
	v_max_u32_e32 v79, v8, v77
	v_min_u32_e32 v81, v22, v48
	v_min_u32_e32 v3, v2, v49
	v_min_u32_e32 v13, v50, v13
	v_min_u32_e32 v8, v8, v77
	v_max_u32_e32 v22, v22, v48
	v_max_u32_e32 v2, v2, v49
	v_max_u32_e32 v80, v76, v79
	v_min_u32_e32 v82, v81, v3
	v_max_u32_e32 v50, v13, v8
	v_min_u32_e32 v48, v22, v2
	v_min_u32_e32 v76, v76, v79
	v_max_u32_e32 v3, v81, v3
	v_min_u32_e32 v8, v13, v8
	v_max_u32_e32 v2, v22, v2
	v_max_u32_e32 v72, v36, v42
	v_max_u32_e32 v73, v18, v45
	v_min_u32_e32 v83, v80, v82
	v_min_u32_e32 v49, v50, v48
	v_min_u32_e32 v79, v76, v3
	v_min_u32_e32 v13, v8, v2
	v_min_u32_e32 v37, v37, v43
	v_min_u32_e32 v43, v46, v44
	v_min_u32_e32 v36, v36, v42
	v_min_u32_e32 v18, v18, v45
	v_max_u32_e32 v46, v80, v82
	v_max_u32_e32 v48, v50, v48
	v_max_u32_e32 v3, v76, v3
	v_max_u32_e32 v2, v8, v2
	v_max_u32_e32 v54, v53, v40
	v_max_u32_e32 v71, v70, v47
	v_max_u32_e32 v74, v72, v73
	v_min_u32_e32 v77, v83, v49
	v_min_u32_e32 v22, v79, v13
	v_max_u32_e32 v44, v37, v43
	v_max_u32_e32 v42, v36, v18
	v_min_u32_e32 v50, v46, v48
	v_min_u32_e32 v8, v3, v2
	v_min_u32_e32 v47, v70, v47
	v_min_u32_e32 v70, v72, v73
	v_max_u32_e32 v49, v83, v49
	v_max_u32_e32 v13, v79, v13
	v_min_u32_e32 v37, v37, v43
	v_min_u32_e32 v18, v36, v18
	v_max_u32_e32 v43, v46, v48
	v_max_u32_e32 v2, v3, v2
	v_max_u32_e32 v56, v54, v55
	v_max_u32_e32 v38, v39, v35
	v_min_u32_e32 v40, v53, v40
	v_min_u32_e32 v54, v54, v55
	v_min_u32_e32 v35, v39, v35
	v_max_u32_e32 v75, v71, v74
	v_min_u32_e32 v81, v77, v22
	v_max_u32_e32 v45, v44, v42
	v_min_u32_e32 v76, v50, v8
	v_max_u32_e32 v72, v47, v70
	v_min_u32_e32 v73, v49, v13
	v_max_u32_e32 v36, v37, v18
	v_min_u32_e32 v3, v43, v2
	v_min_u32_e32 v71, v71, v74
	v_max_u32_e32 v22, v77, v22
	v_min_u32_e32 v42, v44, v42
	v_max_u32_e32 v8, v50, v8
	v_min_u32_e32 v47, v47, v70
	v_max_u32_e32 v13, v49, v13
	v_min_u32_e32 v18, v37, v18
	v_max_u32_e32 v2, v43, v2
	v_max_u32_e32 v53, v40, v17
	v_max_u32_e32 v55, v54, v32
	v_max_u32_e32 v39, v35, v33
	v_min_u32_e32 v17, v40, v17
	v_min_u32_e32 v80, v45, v76
	v_min_u32_e32 v79, v72, v73
	v_min_u32_e32 v46, v36, v3
	v_min_u32_e32 v74, v71, v22
	v_min_u32_e32 v44, v42, v8
	v_min_u32_e32 v49, v47, v13
	v_min_u32_e32 v37, v18, v2
	v_min_u32_e32 v32, v54, v32
	v_min_u32_e32 v33, v35, v33
	v_max_u32_e32 v54, v75, v81
	v_max_u32_e32 v45, v45, v76
	v_max_u32_e32 v72, v72, v73
	v_max_u32_e32 v3, v36, v3
	v_max_u32_e32 v22, v71, v22
	v_max_u32_e32 v8, v42, v8
	v_max_u32_e32 v13, v47, v13
	v_max_u32_e32 v2, v18, v2
	v_max_u32_e32 v57, v56, v27
	v_max_u32_e32 v41, v38, v28
	v_max_u32_e32 v59, v53, v31
	v_max_u32_e32 v61, v60, v34
	v_max_u32_e32 v40, v17, v29
	v_max_u32_e32 v67, v6, v30
	v_min_u32_e32 v27, v56, v27
	v_min_u32_e32 v28, v38, v28
	v_min_u32_e32 v31, v53, v31
	v_min_u32_e32 v34, v60, v34
	v_max_u32_e32 v35, v32, v33
	v_min_u32_e32 v17, v17, v29
	v_min_u32_e32 v6, v6, v30
	v_min_u32_e32 v36, v72, v3
	v_min_u32_e32 v42, v22, v8
	v_min_u32_e32 v18, v13, v2
	v_min_u32_e32 v32, v32, v33
	v_max_u32_e32 v33, v54, v45
	v_max_u32_e32 v3, v72, v3
	v_max_u32_e32 v8, v22, v8
	v_max_u32_e32 v2, v13, v2
	v_max_u32_e32 v58, v57, v41
	v_max_u32_e32 v62, v59, v61
	v_max_u32_e32 v66, v55, v39
	v_max_u32_e32 v68, v40, v67
	v_min_u32_e32 v84, v75, v81
	v_max_u32_e32 v38, v27, v28
	v_max_u32_e32 v53, v31, v34
	v_max_u32_e32 v29, v17, v6
	v_min_u32_e32 v27, v27, v28
	v_min_u32_e32 v28, v31, v34
	v_min_u32_e32 v6, v17, v6
	v_min_u32_e32 v34, v33, v3
	v_min_u32_e32 v13, v8, v2
	v_max_u32_e32 v3, v33, v3
	v_max_u32_e32 v2, v8, v2
	v_max_u32_e32 v63, v58, v62
	v_max_u32_e32 v69, v66, v68
	v_min_u32_e32 v82, v84, v80
	v_min_u32_e32 v48, v79, v46
	v_min_u32_e32 v50, v74, v44
	v_min_u32_e32 v43, v49, v37
	v_min_u32_e32 v60, v54, v45
	v_max_u32_e32 v31, v27, v28
	v_max_u32_e32 v17, v32, v6
	v_min_u32_e32 v27, v27, v28
	v_min_u32_e32 v6, v32, v6
	v_min_u32_e32 v8, v3, v2
	v_min_u32_e32 v83, v82, v48
	v_min_u32_e32 v70, v50, v43
	v_max_u32_e32 v56, v38, v53
	v_max_u32_e32 v30, v35, v29
	v_min_u32_e32 v73, v60, v36
	v_min_u32_e32 v47, v42, v18
	v_min_u32_e32 v41, v57, v41
	v_min_u32_e32 v57, v59, v61
	v_min_u32_e32 v39, v55, v39
	v_min_u32_e32 v40, v40, v67
	v_max3_u32 v28, v27, v6, v8
	v_min_u32_e32 v8, v63, v69
	v_min_u32_e32 v71, v73, v47
	v_max_u32_e32 v59, v41, v57
	v_max_u32_e32 v55, v39, v40
	v_max_u32_e32 v61, v84, v80
	v_max_u32_e32 v46, v79, v46
	v_max_u32_e32 v44, v74, v44
	v_max_u32_e32 v37, v49, v37
	v_min_u32_e32 v38, v38, v53
	v_max3_u32 v53, v8, v83, v70
	v_min_u32_e32 v8, v56, v30
	v_max3_u32 v71, v56, v30, v71
	v_min_u32_e32 v67, v61, v46
	v_min_u32_e32 v49, v44, v37
	v_max3_u32 v30, v8, v73, v47
	v_min_u32_e32 v8, v59, v55
	v_min_u32_e32 v74, v67, v49
	v_min_u32_e32 v58, v58, v62
	v_min_u32_e32 v62, v66, v68
	v_max3_u32 v49, v8, v67, v49
	v_min_u32_e32 v8, v31, v17
	v_min_u32_e32 v22, v34, v13
	v_max_u32_e32 v48, v82, v48
	v_max_u32_e32 v43, v50, v43
	v_min_u32_e32 v29, v35, v29
	v_max3_u32 v13, v8, v34, v13
	v_min_u32_e32 v8, v58, v62
	v_min_u32_e32 v50, v48, v43
; DEV unsigned fkey(float x) { const unsigned u = __float_as_uint(x); return (u & 0x80000000u) ? ~u : (u | 0x80000000u); }
; DEV void topk_group(int hg, const float* scoresT, int* idxo, float* go) {
;     ...
;     for (int gq = 0; gq < 4; ++gq) {
;       unsigned g[16];
; #pragma unroll
;       for (int e = 0; e < 16; ++e) {
;         const int ci = CI[gq * 16 + e], cj = CJ[gq * 16 + e];
;         g[e] = (gq * 16 + e < 50) ? ((fkey(av[ci] + bv[cj]) & ~255u) | (unsigned)(255 - (ci * 16 + cj))) : 0u;
;       }
;       bitonic_sort16_desc(g);
;       if (gq == 0) {
; #pragma unroll
;         for (int e = 0; e < 16; ++e) LC[e] = g[e];
;       } else merge_top16(LC, g);
;     }
	v_max_u32_e32 v35, v60, v36
	v_max_u32_e32 v18, v42, v18
	v_min_u32_e32 v41, v41, v57
	v_min_u32_e32 v39, v39, v40
	v_max3_u32 v43, v8, v48, v43
	v_min_u32_e32 v8, v38, v29
	v_min_u32_e32 v36, v35, v18
	v_max_u32_e32 v40, v61, v46
	v_max_u32_e32 v37, v44, v37
	v_max3_u32 v18, v8, v35, v18
	v_min_u32_e32 v8, v41, v39
	v_max3_u32 v22, v31, v17, v22
	v_max3_u32 v35, v8, v40, v37
	v_min_u32_e32 v6, v27, v6
	v_mov_b32_e32 v17, v12
	v_mov_b32_e32 v8, v5
	v_max3_u32 v6, v6, v3, v2
	v_pk_add_f32 v[2:3], v[16:17], v[8:9]
	v_min_u32_e32 v44, v40, v37
	v_not_b32_e32 v8, v3
	v_or_b32_e32 v9, 0x80000000, v3
	v_cmp_gt_i32_e64 s[6:7], 0, v3
	v_cmp_gt_i32_e32 vcc, 0, v2
	v_max3_u32 v44, v41, v39, v44
	v_cndmask_b32_e64 v3, v9, v8, s[6:7]
	v_not_b32_e32 v8, v2
	v_or_b32_e32 v2, 0x80000000, v2
	v_cndmask_b32_e32 v2, v2, v8, vcc
	v_and_b32_e32 v3, 0xffffff00, v3
	v_and_b32_e32 v2, 0xffffff00, v2
	v_or_b32_e32 v3, 0xcc, v3
	v_or_b32_e32 v2, 0xbf, v2
	v_max_u32_e32 v8, v3, v2
	v_min_u32_e32 v12, v3, v2
	v_mov_b32_e32 v2, v5
	v_mov_b32_e32 v3, v4
	v_pk_add_f32 v[2:3], v[14:15], v[2:3] op_sel_hi:[0,1]
	v_not_b32_e32 v14, v3
	v_or_b32_e32 v39, 0x80000000, v3
	v_cmp_gt_i32_e64 s[6:7], 0, v3
	v_cmp_gt_i32_e32 vcc, 0, v2
	v_max_u32_e32 v9, v8, v51
	v_cndmask_b32_e64 v3, v39, v14, s[6:7]
	v_and_b32_e32 v3, 0xffffff00, v3
	v_or_b32_e32 v14, 0x9e, v3
	v_not_b32_e32 v3, v2
	v_or_b32_e32 v2, 0x80000000, v2
	v_cndmask_b32_e32 v2, v2, v3, vcc
	v_and_b32_e32 v2, 0xffffff00, v2
	v_or_b32_e32 v39, 0x9f, v2
	v_pk_add_f32 v[2:3], v[20:21], v[4:5] op_sel_hi:[0,1]
	v_not_b32_e32 v20, v2
	v_or_b32_e32 v41, 0x80000000, v2
	v_cmp_gt_i32_e64 s[6:7], 0, v2
	v_cmp_gt_i32_e32 vcc, 0, v3
	v_max_u32_e32 v16, v12, v52
	v_cndmask_b32_e64 v2, v41, v20, s[6:7]
	v_not_b32_e32 v20, v3
	v_or_b32_e32 v3, 0x80000000, v3
	v_cndmask_b32_e32 v3, v3, v20, vcc
	v_and_b32_e32 v2, 0xffffff00, v2
	v_and_b32_e32 v3, 0xffffff00, v3
	v_or_b32_e32 v2, 0xae, v2
	v_or_b32_e32 v3, 0xaf, v3
	v_max_u32_e32 v40, v14, v39
	v_min_u32_e32 v20, v3, v2
	v_min_u32_e32 v14, v14, v39
	v_max_u32_e32 v2, v3, v2
	v_min_u32_e32 v8, v8, v51
	v_min_u32_e32 v12, v12, v52
	v_max_u32_e32 v17, v9, v16
	v_min_u32_e32 v41, v40, v20
	v_min_u32_e32 v3, v14, v2
	v_max_u32_e32 v51, v8, v12
	v_max_u32_e32 v20, v40, v20
	v_max_u32_e32 v2, v14, v2
	v_min_u32_e32 v16, v9, v16
	v_min_u32_e32 v12, v8, v12
	v_cmp_gt_i32_e32 vcc, 0, v24
	v_and_b32_e32 v8, 0x7fffff80, v24
	v_and_b32_e32 v9, 0xffffff80, v25
	v_and_b32_e32 v24, 0xffffff80, v24
	v_min_u32_e32 v14, v20, v2
	v_max_u32_e32 v20, v20, v2
	v_cmp_gt_i32_e64 s[6:7], 0, v25
	v_and_b32_e32 v2, 0x7fffff80, v25
	v_xor_b32_e32 v9, -1, v9
	v_xor_b32_e32 v24, -1, v24
	v_min_u32_e32 v39, v41, v3
	v_max_u32_e32 v3, v41, v3
	v_cndmask_b32_e64 v9, v9, v2, s[6:7]
	v_cndmask_b32_e32 v8, v24, v8, vcc
	v_mov_b32_e32 v2, v5
	v_pk_add_f32 v[8:9], v[2:3], v[8:9] op_sel_hi:[0,1]
	v_not_b32_e32 v24, v9
	v_or_b32_e32 v25, 0x80000000, v9
	v_cmp_gt_i32_e64 s[6:7], 0, v9
	v_cmp_gt_i32_e32 vcc, 0, v8
	v_max3_u32 v74, v59, v55, v74
	v_cndmask_b32_e64 v9, v25, v24, s[6:7]
	v_and_or_b32 v24, v9, s57, 47
	v_not_b32_e32 v9, v8
	v_or_b32_e32 v8, 0x80000000, v8
	v_cndmask_b32_e32 v8, v8, v9, vcc
	v_and_or_b32 v25, v8, s57, 63
	v_cmp_gt_i32_e64 s[6:7], 0, v19
	v_and_b32_e32 v8, 0x7fffff80, v19
	v_and_b32_e32 v9, 0xffffff80, v19
	v_and_b32_e32 v19, 0xffffff80, v21
	v_cmp_gt_i32_e32 vcc, 0, v21
	v_and_b32_e32 v59, 0x7fffff80, v21
	v_xor_b32_e32 v9, -1, v9
	v_xor_b32_e32 v19, -1, v19
	v_cndmask_b32_e64 v9, v9, v8, s[6:7]
	v_cndmask_b32_e32 v8, v19, v59, vcc
	v_pk_add_f32 v[8:9], v[2:3], v[8:9] op_sel_hi:[0,1]
	v_not_b32_e32 v19, v9
	v_or_b32_e32 v21, 0x80000000, v9
	v_cmp_gt_i32_e64 s[6:7], 0, v9
	v_pk_add_f32 v[4:5], v[10:11], v[4:5] op_sel_hi:[0,1]
	v_not_b32_e32 v10, v4
	v_cndmask_b32_e64 v9, v21, v19, s[6:7]
	v_or_b32_e32 v59, 0x80000000, v4
	v_cmp_gt_i32_e64 s[6:7], 0, v4
	v_cmp_gt_i32_e32 vcc, 0, v8
	v_not_b32_e32 v19, v8
	v_cndmask_b32_e64 v4, v59, v10, s[6:7]
	v_or_b32_e32 v8, 0x80000000, v8
	v_and_b32_e32 v4, 0xffffff00, v4
	v_cndmask_b32_e32 v8, v8, v19, vcc
	v_cmp_gt_i32_e32 vcc, 0, v5
	v_or_b32_e32 v10, 0x8e, v4
	v_not_b32_e32 v4, v5
	v_or_b32_e32 v5, 0x80000000, v5
	v_cndmask_b32_e32 v4, v5, v4, vcc
	v_and_b32_e32 v4, 0xffffff00, v4
	v_cmp_gt_i32_e32 vcc, 0, v7
	v_and_b32_e32 v61, 0x7fffff80, v7
	v_and_b32_e32 v5, 0xffffff80, v15
	v_and_b32_e32 v7, 0xffffff80, v7
	v_or_b32_e32 v59, 0x8f, v4
	v_cmp_gt_i32_e64 s[6:7], 0, v15
	v_and_b32_e32 v4, 0x7fffff80, v15
	v_xor_b32_e32 v5, -1, v5
	v_xor_b32_e32 v7, -1, v7
	v_cndmask_b32_e64 v5, v5, v4, s[6:7]
	v_cndmask_b32_e32 v4, v7, v61, vcc
	v_pk_add_f32 v[4:5], v[2:3], v[4:5] op_sel_hi:[0,1]
	v_not_b32_e32 v7, v5
	v_or_b32_e32 v15, 0x80000000, v5
	v_cmp_gt_i32_e64 s[6:7], 0, v5
	v_cmp_gt_i32_e32 vcc, 0, v4
	v_and_b32_e32 v9, 0xffffff00, v9
	v_cndmask_b32_e64 v5, v15, v7, s[6:7]
	v_not_b32_e32 v7, v4
	v_or_b32_e32 v4, 0x80000000, v4
	v_cndmask_b32_e32 v4, v4, v7, vcc
	v_and_b32_e32 v8, 0xffffff00, v8
	v_and_b32_e32 v5, 0xffffff00, v5
	v_and_b32_e32 v4, 0xffffff00, v4
	v_or_b32_e32 v9, 0x5f, v9
	v_or_b32_e32 v8, 0x4f, v8
	v_or_b32_e32 v5, 0x6f, v5
	v_or_b32_e32 v4, 0x7f, v4
	v_max3_u32 v50, v58, v62, v50
	v_max_u32_e32 v58, v24, v25
	v_min_u32_e32 v19, v9, v8
	v_min_u32_e32 v24, v24, v25
	v_max_u32_e32 v8, v9, v8
	v_max_u32_e32 v60, v59, v10
	v_min_u32_e32 v7, v5, v4
	v_min_u32_e32 v10, v59, v10
	v_max_u32_e32 v4, v5, v4
	v_max_u32_e32 v21, v58, v19
	v_max_u32_e32 v9, v24, v8
	v_min_u32_e32 v15, v60, v7
	v_min_u32_e32 v5, v10, v4
	v_min_u32_e32 v19, v58, v19
	v_min_u32_e32 v8, v24, v8
	v_max_u32_e32 v7, v60, v7
	v_max_u32_e32 v4, v10, v4
	v_max_u32_e32 v25, v21, v9
; DEV unsigned fkey(float x) { const unsigned u = __float_as_uint(x); return (u & 0x80000000u) ? ~u : (u | 0x80000000u); }
; DEV void merge_top16(unsigned (&R)[16], const unsigned (&G)[16]) {
; #pragma unroll
;   for (int i = 0; i < 16; ++i) R[i] = max(R[i], G[15 - i]);
;   bitonic_merge16_desc(R);
; }
; DEV void topk_group(int hg, const float* scoresT, int* idxo, float* go) {
;     ...
;     for (int gq = 0; gq < 4; ++gq) {
;       unsigned g[16];
; #pragma unroll
;       for (int e = 0; e < 16; ++e) {
;         const int ci = CI[gq * 16 + e], cj = CJ[gq * 16 + e];
;         g[e] = (gq * 16 + e < 50) ? ((fkey(av[ci] + bv[cj]) & ~255u) | (unsigned)(255 - (ci * 16 + cj))) : 0u;
;       }
;       bitonic_sort16_desc(g);
;       if (gq == 0) {
; #pragma unroll
;         for (int e = 0; e < 16; ++e) LC[e] = g[e];
;       } else merge_top16(LC, g);
;     }
	v_min_u32_e32 v59, v15, v5
	v_max_u32_e32 v24, v19, v8
	v_min_u32_e32 v10, v7, v4
	v_min_u32_e32 v9, v21, v9
	v_max_u32_e32 v5, v15, v5
	v_min_u32_e32 v8, v19, v8
	v_max_u32_e32 v4, v7, v4
	v_max_u32_e32 v48, v17, v39
	v_max_u32_e32 v40, v51, v14
	v_max_u32_e32 v41, v16, v3
	v_max_u32_e32 v55, v12, v20
	v_min_u32_e32 v61, v25, v59
	v_min_u32_e32 v58, v24, v10
	v_min_u32_e32 v15, v9, v5
	v_min_u32_e32 v7, v8, v4
	v_min_u32_e32 v17, v17, v39
	v_min_u32_e32 v14, v51, v14
	v_min_u32_e32 v3, v16, v3
	v_min_u32_e32 v12, v12, v20
	v_max_u32_e32 v25, v25, v59
	v_max_u32_e32 v10, v24, v10
	v_max_u32_e32 v5, v9, v5
	v_max_u32_e32 v4, v8, v4
	v_max_u32_e32 v52, v48, v40
	v_max_u32_e32 v56, v41, v55
	v_min_u32_e32 v60, v61, v58
	v_min_u32_e32 v19, v15, v7
	v_max_u32_e32 v39, v17, v14
	v_max_u32_e32 v16, v3, v12
	v_min_u32_e32 v24, v25, v10
	v_min_u32_e32 v8, v5, v4
	v_min_u32_e32 v40, v48, v40
	v_min_u32_e32 v41, v41, v55
	v_max_u32_e32 v55, v61, v58
	v_max_u32_e32 v7, v15, v7
	v_min_u32_e32 v14, v17, v14
	v_min_u32_e32 v3, v3, v12
	v_max_u32_e32 v10, v25, v10
	v_max_u32_e32 v4, v5, v4
	v_min_u32_e32 v77, v83, v70
	v_max_u32_e32 v57, v52, v56
	v_min_u32_e32 v21, v60, v19
	v_max_u32_e32 v20, v39, v16
	v_min_u32_e32 v9, v24, v8
	v_max_u32_e32 v48, v40, v41
	v_min_u32_e32 v15, v55, v7
	v_max_u32_e32 v12, v14, v3
	v_min_u32_e32 v5, v10, v4
	v_min_u32_e32 v52, v52, v56
	v_max_u32_e32 v19, v60, v19
	v_min_u32_e32 v16, v39, v16
	v_max_u32_e32 v8, v24, v8
	v_min_u32_e32 v40, v40, v41
	v_max_u32_e32 v7, v55, v7
	v_min_u32_e32 v3, v14, v3
	v_max_u32_e32 v4, v10, v4
	v_max3_u32 v77, v63, v69, v77
	v_max3_u32 v36, v38, v29, v36
	v_min_u32_e32 v62, v57, v21
	v_min_u32_e32 v51, v20, v9
	v_min_u32_e32 v58, v48, v15
	v_min_u32_e32 v17, v12, v5
	v_min_u32_e32 v56, v52, v19
	v_min_u32_e32 v24, v16, v8
	v_min_u32_e32 v41, v40, v7
	v_min_u32_e32 v10, v3, v4
	v_max_u32_e32 v75, v77, v71
	v_max_u32_e32 v45, v74, v22
	v_max_u32_e32 v42, v50, v36
	v_max_u32_e32 v32, v44, v28
	v_max_u32_e32 v47, v53, v30
	v_max_u32_e32 v31, v49, v13
	v_max_u32_e32 v29, v43, v18
	v_max_u32_e32 v27, v35, v6
	v_min_u32_e32 v59, v62, v51
	v_min_u32_e32 v25, v58, v17
	v_min_u32_e32 v39, v56, v24
	v_min_u32_e32 v14, v41, v10
	v_max_u32_e32 v54, v75, v45
	v_max_u32_e32 v33, v42, v32
	v_max_u32_e32 v34, v47, v31
	v_max_u32_e32 v37, v29, v27
	v_min_u32_e32 v61, v59, v25
	v_min_u32_e32 v55, v39, v14
	v_min_u32_e32 v63, v77, v71
	v_min_u32_e32 v22, v74, v22
	v_min_u32_e32 v36, v50, v36
	v_min_u32_e32 v28, v44, v28
	v_min_u32_e32 v30, v53, v30
	v_min_u32_e32 v13, v49, v13
	v_min_u32_e32 v18, v43, v18
	v_min_u32_e32 v6, v35, v6
	v_max_u32_e32 v21, v57, v21
	v_max_u32_e32 v9, v20, v9
	v_max_u32_e32 v15, v48, v15
	v_max_u32_e32 v5, v12, v5
	v_max_u32_e32 v19, v52, v19
	v_max_u32_e32 v8, v16, v8
	v_max_u32_e32 v7, v40, v7
	v_max_u32_e32 v3, v3, v4
	v_max_u32_e32 v25, v59, v25
	v_max_u32_e32 v14, v39, v14
	v_max_u32_e32 v46, v54, v33
	v_max_u32_e32 v38, v34, v37
	v_max_u32_e32 v66, v63, v22
	v_max_u32_e32 v44, v36, v28
	v_max_u32_e32 v49, v30, v13
	v_max_u32_e32 v35, v18, v6
	v_min_u32_e32 v20, v21, v9
	v_min_u32_e32 v12, v15, v5
	v_min_u32_e32 v16, v19, v8
	v_min_u32_e32 v4, v7, v3
	v_min_u32_e32 v31, v47, v31
	v_max_u32_e32 v47, v62, v51
	v_max_u32_e32 v17, v58, v17
	v_max_u32_e32 v24, v56, v24
	v_max_u32_e32 v10, v41, v10
	v_max_u32_e32 v9, v21, v9
	v_max_u32_e32 v5, v15, v5
	v_max_u32_e32 v8, v19, v8
	v_max_u32_e32 v3, v7, v3
	v_min_u32_e32 v33, v54, v33
	v_min_u32_e32 v34, v34, v37
	v_min_u32_e32 v37, v25, v14
	v_max_u32_e32 v43, v49, v35
	v_min_u32_e32 v45, v75, v45
	v_min_u32_e32 v32, v42, v32
	v_min_u32_e32 v27, v29, v27
	v_min_u32_e32 v51, v47, v17
	v_min_u32_e32 v41, v24, v10
	v_min_u32_e32 v22, v63, v22
	v_min_u32_e32 v28, v36, v28
	v_min_u32_e32 v13, v30, v13
	v_min_u32_e32 v6, v18, v6
	v_min_u32_e32 v15, v9, v5
	v_min_u32_e32 v7, v8, v3
	v_max3_u32 v37, v33, v34, v37
	v_min_u32_e32 v39, v66, v44
	v_min_u32_e32 v35, v49, v35
	v_max_u32_e32 v5, v9, v5
	v_max_u32_e32 v3, v8, v3
	v_min_u32_e32 v33, v33, v34
	v_min_u32_e32 v60, v61, v55
	v_max_u32_e32 v50, v66, v44
	v_min_u32_e32 v48, v20, v12
	v_min_u32_e32 v40, v16, v4
	v_max_u32_e32 v42, v45, v32
	v_max_u32_e32 v29, v31, v27
	v_min_u32_e32 v56, v51, v41
	v_max_u32_e32 v36, v22, v28
	v_max_u32_e32 v18, v13, v6
	v_min_u32_e32 v19, v15, v7
	v_max_u32_e32 v12, v20, v12
	v_max_u32_e32 v4, v16, v4
	v_min_u32_e32 v32, v45, v32
	v_min_u32_e32 v27, v31, v27
	v_min_u32_e32 v22, v22, v28
	v_min_u32_e32 v6, v13, v6
	v_min_u32_e32 v8, v5, v3
	v_max3_u32 v14, v33, v25, v14
	v_min_u32_e32 v25, v39, v35
	v_max3_u32 v60, v46, v38, v60
	v_max3_u32 v56, v42, v29, v56
	v_max3_u32 v19, v36, v18, v19
	v_min_u32_e32 v16, v12, v4
	v_max_u32_e32 v17, v47, v17
	v_max_u32_e32 v10, v24, v10
	v_max3_u32 v8, v22, v6, v8
	v_min_u32_e32 v31, v46, v38
	v_min_u32_e32 v38, v50, v43
	v_min_u32_e32 v29, v42, v29
	v_min_u32_e32 v18, v36, v18
	v_max3_u32 v4, v25, v12, v4
	v_min_u32_e32 v25, v32, v27
	v_min_u32_e32 v6, v22, v6
	v_min_u32_e32 v24, v17, v10
	v_max3_u32 v31, v31, v61, v55
	v_max3_u32 v38, v38, v48, v40
	v_max3_u32 v29, v29, v51, v41
	v_max3_u32 v7, v18, v15, v7
	v_max3_u32 v10, v25, v17, v10
	v_max3_u32 v3, v6, v5, v3
	v_min_u32_e32 v52, v48, v40
	v_max_u32_e32 v40, v31, v38
	v_max_u32_e32 v15, v29, v7
	v_max_u32_e32 v12, v14, v4
	v_max_u32_e32 v5, v10, v3
	v_min_u32_e32 v31, v31, v38
	v_min_u32_e32 v7, v29, v7
	v_min_u32_e32 v4, v14, v4
	v_min_u32_e32 v3, v10, v3
	v_max_u32_e32 v29, v31, v7
	v_max_u32_e32 v10, v4, v3
	v_min_u32_e32 v7, v31, v7
	v_min_u32_e32 v3, v4, v3
	v_max_u32_e32 v4, v7, v3
	v_min_u32_e32 v3, v7, v3
	v_pk_add_f32 v[0:1], v[2:3], v[0:1] op_sel_hi:[0,1]
; DEV float keyf(unsigned k) { const unsigned u = (k & 0x80000000u) ? (k & 0x7fffffffu) : ~k; return __uint_as_float(u); }
; DEV void merge_top16(unsigned (&R)[16], const unsigned (&G)[16]) {
; #pragma unroll
;   for (int i = 0; i < 16; ++i) R[i] = max(R[i], G[15 - i]);
;   bitonic_merge16_desc(R);
; }
; DEV void topk_group(int hg, const float* scoresT, int* idxo, float* go) {
;     ...
;   const float smax = keyf(LC[0] & ~255u);
;   float ev[16], sum = 0.f;
; #pragma unroll
;   for (int k = 0; k < 16; ++k) { ev[k] = __expf(keyf(LC[k] & ~255u) - smax); sum += ev[k]; }
	v_not_b32_e32 v2, v1
	v_or_b32_e32 v7, 0x80000000, v1
	v_cmp_gt_i32_e64 s[6:7], 0, v1
	v_max3_u32 v52, v50, v43, v52
	v_max3_u32 v16, v39, v35, v16
	v_max3_u32 v24, v32, v27, v24
	v_cmp_gt_i32_e32 vcc, 0, v0
	v_cndmask_b32_e64 v1, v7, v2, s[6:7]
	v_not_b32_e32 v2, v0
	v_or_b32_e32 v0, 0x80000000, v0
	v_max_u32_e32 v21, v56, v19
	v_max_u32_e32 v20, v37, v16
	v_max_u32_e32 v9, v24, v8
	v_min_u32_e32 v25, v60, v52
	v_min_u32_e32 v19, v56, v19
	v_min_u32_e32 v16, v37, v16
	v_min_u32_e32 v8, v24, v8
	v_cndmask_b32_e32 v0, v0, v2, vcc
	v_max_u32_e32 v53, v60, v52
	v_max_u32_e32 v27, v25, v19
	v_max_u32_e32 v24, v16, v8
	v_min_u32_e32 v19, v25, v19
	v_min_u32_e32 v8, v16, v8
	v_and_or_b32 v1, v1, s57, 31
	v_and_or_b32 v0, v0, s57, 15
	v_max_u32_e32 v30, v53, v21
	v_max_u32_e32 v13, v20, v9
	v_max_u32_e32 v18, v40, v15
	v_max_u32_e32 v6, v12, v5
	v_min_u32_e32 v21, v53, v21
	v_min_u32_e32 v9, v20, v9
	v_min_u32_e32 v15, v40, v15
	v_min_u32_e32 v5, v12, v5
	v_max_u32_e32 v16, v19, v8
	v_min_u32_e32 v8, v19, v8
	v_min_u32_e32 v2, v1, v0
	v_max_u32_e32 v28, v30, v13
	v_max_u32_e32 v17, v18, v6
	v_max_u32_e32 v32, v27, v24
	v_max_u32_e32 v14, v29, v10
	v_max_u32_e32 v20, v21, v9
	v_max_u32_e32 v12, v15, v5
	v_min_u32_e32 v13, v30, v13
	v_min_u32_e32 v6, v18, v6
	v_min_u32_e32 v24, v27, v24
	v_min_u32_e32 v10, v29, v10
	v_min_u32_e32 v9, v21, v9
	v_min_u32_e32 v5, v15, v5
	v_max3_u32 v2, v8, v3, v2
	v_min_u32_e32 v3, v8, v3
	v_max_u32_e32 v22, v28, v17
	v_max_u32_e32 v33, v32, v14
	v_max_u32_e32 v34, v20, v12
	v_max_u32_e32 v25, v16, v4
	v_max_u32_e32 v18, v13, v6
	v_max_u32_e32 v27, v24, v10
	v_max_u32_e32 v15, v9, v5
	v_min_u32_e32 v17, v28, v17
	v_min_u32_e32 v14, v32, v14
	v_min_u32_e32 v12, v20, v12
	v_min_u32_e32 v4, v16, v4
	v_min_u32_e32 v6, v13, v6
	v_min_u32_e32 v10, v24, v10
	v_min_u32_e32 v5, v9, v5
	v_max3_u32 v0, v3, v1, v0
	v_min_u32_e32 v38, v22, v33
	v_min_u32_e32 v29, v18, v27
	v_min_u32_e32 v7, v15, v2
	v_min_u32_e32 v28, v17, v14
	v_min_u32_e32 v16, v12, v4
	v_min_u32_e32 v13, v6, v10
	v_min_u32_e32 v1, v5, v0
	v_max_u32_e32 v22, v22, v33
	v_max_u32_e32 v24, v34, v25
	v_max_u32_e32 v18, v18, v27
	v_max_u32_e32 v2, v15, v2
	v_max_u32_e32 v14, v17, v14
	v_max_u32_e32 v4, v12, v4
	v_max_u32_e32 v6, v6, v10
	v_max_u32_e32 v0, v5, v0
	v_min_u32_e32 v39, v34, v25
	v_max_u32_e32 v25, v22, v24
	v_max_u32_e32 v15, v18, v2
	v_max_u32_e32 v12, v14, v4
	v_max_u32_e32 v5, v6, v0
	v_max_u32_e32 v27, v25, v15
	v_max_u32_e32 v10, v12, v5
	v_min_u32_e32 v20, v28, v16
	v_min_u32_e32 v8, v13, v1
	v_max_u32_e32 v17, v27, v10
	v_min_u32_e32 v10, v27, v10
	v_min_u32_e32 v15, v25, v15
	v_min_u32_e32 v5, v12, v5
	v_max_u32_e32 v16, v28, v16
	v_max_u32_e32 v1, v13, v1
	v_not_b32_e32 v37, v10
	v_max_u32_e32 v12, v15, v5
	v_min_u32_e32 v5, v15, v5
	v_min_u32_e32 v15, v22, v24
	v_min_u32_e32 v2, v18, v2
	v_min_u32_e32 v4, v14, v4
	v_min_u32_e32 v0, v6, v0
	v_max_u32_e32 v13, v16, v1
	v_min_u32_e32 v1, v16, v1
	v_cmp_gt_i32_e32 vcc, 0, v10
	v_and_b32_e32 v16, 0x7fffff00, v10
	v_bitop3_b32 v10, v10, s60, v10 bitop3:0xcf
	v_not_b32_e32 v36, v12
	v_max_u32_e32 v18, v15, v2
	v_max_u32_e32 v6, v4, v0
	v_cndmask_b32_e32 v10, v10, v16, vcc
	v_cmp_gt_i32_e32 vcc, 0, v12
	v_and_b32_e32 v16, 0x7fffff00, v12
	v_bitop3_b32 v12, v12, s60, v12 bitop3:0xcf
	v_not_b32_e32 v35, v5
	v_max_u32_e32 v14, v18, v6
	v_cndmask_b32_e32 v12, v12, v16, vcc
	v_cmp_gt_i32_e32 vcc, 0, v5
	v_and_b32_e32 v16, 0x7fffff00, v5
	v_bitop3_b32 v5, v5, s60, v5 bitop3:0xcf
	v_not_b32_e32 v34, v14
	v_min_u32_e32 v6, v18, v6
	v_min_u32_e32 v2, v15, v2
	v_min_u32_e32 v0, v4, v0
	v_cndmask_b32_e32 v5, v5, v16, vcc
	v_cmp_gt_i32_e32 vcc, 0, v14
	v_and_b32_e32 v16, 0x7fffff00, v14
	v_bitop3_b32 v14, v14, s60, v14 bitop3:0xcf
	v_min_u32_e32 v19, v29, v7
	v_not_b32_e32 v33, v6
	v_max_u32_e32 v4, v2, v0
	v_min_u32_e32 v0, v2, v0
	v_max_u32_e32 v2, v38, v39
	v_max_u32_e32 v7, v29, v7
	v_cndmask_b32_e32 v14, v14, v16, vcc
	v_cmp_gt_i32_e32 vcc, 0, v6
	v_and_b32_e32 v16, 0x7fffff00, v6
	v_bitop3_b32 v6, v6, s60, v6 bitop3:0xcf
	v_not_b32_e32 v32, v4
	v_max_u32_e32 v15, v2, v7
	v_cndmask_b32_e32 v6, v6, v16, vcc
	v_cmp_gt_i32_e32 vcc, 0, v4
	v_and_b32_e32 v16, 0x7fffff00, v4
	v_bitop3_b32 v4, v4, s60, v4 bitop3:0xcf
	v_not_b32_e32 v31, v0
	v_max_u32_e32 v18, v15, v13
	v_cndmask_b32_e32 v4, v4, v16, vcc
	v_cmp_gt_i32_e32 vcc, 0, v0
	v_and_b32_e32 v16, 0x7fffff00, v0
	v_bitop3_b32 v0, v0, s60, v0 bitop3:0xcf
	v_not_b32_e32 v30, v18
	v_min_u32_e32 v13, v15, v13
	v_min_u32_e32 v2, v2, v7
	v_cndmask_b32_e32 v0, v0, v16, vcc
	v_cmp_gt_i32_e32 vcc, 0, v18
	v_and_b32_e32 v16, 0x7fffff00, v18
	v_bitop3_b32 v18, v18, s60, v18 bitop3:0xcf
	v_min_u32_e32 v40, v38, v39
	v_not_b32_e32 v29, v13
	v_max_u32_e32 v7, v2, v1
	v_cndmask_b32_e32 v38, v18, v16, vcc
	v_cmp_gt_i32_e32 vcc, 0, v13
	v_and_b32_e32 v16, 0x7fffff00, v13
	v_bitop3_b32 v13, v13, s60, v13 bitop3:0xcf
	v_min_u32_e32 v41, v20, v8
	v_not_b32_e32 v28, v7
	v_min_u32_e32 v1, v2, v1
	v_max_u32_e32 v2, v40, v19
	v_max_u32_e32 v8, v20, v8
	v_cndmask_b32_e32 v13, v13, v16, vcc
	v_cmp_gt_i32_e32 vcc, 0, v7
	v_and_b32_e32 v16, 0x7fffff00, v7
	v_bitop3_b32 v7, v7, s60, v7 bitop3:0xcf
	v_not_b32_e32 v27, v1
	v_max_u32_e32 v15, v2, v8
	v_cndmask_b32_e32 v7, v7, v16, vcc
	v_cmp_gt_i32_e32 vcc, 0, v1
	v_and_b32_e32 v16, 0x7fffff00, v1
	v_bitop3_b32 v1, v1, s60, v1 bitop3:0xcf
	v_min_u32_e32 v21, v40, v19
	v_not_b32_e32 v25, v15
	v_min_u32_e32 v2, v2, v8
	v_cndmask_b32_e32 v1, v1, v16, vcc
	v_cmp_gt_i32_e32 vcc, 0, v15
	v_and_b32_e32 v16, 0x7fffff00, v15
	v_bitop3_b32 v15, v15, s60, v15 bitop3:0xcf
	v_not_b32_e32 v24, v2
	v_max_u32_e32 v8, v21, v41
	v_cndmask_b32_e32 v39, v15, v16, vcc
; DEV float keyf(unsigned k) { const unsigned u = (k & 0x80000000u) ? (k & 0x7fffffffu) : ~k; return __uint_as_float(u); }
; DEV void topk_group(int hg, const float* scoresT, int* idxo, float* go) {
;     ...
;   const float smax = keyf(LC[0] & ~255u);
;   float ev[16], sum = 0.f;
; #pragma unroll
;   for (int k = 0; k < 16; ++k) { ev[k] = __expf(keyf(LC[k] & ~255u) - smax); sum += ev[k]; }
;   const float inv = 1.f / sum;
;   const int head = hg * 4 + hl;
; #pragma unroll
;   for (int k = 0; k < 16; ++k) {
;     const int c = 255 - (int)(LC[k] & 255u), i = c >> 4, j = c & 15;
;     const int i1 = 127 - (int)(la[i * 512 + tid] & 127u), i2 = 127 - (int)(lb[j * 512 + tid] & 127u);
;     idxo[token * 128 + head * 16 + k] = i1 * 128 + i2;
;     go[token * 128 + head * 16 + k] = ev[k] * inv;
;   }
	v_cmp_gt_i32_e32 vcc, 0, v2
	v_and_b32_e32 v15, 0x7fffff00, v2
	v_bitop3_b32 v2, v2, s60, v2 bitop3:0xcf
	v_not_b32_e32 v22, v8
	v_cndmask_b32_e32 v2, v2, v15, vcc
	v_cmp_gt_i32_e32 vcc, 0, v8
	v_and_b32_e32 v15, 0x7fffff00, v8
	v_bitop3_b32 v8, v8, s60, v8 bitop3:0xcf
	v_cndmask_b32_e32 v8, v8, v15, vcc
	v_and_b32_e32 v15, 0xffffff00, v17
	v_not_b32_e32 v9, v17
	v_cmp_gt_i32_e32 vcc, 0, v17
	v_and_b32_e32 v17, 0x7fffff00, v17
	v_xor_b32_e32 v15, -1, v15
	v_min_u32_e32 v42, v21, v41
	v_cndmask_b32_e32 v41, v15, v17, vcc
	v_sub_f32_e32 v15, v41, v41
	v_mul_f32_e32 v15, 0x3fb8aa3b, v15
	v_sub_f32_e32 v10, v10, v41
	v_and_b32_e32 v16, 0xffffff00, v42
	v_exp_f32_e32 v20, v15
	v_mul_f32_e32 v10, 0x3fb8aa3b, v10
	v_sub_f32_e32 v12, v12, v41
	v_cmp_gt_i32_e64 s[6:7], 0, v42
	v_and_b32_e32 v18, 0x7fffff00, v42
	v_xor_b32_e32 v16, -1, v16
	v_exp_f32_e32 v21, v10
	v_mul_f32_e32 v12, 0x3fb8aa3b, v12
	v_sub_f32_e32 v5, v5, v41
	v_cndmask_b32_e64 v40, v16, v18, s[6:7]
	v_exp_f32_e32 v18, v12
	v_mul_f32_e32 v5, 0x3fb8aa3b, v5
	v_exp_f32_e32 v19, v5
	v_add_f32_e32 v15, 0, v20
	v_add_f32_e32 v10, v21, v15
	v_add_f32_e32 v10, v18, v10
	v_add_f32_e32 v5, v19, v10
	v_sub_f32_e32 v10, v14, v41
	v_mul_f32_e32 v10, 0x3fb8aa3b, v10
	v_sub_f32_e32 v6, v6, v41
	v_exp_f32_e32 v16, v10
	v_mul_f32_e32 v6, 0x3fb8aa3b, v6
	v_sub_f32_e32 v4, v4, v41
	v_exp_f32_e32 v17, v6
	v_mul_f32_e32 v4, 0x3fb8aa3b, v4
	v_sub_f32_e32 v0, v0, v41
	v_exp_f32_e32 v14, v4
	v_mul_f32_e32 v0, 0x3fb8aa3b, v0
	v_exp_f32_e32 v15, v0
	v_add_f32_e32 v5, v16, v5
	v_add_f32_e32 v5, v17, v5
	v_add_f32_e32 v4, v14, v5
	v_add_f32_e32 v0, v15, v4
	v_sub_f32_e32 v4, v38, v41
	v_mul_f32_e32 v4, 0x3fb8aa3b, v4
	v_exp_f32_e32 v12, v4
	v_sub_f32_e32 v4, v13, v41
	v_mul_f32_e32 v4, 0x3fb8aa3b, v4
	v_sub_f32_e32 v1, v1, v41
	v_exp_f32_e32 v13, v4
	v_sub_f32_e32 v4, v7, v41
	v_mul_f32_e32 v1, 0x3fb8aa3b, v1
	v_mul_f32_e32 v4, 0x3fb8aa3b, v4
	v_exp_f32_e32 v7, v1
	v_sub_f32_e32 v1, v39, v41
	v_exp_f32_e32 v6, v4
	v_mul_f32_e32 v1, 0x3fb8aa3b, v1
	v_exp_f32_e32 v4, v1
	v_sub_f32_e32 v1, v2, v41
	v_add_f32_e32 v0, v12, v0
	v_mul_f32_e32 v1, 0x3fb8aa3b, v1
	v_add_f32_e32 v0, v13, v0
	v_exp_f32_e32 v5, v1
	v_add_f32_e32 v0, v6, v0
	v_add_f32_e32 v0, v7, v0
	v_add_f32_e32 v0, v4, v0
	v_add_f32_e32 v1, v5, v0
	v_sub_f32_e32 v0, v8, v41
	v_mul_f32_e32 v0, 0x3fb8aa3b, v0
	v_exp_f32_e32 v0, v0
	v_not_b32_e32 v3, v42
	v_add_f32_e32 v2, v0, v1
	v_sub_f32_e32 v1, v40, v41
	v_mul_f32_e32 v1, 0x3fb8aa3b, v1
	v_exp_f32_e32 v1, v1
	s_nop 0
	v_add_f32_e32 v2, v1, v2
	v_div_scale_f32 v8, s[0:1], v2, v2, 1.0
	v_rcp_f32_e32 v10, v8
	s_lshl_b32 s0, s12, 6
	s_mov_b32 s12, 1
	v_fma_f32 v38, -v8, v10, 1.0
	v_fmac_f32_e32 v10, v38, v10
	v_div_scale_f32 v38, vcc, 1.0, v2, 1.0
	v_mul_f32_e32 v39, v38, v10
	v_fma_f32 v40, -v8, v39, v38
	v_fmac_f32_e32 v39, v40, v10
	v_fma_f32 v8, -v8, v39, v38
	v_div_fmas_f32 v8, v8, v10, v39
	v_div_fixup_f32 v2, v8, v2, 1.0
	v_lshlrev_b32_e32 v8, 7, v23
	v_lshlrev_b32_e32 v10, 4, v11
	v_add3_u32 v8, v10, s0, v8
	v_lshlrev_b32_e32 v10, 7, v9
	v_and_b32_e32 v10, 0x7800, v10
	v_lshlrev_b32_e32 v9, 11, v9
	v_add_u32_e32 v10, v26, v10
	v_and_b32_e32 v9, 0x7800, v9
	ds_read_b32 v10, v10
	v_add_u32_e32 v9, v26, v9
	ds_read_b32 v9, v9 offset:32768
	v_pk_mul_f32 v[20:21], v[20:21], v[2:3] op_sel_hi:[1,0]
	v_pk_mul_f32 v[18:19], v[18:19], v[2:3] op_sel_hi:[1,0]
	s_waitcnt lgkmcnt(1)
	v_lshlrev_b32_e32 v10, 7, v10
	v_and_b32_e32 v10, 0x3f80, v10
	s_waitcnt lgkmcnt(0)
	v_and_b32_e32 v9, 0x7f, v9
	v_bitop3_b32 v23, v9, s61, v10 bitop3:0x36
	v_ashrrev_i32_e32 v9, 31, v8
	v_lshlrev_b64 v[38:39], 2, v[8:9]
	v_lshl_add_u64 v[10:11], s[38:39], 0, v[38:39]
	v_lshlrev_b32_e32 v9, 7, v37
	flat_store_dword v[10:11], v23
	v_and_b32_e32 v9, 0x7800, v9
	v_lshlrev_b32_e32 v23, 11, v37
	v_add_u32_e32 v9, v26, v9
	v_and_b32_e32 v23, 0x7800, v23
	ds_read_b32 v9, v9
	v_add_u32_e32 v23, v26, v23
	ds_read_b32 v23, v23 offset:32768
	v_lshl_add_u64 v[38:39], s[40:41], 0, v[38:39]
	flat_store_dwordx2 v[38:39], v[20:21]
	s_waitcnt lgkmcnt(0)
	v_lshlrev_b32_e32 v9, 7, v9
	v_and_b32_e32 v9, 0x3f80, v9
	v_and_b32_e32 v23, 0x7f, v23
	v_bitop3_b32 v9, v23, s61, v9 bitop3:0x36
	flat_store_dword v[10:11], v9 offset:4
	v_lshlrev_b32_e32 v9, 7, v36
	v_and_b32_e32 v9, 0x7800, v9
	v_lshlrev_b32_e32 v20, 11, v36
	v_add_u32_e32 v9, v26, v9
	v_and_b32_e32 v20, 0x7800, v20
	ds_read_b32 v9, v9
	v_add_u32_e32 v20, v26, v20
	ds_read_b32 v20, v20 offset:32768
	v_lshlrev_b32_e32 v23, 11, v35
	v_and_b32_e32 v23, 0x7800, v23
	s_waitcnt lgkmcnt(0)
	v_lshlrev_b32_e32 v9, 7, v9
	v_and_b32_e32 v9, 0x3f80, v9
	v_and_b32_e32 v20, 0x7f, v20
	v_bitop3_b32 v9, v20, s61, v9 bitop3:0x36
	v_or_b32_e32 v20, 2, v8
	v_ashrrev_i32_e32 v21, 31, v20
	v_lshlrev_b64 v[20:21], 2, v[20:21]
	v_lshl_add_u64 v[36:37], s[38:39], 0, v[20:21]
	flat_store_dword v[36:37], v9
	v_lshlrev_b32_e32 v9, 7, v35
	v_and_b32_e32 v9, 0x7800, v9
	v_add_u32_e32 v9, v26, v9
	ds_read_b32 v9, v9
	v_add_u32_e32 v23, v26, v23
	ds_read_b32 v23, v23 offset:32768
	v_lshl_add_u64 v[20:21], s[40:41], 0, v[20:21]
	flat_store_dwordx2 v[20:21], v[18:19]
	s_waitcnt lgkmcnt(0)
	v_lshlrev_b32_e32 v9, 7, v9
	v_and_b32_e32 v9, 0x3f80, v9
	v_and_b32_e32 v23, 0x7f, v23
	v_bitop3_b32 v9, v23, s61, v9 bitop3:0x36
	flat_store_dword v[10:11], v9 offset:12
	v_lshlrev_b32_e32 v9, 7, v34
	v_and_b32_e32 v9, 0x7800, v9
	v_lshlrev_b32_e32 v18, 11, v34
	v_add_u32_e32 v9, v26, v9
	v_and_b32_e32 v18, 0x7800, v18
	ds_read_b32 v9, v9
	v_add_u32_e32 v18, v26, v18
	ds_read_b32 v18, v18 offset:32768
	v_pk_mul_f32 v[16:17], v[16:17], v[2:3] op_sel_hi:[1,0]
	v_pk_mul_f32 v[14:15], v[14:15], v[2:3] op_sel_hi:[1,0]
	s_waitcnt lgkmcnt(0)
; DEV void topk_group(int hg, const float* scoresT, int* idxo, float* go) {
;     ...
; #pragma unroll
;   for (int k = 0; k < 16; ++k) {
;     const int c = 255 - (int)(LC[k] & 255u), i = c >> 4, j = c & 15;
;     const int i1 = 127 - (int)(la[i * 512 + tid] & 127u), i2 = 127 - (int)(lb[j * 512 + tid] & 127u);
;     idxo[token * 128 + head * 16 + k] = i1 * 128 + i2;
;     go[token * 128 + head * 16 + k] = ev[k] * inv;
;   }
; DEV void chain_peer_ple(const Params& P, int l, int p) {
;     ...
;     topk_group(hg, scoresT, idxs, gs);
;     __syncthreads();
	v_lshlrev_b32_e32 v9, 7, v9
	v_and_b32_e32 v9, 0x3f80, v9
	v_and_b32_e32 v18, 0x7f, v18
	v_bitop3_b32 v9, v18, s61, v9 bitop3:0x36
	v_or_b32_e32 v18, 4, v8
	v_ashrrev_i32_e32 v19, 31, v18
	v_lshlrev_b64 v[18:19], 2, v[18:19]
	v_lshl_add_u64 v[20:21], s[38:39], 0, v[18:19]
	flat_store_dword v[20:21], v9
	v_lshlrev_b32_e32 v9, 7, v33
	v_and_b32_e32 v9, 0x7800, v9
	v_lshlrev_b32_e32 v20, 11, v33
	v_add_u32_e32 v9, v26, v9
	v_and_b32_e32 v20, 0x7800, v20
	ds_read_b32 v9, v9
	v_add_u32_e32 v20, v26, v20
	ds_read_b32 v20, v20 offset:32768
	v_lshl_add_u64 v[18:19], s[40:41], 0, v[18:19]
	flat_store_dwordx2 v[18:19], v[16:17]
	s_waitcnt lgkmcnt(0)
	v_lshlrev_b32_e32 v9, 7, v9
	v_and_b32_e32 v9, 0x3f80, v9
	v_and_b32_e32 v20, 0x7f, v20
	v_bitop3_b32 v9, v20, s61, v9 bitop3:0x36
	flat_store_dword v[10:11], v9 offset:20
	v_lshlrev_b32_e32 v9, 7, v32
	v_and_b32_e32 v9, 0x7800, v9
	v_lshlrev_b32_e32 v16, 11, v32
	v_add_u32_e32 v9, v26, v9
	v_and_b32_e32 v16, 0x7800, v16
	ds_read_b32 v9, v9
	v_add_u32_e32 v16, v26, v16
	ds_read_b32 v16, v16 offset:32768
	v_pk_mul_f32 v[12:13], v[12:13], v[2:3] op_sel_hi:[1,0]
	v_pk_mul_f32 v[6:7], v[6:7], v[2:3] op_sel_hi:[1,0]
	s_waitcnt lgkmcnt(0)
	v_lshlrev_b32_e32 v9, 7, v9
	v_and_b32_e32 v9, 0x3f80, v9
	v_and_b32_e32 v16, 0x7f, v16
	v_bitop3_b32 v9, v16, s61, v9 bitop3:0x36
	v_or_b32_e32 v16, 6, v8
	v_ashrrev_i32_e32 v17, 31, v16
	v_lshlrev_b64 v[16:17], 2, v[16:17]
	v_lshl_add_u64 v[18:19], s[38:39], 0, v[16:17]
	flat_store_dword v[18:19], v9
	v_lshlrev_b32_e32 v9, 7, v31
	v_and_b32_e32 v9, 0x7800, v9
	v_lshlrev_b32_e32 v18, 11, v31
	v_add_u32_e32 v9, v26, v9
	v_and_b32_e32 v18, 0x7800, v18
	ds_read_b32 v9, v9
	v_add_u32_e32 v18, v26, v18
	ds_read_b32 v18, v18 offset:32768
	v_lshl_add_u64 v[16:17], s[40:41], 0, v[16:17]
	flat_store_dwordx2 v[16:17], v[14:15]
	s_waitcnt lgkmcnt(0)
	v_lshlrev_b32_e32 v9, 7, v9
	v_and_b32_e32 v9, 0x3f80, v9
	v_and_b32_e32 v18, 0x7f, v18
	v_bitop3_b32 v9, v18, s61, v9 bitop3:0x36
	flat_store_dword v[10:11], v9 offset:28
	v_lshlrev_b32_e32 v9, 7, v30
	v_and_b32_e32 v9, 0x7800, v9
	v_lshlrev_b32_e32 v14, 11, v30
	v_add_u32_e32 v9, v26, v9
	v_and_b32_e32 v14, 0x7800, v14
	ds_read_b32 v9, v9
	v_add_u32_e32 v14, v26, v14
	ds_read_b32 v14, v14 offset:32768
	v_pk_mul_f32 v[4:5], v[4:5], v[2:3] op_sel_hi:[1,0]
	s_mov_b64 s[0:1], 0
	s_waitcnt lgkmcnt(0)
	v_lshlrev_b32_e32 v9, 7, v9
	v_and_b32_e32 v9, 0x3f80, v9
	v_and_b32_e32 v14, 0x7f, v14
	v_bitop3_b32 v9, v14, s61, v9 bitop3:0x36
	v_or_b32_e32 v14, 8, v8
	v_ashrrev_i32_e32 v15, 31, v14
	v_lshlrev_b64 v[14:15], 2, v[14:15]
	v_lshl_add_u64 v[16:17], s[38:39], 0, v[14:15]
	flat_store_dword v[16:17], v9
	v_lshlrev_b32_e32 v9, 7, v29
	v_and_b32_e32 v9, 0x7800, v9
	v_lshlrev_b32_e32 v16, 11, v29
	v_add_u32_e32 v9, v26, v9
	v_and_b32_e32 v16, 0x7800, v16
	ds_read_b32 v9, v9
	v_add_u32_e32 v16, v26, v16
	ds_read_b32 v16, v16 offset:32768
	v_lshl_add_u64 v[14:15], s[40:41], 0, v[14:15]
	flat_store_dwordx2 v[14:15], v[12:13]
	s_waitcnt lgkmcnt(0)
	v_lshlrev_b32_e32 v9, 7, v9
	v_and_b32_e32 v9, 0x3f80, v9
	v_and_b32_e32 v16, 0x7f, v16
	v_bitop3_b32 v9, v16, s61, v9 bitop3:0x36
	flat_store_dword v[10:11], v9 offset:36
	v_lshlrev_b32_e32 v9, 7, v28
	v_and_b32_e32 v9, 0x7800, v9
	v_lshlrev_b32_e32 v12, 11, v28
	v_add_u32_e32 v9, v26, v9
	v_and_b32_e32 v12, 0x7800, v12
	ds_read_b32 v9, v9
	v_add_u32_e32 v12, v26, v12
	ds_read_b32 v12, v12 offset:32768
	s_and_b64 vcc, exec, s[8:9]
	s_waitcnt lgkmcnt(0)
	v_lshlrev_b32_e32 v9, 7, v9
	v_and_b32_e32 v9, 0x3f80, v9
	v_and_b32_e32 v12, 0x7f, v12
	v_bitop3_b32 v9, v12, s61, v9 bitop3:0x36
	v_or_b32_e32 v12, 10, v8
	v_ashrrev_i32_e32 v13, 31, v12
	v_lshlrev_b64 v[12:13], 2, v[12:13]
	v_lshl_add_u64 v[14:15], s[38:39], 0, v[12:13]
	flat_store_dword v[14:15], v9
	v_lshlrev_b32_e32 v9, 7, v27
	v_and_b32_e32 v9, 0x7800, v9
	v_lshlrev_b32_e32 v14, 11, v27
	v_add_u32_e32 v9, v26, v9
	v_and_b32_e32 v14, 0x7800, v14
	ds_read_b32 v9, v9
	v_add_u32_e32 v14, v26, v14
	ds_read_b32 v14, v14 offset:32768
	v_lshl_add_u64 v[12:13], s[40:41], 0, v[12:13]
	flat_store_dwordx2 v[12:13], v[6:7]
	s_waitcnt lgkmcnt(0)
	v_lshlrev_b32_e32 v9, 7, v9
	v_and_b32_e32 v9, 0x3f80, v9
	v_and_b32_e32 v14, 0x7f, v14
	v_lshlrev_b32_e32 v6, 7, v25
	v_bitop3_b32 v9, v14, s61, v9 bitop3:0x36
	v_and_b32_e32 v6, 0x7800, v6
	v_lshlrev_b32_e32 v7, 11, v25
	flat_store_dword v[10:11], v9 offset:44
	v_add_u32_e32 v6, v26, v6
	v_and_b32_e32 v7, 0x7800, v7
	ds_read_b32 v6, v6
	v_add_u32_e32 v7, v26, v7
	ds_read_b32 v7, v7 offset:32768
	s_waitcnt lgkmcnt(0)
	v_lshlrev_b32_e32 v6, 7, v6
	v_and_b32_e32 v6, 0x3f80, v6
	v_and_b32_e32 v7, 0x7f, v7
	v_bitop3_b32 v9, v7, s61, v6 bitop3:0x36
	v_or_b32_e32 v6, 12, v8
	v_ashrrev_i32_e32 v7, 31, v6
	v_lshlrev_b64 v[6:7], 2, v[6:7]
	v_lshl_add_u64 v[12:13], s[38:39], 0, v[6:7]
	flat_store_dword v[12:13], v9
	v_lshlrev_b32_e32 v9, 7, v24
	v_and_b32_e32 v9, 0x7800, v9
	v_lshlrev_b32_e32 v12, 11, v24
	v_add_u32_e32 v9, v26, v9
	v_and_b32_e32 v12, 0x7800, v12
	ds_read_b32 v9, v9
	v_add_u32_e32 v12, v26, v12
	ds_read_b32 v12, v12 offset:32768
	v_lshl_add_u64 v[6:7], s[40:41], 0, v[6:7]
	flat_store_dwordx2 v[6:7], v[4:5]
	s_waitcnt lgkmcnt(0)
	v_lshlrev_b32_e32 v9, 7, v9
	v_and_b32_e32 v9, 0x3f80, v9
	v_and_b32_e32 v12, 0x7f, v12
	v_lshlrev_b32_e32 v4, 7, v22
	v_bitop3_b32 v9, v12, s61, v9 bitop3:0x36
	v_and_b32_e32 v4, 0x7800, v4
	v_lshlrev_b32_e32 v5, 11, v22
	flat_store_dword v[10:11], v9 offset:52
	v_add_u32_e32 v4, v26, v4
	v_and_b32_e32 v5, 0x7800, v5
	ds_read_b32 v4, v4
	v_add_u32_e32 v5, v26, v5
	ds_read_b32 v5, v5 offset:32768
	s_waitcnt lgkmcnt(0)
	v_lshlrev_b32_e32 v4, 7, v4
	v_and_b32_e32 v4, 0x3f80, v4
	v_and_b32_e32 v5, 0x7f, v5
	v_bitop3_b32 v9, v5, s61, v4 bitop3:0x36
	v_or_b32_e32 v4, 14, v8
	v_ashrrev_i32_e32 v5, 31, v4
	v_lshlrev_b64 v[4:5], 2, v[4:5]
	v_lshl_add_u64 v[6:7], s[38:39], 0, v[4:5]
	flat_store_dword v[6:7], v9
	v_lshlrev_b32_e32 v6, 7, v3
	v_and_b32_e32 v6, 0x7800, v6
	v_lshlrev_b32_e32 v3, 11, v3
	v_add_u32_e32 v6, v26, v6
	v_and_b32_e32 v3, 0x7800, v3
	ds_read_b32 v6, v6
	v_add_u32_e32 v3, v26, v3
	ds_read_b32 v3, v3 offset:32768
	v_lshl_add_u64 v[4:5], s[40:41], 0, v[4:5]
	s_waitcnt lgkmcnt(0)
	v_lshlrev_b32_e32 v6, 7, v6
	v_and_b32_e32 v6, 0x3f80, v6
	v_and_b32_e32 v3, 0x7f, v3
	v_bitop3_b32 v3, v3, s61, v6 bitop3:0x36
	v_pk_mul_f32 v[0:1], v[0:1], v[2:3] op_sel_hi:[1,0]
	flat_store_dword v[10:11], v3 offset:60
	flat_store_dwordx2 v[4:5], v[0:1]
	s_waitcnt lgkmcnt(0)
	s_barrier
	s_cbranch_vccnz .LBB0_311

; DEV void p5_pre(const Params& P, int p) {
;     ...
;     for (int tb = 0; tb < 128; tb += 32) {
;       unsigned lv[32], uv[32], gv[32];
; #pragma unroll
;       for (int i = 0; i < 32; ++i) { lv[i] = *(const unsigned*)(la + (size_t)(m0 + tb + i) * DM + ch); uv[i] = *(const unsigned*)(ub + (size_t)(tb + i) * DM + ch); gv[i] = *(const unsigned*)(zz + (size_t)(tb + i) * 2048 + ch); }
.LBB0_709:
	s_add_i32 s4, s74, s72
	s_add_i32 s6, s4, 32
	s_ashr_i32 s7, s6, 31
	s_lshl_b64 s[66:67], s[6:7], 11
	v_lshl_add_u64 v[8:9], v[2:3], 0, s[66:67]
	flat_load_dword v85, v[8:9]
	v_lshl_add_u64 v[8:9], s[0:1], 0, v[0:1]
	v_add_co_u32_e32 v12, vcc, 0x10c80000, v8
	v_lshl_add_u64 v[10:11], s[2:3], 0, v[0:1]
	s_nop 0
	v_addc_co_u32_e32 v13, vcc, 0, v9, vcc
	s_add_i32 s6, s4, 33
	v_add_co_u32_e32 v14, vcc, 0x10c00000, v10
	s_ashr_i32 s7, s6, 31
	s_nop 0
	v_addc_co_u32_e32 v15, vcc, 0, v11, vcc
	s_lshl_b64 s[68:69], s[6:7], 11
	flat_load_dword v89, v[14:15]
	v_lshl_add_u64 v[14:15], v[2:3], 0, s[68:69]
	s_add_i32 s6, s4, 34
	flat_load_dword v88, v[12:13]
	flat_load_dword v90, v[14:15]
	flat_load_dword v91, v[12:13] offset:2048
	v_add_co_u32_e32 v12, vcc, 0x10c01000, v10
	s_ashr_i32 s7, s6, 31
	s_nop 0
	v_addc_co_u32_e32 v13, vcc, 0, v11, vcc
	s_lshl_b64 s[64:65], s[6:7], 11
	flat_load_dword v92, v[12:13]
	v_lshl_add_u64 v[12:13], v[2:3], 0, s[64:65]
	flat_load_dword v93, v[12:13]
	v_add_co_u32_e32 v12, vcc, 0x10c81000, v8
	s_add_i32 s6, s4, 35
	s_nop 0
	v_addc_co_u32_e32 v13, vcc, 0, v9, vcc
	v_add_co_u32_e32 v14, vcc, 0x10c02000, v10
	s_ashr_i32 s7, s6, 31
	s_nop 0
	v_addc_co_u32_e32 v15, vcc, 0, v11, vcc
	s_lshl_b64 s[62:63], s[6:7], 11
	flat_load_dword v95, v[14:15]
	v_lshl_add_u64 v[14:15], v[2:3], 0, s[62:63]
	s_add_i32 s6, s4, 36
	flat_load_dword v94, v[12:13]
	flat_load_dword v96, v[14:15]
	flat_load_dword v97, v[12:13] offset:2048
	v_add_co_u32_e32 v12, vcc, 0x10c03000, v10
	s_ashr_i32 s7, s6, 31
	s_nop 0
	v_addc_co_u32_e32 v13, vcc, 0, v11, vcc
	s_lshl_b64 s[60:61], s[6:7], 11
	flat_load_dword v98, v[12:13]
	v_lshl_add_u64 v[12:13], v[2:3], 0, s[60:61]
	flat_load_dword v99, v[12:13]
	v_add_co_u32_e32 v12, vcc, 0x10c82000, v8
	s_add_i32 s6, s4, 37
	s_nop 0
	v_addc_co_u32_e32 v13, vcc, 0, v9, vcc
	v_add_co_u32_e32 v14, vcc, 0x10c04000, v10
	s_ashr_i32 s7, s6, 31
	s_nop 0
	v_addc_co_u32_e32 v15, vcc, 0, v11, vcc
	s_lshl_b64 s[58:59], s[6:7], 11
	flat_load_dword v101, v[14:15]
	v_lshl_add_u64 v[14:15], v[2:3], 0, s[58:59]
	s_add_i32 s6, s4, 38
	flat_load_dword v100, v[12:13]
	flat_load_dword v102, v[14:15]
	flat_load_dword v103, v[12:13] offset:2048
	v_add_co_u32_e32 v12, vcc, 0x10c05000, v10
	s_ashr_i32 s7, s6, 31
	s_nop 0
	v_addc_co_u32_e32 v13, vcc, 0, v11, vcc
	s_lshl_b64 s[56:57], s[6:7], 11
	flat_load_dword v104, v[12:13]
	v_lshl_add_u64 v[12:13], v[2:3], 0, s[56:57]
	flat_load_dword v105, v[12:13]
	v_add_co_u32_e32 v12, vcc, 0x10c83000, v8
	s_add_i32 s6, s4, 39
	s_nop 0
	v_addc_co_u32_e32 v13, vcc, 0, v9, vcc
	v_add_co_u32_e32 v14, vcc, 0x10c06000, v10
	s_ashr_i32 s7, s6, 31
	s_nop 0
	v_addc_co_u32_e32 v15, vcc, 0, v11, vcc
	s_lshl_b64 s[54:55], s[6:7], 11
	flat_load_dword v107, v[14:15]
	v_lshl_add_u64 v[14:15], v[2:3], 0, s[54:55]
	s_add_i32 s6, s4, 40
	flat_load_dword v106, v[12:13]
	flat_load_dword v83, v[14:15]
	flat_load_dword v82, v[12:13] offset:2048
	v_add_co_u32_e32 v12, vcc, 0x10c07000, v10
	s_ashr_i32 s7, s6, 31
	s_nop 0
	v_addc_co_u32_e32 v13, vcc, 0, v11, vcc
	s_lshl_b64 s[52:53], s[6:7], 11
	flat_load_dword v84, v[12:13]
	v_lshl_add_u64 v[12:13], v[2:3], 0, s[52:53]
	flat_load_dword v79, v[12:13]
	v_add_co_u32_e32 v12, vcc, 0x10c84000, v8
	s_add_i32 s6, s4, 41
	s_nop 0
	v_addc_co_u32_e32 v13, vcc, 0, v9, vcc
	v_add_co_u32_e32 v14, vcc, 0x10c08000, v10
	s_ashr_i32 s7, s6, 31
	s_nop 0
	v_addc_co_u32_e32 v15, vcc, 0, v11, vcc
	s_lshl_b64 s[50:51], s[6:7], 11
	flat_load_dword v81, v[14:15]
	v_lshl_add_u64 v[14:15], v[2:3], 0, s[50:51]
	s_add_i32 s6, s4, 42
	flat_load_dword v80, v[12:13]
	flat_load_dword v77, v[14:15]
	flat_load_dword v76, v[12:13] offset:2048
	v_add_co_u32_e32 v12, vcc, 0x10c09000, v10
	s_ashr_i32 s7, s6, 31
	s_nop 0
	v_addc_co_u32_e32 v13, vcc, 0, v11, vcc
	s_lshl_b64 s[48:49], s[6:7], 11
	flat_load_dword v78, v[12:13]
	v_lshl_add_u64 v[12:13], v[2:3], 0, s[48:49]
	flat_load_dword v73, v[12:13]
	v_add_co_u32_e32 v12, vcc, 0x10c85000, v8
	s_add_i32 s6, s4, 43
	s_nop 0
	v_addc_co_u32_e32 v13, vcc, 0, v9, vcc
	v_add_co_u32_e32 v14, vcc, 0x10c0a000, v10
	s_ashr_i32 s7, s6, 31
	s_nop 0
	v_addc_co_u32_e32 v15, vcc, 0, v11, vcc
	s_lshl_b64 s[46:47], s[6:7], 11
	flat_load_dword v75, v[14:15]
	v_lshl_add_u64 v[14:15], v[2:3], 0, s[46:47]
	s_add_i32 s6, s4, 44
	flat_load_dword v74, v[12:13]
	flat_load_dword v71, v[14:15]
	flat_load_dword v70, v[12:13] offset:2048
	v_add_co_u32_e32 v12, vcc, 0x10c0b000, v10
	s_ashr_i32 s7, s6, 31
	s_nop 0
	v_addc_co_u32_e32 v13, vcc, 0, v11, vcc
	s_lshl_b64 s[44:45], s[6:7], 11
	flat_load_dword v72, v[12:13]
	v_lshl_add_u64 v[12:13], v[2:3], 0, s[44:45]
	flat_load_dword v67, v[12:13]
	v_add_co_u32_e32 v12, vcc, 0x10c86000, v8
	s_add_i32 s6, s4, 45
	s_nop 0
	v_addc_co_u32_e32 v13, vcc, 0, v9, vcc
	v_add_co_u32_e32 v14, vcc, 0x10c0c000, v10
	s_ashr_i32 s7, s6, 31
	s_nop 0
	v_addc_co_u32_e32 v15, vcc, 0, v11, vcc
	s_lshl_b64 s[42:43], s[6:7], 11
	flat_load_dword v69, v[14:15]
	v_lshl_add_u64 v[14:15], v[2:3], 0, s[42:43]
	s_add_i32 s6, s4, 46
	flat_load_dword v68, v[12:13]
	flat_load_dword v65, v[14:15]
	flat_load_dword v64, v[12:13] offset:2048
	v_add_co_u32_e32 v12, vcc, 0x10c0d000, v10
	s_ashr_i32 s7, s6, 31
	s_nop 0
	v_addc_co_u32_e32 v13, vcc, 0, v11, vcc
	s_lshl_b64 s[40:41], s[6:7], 11
	flat_load_dword v66, v[12:13]
	v_lshl_add_u64 v[12:13], v[2:3], 0, s[40:41]
	flat_load_dword v61, v[12:13]
	v_add_co_u32_e32 v12, vcc, 0x10c87000, v8
	s_add_i32 s6, s4, 47
	s_nop 0
	v_addc_co_u32_e32 v13, vcc, 0, v9, vcc
	v_add_co_u32_e32 v14, vcc, 0x10c0e000, v10
	s_ashr_i32 s7, s6, 31
	s_nop 0
	v_addc_co_u32_e32 v15, vcc, 0, v11, vcc
	s_lshl_b64 s[38:39], s[6:7], 11
; DEV void p5_pre(const Params& P, int p) {
;     ...
;       for (int i = 0; i < 32; ++i) { lv[i] = *(const unsigned*)(la + (size_t)(m0 + tb + i) * DM + ch); uv[i] = *(const unsigned*)(ub + (size_t)(tb + i) * DM + ch); gv[i] = *(const unsigned*)(zz + (size_t)(tb + i) * 2048 + ch); }
	flat_load_dword v63, v[14:15]
	v_lshl_add_u64 v[14:15], v[2:3], 0, s[38:39]
	s_add_i32 s6, s4, 48
	flat_load_dword v62, v[12:13]
	flat_load_dword v59, v[14:15]
	flat_load_dword v58, v[12:13] offset:2048
	v_add_co_u32_e32 v12, vcc, 0x10c0f000, v10
	s_ashr_i32 s7, s6, 31
	s_nop 0
	v_addc_co_u32_e32 v13, vcc, 0, v11, vcc
	s_lshl_b64 s[36:37], s[6:7], 11
	flat_load_dword v60, v[12:13]
	v_lshl_add_u64 v[12:13], v[2:3], 0, s[36:37]
	flat_load_dword v55, v[12:13]
	v_add_co_u32_e32 v12, vcc, 0x10c88000, v8
	s_add_i32 s6, s4, 49
	s_nop 0
	v_addc_co_u32_e32 v13, vcc, 0, v9, vcc
	v_add_co_u32_e32 v14, vcc, 0x10c10000, v10
	s_ashr_i32 s7, s6, 31
	s_nop 0
	v_addc_co_u32_e32 v15, vcc, 0, v11, vcc
	s_lshl_b64 s[34:35], s[6:7], 11
	flat_load_dword v57, v[14:15]
	v_lshl_add_u64 v[14:15], v[2:3], 0, s[34:35]
	s_add_i32 s6, s4, 50
	flat_load_dword v56, v[12:13]
	flat_load_dword v53, v[14:15]
	flat_load_dword v52, v[12:13] offset:2048
	v_add_co_u32_e32 v12, vcc, 0x10c11000, v10
	s_ashr_i32 s7, s6, 31
	s_nop 0
	v_addc_co_u32_e32 v13, vcc, 0, v11, vcc
	s_lshl_b64 s[30:31], s[6:7], 11
	flat_load_dword v54, v[12:13]
	v_lshl_add_u64 v[12:13], v[2:3], 0, s[30:31]
	flat_load_dword v49, v[12:13]
	v_add_co_u32_e32 v12, vcc, 0x10c89000, v8
	s_add_i32 s6, s4, 51
	s_nop 0
	v_addc_co_u32_e32 v13, vcc, 0, v9, vcc
	v_add_co_u32_e32 v14, vcc, 0x10c12000, v10
	s_ashr_i32 s7, s6, 31
	s_nop 0
	v_addc_co_u32_e32 v15, vcc, 0, v11, vcc
	s_lshl_b64 s[28:29], s[6:7], 11
	flat_load_dword v51, v[14:15]
	v_lshl_add_u64 v[14:15], v[2:3], 0, s[28:29]
	s_add_i32 s6, s4, 52
	flat_load_dword v50, v[12:13]
	flat_load_dword v47, v[14:15]
	flat_load_dword v46, v[12:13] offset:2048
	v_add_co_u32_e32 v12, vcc, 0x10c13000, v10
	s_ashr_i32 s7, s6, 31
	s_nop 0
	v_addc_co_u32_e32 v13, vcc, 0, v11, vcc
	s_lshl_b64 s[26:27], s[6:7], 11
	flat_load_dword v48, v[12:13]
	v_lshl_add_u64 v[12:13], v[2:3], 0, s[26:27]
	flat_load_dword v43, v[12:13]
	v_add_co_u32_e32 v12, vcc, 0x10c8a000, v8
	s_add_i32 s6, s4, 53
	s_nop 0
	v_addc_co_u32_e32 v13, vcc, 0, v9, vcc
	v_add_co_u32_e32 v14, vcc, 0x10c14000, v10
	s_ashr_i32 s7, s6, 31
	s_nop 0
	v_addc_co_u32_e32 v15, vcc, 0, v11, vcc
	s_lshl_b64 s[24:25], s[6:7], 11
	flat_load_dword v45, v[14:15]
	v_lshl_add_u64 v[14:15], v[2:3], 0, s[24:25]
	s_add_i32 s6, s4, 54
	flat_load_dword v44, v[12:13]
	flat_load_dword v41, v[14:15]
	flat_load_dword v40, v[12:13] offset:2048
	v_add_co_u32_e32 v12, vcc, 0x10c15000, v10
	s_ashr_i32 s7, s6, 31
	s_nop 0
	v_addc_co_u32_e32 v13, vcc, 0, v11, vcc
	s_lshl_b64 s[22:23], s[6:7], 11
	flat_load_dword v42, v[12:13]
	v_lshl_add_u64 v[12:13], v[2:3], 0, s[22:23]
	flat_load_dword v37, v[12:13]
	v_add_co_u32_e32 v12, vcc, 0x10c8b000, v8
	s_add_i32 s6, s4, 55
	s_nop 0
	v_addc_co_u32_e32 v13, vcc, 0, v9, vcc
	v_add_co_u32_e32 v14, vcc, 0x10c16000, v10
	s_ashr_i32 s7, s6, 31
	s_nop 0
	v_addc_co_u32_e32 v15, vcc, 0, v11, vcc
	s_lshl_b64 s[20:21], s[6:7], 11
	flat_load_dword v39, v[14:15]
	v_lshl_add_u64 v[14:15], v[2:3], 0, s[20:21]
	s_add_i32 s6, s4, 56
	flat_load_dword v38, v[12:13]
	flat_load_dword v35, v[14:15]
	flat_load_dword v34, v[12:13] offset:2048
	v_add_co_u32_e32 v12, vcc, 0x10c17000, v10
	s_ashr_i32 s7, s6, 31
	s_nop 0
	v_addc_co_u32_e32 v13, vcc, 0, v11, vcc
	s_lshl_b64 s[18:19], s[6:7], 11
	flat_load_dword v36, v[12:13]
	v_lshl_add_u64 v[12:13], v[2:3], 0, s[18:19]
	flat_load_dword v31, v[12:13]
	v_add_co_u32_e32 v12, vcc, 0x10c8c000, v8
	s_add_i32 s6, s4, 57
	s_nop 0
	v_addc_co_u32_e32 v13, vcc, 0, v9, vcc
	v_add_co_u32_e32 v14, vcc, 0x10c18000, v10
	s_ashr_i32 s7, s6, 31
	s_nop 0
	v_addc_co_u32_e32 v15, vcc, 0, v11, vcc
	s_lshl_b64 s[10:11], s[6:7], 11
	flat_load_dword v33, v[14:15]
	v_lshl_add_u64 v[14:15], v[2:3], 0, s[10:11]
	flat_load_dword v32, v[12:13]
	flat_load_dword v29, v[14:15]
	flat_load_dword v28, v[12:13] offset:2048
	v_add_co_u32_e32 v12, vcc, 0x10c19000, v10
	s_add_i32 s6, s4, 58
	s_nop 0
	v_addc_co_u32_e32 v13, vcc, 0, v11, vcc
	v_add_co_u32_e32 v18, vcc, 0x10c8d000, v8
	s_add_i32 s8, s4, 59
	s_nop 0
	v_addc_co_u32_e32 v19, vcc, 0, v9, vcc
	s_ashr_i32 s7, s6, 31
	v_add_co_u32_e32 v16, vcc, 0x10c1a000, v10
	s_ashr_i32 s9, s8, 31
	s_lshl_b64 s[6:7], s[6:7], 11
	v_addc_co_u32_e32 v17, vcc, 0, v11, vcc
	s_lshl_b64 s[12:13], s[8:9], 11
	flat_load_dword v30, v[12:13]
	flat_load_dword v21, v[16:17]
	v_lshl_add_u64 v[12:13], v[2:3], 0, s[6:7]
	v_lshl_add_u64 v[16:17], v[2:3], 0, s[12:13]
	flat_load_dword v12, v[12:13]
	s_add_i32 s8, s4, 60
	flat_load_dword v14, v[18:19]
	s_nop 0
	flat_load_dword v17, v[16:17]
	s_nop 0
	flat_load_dword v13, v[18:19] offset:2048
	v_add_co_u32_e32 v18, vcc, 0x10c1b000, v10
	s_ashr_i32 s9, s8, 31
	s_nop 0
	v_addc_co_u32_e32 v19, vcc, 0, v11, vcc
	s_lshl_b64 s[8:9], s[8:9], 11
	v_add_co_u32_e32 v26, vcc, 0x10c8e000, v8
	v_lshl_add_u64 v[22:23], v[2:3], 0, s[8:9]
	s_nop 0
	v_addc_co_u32_e32 v27, vcc, 0, v9, vcc
	s_add_i32 s14, s4, 61
	flat_load_dword v15, v[22:23]
	v_add_co_u32_e32 v22, vcc, 0x10c1c000, v10
	s_ashr_i32 s15, s14, 31
	s_nop 0
	v_addc_co_u32_e32 v23, vcc, 0, v11, vcc
	s_lshl_b64 s[16:17], s[14:15], 11
	flat_load_dword v25, v[22:23]
	v_lshl_add_u64 v[22:23], v[2:3], 0, s[16:17]
	flat_load_dword v18, v[18:19]
	s_add_i32 s14, s4, 62
	flat_load_dword v19, v[26:27]
	s_nop 0
	flat_load_dword v22, v[22:23]
	s_nop 0
	flat_load_dword v16, v[26:27] offset:2048
	v_add_co_u32_e32 v26, vcc, 0x10c1d000, v10
	s_ashr_i32 s15, s14, 31
	s_nop 0
	v_addc_co_u32_e32 v27, vcc, 0, v11, vcc
	s_lshl_b64 s[14:15], s[14:15], 11
	v_add_co_u32_e32 v8, vcc, 0x10c8f000, v8
	flat_load_dword v23, v[26:27]
	v_lshl_add_u64 v[26:27], v[2:3], 0, s[14:15]
	v_addc_co_u32_e32 v9, vcc, 0, v9, vcc
	flat_load_dword v20, v[26:27]
	v_add_co_u32_e32 v26, vcc, 0x10c1e000, v10
	s_add_i32 s4, s4, 63
	s_nop 0
	v_addc_co_u32_e32 v27, vcc, 0, v11, vcc
	s_ashr_i32 s5, s4, 31
	s_lshl_b64 s[4:5], s[4:5], 11
	v_add_co_u32_e32 v10, vcc, 0x10c1f000, v10
	v_lshl_add_u64 v[86:87], v[2:3], 0, s[4:5]
	s_nop 0
	v_addc_co_u32_e32 v11, vcc, 0, v11, vcc
	flat_load_dword v24, v[8:9]
	s_add_i32 s72, s72, 32
	flat_load_dword v27, v[26:27]
	s_nop 0
	flat_load_dword v26, v[86:87]
	s_nop 0
	flat_load_dword v9, v[8:9] offset:2048
	flat_load_dword v233, v[10:11]
	s_waitcnt vmcnt(0) lgkmcnt(0)
; DEV unsigned pk2(float lo, float hi) { f32x2_t v = {lo, hi}; bf16x2_t b = __builtin_convertvector(v, bf16x2_t); return __builtin_bit_cast(unsigned, b); }
; DEV float bflo(unsigned u) { return __uint_as_float(u << 16); }
; DEV float bfhi(unsigned u) { return __uint_as_float(u & 0xffff0000u); }
; DEV float gelu_tanh(float x) { const float u = 1.5957691216057308f * (x + 0.044715f * x * x * x); return x * __builtin_amdgcn_rcpf(1.f + __expf(-u)); }
; DEV void p5_pre(const Params& P, int p) {
;     ...
; #pragma unroll
;       for (int i = 0; i < 32; ++i) {
;         Ha = __expf(bflo(lv[i])) * Ha + bflo(uv[i]); Hb = __expf(bfhi(lv[i])) * Hb + bfhi(uv[i]);
;         *(unsigned*)(y + (size_t)(m0 + tb + i) * DM + ch) = pk2(Ha * gelu_tanh(bflo(gv[i])), Hb * gelu_tanh(bfhi(gv[i])));
;       }
	v_lshlrev_b32_e32 v86, 16, v88
	v_lshlrev_b32_e32 v10, 16, v85
	v_and_b32_e32 v11, 0xffff0000, v85
	v_mul_f32_e32 v10, 0x3fb8aa3b, v10
	v_mul_f32_e32 v11, 0x3fb8aa3b, v11
	v_exp_f32_e32 v10, v10
	v_exp_f32_e32 v11, v11
	v_and_b32_e32 v87, 0xffff0000, v88
	v_lshlrev_b32_e32 v88, 16, v89
	v_and_b32_e32 v89, 0xffff0000, v89
	v_pk_fma_f32 v[6:7], v[6:7], v[10:11], v[86:87]
	v_mul_f32_e32 v10, 0x3d372713, v88
	v_mul_f32_e32 v10, v10, v88
	v_mov_b32_e32 v11, v88
	v_fmac_f32_e32 v11, v10, v11
	v_mul_f32_e32 v10, 0xbfcc422a, v11
	v_mul_f32_e32 v11, 0x3d372713, v89
	v_mul_f32_e32 v11, v11, v89
	v_mov_b32_e32 v85, v89
	v_fmac_f32_e32 v85, v11, v85
	v_mul_f32_e32 v11, 0xbfcc422a, v85
	v_mul_f32_e32 v10, 0x3fb8aa3b, v10
	v_mul_f32_e32 v11, 0x3fb8aa3b, v11
	v_exp_f32_e32 v10, v10
	v_exp_f32_e32 v11, v11
	v_lshlrev_b32_e32 v86, 16, v91
	v_and_b32_e32 v87, 0xffff0000, v91
	v_add_f32_e32 v10, 1.0, v10
	v_add_f32_e32 v11, 1.0, v11
	v_rcp_f32_e32 v10, v10
	v_rcp_f32_e32 v11, v11
	s_add_u32 s2, s2, 0x20000
	s_addc_u32 s3, s3, 0
	s_add_u32 s0, s0, 0x10000
	v_pk_mul_f32 v[10:11], v[10:11], v[88:89]
	v_lshlrev_b32_e32 v88, 16, v92
	v_pk_mul_f32 v[10:11], v[6:7], v[10:11]
	v_and_b32_e32 v89, 0xffff0000, v92
	v_cvt_pk_bf16_f32 v85, v10, v11
	v_lshl_add_u64 v[10:11], v[4:5], 0, s[66:67]
	flat_store_dword v[10:11], v85
	v_lshlrev_b32_e32 v10, 16, v90
	v_and_b32_e32 v11, 0xffff0000, v90
	v_mul_f32_e32 v10, 0x3fb8aa3b, v10
	v_mul_f32_e32 v11, 0x3fb8aa3b, v11
	v_exp_f32_e32 v10, v10
	v_exp_f32_e32 v11, v11
	v_mov_b32_e32 v85, v89
	s_addc_u32 s1, s1, 0
	s_cmpk_lt_u32 s72, 0x60
	v_pk_fma_f32 v[6:7], v[6:7], v[10:11], v[86:87]
	v_mul_f32_e32 v10, 0x3d372713, v88
	v_mul_f32_e32 v10, v10, v88
	v_mov_b32_e32 v11, v88
	v_fmac_f32_e32 v11, v10, v11
	v_mul_f32_e32 v10, 0xbfcc422a, v11
	v_mul_f32_e32 v11, 0x3d372713, v89
	v_mul_f32_e32 v11, v11, v89
	v_fmac_f32_e32 v85, v11, v85
	v_mul_f32_e32 v11, 0xbfcc422a, v85
	v_mul_f32_e32 v10, 0x3fb8aa3b, v10
	v_mul_f32_e32 v11, 0x3fb8aa3b, v11
	v_exp_f32_e32 v10, v10
	v_exp_f32_e32 v11, v11
	v_lshlrev_b32_e32 v86, 16, v94
	v_and_b32_e32 v87, 0xffff0000, v94
	v_add_f32_e32 v10, 1.0, v10
	v_add_f32_e32 v11, 1.0, v11
	v_rcp_f32_e32 v10, v10
	v_rcp_f32_e32 v11, v11
	s_nop 0
	v_pk_mul_f32 v[10:11], v[10:11], v[88:89]
	s_nop 0
	v_pk_mul_f32 v[10:11], v[6:7], v[10:11]
	v_lshlrev_b32_e32 v88, 16, v95
	v_cvt_pk_bf16_f32 v85, v10, v11
	v_lshl_add_u64 v[10:11], v[4:5], 0, s[68:69]
	flat_store_dword v[10:11], v85
	v_lshlrev_b32_e32 v10, 16, v93
	v_and_b32_e32 v11, 0xffff0000, v93
	v_mul_f32_e32 v10, 0x3fb8aa3b, v10
	v_mul_f32_e32 v11, 0x3fb8aa3b, v11
	v_exp_f32_e32 v10, v10
	v_exp_f32_e32 v11, v11
	v_and_b32_e32 v89, 0xffff0000, v95
	v_mov_b32_e32 v85, v89
	v_pk_fma_f32 v[6:7], v[6:7], v[10:11], v[86:87]
	v_mul_f32_e32 v10, 0x3d372713, v88
	v_mul_f32_e32 v10, v10, v88
	v_mov_b32_e32 v11, v88
	v_fmac_f32_e32 v11, v10, v11
	v_mul_f32_e32 v10, 0xbfcc422a, v11
	v_mul_f32_e32 v11, 0x3d372713, v89
	v_mul_f32_e32 v11, v11, v89
	v_fmac_f32_e32 v85, v11, v85
	v_mul_f32_e32 v11, 0xbfcc422a, v85
	v_mul_f32_e32 v10, 0x3fb8aa3b, v10
	v_mul_f32_e32 v11, 0x3fb8aa3b, v11
	v_exp_f32_e32 v10, v10
	v_exp_f32_e32 v11, v11
	v_lshlrev_b32_e32 v86, 16, v97
	v_and_b32_e32 v87, 0xffff0000, v97
	v_add_f32_e32 v10, 1.0, v10
	v_add_f32_e32 v11, 1.0, v11
	v_rcp_f32_e32 v10, v10
	v_rcp_f32_e32 v11, v11
	s_nop 0
	v_pk_mul_f32 v[10:11], v[10:11], v[88:89]
	s_nop 0
	v_pk_mul_f32 v[10:11], v[6:7], v[10:11]
	v_lshlrev_b32_e32 v88, 16, v98
	v_cvt_pk_bf16_f32 v85, v10, v11
	v_lshl_add_u64 v[10:11], v[4:5], 0, s[64:65]
	flat_store_dword v[10:11], v85
	v_lshlrev_b32_e32 v10, 16, v96
	v_and_b32_e32 v11, 0xffff0000, v96
	v_mul_f32_e32 v10, 0x3fb8aa3b, v10
	v_mul_f32_e32 v11, 0x3fb8aa3b, v11
	v_exp_f32_e32 v10, v10
	v_exp_f32_e32 v11, v11
	v_and_b32_e32 v89, 0xffff0000, v98
	v_mov_b32_e32 v85, v89
	v_pk_fma_f32 v[6:7], v[6:7], v[10:11], v[86:87]
	v_mul_f32_e32 v10, 0x3d372713, v88
	v_mul_f32_e32 v10, v10, v88
	v_mov_b32_e32 v11, v88
	v_fmac_f32_e32 v11, v10, v11
	v_mul_f32_e32 v10, 0xbfcc422a, v11
	v_mul_f32_e32 v11, 0x3d372713, v89
	v_mul_f32_e32 v11, v11, v89
	v_fmac_f32_e32 v85, v11, v85
	v_mul_f32_e32 v11, 0xbfcc422a, v85
	v_mul_f32_e32 v10, 0x3fb8aa3b, v10
	v_mul_f32_e32 v11, 0x3fb8aa3b, v11
	v_exp_f32_e32 v10, v10
	v_exp_f32_e32 v11, v11
	v_lshlrev_b32_e32 v86, 16, v100
	v_and_b32_e32 v87, 0xffff0000, v100
	v_add_f32_e32 v10, 1.0, v10
	v_add_f32_e32 v11, 1.0, v11
	v_rcp_f32_e32 v10, v10
	v_rcp_f32_e32 v11, v11
	s_nop 0
	v_pk_mul_f32 v[10:11], v[10:11], v[88:89]
	s_nop 0
	v_pk_mul_f32 v[10:11], v[6:7], v[10:11]
	v_lshlrev_b32_e32 v88, 16, v101
	v_cvt_pk_bf16_f32 v85, v10, v11
	v_lshl_add_u64 v[10:11], v[4:5], 0, s[62:63]
	flat_store_dword v[10:11], v85
	v_lshlrev_b32_e32 v10, 16, v99
	v_and_b32_e32 v11, 0xffff0000, v99
	v_mul_f32_e32 v10, 0x3fb8aa3b, v10
	v_mul_f32_e32 v11, 0x3fb8aa3b, v11
	v_exp_f32_e32 v10, v10
	v_exp_f32_e32 v11, v11
	v_and_b32_e32 v89, 0xffff0000, v101
	v_mov_b32_e32 v85, v89
	v_pk_fma_f32 v[6:7], v[6:7], v[10:11], v[86:87]
	v_mul_f32_e32 v10, 0x3d372713, v88
	v_mul_f32_e32 v10, v10, v88
	v_mov_b32_e32 v11, v88
	v_fmac_f32_e32 v11, v10, v11
	v_mul_f32_e32 v10, 0xbfcc422a, v11
	v_mul_f32_e32 v11, 0x3d372713, v89
	v_mul_f32_e32 v11, v11, v89
	v_fmac_f32_e32 v85, v11, v85
	v_mul_f32_e32 v11, 0xbfcc422a, v85
	v_mul_f32_e32 v10, 0x3fb8aa3b, v10
	v_mul_f32_e32 v11, 0x3fb8aa3b, v11
	v_exp_f32_e32 v10, v10
	v_exp_f32_e32 v11, v11
	v_lshlrev_b32_e32 v86, 16, v103
	v_and_b32_e32 v87, 0xffff0000, v103
	v_add_f32_e32 v10, 1.0, v10
	v_add_f32_e32 v11, 1.0, v11
	v_rcp_f32_e32 v10, v10
	v_rcp_f32_e32 v11, v11
	s_nop 0
	v_pk_mul_f32 v[10:11], v[10:11], v[88:89]
	s_nop 0
; DEV unsigned pk2(float lo, float hi) { f32x2_t v = {lo, hi}; bf16x2_t b = __builtin_convertvector(v, bf16x2_t); return __builtin_bit_cast(unsigned, b); }
; DEV float bflo(unsigned u) { return __uint_as_float(u << 16); }
; DEV float bfhi(unsigned u) { return __uint_as_float(u & 0xffff0000u); }
; DEV float gelu_tanh(float x) { const float u = 1.5957691216057308f * (x + 0.044715f * x * x * x); return x * __builtin_amdgcn_rcpf(1.f + __expf(-u)); }
; DEV void p5_pre(const Params& P, int p) {
;     ...
;       for (int i = 0; i < 32; ++i) {
;         Ha = __expf(bflo(lv[i])) * Ha + bflo(uv[i]); Hb = __expf(bfhi(lv[i])) * Hb + bfhi(uv[i]);
;         *(unsigned*)(y + (size_t)(m0 + tb + i) * DM + ch) = pk2(Ha * gelu_tanh(bflo(gv[i])), Hb * gelu_tanh(bfhi(gv[i])));
;       }
	v_pk_mul_f32 v[10:11], v[6:7], v[10:11]
	v_lshlrev_b32_e32 v88, 16, v104
	v_cvt_pk_bf16_f32 v85, v10, v11
	v_lshl_add_u64 v[10:11], v[4:5], 0, s[60:61]
	flat_store_dword v[10:11], v85
	v_lshlrev_b32_e32 v10, 16, v102
	v_and_b32_e32 v11, 0xffff0000, v102
	v_mul_f32_e32 v10, 0x3fb8aa3b, v10
	v_mul_f32_e32 v11, 0x3fb8aa3b, v11
	v_exp_f32_e32 v10, v10
	v_exp_f32_e32 v11, v11
	v_and_b32_e32 v89, 0xffff0000, v104
	v_mov_b32_e32 v85, v89
	v_pk_fma_f32 v[6:7], v[6:7], v[10:11], v[86:87]
	v_mul_f32_e32 v10, 0x3d372713, v88
	v_mul_f32_e32 v10, v10, v88
	v_mov_b32_e32 v11, v88
	v_fmac_f32_e32 v11, v10, v11
	v_mul_f32_e32 v10, 0xbfcc422a, v11
	v_mul_f32_e32 v11, 0x3d372713, v89
	v_mul_f32_e32 v11, v11, v89
	v_fmac_f32_e32 v85, v11, v85
	v_mul_f32_e32 v11, 0xbfcc422a, v85
	v_mul_f32_e32 v10, 0x3fb8aa3b, v10
	v_mul_f32_e32 v11, 0x3fb8aa3b, v11
	v_exp_f32_e32 v10, v10
	v_exp_f32_e32 v11, v11
	v_lshlrev_b32_e32 v86, 16, v106
	v_and_b32_e32 v87, 0xffff0000, v106
	v_add_f32_e32 v10, 1.0, v10
	v_add_f32_e32 v11, 1.0, v11
	v_rcp_f32_e32 v10, v10
	v_rcp_f32_e32 v11, v11
	s_nop 0
	v_pk_mul_f32 v[10:11], v[10:11], v[88:89]
	s_nop 0
	v_pk_mul_f32 v[10:11], v[6:7], v[10:11]
	v_lshlrev_b32_e32 v88, 16, v107
	v_cvt_pk_bf16_f32 v85, v10, v11
	v_lshl_add_u64 v[10:11], v[4:5], 0, s[58:59]
	flat_store_dword v[10:11], v85
	v_lshlrev_b32_e32 v10, 16, v105
	v_and_b32_e32 v11, 0xffff0000, v105
	v_mul_f32_e32 v10, 0x3fb8aa3b, v10
	v_mul_f32_e32 v11, 0x3fb8aa3b, v11
	v_exp_f32_e32 v10, v10
	v_exp_f32_e32 v11, v11
	v_and_b32_e32 v89, 0xffff0000, v107
	v_mov_b32_e32 v85, v89
	v_pk_fma_f32 v[6:7], v[6:7], v[10:11], v[86:87]
	v_mul_f32_e32 v10, 0x3d372713, v88
	v_mul_f32_e32 v10, v10, v88
	v_mov_b32_e32 v11, v88
	v_fmac_f32_e32 v11, v10, v11
	v_mul_f32_e32 v10, 0xbfcc422a, v11
	v_mul_f32_e32 v11, 0x3d372713, v89
	v_mul_f32_e32 v11, v11, v89
	v_fmac_f32_e32 v85, v11, v85
	v_mul_f32_e32 v11, 0xbfcc422a, v85
	v_mul_f32_e32 v10, 0x3fb8aa3b, v10
	v_mul_f32_e32 v11, 0x3fb8aa3b, v11
	v_exp_f32_e32 v10, v10
	v_exp_f32_e32 v11, v11
	v_lshlrev_b32_e32 v86, 16, v82
	v_and_b32_e32 v87, 0xffff0000, v82
	v_add_f32_e32 v10, 1.0, v10
	v_add_f32_e32 v11, 1.0, v11
	v_rcp_f32_e32 v10, v10
	v_rcp_f32_e32 v11, v11
	v_lshlrev_b32_e32 v82, 16, v84
	v_pk_mul_f32 v[10:11], v[10:11], v[88:89]
	s_nop 0
	v_pk_mul_f32 v[10:11], v[6:7], v[10:11]
	s_nop 0
	v_cvt_pk_bf16_f32 v85, v10, v11
	v_lshl_add_u64 v[10:11], v[4:5], 0, s[56:57]
	flat_store_dword v[10:11], v85
	v_lshlrev_b32_e32 v10, 16, v83
	v_and_b32_e32 v11, 0xffff0000, v83
	v_mul_f32_e32 v10, 0x3fb8aa3b, v10
	v_mul_f32_e32 v11, 0x3fb8aa3b, v11
	v_exp_f32_e32 v10, v10
	v_exp_f32_e32 v11, v11
	v_and_b32_e32 v83, 0xffff0000, v84
	v_mov_b32_e32 v84, v83
	v_pk_fma_f32 v[6:7], v[6:7], v[10:11], v[86:87]
	v_mul_f32_e32 v10, 0x3d372713, v82
	v_mul_f32_e32 v10, v10, v82
	v_mov_b32_e32 v11, v82
	v_fmac_f32_e32 v11, v10, v11
	v_mul_f32_e32 v10, 0xbfcc422a, v11
	v_mul_f32_e32 v11, 0x3d372713, v83
	v_mul_f32_e32 v11, v11, v83
	v_fmac_f32_e32 v84, v11, v84
	v_mul_f32_e32 v11, 0xbfcc422a, v84
	v_mul_f32_e32 v10, 0x3fb8aa3b, v10
	v_mul_f32_e32 v11, 0x3fb8aa3b, v11
	v_exp_f32_e32 v10, v10
	v_exp_f32_e32 v11, v11
	v_add_f32_e32 v10, 1.0, v10
	v_add_f32_e32 v11, 1.0, v11
	v_rcp_f32_e32 v10, v10
	v_rcp_f32_e32 v11, v11
	s_nop 0
	v_pk_mul_f32 v[10:11], v[10:11], v[82:83]
	s_nop 0
	v_pk_mul_f32 v[10:11], v[6:7], v[10:11]
	v_and_b32_e32 v83, 0xffff0000, v80
	v_cvt_pk_bf16_f32 v82, v10, v11
	v_lshl_add_u64 v[10:11], v[4:5], 0, s[54:55]
	flat_store_dword v[10:11], v82
	v_lshlrev_b32_e32 v10, 16, v79
	v_and_b32_e32 v11, 0xffff0000, v79
	v_mul_f32_e32 v10, 0x3fb8aa3b, v10
	v_mul_f32_e32 v11, 0x3fb8aa3b, v11
	v_exp_f32_e32 v10, v10
	v_exp_f32_e32 v11, v11
	v_lshlrev_b32_e32 v82, 16, v80
	v_lshlrev_b32_e32 v80, 16, v81
	v_and_b32_e32 v81, 0xffff0000, v81
	v_pk_fma_f32 v[6:7], v[6:7], v[10:11], v[82:83]
	v_mul_f32_e32 v10, 0x3d372713, v80
	v_mul_f32_e32 v10, v10, v80
	v_mov_b32_e32 v11, v80
	v_fmac_f32_e32 v11, v10, v11
	v_mul_f32_e32 v10, 0xbfcc422a, v11
	v_mul_f32_e32 v11, 0x3d372713, v81
	v_mul_f32_e32 v11, v11, v81
	v_mov_b32_e32 v79, v81
	v_fmac_f32_e32 v79, v11, v79
	v_mul_f32_e32 v11, 0xbfcc422a, v79
	v_mul_f32_e32 v10, 0x3fb8aa3b, v10
	v_mul_f32_e32 v11, 0x3fb8aa3b, v11
	v_exp_f32_e32 v10, v10
	v_exp_f32_e32 v11, v11
	v_add_f32_e32 v10, 1.0, v10
	v_add_f32_e32 v11, 1.0, v11
	v_rcp_f32_e32 v10, v10
	v_rcp_f32_e32 v11, v11
	s_nop 0
	v_pk_mul_f32 v[10:11], v[10:11], v[80:81]
	s_nop 0
	v_pk_mul_f32 v[10:11], v[6:7], v[10:11]
	v_lshlrev_b32_e32 v80, 16, v76
	v_cvt_pk_bf16_f32 v79, v10, v11
	v_lshl_add_u64 v[10:11], v[4:5], 0, s[52:53]
	flat_store_dword v[10:11], v79
	v_lshlrev_b32_e32 v10, 16, v77
	v_and_b32_e32 v11, 0xffff0000, v77
	v_mul_f32_e32 v10, 0x3fb8aa3b, v10
	v_mul_f32_e32 v11, 0x3fb8aa3b, v11
	v_exp_f32_e32 v10, v10
	v_exp_f32_e32 v11, v11
	v_and_b32_e32 v81, 0xffff0000, v76
	v_lshlrev_b32_e32 v76, 16, v78
	v_and_b32_e32 v77, 0xffff0000, v78
	v_pk_fma_f32 v[6:7], v[6:7], v[10:11], v[80:81]
	v_mul_f32_e32 v10, 0x3d372713, v76
	v_mul_f32_e32 v10, v10, v76
	v_mov_b32_e32 v11, v76
	v_fmac_f32_e32 v11, v10, v11
	v_mul_f32_e32 v10, 0xbfcc422a, v11
	v_mul_f32_e32 v11, 0x3d372713, v77
	v_mul_f32_e32 v11, v11, v77
	v_mov_b32_e32 v78, v77
	v_fmac_f32_e32 v78, v11, v78
	v_mul_f32_e32 v11, 0xbfcc422a, v78
	v_mul_f32_e32 v10, 0x3fb8aa3b, v10
	v_mul_f32_e32 v11, 0x3fb8aa3b, v11
	v_exp_f32_e32 v10, v10
	v_exp_f32_e32 v11, v11
	v_add_f32_e32 v10, 1.0, v10
	v_add_f32_e32 v11, 1.0, v11
	v_rcp_f32_e32 v10, v10
	v_rcp_f32_e32 v11, v11
	s_nop 0
	v_pk_mul_f32 v[10:11], v[10:11], v[76:77]
	s_nop 0
	v_pk_mul_f32 v[10:11], v[6:7], v[10:11]
	v_and_b32_e32 v77, 0xffff0000, v74
; DEV unsigned pk2(float lo, float hi) { f32x2_t v = {lo, hi}; bf16x2_t b = __builtin_convertvector(v, bf16x2_t); return __builtin_bit_cast(unsigned, b); }
; DEV float bflo(unsigned u) { return __uint_as_float(u << 16); }
; DEV float bfhi(unsigned u) { return __uint_as_float(u & 0xffff0000u); }
; DEV float gelu_tanh(float x) { const float u = 1.5957691216057308f * (x + 0.044715f * x * x * x); return x * __builtin_amdgcn_rcpf(1.f + __expf(-u)); }
; DEV void p5_pre(const Params& P, int p) {
;     ...
;       for (int i = 0; i < 32; ++i) {
;         Ha = __expf(bflo(lv[i])) * Ha + bflo(uv[i]); Hb = __expf(bfhi(lv[i])) * Hb + bfhi(uv[i]);
;         *(unsigned*)(y + (size_t)(m0 + tb + i) * DM + ch) = pk2(Ha * gelu_tanh(bflo(gv[i])), Hb * gelu_tanh(bfhi(gv[i])));
;       }
	v_cvt_pk_bf16_f32 v76, v10, v11
	v_lshl_add_u64 v[10:11], v[4:5], 0, s[50:51]
	flat_store_dword v[10:11], v76
	v_lshlrev_b32_e32 v10, 16, v73
	v_and_b32_e32 v11, 0xffff0000, v73
	v_mul_f32_e32 v10, 0x3fb8aa3b, v10
	v_mul_f32_e32 v11, 0x3fb8aa3b, v11
	v_exp_f32_e32 v10, v10
	v_exp_f32_e32 v11, v11
	v_lshlrev_b32_e32 v76, 16, v74
	v_lshlrev_b32_e32 v74, 16, v75
	v_and_b32_e32 v75, 0xffff0000, v75
	v_pk_fma_f32 v[6:7], v[6:7], v[10:11], v[76:77]
	v_mul_f32_e32 v10, 0x3d372713, v74
	v_mul_f32_e32 v10, v10, v74
	v_mov_b32_e32 v11, v74
	v_fmac_f32_e32 v11, v10, v11
	v_mul_f32_e32 v10, 0xbfcc422a, v11
	v_mul_f32_e32 v11, 0x3d372713, v75
	v_mul_f32_e32 v11, v11, v75
	v_mov_b32_e32 v73, v75
	v_fmac_f32_e32 v73, v11, v73
	v_mul_f32_e32 v11, 0xbfcc422a, v73
	v_mul_f32_e32 v10, 0x3fb8aa3b, v10
	v_mul_f32_e32 v11, 0x3fb8aa3b, v11
	v_exp_f32_e32 v10, v10
	v_exp_f32_e32 v11, v11
	v_add_f32_e32 v10, 1.0, v10
	v_add_f32_e32 v11, 1.0, v11
	v_rcp_f32_e32 v10, v10
	v_rcp_f32_e32 v11, v11
	s_nop 0
	v_pk_mul_f32 v[10:11], v[10:11], v[74:75]
	s_nop 0
	v_pk_mul_f32 v[10:11], v[6:7], v[10:11]
	v_lshlrev_b32_e32 v74, 16, v70
	v_cvt_pk_bf16_f32 v73, v10, v11
	v_lshl_add_u64 v[10:11], v[4:5], 0, s[48:49]
	flat_store_dword v[10:11], v73
	v_lshlrev_b32_e32 v10, 16, v71
	v_and_b32_e32 v11, 0xffff0000, v71
	v_mul_f32_e32 v10, 0x3fb8aa3b, v10
	v_mul_f32_e32 v11, 0x3fb8aa3b, v11
	v_exp_f32_e32 v10, v10
	v_exp_f32_e32 v11, v11
	v_and_b32_e32 v75, 0xffff0000, v70
	v_lshlrev_b32_e32 v70, 16, v72
	v_and_b32_e32 v71, 0xffff0000, v72
	v_pk_fma_f32 v[6:7], v[6:7], v[10:11], v[74:75]
	v_mul_f32_e32 v10, 0x3d372713, v70
	v_mul_f32_e32 v10, v10, v70
	v_mov_b32_e32 v11, v70
	v_fmac_f32_e32 v11, v10, v11
	v_mul_f32_e32 v10, 0xbfcc422a, v11
	v_mul_f32_e32 v11, 0x3d372713, v71
	v_mul_f32_e32 v11, v11, v71
	v_mov_b32_e32 v72, v71
	v_fmac_f32_e32 v72, v11, v72
	v_mul_f32_e32 v11, 0xbfcc422a, v72
	v_mul_f32_e32 v10, 0x3fb8aa3b, v10
	v_mul_f32_e32 v11, 0x3fb8aa3b, v11
	v_exp_f32_e32 v10, v10
	v_exp_f32_e32 v11, v11
	v_add_f32_e32 v10, 1.0, v10
	v_add_f32_e32 v11, 1.0, v11
	v_rcp_f32_e32 v10, v10
	v_rcp_f32_e32 v11, v11
	s_nop 0
	v_pk_mul_f32 v[10:11], v[10:11], v[70:71]
	s_nop 0
	v_pk_mul_f32 v[10:11], v[6:7], v[10:11]
	v_and_b32_e32 v71, 0xffff0000, v68
	v_cvt_pk_bf16_f32 v70, v10, v11
	v_lshl_add_u64 v[10:11], v[4:5], 0, s[46:47]
	flat_store_dword v[10:11], v70
	v_lshlrev_b32_e32 v10, 16, v67
	v_and_b32_e32 v11, 0xffff0000, v67
	v_mul_f32_e32 v10, 0x3fb8aa3b, v10
	v_mul_f32_e32 v11, 0x3fb8aa3b, v11
	v_exp_f32_e32 v10, v10
	v_exp_f32_e32 v11, v11
	v_lshlrev_b32_e32 v70, 16, v68
	v_lshlrev_b32_e32 v68, 16, v69
	v_and_b32_e32 v69, 0xffff0000, v69
	v_pk_fma_f32 v[6:7], v[6:7], v[10:11], v[70:71]
	v_mul_f32_e32 v10, 0x3d372713, v68
	v_mul_f32_e32 v10, v10, v68
	v_mov_b32_e32 v11, v68
	v_fmac_f32_e32 v11, v10, v11
	v_mul_f32_e32 v10, 0xbfcc422a, v11
	v_mul_f32_e32 v11, 0x3d372713, v69
	v_mul_f32_e32 v11, v11, v69
	v_mov_b32_e32 v67, v69
	v_fmac_f32_e32 v67, v11, v67
	v_mul_f32_e32 v11, 0xbfcc422a, v67
	v_mul_f32_e32 v10, 0x3fb8aa3b, v10
	v_mul_f32_e32 v11, 0x3fb8aa3b, v11
	v_exp_f32_e32 v10, v10
	v_exp_f32_e32 v11, v11
	v_add_f32_e32 v10, 1.0, v10
	v_add_f32_e32 v11, 1.0, v11
	v_rcp_f32_e32 v10, v10
	v_rcp_f32_e32 v11, v11
	s_nop 0
	v_pk_mul_f32 v[10:11], v[10:11], v[68:69]
	s_nop 0
	v_pk_mul_f32 v[10:11], v[6:7], v[10:11]
	v_lshlrev_b32_e32 v68, 16, v64
	v_cvt_pk_bf16_f32 v67, v10, v11
	v_lshl_add_u64 v[10:11], v[4:5], 0, s[44:45]
	flat_store_dword v[10:11], v67
	v_lshlrev_b32_e32 v10, 16, v65
	v_and_b32_e32 v11, 0xffff0000, v65
	v_mul_f32_e32 v10, 0x3fb8aa3b, v10
	v_mul_f32_e32 v11, 0x3fb8aa3b, v11
	v_exp_f32_e32 v10, v10
	v_exp_f32_e32 v11, v11
	v_and_b32_e32 v69, 0xffff0000, v64
	v_lshlrev_b32_e32 v64, 16, v66
	v_and_b32_e32 v65, 0xffff0000, v66
	v_pk_fma_f32 v[6:7], v[6:7], v[10:11], v[68:69]
	v_mul_f32_e32 v10, 0x3d372713, v64
	v_mul_f32_e32 v10, v10, v64
	v_mov_b32_e32 v11, v64
	v_fmac_f32_e32 v11, v10, v11
	v_mul_f32_e32 v10, 0xbfcc422a, v11
	v_mul_f32_e32 v11, 0x3d372713, v65
	v_mul_f32_e32 v11, v11, v65
	v_mov_b32_e32 v66, v65
	v_fmac_f32_e32 v66, v11, v66
	v_mul_f32_e32 v11, 0xbfcc422a, v66
	v_mul_f32_e32 v10, 0x3fb8aa3b, v10
	v_mul_f32_e32 v11, 0x3fb8aa3b, v11
	v_exp_f32_e32 v10, v10
	v_exp_f32_e32 v11, v11
	v_add_f32_e32 v10, 1.0, v10
	v_add_f32_e32 v11, 1.0, v11
	v_rcp_f32_e32 v10, v10
	v_rcp_f32_e32 v11, v11
	s_nop 0
	v_pk_mul_f32 v[10:11], v[10:11], v[64:65]
	s_nop 0
	v_pk_mul_f32 v[10:11], v[6:7], v[10:11]
	v_and_b32_e32 v65, 0xffff0000, v62
	v_cvt_pk_bf16_f32 v64, v10, v11
	v_lshl_add_u64 v[10:11], v[4:5], 0, s[42:43]
	flat_store_dword v[10:11], v64
	v_lshlrev_b32_e32 v10, 16, v61
	v_and_b32_e32 v11, 0xffff0000, v61
	v_mul_f32_e32 v10, 0x3fb8aa3b, v10
	v_mul_f32_e32 v11, 0x3fb8aa3b, v11
	v_exp_f32_e32 v10, v10
	v_exp_f32_e32 v11, v11
	v_lshlrev_b32_e32 v64, 16, v62
	v_lshlrev_b32_e32 v62, 16, v63
	v_and_b32_e32 v63, 0xffff0000, v63
	v_pk_fma_f32 v[6:7], v[6:7], v[10:11], v[64:65]
	v_mul_f32_e32 v10, 0x3d372713, v62
	v_mul_f32_e32 v10, v10, v62
	v_mov_b32_e32 v11, v62
	v_fmac_f32_e32 v11, v10, v11
	v_mul_f32_e32 v10, 0xbfcc422a, v11
	v_mul_f32_e32 v11, 0x3d372713, v63
	v_mul_f32_e32 v11, v11, v63
	v_mov_b32_e32 v61, v63
	v_fmac_f32_e32 v61, v11, v61
	v_mul_f32_e32 v11, 0xbfcc422a, v61
	v_mul_f32_e32 v10, 0x3fb8aa3b, v10
	v_mul_f32_e32 v11, 0x3fb8aa3b, v11
	v_exp_f32_e32 v10, v10
	v_exp_f32_e32 v11, v11
	v_add_f32_e32 v10, 1.0, v10
	v_add_f32_e32 v11, 1.0, v11
	v_rcp_f32_e32 v10, v10
	v_rcp_f32_e32 v11, v11
	s_nop 0
	v_pk_mul_f32 v[10:11], v[10:11], v[62:63]
	s_nop 0
	v_pk_mul_f32 v[10:11], v[6:7], v[10:11]
	v_lshlrev_b32_e32 v62, 16, v58
	v_cvt_pk_bf16_f32 v61, v10, v11
; DEV unsigned pk2(float lo, float hi) { f32x2_t v = {lo, hi}; bf16x2_t b = __builtin_convertvector(v, bf16x2_t); return __builtin_bit_cast(unsigned, b); }
; DEV float bflo(unsigned u) { return __uint_as_float(u << 16); }
; DEV float bfhi(unsigned u) { return __uint_as_float(u & 0xffff0000u); }
; DEV float gelu_tanh(float x) { const float u = 1.5957691216057308f * (x + 0.044715f * x * x * x); return x * __builtin_amdgcn_rcpf(1.f + __expf(-u)); }
; DEV void p5_pre(const Params& P, int p) {
;     ...
;       for (int i = 0; i < 32; ++i) {
;         Ha = __expf(bflo(lv[i])) * Ha + bflo(uv[i]); Hb = __expf(bfhi(lv[i])) * Hb + bfhi(uv[i]);
;         *(unsigned*)(y + (size_t)(m0 + tb + i) * DM + ch) = pk2(Ha * gelu_tanh(bflo(gv[i])), Hb * gelu_tanh(bfhi(gv[i])));
;       }
	v_lshl_add_u64 v[10:11], v[4:5], 0, s[40:41]
	flat_store_dword v[10:11], v61
	v_lshlrev_b32_e32 v10, 16, v59
	v_and_b32_e32 v11, 0xffff0000, v59
	v_mul_f32_e32 v10, 0x3fb8aa3b, v10
	v_mul_f32_e32 v11, 0x3fb8aa3b, v11
	v_exp_f32_e32 v10, v10
	v_exp_f32_e32 v11, v11
	v_and_b32_e32 v63, 0xffff0000, v58
	v_lshlrev_b32_e32 v58, 16, v60
	v_and_b32_e32 v59, 0xffff0000, v60
	v_pk_fma_f32 v[6:7], v[6:7], v[10:11], v[62:63]
	v_mul_f32_e32 v10, 0x3d372713, v58
	v_mul_f32_e32 v10, v10, v58
	v_mov_b32_e32 v11, v58
	v_fmac_f32_e32 v11, v10, v11
	v_mul_f32_e32 v10, 0xbfcc422a, v11
	v_mul_f32_e32 v11, 0x3d372713, v59
	v_mul_f32_e32 v11, v11, v59
	v_mov_b32_e32 v60, v59
	v_fmac_f32_e32 v60, v11, v60
	v_mul_f32_e32 v11, 0xbfcc422a, v60
	v_mul_f32_e32 v10, 0x3fb8aa3b, v10
	v_mul_f32_e32 v11, 0x3fb8aa3b, v11
	v_exp_f32_e32 v10, v10
	v_exp_f32_e32 v11, v11
	v_add_f32_e32 v10, 1.0, v10
	v_add_f32_e32 v11, 1.0, v11
	v_rcp_f32_e32 v10, v10
	v_rcp_f32_e32 v11, v11
	s_nop 0
	v_pk_mul_f32 v[10:11], v[10:11], v[58:59]
	s_nop 0
	v_pk_mul_f32 v[10:11], v[6:7], v[10:11]
	v_and_b32_e32 v59, 0xffff0000, v56
	v_cvt_pk_bf16_f32 v58, v10, v11
	v_lshl_add_u64 v[10:11], v[4:5], 0, s[38:39]
	flat_store_dword v[10:11], v58
	v_lshlrev_b32_e32 v10, 16, v55
	v_and_b32_e32 v11, 0xffff0000, v55
	v_mul_f32_e32 v10, 0x3fb8aa3b, v10
	v_mul_f32_e32 v11, 0x3fb8aa3b, v11
	v_exp_f32_e32 v10, v10
	v_exp_f32_e32 v11, v11
	v_lshlrev_b32_e32 v58, 16, v56
	v_lshlrev_b32_e32 v56, 16, v57
	v_and_b32_e32 v57, 0xffff0000, v57
	v_pk_fma_f32 v[6:7], v[6:7], v[10:11], v[58:59]
	v_mul_f32_e32 v10, 0x3d372713, v56
	v_mul_f32_e32 v10, v10, v56
	v_mov_b32_e32 v11, v56
	v_fmac_f32_e32 v11, v10, v11
	v_mul_f32_e32 v10, 0xbfcc422a, v11
	v_mul_f32_e32 v11, 0x3d372713, v57
	v_mul_f32_e32 v11, v11, v57
	v_mov_b32_e32 v55, v57
	v_fmac_f32_e32 v55, v11, v55
	v_mul_f32_e32 v11, 0xbfcc422a, v55
	v_mul_f32_e32 v10, 0x3fb8aa3b, v10
	v_mul_f32_e32 v11, 0x3fb8aa3b, v11
	v_exp_f32_e32 v10, v10
	v_exp_f32_e32 v11, v11
	v_add_f32_e32 v10, 1.0, v10
	v_add_f32_e32 v11, 1.0, v11
	v_rcp_f32_e32 v10, v10
	v_rcp_f32_e32 v11, v11
	s_nop 0
	v_pk_mul_f32 v[10:11], v[10:11], v[56:57]
	s_nop 0
	v_pk_mul_f32 v[10:11], v[6:7], v[10:11]
	v_lshlrev_b32_e32 v56, 16, v52
	v_cvt_pk_bf16_f32 v55, v10, v11
	v_lshl_add_u64 v[10:11], v[4:5], 0, s[36:37]
	flat_store_dword v[10:11], v55
	v_lshlrev_b32_e32 v10, 16, v53
	v_and_b32_e32 v11, 0xffff0000, v53
	v_mul_f32_e32 v10, 0x3fb8aa3b, v10
	v_mul_f32_e32 v11, 0x3fb8aa3b, v11
	v_exp_f32_e32 v10, v10
	v_exp_f32_e32 v11, v11
	v_and_b32_e32 v57, 0xffff0000, v52
	v_lshlrev_b32_e32 v52, 16, v54
	v_and_b32_e32 v53, 0xffff0000, v54
	v_pk_fma_f32 v[6:7], v[6:7], v[10:11], v[56:57]
	v_mul_f32_e32 v10, 0x3d372713, v52
	v_mul_f32_e32 v10, v10, v52
	v_mov_b32_e32 v11, v52
	v_fmac_f32_e32 v11, v10, v11
	v_mul_f32_e32 v10, 0xbfcc422a, v11
	v_mul_f32_e32 v11, 0x3d372713, v53
	v_mul_f32_e32 v11, v11, v53
	v_mov_b32_e32 v54, v53
	v_fmac_f32_e32 v54, v11, v54
	v_mul_f32_e32 v11, 0xbfcc422a, v54
	v_mul_f32_e32 v10, 0x3fb8aa3b, v10
	v_mul_f32_e32 v11, 0x3fb8aa3b, v11
	v_exp_f32_e32 v10, v10
	v_exp_f32_e32 v11, v11
	v_lshlrev_b32_e32 v54, 16, v9
	v_and_b32_e32 v55, 0xffff0000, v9
	v_add_f32_e32 v10, 1.0, v10
	v_add_f32_e32 v11, 1.0, v11
	v_rcp_f32_e32 v10, v10
	v_rcp_f32_e32 v11, v11
	s_nop 0
	v_pk_mul_f32 v[10:11], v[10:11], v[52:53]
	s_nop 0
	v_pk_mul_f32 v[10:11], v[6:7], v[10:11]
	v_and_b32_e32 v53, 0xffff0000, v50
	v_cvt_pk_bf16_f32 v52, v10, v11
	v_lshl_add_u64 v[10:11], v[4:5], 0, s[34:35]
	flat_store_dword v[10:11], v52
	v_lshlrev_b32_e32 v10, 16, v49
	v_and_b32_e32 v11, 0xffff0000, v49
	v_mul_f32_e32 v10, 0x3fb8aa3b, v10
	v_mul_f32_e32 v11, 0x3fb8aa3b, v11
	v_exp_f32_e32 v10, v10
	v_exp_f32_e32 v11, v11
	v_lshlrev_b32_e32 v52, 16, v50
	v_lshlrev_b32_e32 v50, 16, v51
	v_and_b32_e32 v51, 0xffff0000, v51
	v_pk_fma_f32 v[6:7], v[6:7], v[10:11], v[52:53]
	v_mul_f32_e32 v10, 0x3d372713, v50
	v_mul_f32_e32 v10, v10, v50
	v_mov_b32_e32 v11, v50
	v_fmac_f32_e32 v11, v10, v11
	v_mul_f32_e32 v10, 0xbfcc422a, v11
	v_mul_f32_e32 v11, 0x3d372713, v51
	v_mul_f32_e32 v11, v11, v51
	v_mov_b32_e32 v49, v51
	v_fmac_f32_e32 v49, v11, v49
	v_mul_f32_e32 v11, 0xbfcc422a, v49
	v_mul_f32_e32 v10, 0x3fb8aa3b, v10
	v_mul_f32_e32 v11, 0x3fb8aa3b, v11
	v_exp_f32_e32 v10, v10
	v_exp_f32_e32 v11, v11
	v_add_f32_e32 v10, 1.0, v10
	v_add_f32_e32 v11, 1.0, v11
	v_rcp_f32_e32 v10, v10
	v_rcp_f32_e32 v11, v11
	s_nop 0
	v_pk_mul_f32 v[10:11], v[10:11], v[50:51]
	s_nop 0
	v_pk_mul_f32 v[10:11], v[6:7], v[10:11]
	v_lshlrev_b32_e32 v50, 16, v46
	v_cvt_pk_bf16_f32 v49, v10, v11
	v_lshl_add_u64 v[10:11], v[4:5], 0, s[30:31]
	flat_store_dword v[10:11], v49
	v_lshlrev_b32_e32 v10, 16, v47
	v_and_b32_e32 v11, 0xffff0000, v47
	v_mul_f32_e32 v10, 0x3fb8aa3b, v10
	v_mul_f32_e32 v11, 0x3fb8aa3b, v11
	v_exp_f32_e32 v10, v10
	v_exp_f32_e32 v11, v11
	v_and_b32_e32 v51, 0xffff0000, v46
	v_lshlrev_b32_e32 v46, 16, v48
	v_and_b32_e32 v47, 0xffff0000, v48
	v_pk_fma_f32 v[6:7], v[6:7], v[10:11], v[50:51]
	v_mul_f32_e32 v10, 0x3d372713, v46
	v_mul_f32_e32 v10, v10, v46
	v_mov_b32_e32 v11, v46
	v_fmac_f32_e32 v11, v10, v11
	v_mul_f32_e32 v10, 0xbfcc422a, v11
	v_mul_f32_e32 v11, 0x3d372713, v47
	v_mul_f32_e32 v11, v11, v47
	v_mov_b32_e32 v48, v47
	v_fmac_f32_e32 v48, v11, v48
	v_mul_f32_e32 v11, 0xbfcc422a, v48
	v_mul_f32_e32 v10, 0x3fb8aa3b, v10
	v_mul_f32_e32 v11, 0x3fb8aa3b, v11
	v_exp_f32_e32 v10, v10
	v_exp_f32_e32 v11, v11
	v_lshlrev_b32_e32 v50, 16, v24
	v_and_b32_e32 v51, 0xffff0000, v24
	v_add_f32_e32 v10, 1.0, v10
	v_add_f32_e32 v11, 1.0, v11
	v_rcp_f32_e32 v10, v10
	v_rcp_f32_e32 v11, v11
	s_nop 0
	v_pk_mul_f32 v[10:11], v[10:11], v[46:47]
	s_nop 0
; DEV unsigned pk2(float lo, float hi) { f32x2_t v = {lo, hi}; bf16x2_t b = __builtin_convertvector(v, bf16x2_t); return __builtin_bit_cast(unsigned, b); }
; DEV float bflo(unsigned u) { return __uint_as_float(u << 16); }
; DEV float bfhi(unsigned u) { return __uint_as_float(u & 0xffff0000u); }
; DEV float gelu_tanh(float x) { const float u = 1.5957691216057308f * (x + 0.044715f * x * x * x); return x * __builtin_amdgcn_rcpf(1.f + __expf(-u)); }
; DEV void p5_pre(const Params& P, int p) {
;     ...
;       for (int i = 0; i < 32; ++i) {
;         Ha = __expf(bflo(lv[i])) * Ha + bflo(uv[i]); Hb = __expf(bfhi(lv[i])) * Hb + bfhi(uv[i]);
;         *(unsigned*)(y + (size_t)(m0 + tb + i) * DM + ch) = pk2(Ha * gelu_tanh(bflo(gv[i])), Hb * gelu_tanh(bfhi(gv[i])));
;       }
	v_pk_mul_f32 v[10:11], v[6:7], v[10:11]
	v_and_b32_e32 v47, 0xffff0000, v44
	v_cvt_pk_bf16_f32 v46, v10, v11
	v_lshl_add_u64 v[10:11], v[4:5], 0, s[28:29]
	flat_store_dword v[10:11], v46
	v_lshlrev_b32_e32 v10, 16, v43
	v_and_b32_e32 v11, 0xffff0000, v43
	v_mul_f32_e32 v10, 0x3fb8aa3b, v10
	v_mul_f32_e32 v11, 0x3fb8aa3b, v11
	v_exp_f32_e32 v10, v10
	v_exp_f32_e32 v11, v11
	v_lshlrev_b32_e32 v46, 16, v44
	v_lshlrev_b32_e32 v44, 16, v45
	v_and_b32_e32 v45, 0xffff0000, v45
	v_pk_fma_f32 v[6:7], v[6:7], v[10:11], v[46:47]
	v_mul_f32_e32 v10, 0x3d372713, v44
	v_mul_f32_e32 v10, v10, v44
	v_mov_b32_e32 v11, v44
	v_fmac_f32_e32 v11, v10, v11
	v_mul_f32_e32 v10, 0xbfcc422a, v11
	v_mul_f32_e32 v11, 0x3d372713, v45
	v_mul_f32_e32 v11, v11, v45
	v_mov_b32_e32 v43, v45
	v_fmac_f32_e32 v43, v11, v43
	v_mul_f32_e32 v11, 0xbfcc422a, v43
	v_mul_f32_e32 v10, 0x3fb8aa3b, v10
	v_mul_f32_e32 v11, 0x3fb8aa3b, v11
	v_exp_f32_e32 v10, v10
	v_exp_f32_e32 v11, v11
	v_lshlrev_b32_e32 v46, 16, v16
	v_and_b32_e32 v47, 0xffff0000, v16
	v_add_f32_e32 v10, 1.0, v10
	v_add_f32_e32 v11, 1.0, v11
	v_rcp_f32_e32 v10, v10
	v_rcp_f32_e32 v11, v11
	v_lshlrev_b32_e32 v16, 16, v23
	v_pk_mul_f32 v[10:11], v[10:11], v[44:45]
	s_nop 0
	v_pk_mul_f32 v[10:11], v[6:7], v[10:11]
	v_lshlrev_b32_e32 v44, 16, v40
	v_cvt_pk_bf16_f32 v43, v10, v11
	v_lshl_add_u64 v[10:11], v[4:5], 0, s[26:27]
	flat_store_dword v[10:11], v43
	v_lshlrev_b32_e32 v10, 16, v41
	v_and_b32_e32 v11, 0xffff0000, v41
	v_mul_f32_e32 v10, 0x3fb8aa3b, v10
	v_mul_f32_e32 v11, 0x3fb8aa3b, v11
	v_exp_f32_e32 v10, v10
	v_exp_f32_e32 v11, v11
	v_and_b32_e32 v45, 0xffff0000, v40
	v_lshlrev_b32_e32 v40, 16, v42
	v_and_b32_e32 v41, 0xffff0000, v42
	v_pk_fma_f32 v[6:7], v[6:7], v[10:11], v[44:45]
	v_mul_f32_e32 v10, 0x3d372713, v40
	v_mul_f32_e32 v10, v10, v40
	v_mov_b32_e32 v11, v40
	v_fmac_f32_e32 v11, v10, v11
	v_mul_f32_e32 v10, 0xbfcc422a, v11
	v_mul_f32_e32 v11, 0x3d372713, v41
	v_mul_f32_e32 v11, v11, v41
	v_mov_b32_e32 v42, v41
	v_fmac_f32_e32 v42, v11, v42
	v_mul_f32_e32 v11, 0xbfcc422a, v42
	v_mul_f32_e32 v10, 0x3fb8aa3b, v10
	v_mul_f32_e32 v11, 0x3fb8aa3b, v11
	v_exp_f32_e32 v10, v10
	v_exp_f32_e32 v11, v11
	v_lshl_add_u64 v[42:43], v[4:5], 0, s[8:9]
	v_add_f32_e32 v10, 1.0, v10
	v_add_f32_e32 v11, 1.0, v11
	v_rcp_f32_e32 v10, v10
	v_rcp_f32_e32 v11, v11
	s_nop 0
	v_pk_mul_f32 v[10:11], v[10:11], v[40:41]
	s_nop 0
	v_pk_mul_f32 v[10:11], v[6:7], v[10:11]
	v_and_b32_e32 v41, 0xffff0000, v38
	v_cvt_pk_bf16_f32 v40, v10, v11
	v_lshl_add_u64 v[10:11], v[4:5], 0, s[24:25]
	flat_store_dword v[10:11], v40
	v_lshlrev_b32_e32 v10, 16, v37
	v_and_b32_e32 v11, 0xffff0000, v37
	v_mul_f32_e32 v10, 0x3fb8aa3b, v10
	v_mul_f32_e32 v11, 0x3fb8aa3b, v11
	v_exp_f32_e32 v10, v10
	v_exp_f32_e32 v11, v11
	v_lshlrev_b32_e32 v40, 16, v38
	v_lshlrev_b32_e32 v38, 16, v39
	v_and_b32_e32 v39, 0xffff0000, v39
	v_pk_fma_f32 v[6:7], v[6:7], v[10:11], v[40:41]
	v_mul_f32_e32 v10, 0x3d372713, v38
	v_mul_f32_e32 v10, v10, v38
	v_mov_b32_e32 v11, v38
	v_fmac_f32_e32 v11, v10, v11
	v_mul_f32_e32 v10, 0xbfcc422a, v11
	v_mul_f32_e32 v11, 0x3d372713, v39
	v_mul_f32_e32 v11, v11, v39
	v_mov_b32_e32 v37, v39
	v_fmac_f32_e32 v37, v11, v37
	v_mul_f32_e32 v11, 0xbfcc422a, v37
	v_mul_f32_e32 v10, 0x3fb8aa3b, v10
	v_mul_f32_e32 v11, 0x3fb8aa3b, v11
	v_exp_f32_e32 v10, v10
	v_exp_f32_e32 v11, v11
	v_lshlrev_b32_e32 v40, 16, v25
	v_and_b32_e32 v41, 0xffff0000, v25
	v_add_f32_e32 v10, 1.0, v10
	v_add_f32_e32 v11, 1.0, v11
	v_rcp_f32_e32 v10, v10
	v_rcp_f32_e32 v11, v11
	v_lshl_add_u64 v[24:25], v[4:5], 0, s[14:15]
	v_pk_mul_f32 v[10:11], v[10:11], v[38:39]
	s_nop 0
	v_pk_mul_f32 v[10:11], v[6:7], v[10:11]
	v_lshlrev_b32_e32 v38, 16, v34
	v_cvt_pk_bf16_f32 v37, v10, v11
	v_lshl_add_u64 v[10:11], v[4:5], 0, s[22:23]
	flat_store_dword v[10:11], v37
	v_lshlrev_b32_e32 v10, 16, v35
	v_and_b32_e32 v11, 0xffff0000, v35
	v_mul_f32_e32 v10, 0x3fb8aa3b, v10
	v_mul_f32_e32 v11, 0x3fb8aa3b, v11
	v_exp_f32_e32 v10, v10
	v_exp_f32_e32 v11, v11
	v_and_b32_e32 v39, 0xffff0000, v34
	v_lshlrev_b32_e32 v34, 16, v36
	v_and_b32_e32 v35, 0xffff0000, v36
	v_pk_fma_f32 v[6:7], v[6:7], v[10:11], v[38:39]
	v_mul_f32_e32 v10, 0x3d372713, v34
	v_mul_f32_e32 v10, v10, v34
	v_mov_b32_e32 v11, v34
	v_fmac_f32_e32 v11, v10, v11
	v_mul_f32_e32 v10, 0xbfcc422a, v11
	v_mul_f32_e32 v11, 0x3d372713, v35
	v_mul_f32_e32 v11, v11, v35
	v_mov_b32_e32 v36, v35
	v_fmac_f32_e32 v36, v11, v36
	v_mul_f32_e32 v11, 0xbfcc422a, v36
	v_mul_f32_e32 v10, 0x3fb8aa3b, v10
	v_mul_f32_e32 v11, 0x3fb8aa3b, v11
	v_exp_f32_e32 v10, v10
	v_exp_f32_e32 v11, v11
	v_lshlrev_b32_e32 v36, 16, v18
	v_and_b32_e32 v37, 0xffff0000, v18
	v_add_f32_e32 v10, 1.0, v10
	v_add_f32_e32 v11, 1.0, v11
	v_rcp_f32_e32 v10, v10
	v_rcp_f32_e32 v11, v11
	v_lshl_add_u64 v[38:39], v[4:5], 0, s[12:13]
	v_lshlrev_b32_e32 v18, 16, v19
	v_and_b32_e32 v19, 0xffff0000, v19
	v_pk_mul_f32 v[10:11], v[10:11], v[34:35]
	v_and_b32_e32 v35, 0xffff0000, v32
	v_pk_mul_f32 v[10:11], v[6:7], v[10:11]
	s_nop 0
	v_cvt_pk_bf16_f32 v34, v10, v11
	v_lshl_add_u64 v[10:11], v[4:5], 0, s[20:21]
	flat_store_dword v[10:11], v34
	v_lshlrev_b32_e32 v10, 16, v31
	v_and_b32_e32 v11, 0xffff0000, v31
	v_mul_f32_e32 v10, 0x3fb8aa3b, v10
	v_mul_f32_e32 v11, 0x3fb8aa3b, v11
	v_exp_f32_e32 v10, v10
	v_exp_f32_e32 v11, v11
	v_lshlrev_b32_e32 v34, 16, v32
	v_lshlrev_b32_e32 v32, 16, v33
	v_and_b32_e32 v33, 0xffff0000, v33
	v_pk_fma_f32 v[6:7], v[6:7], v[10:11], v[34:35]
	v_mul_f32_e32 v10, 0x3d372713, v32
	v_mul_f32_e32 v10, v10, v32
	v_mov_b32_e32 v11, v32
	v_fmac_f32_e32 v11, v10, v11
	v_mul_f32_e32 v10, 0xbfcc422a, v11
	v_mul_f32_e32 v11, 0x3d372713, v33
	v_mul_f32_e32 v11, v11, v33
; DEV unsigned pk2(float lo, float hi) { f32x2_t v = {lo, hi}; bf16x2_t b = __builtin_convertvector(v, bf16x2_t); return __builtin_bit_cast(unsigned, b); }
; DEV float bflo(unsigned u) { return __uint_as_float(u << 16); }
; DEV float bfhi(unsigned u) { return __uint_as_float(u & 0xffff0000u); }
; DEV float gelu_tanh(float x) { const float u = 1.5957691216057308f * (x + 0.044715f * x * x * x); return x * __builtin_amdgcn_rcpf(1.f + __expf(-u)); }
; DEV void p5_pre(const Params& P, int p) {
;     ...
;       for (int i = 0; i < 32; ++i) {
;         Ha = __expf(bflo(lv[i])) * Ha + bflo(uv[i]); Hb = __expf(bfhi(lv[i])) * Hb + bfhi(uv[i]);
;         *(unsigned*)(y + (size_t)(m0 + tb + i) * DM + ch) = pk2(Ha * gelu_tanh(bflo(gv[i])), Hb * gelu_tanh(bfhi(gv[i])));
;       }
	v_mov_b32_e32 v31, v33
	v_fmac_f32_e32 v31, v11, v31
	v_mul_f32_e32 v11, 0xbfcc422a, v31
	v_mul_f32_e32 v10, 0x3fb8aa3b, v10
	v_mul_f32_e32 v11, 0x3fb8aa3b, v11
	v_exp_f32_e32 v10, v10
	v_exp_f32_e32 v11, v11
	v_add_f32_e32 v10, 1.0, v10
	v_add_f32_e32 v11, 1.0, v11
	v_rcp_f32_e32 v10, v10
	v_rcp_f32_e32 v11, v11
	s_nop 0
	v_pk_mul_f32 v[10:11], v[10:11], v[32:33]
	s_nop 0
	v_pk_mul_f32 v[10:11], v[6:7], v[10:11]
	v_lshlrev_b32_e32 v32, 16, v28
	v_cvt_pk_bf16_f32 v31, v10, v11
	v_lshl_add_u64 v[10:11], v[4:5], 0, s[18:19]
	flat_store_dword v[10:11], v31
	v_lshlrev_b32_e32 v10, 16, v29
	v_and_b32_e32 v11, 0xffff0000, v29
	v_mul_f32_e32 v10, 0x3fb8aa3b, v10
	v_mul_f32_e32 v11, 0x3fb8aa3b, v11
	v_exp_f32_e32 v10, v10
	v_exp_f32_e32 v11, v11
	v_and_b32_e32 v33, 0xffff0000, v28
	v_lshlrev_b32_e32 v28, 16, v30
	v_and_b32_e32 v29, 0xffff0000, v30
	v_pk_fma_f32 v[6:7], v[6:7], v[10:11], v[32:33]
	v_mul_f32_e32 v10, 0x3d372713, v28
	v_mul_f32_e32 v10, v10, v28
	v_mov_b32_e32 v11, v28
	v_fmac_f32_e32 v11, v10, v11
	v_mul_f32_e32 v10, 0xbfcc422a, v11
	v_mul_f32_e32 v11, 0x3d372713, v29
	v_mul_f32_e32 v11, v11, v29
	v_mov_b32_e32 v30, v29
	v_fmac_f32_e32 v30, v11, v30
	v_mul_f32_e32 v11, 0xbfcc422a, v30
	v_mul_f32_e32 v10, 0x3fb8aa3b, v10
	v_mul_f32_e32 v11, 0x3fb8aa3b, v11
	v_exp_f32_e32 v10, v10
	v_exp_f32_e32 v11, v11
	v_lshlrev_b32_e32 v30, 16, v21
	v_mul_f32_e32 v9, 0x3d372713, v30
	v_add_f32_e32 v10, 1.0, v10
	v_add_f32_e32 v11, 1.0, v11
	v_rcp_f32_e32 v10, v10
	v_rcp_f32_e32 v11, v11
	v_mul_f32_e32 v9, v9, v30
	v_and_b32_e32 v31, 0xffff0000, v21
	v_lshl_add_u64 v[32:33], v[4:5], 0, s[6:7]
	v_pk_mul_f32 v[10:11], v[10:11], v[28:29]
	v_and_b32_e32 v29, 0xffff0000, v14
	v_pk_mul_f32 v[10:11], v[6:7], v[10:11]
	v_lshlrev_b32_e32 v21, 16, v20
	v_cvt_pk_bf16_f32 v28, v10, v11
	v_lshl_add_u64 v[10:11], v[4:5], 0, s[10:11]
	flat_store_dword v[10:11], v28
	v_lshlrev_b32_e32 v10, 16, v12
	v_and_b32_e32 v11, 0xffff0000, v12
	v_mul_f32_e32 v10, 0x3fb8aa3b, v10
	v_mul_f32_e32 v11, 0x3fb8aa3b, v11
	v_exp_f32_e32 v10, v10
	v_exp_f32_e32 v11, v11
	v_lshlrev_b32_e32 v28, 16, v14
	v_lshlrev_b32_e32 v12, 16, v17
	v_and_b32_e32 v14, 0xffff0000, v17
	v_pk_fma_f32 v[6:7], v[6:7], v[10:11], v[28:29]
	v_mov_b32_e32 v10, v30
	v_fmac_f32_e32 v10, v9, v10
	v_mul_f32_e32 v9, 0xbfcc422a, v10
	v_mul_f32_e32 v9, 0x3fb8aa3b, v9
	v_exp_f32_e32 v9, v9
	v_mov_b32_e32 v11, v31
	v_mul_f32_e32 v12, 0x3fb8aa3b, v12
	v_mul_f32_e32 v14, 0x3fb8aa3b, v14
	v_add_f32_e32 v9, 1.0, v9
	v_rcp_f32_e32 v10, v9
	v_mul_f32_e32 v9, 0x3d372713, v31
	v_mul_f32_e32 v9, v9, v31
	v_fmac_f32_e32 v11, v9, v11
	v_mul_f32_e32 v9, 0xbfcc422a, v11
	v_mul_f32_e32 v9, 0x3fb8aa3b, v9
	v_exp_f32_e32 v9, v9
	v_exp_f32_e32 v34, v12
	v_exp_f32_e32 v35, v14
	v_lshlrev_b32_e32 v12, 16, v13
	v_add_f32_e32 v9, 1.0, v9
	v_rcp_f32_e32 v11, v9
	v_and_b32_e32 v13, 0xffff0000, v13
	v_lshlrev_b32_e32 v14, 16, v15
	v_and_b32_e32 v15, 0xffff0000, v15
	v_pk_mul_f32 v[10:11], v[10:11], v[30:31]
	v_mul_f32_e32 v14, 0x3fb8aa3b, v14
	v_pk_mul_f32 v[10:11], v[6:7], v[10:11]
	v_pk_fma_f32 v[6:7], v[6:7], v[34:35], v[12:13]
	v_cvt_pk_bf16_f32 v9, v10, v11
	flat_store_dword v[32:33], v9
	v_mul_f32_e32 v9, 0x3d372713, v36
	v_mul_f32_e32 v9, v9, v36
	v_mov_b32_e32 v10, v36
	v_fmac_f32_e32 v10, v9, v10
	v_mul_f32_e32 v9, 0xbfcc422a, v10
	v_mul_f32_e32 v9, 0x3fb8aa3b, v9
	v_exp_f32_e32 v9, v9
	v_mov_b32_e32 v11, v37
	v_mul_f32_e32 v15, 0x3fb8aa3b, v15
	v_exp_f32_e32 v14, v14
	v_add_f32_e32 v9, 1.0, v9
	v_rcp_f32_e32 v10, v9
	v_mul_f32_e32 v9, 0x3d372713, v37
	v_mul_f32_e32 v9, v9, v37
	v_fmac_f32_e32 v11, v9, v11
	v_mul_f32_e32 v9, 0xbfcc422a, v11
	v_mul_f32_e32 v9, 0x3fb8aa3b, v9
	v_exp_f32_e32 v9, v9
	v_exp_f32_e32 v15, v15
	v_lshlrev_b32_e32 v17, 16, v22
	v_mul_f32_e32 v17, 0x3fb8aa3b, v17
	v_add_f32_e32 v9, 1.0, v9
	v_rcp_f32_e32 v11, v9
	v_exp_f32_e32 v44, v17
	v_and_b32_e32 v17, 0xffff0000, v22
	v_mul_f32_e32 v17, 0x3fb8aa3b, v17
	v_pk_mul_f32 v[10:11], v[10:11], v[36:37]
	v_exp_f32_e32 v45, v17
	v_pk_mul_f32 v[10:11], v[6:7], v[10:11]
	v_pk_fma_f32 v[6:7], v[6:7], v[14:15], v[18:19]
	v_cvt_pk_bf16_f32 v9, v10, v11
	flat_store_dword v[38:39], v9
	v_mul_f32_e32 v9, 0x3d372713, v40
	v_mul_f32_e32 v9, v9, v40
	v_mov_b32_e32 v10, v40
	v_fmac_f32_e32 v10, v9, v10
	v_mul_f32_e32 v9, 0xbfcc422a, v10
	v_mul_f32_e32 v9, 0x3fb8aa3b, v9
	v_exp_f32_e32 v9, v9
	v_mov_b32_e32 v11, v41
	v_and_b32_e32 v17, 0xffff0000, v23
	v_and_b32_e32 v20, 0xffff0000, v20
	v_add_f32_e32 v9, 1.0, v9
	v_rcp_f32_e32 v10, v9
	v_mul_f32_e32 v9, 0x3d372713, v41
	v_mul_f32_e32 v9, v9, v41
	v_fmac_f32_e32 v11, v9, v11
	v_mul_f32_e32 v9, 0xbfcc422a, v11
	v_mul_f32_e32 v9, 0x3fb8aa3b, v9
	v_exp_f32_e32 v9, v9
	v_mul_f32_e32 v20, 0x3fb8aa3b, v20
	v_lshl_add_u64 v[22:23], v[4:5], 0, s[16:17]
	v_exp_f32_e32 v49, v20
	v_add_f32_e32 v9, 1.0, v9
	v_rcp_f32_e32 v11, v9
	v_lshlrev_b32_e32 v20, 16, v27
	v_mul_f32_e32 v21, 0x3fb8aa3b, v21
	v_exp_f32_e32 v48, v21
	v_pk_mul_f32 v[10:11], v[10:11], v[40:41]
	v_and_b32_e32 v21, 0xffff0000, v27
	v_pk_mul_f32 v[10:11], v[6:7], v[10:11]
	v_pk_fma_f32 v[6:7], v[6:7], v[44:45], v[46:47]
	v_cvt_pk_bf16_f32 v9, v10, v11
	flat_store_dword v[42:43], v9
	v_mul_f32_e32 v9, 0x3d372713, v16
	v_mul_f32_e32 v9, v9, v16
	v_mov_b32_e32 v10, v16
	v_fmac_f32_e32 v10, v9, v10
	v_mul_f32_e32 v9, 0xbfcc422a, v10
	v_mul_f32_e32 v9, 0x3fb8aa3b, v9
	v_exp_f32_e32 v9, v9
	v_mov_b32_e32 v11, v17
	v_lshlrev_b32_e32 v27, 16, v26
	v_and_b32_e32 v26, 0xffff0000, v26
	v_add_f32_e32 v9, 1.0, v9
	v_rcp_f32_e32 v10, v9
	v_mul_f32_e32 v9, 0x3d372713, v17
	v_mul_f32_e32 v9, v9, v17
	v_fmac_f32_e32 v11, v9, v11
	v_mul_f32_e32 v9, 0xbfcc422a, v11
	v_mul_f32_e32 v9, 0x3fb8aa3b, v9
	v_exp_f32_e32 v9, v9
	v_mul_f32_e32 v27, 0x3fb8aa3b, v27
	v_mul_f32_e32 v26, 0x3fb8aa3b, v26
	v_exp_f32_e32 v52, v27
	v_add_f32_e32 v9, 1.0, v9
	v_rcp_f32_e32 v11, v9
	v_exp_f32_e32 v53, v26
	v_pk_mul_f32 v[10:11], v[10:11], v[16:17]
	s_nop 0
	v_pk_mul_f32 v[10:11], v[6:7], v[10:11]
	v_pk_fma_f32 v[6:7], v[6:7], v[48:49], v[50:51]
	v_cvt_pk_bf16_f32 v9, v10, v11
	flat_store_dword v[22:23], v9
	v_mul_f32_e32 v9, 0x3d372713, v20
	v_mul_f32_e32 v9, v9, v20
	v_mov_b32_e32 v10, v20
	v_fmac_f32_e32 v10, v9, v10
	v_mul_f32_e32 v9, 0xbfcc422a, v10
	v_mul_f32_e32 v9, 0x3fb8aa3b, v9
	v_exp_f32_e32 v9, v9
	v_mov_b32_e32 v11, v21
	v_add_f32_e32 v9, 1.0, v9
	v_rcp_f32_e32 v10, v9
	v_mul_f32_e32 v9, 0x3d372713, v21
	v_mul_f32_e32 v9, v9, v21
	v_fmac_f32_e32 v11, v9, v11
	v_mul_f32_e32 v9, 0xbfcc422a, v11
	v_mul_f32_e32 v9, 0x3fb8aa3b, v9
	v_exp_f32_e32 v9, v9
	s_nop 0
	v_add_f32_e32 v9, 1.0, v9
	v_rcp_f32_e32 v11, v9
	s_nop 0
	v_pk_mul_f32 v[10:11], v[10:11], v[20:21]
	s_nop 0
	v_pk_mul_f32 v[10:11], v[6:7], v[10:11]
	v_pk_fma_f32 v[6:7], v[6:7], v[52:53], v[54:55]
	v_cvt_pk_bf16_f32 v9, v10, v11
	s_waitcnt vmcnt(0) lgkmcnt(0)
; DEV unsigned pk2(float lo, float hi) { f32x2_t v = {lo, hi}; bf16x2_t b = __builtin_convertvector(v, bf16x2_t); return __builtin_bit_cast(unsigned, b); }
; DEV float bflo(unsigned u) { return __uint_as_float(u << 16); }
; DEV float bfhi(unsigned u) { return __uint_as_float(u & 0xffff0000u); }
; DEV int tid_l() { int t = threadIdx.x; asm volatile("" : "+v"(t)); return t; }
; DEV float gelu_tanh(float x) { const float u = 1.5957691216057308f * (x + 0.044715f * x * x * x); return x * __builtin_amdgcn_rcpf(1.f + __expf(-u)); }
; DEV int stage_next(int s) { return (s == 2 * GS_STAGE) ? 0 : s + GS_STAGE; }
; DEV void gk_issue2(const GTile& t, int s0) {
;   const int tid = tid_l(), lane = tid & 63, wid = __builtin_amdgcn_readfirstlane(tid >> 6);
;   GK_SRC(t)
;   asm volatile("" ::: "memory");
;   GK_DMA(s0, 0);
;   GK_DMA(stage_next(s0), 1);
;   asm volatile("" ::: "memory");
; }
; DEV void p5_pre(const Params& P, int p) {
;     ...
;         *(unsigned*)(y + (size_t)(m0 + tb + i) * DM + ch) = pk2(Ha * gelu_tanh(bflo(gv[i])), Hb * gelu_tanh(bfhi(gv[i])));
;       }
	v_lshlrev_b32_e32 v10, 16, v233
	v_and_b32_e32 v11, 0xffff0000, v233
	v_mul_f32_e32 v8, 0x3d372713, v10
	flat_store_dword v[24:25], v9
	v_mul_f32_e32 v8, v8, v10
	v_mov_b32_e32 v9, v10
	v_fmac_f32_e32 v9, v8, v9
	v_mul_f32_e32 v8, 0xbfcc422a, v9
	v_mul_f32_e32 v9, 0x3d372713, v11
	v_mul_f32_e32 v9, v9, v11
	v_mov_b32_e32 v12, v11
	v_fmac_f32_e32 v12, v9, v12
	v_mul_f32_e32 v9, 0xbfcc422a, v12
	v_mul_f32_e32 v8, 0x3fb8aa3b, v8
	v_mul_f32_e32 v9, 0x3fb8aa3b, v9
	v_exp_f32_e32 v8, v8
	v_exp_f32_e32 v9, v9
	v_add_f32_e32 v8, 1.0, v8
	v_add_f32_e32 v9, 1.0, v9
	v_rcp_f32_e32 v8, v8
	v_rcp_f32_e32 v9, v9
	s_nop 0
	v_pk_mul_f32 v[8:9], v[8:9], v[10:11]
	s_nop 0
	v_pk_mul_f32 v[8:9], v[6:7], v[8:9]
	s_nop 0
	v_cvt_pk_bf16_f32 v10, v8, v9
	v_lshl_add_u64 v[8:9], v[4:5], 0, s[4:5]
	flat_store_dword v[8:9], v10
	s_cbranch_scc1 .LBB0_709
	s_ashr_i32 s75, s74, 31
	s_lshl_b64 s[2:3], s[74:75], 11
	s_lshl_b32 s92, s84, 7
	s_add_u32 s0, s80, 0x1100000
	s_addc_u32 s1, s81, 0
	s_ashr_i32 s93, s92, 31
	s_lshl_b64 s[4:5], s[92:93], 11
	v_mov_b32_e32 v2, v176
	s_waitcnt lgkmcnt(0)
	s_barrier
	s_barrier
	s_add_u32 s46, s76, s4
	s_addc_u32 s47, s77, s5
	v_readfirstlane_b32 s4, v2
	s_ashr_i32 s4, s4, 6
	v_bfe_u32 v0, v2, 3, 3
	v_lshl_or_b32 v0, s4, 3, v0
	v_lshrrev_b32_e32 v3, 1, v0
	v_xor_b32_e32 v2, v3, v2
	v_ashrrev_i32_e32 v1, 31, v0
	v_lshlrev_b32_e32 v2, 4, v2
	v_and_b32_e32 v120, 0x70, v2
	v_lshlrev_b64 v[0:1], 11, v[0:1]
	s_lshl_b32 s4, s4, 10
	v_or_b32_e32 v2, v0, v120
	v_mov_b32_e32 v3, v1
	s_add_i32 s4, s4, 0
	v_lshl_add_u64 v[4:5], s[46:47], 0, v[2:3]
	v_lshl_add_u64 v[6:7], v[2:3], 0, s[86:87]
	s_mov_b32 m0, s4
	v_lshl_add_u64 v[8:9], s[46:47], 0, v[6:7]
	global_load_lds_dwordx4 v[4:5], off
	s_add_i32 m0, s4, 0x2000
	v_lshl_add_u64 v[2:3], s[0:1], 0, v[2:3]
	v_lshl_add_u64 v[0:1], s[0:1], 0, v[0:1]
	global_load_lds_dwordx4 v[8:9], off
	s_add_i32 m0, s4, 0x4000
	v_lshl_add_u64 v[6:7], s[0:1], 0, v[6:7]
	v_lshl_add_u64 v[0:1], v[0:1], 0, v[120:121]
	s_mov_b64 s[22:23], 0x40000
	global_load_lds_dwordx4 v[2:3], off
	s_add_i32 m0, s4, 0x6000
	v_lshl_add_u64 v[10:11], v[0:1], 0, s[22:23]
	s_mov_b64 s[24:25], 0x60000
	global_load_lds_dwordx4 v[6:7], off
	s_add_i32 m0, s4, 0x8000
	v_lshl_add_u64 v[12:13], v[0:1], 0, s[24:25]
	global_load_lds_dwordx4 v[10:11], off
	s_add_i32 m0, s4, 0xa000
	v_lshl_add_u64 v[4:5], v[4:5], 0, s[94:95]
	global_load_lds_dwordx4 v[12:13], off
	s_add_i32 m0, s4, 0xc000
	v_lshl_add_u64 v[2:3], v[2:3], 0, s[94:95]
	global_load_lds_dwordx4 v[4:5], off
	v_lshl_add_u64 v[4:5], v[8:9], 0, s[94:95]
	s_add_i32 m0, s4, 0xe000
	s_mov_b64 s[30:31], 0x40080
	global_load_lds_dwordx4 v[4:5], off
	s_add_i32 m0, s4, 0x10000
	s_mov_b64 s[34:35], 0x60080
	global_load_lds_dwordx4 v[2:3], off
	v_lshl_add_u64 v[2:3], v[6:7], 0, s[94:95]
	s_add_i32 m0, s4, 0x12000
	v_readlane_b32 s28, v232, 21
	global_load_lds_dwordx4 v[2:3], off
	v_lshl_add_u64 v[2:3], v[0:1], 0, s[30:31]
	s_add_i32 m0, s4, 0x14000
	v_lshl_add_u64 v[0:1], v[0:1], 0, s[34:35]
	global_load_lds_dwordx4 v[2:3], off
	s_add_i32 m0, s4, 0x16000
	s_add_u32 s2, s80, s2
	global_load_lds_dwordx4 v[0:1], off
	s_addc_u32 s3, s81, s3
	s_add_u32 s8, s2, 0xcc00100
	s_addc_u32 s9, s3, 0
	s_mov_b32 s11, 0
	s_mov_b32 s12, 0
	s_mov_b64 s[4:5], s[0:1]
	s_mov_b32 s16, 0x10000
	s_mov_b32 s17, 0x18000
	s_movk_i32 s18, 0x1800
	s_mov_b32 s19, 0x20000
	s_mov_b32 s20, 0x28000
	s_mov_b32 s21, 0x30000
	s_mov_b32 s26, 0x38000
	v_readlane_b32 s29, v232, 22
	s_branch .LBB0_712
